# hyena input short-conv: the 96 two-byte loads per channel issued up front with two counted waits instead of ~15 dependent groups each closed by vmcnt(0)
# speedup vs baseline: 1.1086x; 1.0136x over previous
.LBB0_536:
	s_nop 1
	v_lshlrev_b32_e32 v0, 2, v146
	s_add_i32 s47, 16, 0x10000
	v_add_u32_e32 v64, 16, v0
	v_add_u32_e32 v65, s47, v0
	s_waitcnt lgkmcnt(0)
	s_barrier
	ds_read2st64_b32 v[2:3], v64 offset1:8
	ds_read2st64_b32 v[4:5], v65 offset1:8
	ds_read2st64_b32 v[8:9], v64 offset0:16 offset1:24
	ds_read2st64_b32 v[10:11], v65 offset0:16 offset1:24
	ds_read2st64_b32 v[12:13], v64 offset0:32 offset1:40
	ds_read2st64_b32 v[14:15], v65 offset0:32 offset1:40
	s_mov_b32 s49, s40
	s_waitcnt lgkmcnt(5)
	v_mov_b32_e32 v6, v2
	s_waitcnt lgkmcnt(4)
	v_mov_b32_e32 v7, v4
	v_mov_b32_e32 v4, v3
	s_waitcnt lgkmcnt(3)
	v_mov_b32_e32 v2, v8
	s_waitcnt lgkmcnt(2)
	v_mov_b32_e32 v3, v10
	v_mov_b32_e32 v10, v9
	ds_read2st64_b32 v[8:9], v64 offset0:48 offset1:56
	ds_read2st64_b32 v[16:17], v65 offset0:48 offset1:56
	s_waitcnt lgkmcnt(3)
	v_mov_b32_e32 v18, v12
	s_waitcnt lgkmcnt(2)
	v_mov_b32_e32 v19, v14
	v_mov_b32_e32 v14, v13
	s_waitcnt lgkmcnt(1)
	v_mov_b32_e32 v12, v8
	s_waitcnt lgkmcnt(0)
	v_mov_b32_e32 v13, v16
	ds_read2st64_b32 v[20:21], v64 offset0:64 offset1:72
	ds_read2st64_b32 v[22:23], v65 offset0:64 offset1:72
	v_mov_b32_e32 v16, v9
	ds_read2st64_b32 v[8:9], v64 offset0:80 offset1:88
	ds_read2st64_b32 v[24:25], v65 offset0:80 offset1:88
	s_mov_b32 s41, s45
	s_waitcnt lgkmcnt(3)
	v_mov_b32_e32 v26, v20
	s_waitcnt lgkmcnt(2)
	v_mov_b32_e32 v27, v22
	v_mov_b32_e32 v22, v21
	s_waitcnt lgkmcnt(1)
	v_mov_b32_e32 v28, v8
	s_waitcnt lgkmcnt(0)
	v_mov_b32_e32 v29, v24
	ds_read2st64_b32 v[20:21], v64 offset0:96 offset1:104
	ds_read2st64_b32 v[30:31], v65 offset0:96 offset1:104
	v_mov_b32_e32 v24, v9
	ds_read2st64_b32 v[8:9], v64 offset0:112 offset1:120
	ds_read2st64_b32 v[32:33], v65 offset0:112 offset1:120
	v_and_b32_e32 v196, 63, v146
	v_lshlrev_b32_e32 v196, 2, v196
	v_and_b32_e32 v0, 0xffffffc0, v146
	v_lshl_add_u32 v0, v0, 5, v196
	v_add_u32_e32 v0, 0x400, v0
	s_waitcnt lgkmcnt(3)
	v_mov_b32_e32 v34, v20
	s_waitcnt lgkmcnt(2)
	v_mov_b32_e32 v35, v30
	v_mov_b32_e32 v30, v21
	s_waitcnt lgkmcnt(1)
	v_mov_b32_e32 v36, v8
	s_waitcnt lgkmcnt(0)
	v_mov_b32_e32 v37, v32
	ds_read2st64_b32 v[20:21], v64 offset0:128 offset1:136
	ds_read2st64_b32 v[38:39], v65 offset0:128 offset1:136
	v_mov_b32_e32 v32, v9
	ds_read2st64_b32 v[8:9], v64 offset0:144 offset1:152
	ds_read2st64_b32 v[40:41], v65 offset0:144 offset1:152
	v_readlane_b32 s0, v252, 48
	s_waitcnt lgkmcnt(3)
	v_mov_b32_e32 v42, v20
	s_waitcnt lgkmcnt(2)
	v_mov_b32_e32 v43, v38
	v_mov_b32_e32 v38, v21
	s_waitcnt lgkmcnt(1)
	v_mov_b32_e32 v44, v8
	s_waitcnt lgkmcnt(0)
	v_mov_b32_e32 v45, v40
	ds_read2st64_b32 v[20:21], v64 offset0:160 offset1:168
	ds_read2st64_b32 v[46:47], v65 offset0:160 offset1:168
	v_mov_b32_e32 v40, v9
	ds_read2st64_b32 v[8:9], v64 offset0:176 offset1:184
	ds_read2st64_b32 v[48:49], v65 offset0:176 offset1:184
	v_ashrrev_i32_e32 v1, 31, v0
	s_waitcnt lgkmcnt(3)
	v_mov_b32_e32 v50, v20
	s_waitcnt lgkmcnt(2)
	v_mov_b32_e32 v51, v46
	v_mov_b32_e32 v46, v21
	s_waitcnt lgkmcnt(1)
	v_mov_b32_e32 v52, v8
	s_waitcnt lgkmcnt(0)
	v_mov_b32_e32 v53, v48
	ds_read2st64_b32 v[20:21], v64 offset0:192 offset1:200
	ds_read2st64_b32 v[54:55], v65 offset0:192 offset1:200
	v_mov_b32_e32 v48, v9
	ds_read2st64_b32 v[8:9], v64 offset0:208 offset1:216
	ds_read2st64_b32 v[56:57], v65 offset0:208 offset1:216
	v_readlane_b32 s1, v252, 49
	s_waitcnt lgkmcnt(3)
	v_mov_b32_e32 v58, v20
	s_waitcnt lgkmcnt(2)
	v_mov_b32_e32 v59, v54
	v_mov_b32_e32 v54, v21
	s_waitcnt lgkmcnt(1)
	v_mov_b32_e32 v60, v8
	s_waitcnt lgkmcnt(0)
	v_mov_b32_e32 v61, v56
	ds_read2st64_b32 v[20:21], v64 offset0:224 offset1:232
	ds_read2st64_b32 v[62:63], v65 offset0:224 offset1:232
	v_mov_b32_e32 v56, v9
	ds_read2st64_b32 v[8:9], v64 offset0:240 offset1:248
	ds_read2st64_b32 v[64:65], v65 offset0:240 offset1:248
	s_waitcnt lgkmcnt(0)
	v_mov_b32_e32 v66, v20
	v_mov_b32_e32 v67, v62
	v_mov_b32_e32 v72, v8
	v_mov_b32_e32 v73, v64
	v_mov_b32_e32 v64, v9
	v_pk_add_f32 v[8:9], v[6:7], v[42:43]
	v_pk_add_f32 v[6:7], v[6:7], v[42:43] neg_lo:[0,1] neg_hi:[0,1]
	v_pk_add_f32 v[42:43], v[4:5], v[38:39]
	v_pk_add_f32 v[4:5], v[4:5], v[38:39] neg_lo:[0,1] neg_hi:[0,1]
	v_mov_b32_e32 v62, v21
	v_xor_b32_e32 v39, 0x80000000, v4
	v_mov_b32_e32 v38, v5
	v_pk_mul_f32 v[38:39], v[38:39], s[58:59] op_sel_hi:[1,0]
	v_mov_b32_e32 v21, v146
	v_pk_fma_f32 v[4:5], v[4:5], s[46:47], v[38:39] op_sel_hi:[1,0,1]
	v_pk_add_f32 v[38:39], v[2:3], v[44:45]
	v_pk_add_f32 v[2:3], v[2:3], v[44:45] neg_lo:[0,1] neg_hi:[0,1]
	s_barrier
	v_xor_b32_e32 v45, 0x80000000, v2
	v_mov_b32_e32 v44, v3
	v_pk_mul_f32 v[44:45], v[44:45], s[62:63] op_sel_hi:[1,0]
	s_nop 0
	v_pk_fma_f32 v[2:3], v[2:3], s[60:61], v[44:45] op_sel_hi:[1,0,1]
	v_pk_add_f32 v[44:45], v[10:11], v[40:41]
	v_pk_add_f32 v[10:11], v[10:11], v[40:41] neg_lo:[0,1] neg_hi:[0,1]
	s_lshl_b64 s[10:11], s[68:69], 2
	v_xor_b32_e32 v41, 0x80000000, v10
	v_mov_b32_e32 v40, v11
	v_pk_mul_f32 v[40:41], v[40:41], s[66:67] op_sel_hi:[1,0]
	s_add_u32 s90, s54, s10
	v_pk_fma_f32 v[10:11], v[10:11], s[64:65], v[40:41] op_sel_hi:[1,0,1]
	v_pk_add_f32 v[40:41], v[18:19], v[50:51]
	v_pk_add_f32 v[18:19], v[18:19], v[50:51] neg_lo:[0,1] neg_hi:[0,1]
	s_addc_u32 s91, s55, s11
	v_xor_b32_e32 v51, 0x80000000, v18
	v_mov_b32_e32 v50, v19
	v_pk_mul_f32 v[50:51], v[50:51], s[70:71] op_sel_hi:[1,0]
	v_add_u32_e32 v70, 0x200, v146
	v_pk_fma_f32 v[18:19], v[18:19], s[70:71], v[50:51] op_sel_hi:[1,0,1]
	v_pk_add_f32 v[50:51], v[14:15], v[46:47]
	v_pk_add_f32 v[14:15], v[14:15], v[46:47] neg_lo:[0,1] neg_hi:[0,1]
	v_ashrrev_i32_e32 v147, 31, v146
	v_xor_b32_e32 v47, 0x80000000, v14
	v_mov_b32_e32 v46, v15
	v_pk_mul_f32 v[46:47], v[46:47], s[64:65] op_sel_hi:[1,0]
	v_add_u32_e32 v69, 0x400, v146
	v_pk_fma_f32 v[14:15], v[14:15], s[66:67], v[46:47] op_sel_hi:[1,0,1]
	v_pk_add_f32 v[46:47], v[12:13], v[52:53]
	v_pk_add_f32 v[12:13], v[12:13], v[52:53] neg_lo:[0,1] neg_hi:[0,1]
	v_add_u32_e32 v68, 0x600, v146
	v_xor_b32_e32 v53, 0x80000000, v12
	v_mov_b32_e32 v52, v13
	v_pk_mul_f32 v[52:53], v[52:53], s[60:61] op_sel_hi:[1,0]
	s_mov_b32 s16, 0
	v_pk_fma_f32 v[12:13], v[12:13], s[62:63], v[52:53] op_sel_hi:[1,0,1]
	v_pk_add_f32 v[52:53], v[16:17], v[48:49]
	v_pk_add_f32 v[16:17], v[16:17], v[48:49] neg_lo:[0,1] neg_hi:[0,1]
	s_nop 0
	v_xor_b32_e32 v49, 0x80000000, v16
	v_mov_b32_e32 v48, v17
	v_pk_mul_f32 v[48:49], v[48:49], s[46:47] op_sel_hi:[1,0]
	s_nop 0
	v_pk_fma_f32 v[16:17], v[16:17], s[58:59], v[48:49] op_sel_hi:[1,0,1]
	v_pk_add_f32 v[48:49], v[26:27], v[58:59]
	v_pk_add_f32 v[26:27], v[26:27], v[58:59] neg_lo:[0,1] neg_hi:[0,1]
	s_nop 0
	v_xor_b32_e32 v59, 0x80000000, v26
	v_mov_b32_e32 v58, v27
	v_pk_add_f32 v[26:27], v[22:23], v[54:55]
	v_pk_add_f32 v[22:23], v[22:23], v[54:55] neg_lo:[0,1] neg_hi:[0,1]
	s_nop 0
	v_pk_mul_f32 v[54:55], v[22:23], s[58:59] op_sel_hi:[1,0]
	v_xor_b32_e32 v75, 0x80000000, v22
	v_mov_b32_e32 v74, v23
	v_pk_fma_f32 v[22:23], v[74:75], s[46:47], v[54:55] op_sel_hi:[1,0,1] neg_lo:[0,0,1] neg_hi:[0,0,1]
	v_pk_add_f32 v[54:55], v[28:29], v[60:61]
	v_pk_add_f32 v[28:29], v[28:29], v[60:61] neg_lo:[0,1] neg_hi:[0,1]
	s_nop 0
	v_pk_mul_f32 v[60:61], v[28:29], s[62:63] op_sel_hi:[1,0]
	v_xor_b32_e32 v75, 0x80000000, v28
	v_mov_b32_e32 v74, v29
	v_pk_fma_f32 v[28:29], v[74:75], s[60:61], v[60:61] op_sel_hi:[1,0,1] neg_lo:[0,0,1] neg_hi:[0,0,1]
	v_pk_add_f32 v[60:61], v[24:25], v[56:57]
	v_pk_add_f32 v[24:25], v[24:25], v[56:57] neg_lo:[0,1] neg_hi:[0,1]
	s_nop 0
	v_pk_mul_f32 v[56:57], v[24:25], s[66:67] op_sel_hi:[1,0]
	v_xor_b32_e32 v75, 0x80000000, v24
	v_mov_b32_e32 v74, v25
	v_pk_fma_f32 v[24:25], v[74:75], s[64:65], v[56:57] op_sel_hi:[1,0,1] neg_lo:[0,0,1] neg_hi:[0,0,1]
	v_pk_add_f32 v[56:57], v[34:35], v[66:67]
	v_pk_add_f32 v[34:35], v[34:35], v[66:67] neg_lo:[0,1] neg_hi:[0,1]
	s_nop 0
	v_pk_mul_f32 v[66:67], v[34:35], s[70:71] op_sel_hi:[1,0]
	v_xor_b32_e32 v75, 0x80000000, v34
	v_mov_b32_e32 v74, v35
	v_pk_fma_f32 v[34:35], v[74:75], s[70:71], v[66:67] op_sel_hi:[1,0,1] neg_lo:[0,0,1] neg_hi:[0,0,1]
	v_pk_add_f32 v[66:67], v[30:31], v[62:63]
	v_pk_add_f32 v[30:31], v[30:31], v[62:63] neg_lo:[0,1] neg_hi:[0,1]
	s_nop 0
	v_pk_mul_f32 v[62:63], v[30:31], s[64:65] op_sel_hi:[1,0]
	v_xor_b32_e32 v75, 0x80000000, v30
	v_mov_b32_e32 v74, v31
	v_pk_fma_f32 v[30:31], v[74:75], s[66:67], v[62:63] op_sel_hi:[1,0,1] neg_lo:[0,0,1] neg_hi:[0,0,1]
	v_pk_add_f32 v[62:63], v[36:37], v[72:73]
	v_pk_add_f32 v[36:37], v[36:37], v[72:73] neg_lo:[0,1] neg_hi:[0,1]
	s_nop 0
	v_pk_mul_f32 v[72:73], v[36:37], s[60:61] op_sel_hi:[1,0]
	v_xor_b32_e32 v75, 0x80000000, v36
	v_mov_b32_e32 v74, v37
	v_pk_fma_f32 v[36:37], v[74:75], s[62:63], v[72:73] op_sel_hi:[1,0,1] neg_lo:[0,0,1] neg_hi:[0,0,1]
	v_pk_add_f32 v[72:73], v[32:33], v[64:65]
	v_pk_add_f32 v[32:33], v[32:33], v[64:65] neg_lo:[0,1] neg_hi:[0,1]
	s_nop 0
	v_pk_mul_f32 v[64:65], v[32:33], s[46:47] op_sel_hi:[1,0]
	v_xor_b32_e32 v75, 0x80000000, v32
	v_mov_b32_e32 v74, v33
	v_pk_fma_f32 v[32:33], v[74:75], s[58:59], v[64:65] op_sel_hi:[1,0,1] neg_lo:[0,0,1] neg_hi:[0,0,1]
	v_pk_add_f32 v[64:65], v[8:9], v[48:49]
	v_pk_add_f32 v[8:9], v[8:9], v[48:49] neg_lo:[0,1] neg_hi:[0,1]
	v_pk_add_f32 v[48:49], v[42:43], v[26:27]
	v_pk_add_f32 v[26:27], v[42:43], v[26:27] neg_lo:[0,1] neg_hi:[0,1]
	s_nop 0
	v_xor_b32_e32 v43, 0x80000000, v26
	v_mov_b32_e32 v42, v27
	v_pk_mul_f32 v[42:43], v[42:43], s[62:63] op_sel_hi:[1,0]
	s_nop 0
	v_pk_fma_f32 v[26:27], v[26:27], s[60:61], v[42:43] op_sel_hi:[1,0,1]
	v_pk_add_f32 v[42:43], v[38:39], v[54:55]
	v_pk_add_f32 v[38:39], v[38:39], v[54:55] neg_lo:[0,1] neg_hi:[0,1]
	s_nop 0
	v_xor_b32_e32 v55, 0x80000000, v38
	v_mov_b32_e32 v54, v39
	v_pk_mul_f32 v[54:55], v[54:55], s[70:71] op_sel_hi:[1,0]
	s_nop 0
	v_pk_fma_f32 v[38:39], v[38:39], s[70:71], v[54:55] op_sel_hi:[1,0,1]
	v_pk_add_f32 v[54:55], v[44:45], v[60:61]
	v_pk_add_f32 v[44:45], v[44:45], v[60:61] neg_lo:[0,1] neg_hi:[0,1]
	s_nop 0
	v_xor_b32_e32 v61, 0x80000000, v44
	v_mov_b32_e32 v60, v45
	v_pk_mul_f32 v[60:61], v[60:61], s[60:61] op_sel_hi:[1,0]
	s_nop 0
	v_pk_fma_f32 v[44:45], v[44:45], s[62:63], v[60:61] op_sel_hi:[1,0,1]
	v_pk_add_f32 v[60:61], v[40:41], v[56:57]
	v_pk_add_f32 v[40:41], v[40:41], v[56:57] neg_lo:[0,1] neg_hi:[0,1]
	s_nop 0
	v_xor_b32_e32 v57, 0x80000000, v40
	v_mov_b32_e32 v56, v41
	v_pk_add_f32 v[40:41], v[50:51], v[66:67]
	v_pk_add_f32 v[50:51], v[50:51], v[66:67] neg_lo:[0,1] neg_hi:[0,1]
	s_nop 0
	v_pk_mul_f32 v[66:67], v[50:51], s[62:63] op_sel_hi:[1,0]
	v_xor_b32_e32 v75, 0x80000000, v50
	v_mov_b32_e32 v74, v51
	v_pk_fma_f32 v[50:51], v[74:75], s[60:61], v[66:67] op_sel_hi:[1,0,1] neg_lo:[0,0,1] neg_hi:[0,0,1]
	v_pk_add_f32 v[66:67], v[46:47], v[62:63]
	v_pk_add_f32 v[46:47], v[46:47], v[62:63] neg_lo:[0,1] neg_hi:[0,1]
	s_nop 0
	v_pk_mul_f32 v[62:63], v[46:47], s[70:71] op_sel_hi:[1,0]
	v_xor_b32_e32 v75, 0x80000000, v46
	v_mov_b32_e32 v74, v47
	v_pk_fma_f32 v[46:47], v[74:75], s[70:71], v[62:63] op_sel_hi:[1,0,1] neg_lo:[0,0,1] neg_hi:[0,0,1]
	v_pk_add_f32 v[62:63], v[52:53], v[72:73]
	v_pk_add_f32 v[52:53], v[52:53], v[72:73] neg_lo:[0,1] neg_hi:[0,1]
	s_nop 0
	v_pk_mul_f32 v[72:73], v[52:53], s[60:61] op_sel_hi:[1,0]
	v_xor_b32_e32 v75, 0x80000000, v52
	v_mov_b32_e32 v74, v53
	v_pk_fma_f32 v[52:53], v[74:75], s[62:63], v[72:73] op_sel_hi:[1,0,1] neg_lo:[0,0,1] neg_hi:[0,0,1]
	v_pk_add_f32 v[72:73], v[6:7], v[58:59]
	v_pk_add_f32 v[6:7], v[6:7], v[58:59] neg_lo:[0,1] neg_hi:[0,1]
	v_pk_add_f32 v[58:59], v[4:5], v[22:23]
	v_pk_add_f32 v[4:5], v[4:5], v[22:23] neg_lo:[0,1] neg_hi:[0,1]
	s_nop 0
	v_xor_b32_e32 v23, 0x80000000, v4
	v_mov_b32_e32 v22, v5
	v_pk_mul_f32 v[22:23], v[22:23], s[62:63] op_sel_hi:[1,0]
	s_nop 0
	v_pk_fma_f32 v[4:5], v[4:5], s[60:61], v[22:23] op_sel_hi:[1,0,1]
	v_pk_add_f32 v[22:23], v[2:3], v[28:29]
	v_pk_add_f32 v[2:3], v[2:3], v[28:29] neg_lo:[0,1] neg_hi:[0,1]
	s_nop 0
	v_xor_b32_e32 v29, 0x80000000, v2
	v_mov_b32_e32 v28, v3
	v_pk_mul_f32 v[28:29], v[28:29], s[70:71] op_sel_hi:[1,0]
	s_nop 0
	v_pk_fma_f32 v[2:3], v[2:3], s[70:71], v[28:29] op_sel_hi:[1,0,1]
	v_pk_add_f32 v[28:29], v[10:11], v[24:25]
	v_pk_add_f32 v[10:11], v[10:11], v[24:25] neg_lo:[0,1] neg_hi:[0,1]
	s_nop 0
	v_xor_b32_e32 v25, 0x80000000, v10
	v_mov_b32_e32 v24, v11
	v_pk_mul_f32 v[24:25], v[24:25], s[60:61] op_sel_hi:[1,0]
	s_nop 0
	v_pk_fma_f32 v[10:11], v[10:11], s[62:63], v[24:25] op_sel_hi:[1,0,1]
	v_pk_add_f32 v[24:25], v[18:19], v[34:35]
	v_pk_add_f32 v[18:19], v[18:19], v[34:35] neg_lo:[0,1] neg_hi:[0,1]
	s_nop 0
	v_xor_b32_e32 v35, 0x80000000, v18
	v_mov_b32_e32 v34, v19
	v_pk_add_f32 v[18:19], v[14:15], v[30:31]
	v_pk_add_f32 v[14:15], v[14:15], v[30:31] neg_lo:[0,1] neg_hi:[0,1]
	s_nop 0
	v_pk_mul_f32 v[30:31], v[14:15], s[62:63] op_sel_hi:[1,0]
	v_xor_b32_e32 v75, 0x80000000, v14
	v_mov_b32_e32 v74, v15
	v_pk_fma_f32 v[14:15], v[74:75], s[60:61], v[30:31] op_sel_hi:[1,0,1] neg_lo:[0,0,1] neg_hi:[0,0,1]
	v_pk_add_f32 v[30:31], v[12:13], v[36:37]
	v_pk_add_f32 v[12:13], v[12:13], v[36:37] neg_lo:[0,1] neg_hi:[0,1]
	s_nop 0
	v_pk_mul_f32 v[36:37], v[12:13], s[70:71] op_sel_hi:[1,0]
	v_xor_b32_e32 v75, 0x80000000, v12
	v_mov_b32_e32 v74, v13
	v_pk_fma_f32 v[12:13], v[74:75], s[70:71], v[36:37] op_sel_hi:[1,0,1] neg_lo:[0,0,1] neg_hi:[0,0,1]
	v_pk_add_f32 v[36:37], v[16:17], v[32:33]
	v_pk_add_f32 v[16:17], v[16:17], v[32:33] neg_lo:[0,1] neg_hi:[0,1]
	s_nop 0
	v_pk_mul_f32 v[32:33], v[16:17], s[60:61] op_sel_hi:[1,0]
	v_xor_b32_e32 v75, 0x80000000, v16
	v_mov_b32_e32 v74, v17
	v_pk_fma_f32 v[16:17], v[74:75], s[62:63], v[32:33] op_sel_hi:[1,0,1] neg_lo:[0,0,1] neg_hi:[0,0,1]
	v_pk_add_f32 v[32:33], v[64:65], v[60:61]
	v_pk_add_f32 v[60:61], v[64:65], v[60:61] neg_lo:[0,1] neg_hi:[0,1]
	v_pk_add_f32 v[64:65], v[48:49], v[40:41]
	v_pk_add_f32 v[40:41], v[48:49], v[40:41] neg_lo:[0,1] neg_hi:[0,1]
	s_nop 0
	v_xor_b32_e32 v49, 0x80000000, v40
	v_mov_b32_e32 v48, v41
	v_pk_mul_f32 v[48:49], v[48:49], s[70:71] op_sel_hi:[1,0]
	s_nop 0
	v_pk_fma_f32 v[40:41], v[40:41], s[70:71], v[48:49] op_sel_hi:[1,0,1]
	v_pk_add_f32 v[48:49], v[42:43], v[66:67]
	v_pk_add_f32 v[42:43], v[42:43], v[66:67] neg_lo:[0,1] neg_hi:[0,1]
	s_nop 0
	v_xor_b32_e32 v67, 0x80000000, v42
	v_mov_b32_e32 v66, v43
	v_pk_add_f32 v[42:43], v[54:55], v[62:63]
	v_pk_add_f32 v[54:55], v[54:55], v[62:63] neg_lo:[0,1] neg_hi:[0,1]
	s_nop 0
	v_pk_mul_f32 v[62:63], v[54:55], s[70:71] op_sel_hi:[1,0]
	v_xor_b32_e32 v75, 0x80000000, v54
	v_mov_b32_e32 v74, v55
	v_pk_fma_f32 v[54:55], v[74:75], s[70:71], v[62:63] op_sel_hi:[1,0,1] neg_lo:[0,0,1] neg_hi:[0,0,1]
	v_pk_add_f32 v[62:63], v[8:9], v[56:57]
	v_pk_add_f32 v[8:9], v[8:9], v[56:57] neg_lo:[0,1] neg_hi:[0,1]
	v_pk_add_f32 v[56:57], v[26:27], v[50:51]
	v_pk_add_f32 v[26:27], v[26:27], v[50:51] neg_lo:[0,1] neg_hi:[0,1]
	s_nop 0
	v_xor_b32_e32 v51, 0x80000000, v26
	v_mov_b32_e32 v50, v27
	v_pk_mul_f32 v[50:51], v[50:51], s[70:71] op_sel_hi:[1,0]
	s_nop 0
	v_pk_fma_f32 v[26:27], v[26:27], s[70:71], v[50:51] op_sel_hi:[1,0,1]
	v_pk_add_f32 v[50:51], v[38:39], v[46:47]
	v_pk_add_f32 v[38:39], v[38:39], v[46:47] neg_lo:[0,1] neg_hi:[0,1]
	s_nop 0
	v_xor_b32_e32 v47, 0x80000000, v38
	v_mov_b32_e32 v46, v39
	v_pk_add_f32 v[38:39], v[44:45], v[52:53]
	v_pk_add_f32 v[44:45], v[44:45], v[52:53] neg_lo:[0,1] neg_hi:[0,1]
	s_nop 0
	v_pk_mul_f32 v[52:53], v[44:45], s[70:71] op_sel_hi:[1,0]
	v_xor_b32_e32 v75, 0x80000000, v44
	v_mov_b32_e32 v74, v45
	v_pk_fma_f32 v[44:45], v[74:75], s[70:71], v[52:53] op_sel_hi:[1,0,1] neg_lo:[0,0,1] neg_hi:[0,0,1]
	v_pk_add_f32 v[52:53], v[72:73], v[24:25]
	v_pk_add_f32 v[24:25], v[72:73], v[24:25] neg_lo:[0,1] neg_hi:[0,1]
	v_pk_add_f32 v[72:73], v[58:59], v[18:19]
	v_pk_add_f32 v[18:19], v[58:59], v[18:19] neg_lo:[0,1] neg_hi:[0,1]
	s_nop 0
	v_xor_b32_e32 v59, 0x80000000, v18
	v_mov_b32_e32 v58, v19
	v_pk_mul_f32 v[58:59], v[58:59], s[70:71] op_sel_hi:[1,0]
	s_nop 0
	v_pk_fma_f32 v[18:19], v[18:19], s[70:71], v[58:59] op_sel_hi:[1,0,1]
	v_pk_add_f32 v[58:59], v[22:23], v[30:31]
	v_pk_add_f32 v[22:23], v[22:23], v[30:31] neg_lo:[0,1] neg_hi:[0,1]
	s_nop 0
	v_xor_b32_e32 v31, 0x80000000, v22
	v_mov_b32_e32 v30, v23
	v_pk_add_f32 v[22:23], v[28:29], v[36:37]
	v_pk_add_f32 v[28:29], v[28:29], v[36:37] neg_lo:[0,1] neg_hi:[0,1]
	v_pk_add_f32 v[76:77], v[24:25], v[30:31]
	v_pk_mul_f32 v[36:37], v[28:29], s[70:71] op_sel_hi:[1,0]
	v_xor_b32_e32 v75, 0x80000000, v28
	v_mov_b32_e32 v74, v29
	v_pk_fma_f32 v[28:29], v[74:75], s[70:71], v[36:37] op_sel_hi:[1,0,1] neg_lo:[0,0,1] neg_hi:[0,0,1]
	v_pk_add_f32 v[36:37], v[6:7], v[34:35]
	v_pk_add_f32 v[6:7], v[6:7], v[34:35] neg_lo:[0,1] neg_hi:[0,1]
	v_pk_add_f32 v[34:35], v[4:5], v[14:15]
	v_pk_add_f32 v[4:5], v[4:5], v[14:15] neg_lo:[0,1] neg_hi:[0,1]
	v_pk_add_f32 v[78:79], v[18:19], v[28:29]
	v_xor_b32_e32 v15, 0x80000000, v4
	v_mov_b32_e32 v14, v5
	v_pk_mul_f32 v[14:15], v[14:15], s[70:71] op_sel_hi:[1,0]
	v_pk_add_f32 v[18:19], v[18:19], v[28:29] neg_lo:[0,1] neg_hi:[0,1]
	v_pk_fma_f32 v[4:5], v[4:5], s[70:71], v[14:15] op_sel_hi:[1,0,1]
	v_pk_add_f32 v[14:15], v[2:3], v[12:13]
	v_pk_add_f32 v[2:3], v[2:3], v[12:13] neg_lo:[0,1] neg_hi:[0,1]
	v_xor_b32_e32 v81, 0x80000000, v18
	v_xor_b32_e32 v13, 0x80000000, v2
	v_mov_b32_e32 v12, v3
	v_pk_add_f32 v[2:3], v[10:11], v[16:17]
	v_pk_add_f32 v[10:11], v[10:11], v[16:17] neg_lo:[0,1] neg_hi:[0,1]
	v_mov_b32_e32 v80, v19
	v_pk_mul_f32 v[16:17], v[10:11], s[70:71] op_sel_hi:[1,0]
	v_xor_b32_e32 v75, 0x80000000, v10
	v_mov_b32_e32 v74, v11
	v_pk_fma_f32 v[10:11], v[74:75], s[70:71], v[16:17] op_sel_hi:[1,0,1] neg_lo:[0,0,1] neg_hi:[0,0,1]
	v_pk_add_f32 v[74:75], v[62:63], v[50:51]
	v_pk_add_f32 v[50:51], v[62:63], v[50:51] neg_lo:[0,1] neg_hi:[0,1]
	v_pk_add_f32 v[62:63], v[56:57], v[38:39]
	v_pk_add_f32 v[38:39], v[56:57], v[38:39] neg_lo:[0,1] neg_hi:[0,1]
	v_pk_add_f32 v[16:17], v[32:33], v[48:49]
	v_pk_add_f32 v[32:33], v[32:33], v[48:49] neg_lo:[0,1] neg_hi:[0,1]
	v_pk_add_f32 v[48:49], v[64:65], v[42:43]
	v_pk_add_f32 v[42:43], v[64:65], v[42:43] neg_lo:[0,1] neg_hi:[0,1]
	v_xor_b32_e32 v57, 0x80000000, v38
	v_mov_b32_e32 v56, v39
	v_pk_add_f32 v[38:39], v[8:9], v[46:47]
	v_pk_add_f32 v[8:9], v[8:9], v[46:47] neg_lo:[0,1] neg_hi:[0,1]
	v_pk_add_f32 v[46:47], v[26:27], v[44:45]
	v_pk_add_f32 v[26:27], v[26:27], v[44:45] neg_lo:[0,1] neg_hi:[0,1]
	v_xor_b32_e32 v65, 0x80000000, v42
	v_mov_b32_e32 v64, v43
	v_pk_add_f32 v[42:43], v[60:61], v[66:67]
	v_pk_add_f32 v[60:61], v[60:61], v[66:67] neg_lo:[0,1] neg_hi:[0,1]
	v_pk_add_f32 v[66:67], v[40:41], v[54:55]
	v_pk_add_f32 v[40:41], v[40:41], v[54:55] neg_lo:[0,1] neg_hi:[0,1]
	v_xor_b32_e32 v45, 0x80000000, v26
	v_mov_b32_e32 v44, v27
	v_pk_add_f32 v[26:27], v[52:53], v[58:59]
	v_pk_add_f32 v[52:53], v[52:53], v[58:59] neg_lo:[0,1] neg_hi:[0,1]
	v_pk_add_f32 v[58:59], v[72:73], v[22:23]
	v_pk_add_f32 v[22:23], v[72:73], v[22:23] neg_lo:[0,1] neg_hi:[0,1]
	v_pk_add_f32 v[18:19], v[36:37], v[14:15]
	v_pk_add_f32 v[14:15], v[36:37], v[14:15] neg_lo:[0,1] neg_hi:[0,1]
	v_pk_add_f32 v[36:37], v[34:35], v[2:3]
	v_pk_add_f32 v[2:3], v[34:35], v[2:3] neg_lo:[0,1] neg_hi:[0,1]
	v_xor_b32_e32 v55, 0x80000000, v40
	v_mov_b32_e32 v54, v41
	v_xor_b32_e32 v73, 0x80000000, v22
	v_mov_b32_e32 v72, v23
	v_xor_b32_e32 v35, 0x80000000, v2
	v_mov_b32_e32 v34, v3
	v_pk_add_f32 v[2:3], v[4:5], v[10:11] neg_lo:[0,1] neg_hi:[0,1]
	v_pk_add_f32 v[24:25], v[24:25], v[30:31] neg_lo:[0,1] neg_hi:[0,1]
	v_pk_add_f32 v[82:83], v[6:7], v[12:13]
	v_pk_add_f32 v[12:13], v[6:7], v[12:13] neg_lo:[0,1] neg_hi:[0,1]
	v_xor_b32_e32 v87, 0x80000000, v2
	v_mov_b32_e32 v86, v3
	v_pk_add_f32 v[2:3], v[16:17], v[48:49]
	v_pk_add_f32 v[88:89], v[16:17], v[48:49] neg_lo:[0,1] neg_hi:[0,1]
	v_pk_add_f32 v[48:49], v[32:33], v[64:65]
	v_pk_add_f32 v[28:29], v[32:33], v[64:65] neg_lo:[0,1] neg_hi:[0,1]
	v_pk_add_f32 v[64:65], v[60:61], v[54:55]
	v_pk_add_f32 v[6:7], v[60:61], v[54:55] neg_lo:[0,1] neg_hi:[0,1]
	v_pk_add_f32 v[60:61], v[50:51], v[56:57]
	v_pk_add_f32 v[22:23], v[50:51], v[56:57] neg_lo:[0,1] neg_hi:[0,1]
	v_pk_add_f32 v[50:51], v[52:53], v[72:73]
	v_pk_add_f32 v[30:31], v[52:53], v[72:73] neg_lo:[0,1] neg_hi:[0,1]
	v_pk_add_f32 v[52:53], v[18:19], v[36:37]
	v_pk_add_f32 v[56:57], v[18:19], v[36:37] neg_lo:[0,1] neg_hi:[0,1]
	v_mov_b32_e32 v18, v21
	v_pk_add_f32 v[84:85], v[4:5], v[10:11]
	v_cvt_f32_i32_e32 v18, v18
	v_pk_add_f32 v[32:33], v[42:43], v[66:67]
	v_pk_add_f32 v[40:41], v[42:43], v[66:67] neg_lo:[0,1] neg_hi:[0,1]
	v_pk_add_f32 v[66:67], v[24:25], v[80:81]
	v_pk_add_f32 v[10:11], v[24:25], v[80:81] neg_lo:[0,1] neg_hi:[0,1]
	v_pk_add_f32 v[72:73], v[14:15], v[34:35]
	v_pk_add_f32 v[24:25], v[14:15], v[34:35] neg_lo:[0,1] neg_hi:[0,1]
	v_mul_f32_e32 v15, 0x38800000, v18
	v_cos_f32_e32 v14, v15
	v_sin_f32_e32 v15, v15
	v_pk_add_f32 v[16:17], v[74:75], v[62:63]
	v_pk_add_f32 v[54:55], v[74:75], v[62:63] neg_lo:[0,1] neg_hi:[0,1]
	v_pk_add_f32 v[62:63], v[8:9], v[44:45]
	v_pk_add_f32 v[4:5], v[8:9], v[44:45] neg_lo:[0,1] neg_hi:[0,1]
	v_pk_add_f32 v[8:9], v[26:27], v[58:59]
	v_add_f32_e32 v20, v14, v14
	v_pk_add_f32 v[42:43], v[38:39], v[46:47]
	v_pk_add_f32 v[38:39], v[38:39], v[46:47] neg_lo:[0,1] neg_hi:[0,1]
	v_pk_add_f32 v[58:59], v[26:27], v[58:59] neg_lo:[0,1] neg_hi:[0,1]
	v_pk_add_f32 v[26:27], v[76:77], v[78:79]
	v_pk_add_f32 v[46:47], v[76:77], v[78:79] neg_lo:[0,1] neg_hi:[0,1]
	v_pk_mul_f32 v[18:19], v[14:15], v[14:15]
	v_mul_f32_e32 v20, v15, v20
	v_xor_b32_e32 v34, 0x80000000, v15
	v_mov_b32_e32 v35, v14
	v_xor_b32_e32 v37, 0x80000000, v8
	v_mov_b32_e32 v36, v9
	v_mov_b32_e32 v78, v15
	v_pk_add_f32 v[18:19], v[18:19], v[18:19] op_sel:[0,1] op_sel_hi:[0,1] neg_lo:[0,1] neg_hi:[0,1]
	v_pk_mul_f32 v[34:35], v[34:35], v[20:21] op_sel_hi:[1,0]
	v_pk_mul_f32 v[36:37], v[78:79], v[36:37] op_sel_hi:[0,1]
	v_pk_fma_f32 v[34:35], v[14:15], v[18:19], v[34:35]
	v_pk_fma_f32 v[8:9], v[14:15], v[8:9], v[36:37] op_sel_hi:[0,1,1]
	v_pk_mul_f32 v[14:15], v[20:21], s[48:49] op_sel_hi:[0,1]
	v_pk_fma_f32 v[36:37], v[18:19], s[40:41], v[14:15]
	v_xor_b32_e32 v15, 0x80000000, v16
	v_mov_b32_e32 v14, v17
	v_pk_mul_f32 v[14:15], v[14:15], v[36:37] op_sel:[0,1]
	v_pk_add_f32 v[74:75], v[82:83], v[84:85]
	v_pk_fma_f32 v[16:17], v[16:17], v[36:37], v[14:15] op_sel_hi:[1,0,1]
	v_xor_b32_e32 v14, 0x80000000, v35
	v_mov_b32_e32 v15, v34
	v_pk_mul_f32 v[14:15], v[20:21], v[14:15] op_sel_hi:[0,1]
	v_pk_fma_f32 v[78:79], v[18:19], v[34:35], v[14:15]
	v_xor_b32_e32 v15, 0x80000000, v52
	v_mov_b32_e32 v14, v53
	v_pk_mul_f32 v[14:15], v[34:35], v[14:15] op_sel:[1,0]
	v_pk_add_f32 v[76:77], v[12:13], v[86:87]
	v_pk_fma_f32 v[14:15], v[34:35], v[52:53], v[14:15] op_sel_hi:[0,1,1]
	v_xor_b32_e32 v34, 0x80000000, v37
	v_mov_b32_e32 v35, v36
	v_pk_mul_f32 v[34:35], v[20:21], v[34:35] op_sel_hi:[0,1]
	v_xor_b32_e32 v53, 0x80000000, v26
	v_mov_b32_e32 v52, v27
	v_pk_fma_f32 v[36:37], v[18:19], v[36:37], v[34:35]
	v_xor_b32_e32 v35, 0x80000000, v32
	v_mov_b32_e32 v34, v33
	v_pk_mul_f32 v[52:53], v[52:53], v[78:79] op_sel:[0,1]
	v_pk_mul_f32 v[34:35], v[34:35], v[36:37] op_sel:[0,1]
	v_pk_fma_f32 v[26:27], v[26:27], v[78:79], v[52:53] op_sel_hi:[1,0,1]
	v_xor_b32_e32 v52, 0x80000000, v37
	v_mov_b32_e32 v53, v36
	v_pk_fma_f32 v[34:35], v[32:33], v[36:37], v[34:35] op_sel_hi:[1,0,1]
	v_xor_b32_e32 v32, 0x80000000, v79
	v_mov_b32_e32 v33, v78
	v_pk_mul_f32 v[52:53], v[20:21], v[52:53] op_sel_hi:[0,1]
	v_pk_mul_f32 v[32:33], v[20:21], v[32:33] op_sel_hi:[0,1]
	v_pk_fma_f32 v[52:53], v[18:19], v[36:37], v[52:53]
	v_xor_b32_e32 v37, 0x80000000, v42
	v_mov_b32_e32 v36, v43
	v_pk_fma_f32 v[32:33], v[18:19], v[78:79], v[32:33]
	v_pk_mul_f32 v[36:37], v[36:37], v[52:53] op_sel:[0,1]
	v_xor_b32_e32 v79, 0x80000000, v74
	v_pk_fma_f32 v[36:37], v[42:43], v[52:53], v[36:37] op_sel_hi:[1,0,1]
	v_xor_b32_e32 v42, 0x80000000, v33
	v_mov_b32_e32 v43, v32
	v_mov_b32_e32 v78, v75
	v_pk_mul_f32 v[42:43], v[20:21], v[42:43] op_sel_hi:[0,1]
	v_pk_mul_f32 v[78:79], v[78:79], v[32:33] op_sel:[0,1]
	v_pk_fma_f32 v[42:43], v[18:19], v[32:33], v[42:43]
	v_pk_fma_f32 v[32:33], v[74:75], v[32:33], v[78:79] op_sel_hi:[1,0,1]
	v_xor_b32_e32 v74, 0x80000000, v53
	v_mov_b32_e32 v75, v52
	v_pk_mul_f32 v[74:75], v[20:21], v[74:75] op_sel_hi:[0,1]
	v_pk_fma_f32 v[52:53], v[18:19], v[52:53], v[74:75]
	v_xor_b32_e32 v75, 0x80000000, v48
	v_mov_b32_e32 v74, v49
	v_pk_mul_f32 v[74:75], v[74:75], v[52:53] op_sel:[0,1]
	v_xor_b32_e32 v79, 0x80000000, v50
	v_pk_fma_f32 v[48:49], v[48:49], v[52:53], v[74:75] op_sel_hi:[1,0,1]
	v_xor_b32_e32 v74, 0x80000000, v43
	v_mov_b32_e32 v75, v42
	v_mov_b32_e32 v78, v51
	v_pk_mul_f32 v[74:75], v[20:21], v[74:75] op_sel_hi:[0,1]
	v_pk_mul_f32 v[78:79], v[78:79], v[42:43] op_sel:[0,1]
	v_pk_fma_f32 v[74:75], v[18:19], v[42:43], v[74:75]
	v_pk_fma_f32 v[42:43], v[50:51], v[42:43], v[78:79] op_sel_hi:[1,0,1]
	v_xor_b32_e32 v50, 0x80000000, v53
	v_mov_b32_e32 v51, v52
	v_pk_mul_f32 v[50:51], v[20:21], v[50:51] op_sel_hi:[0,1]
	v_pk_fma_f32 v[78:79], v[18:19], v[52:53], v[50:51]
	v_xor_b32_e32 v51, 0x80000000, v60
	v_mov_b32_e32 v50, v61
	v_pk_mul_f32 v[50:51], v[50:51], v[78:79] op_sel:[0,1]
	v_xor_b32_e32 v81, 0x80000000, v58
	v_pk_fma_f32 v[52:53], v[60:61], v[78:79], v[50:51] op_sel_hi:[1,0,1]
	v_xor_b32_e32 v50, 0x80000000, v75
	v_mov_b32_e32 v51, v74
	v_pk_mul_f32 v[50:51], v[20:21], v[50:51] op_sel_hi:[0,1]
	v_pk_fma_f32 v[60:61], v[18:19], v[74:75], v[50:51]
	v_xor_b32_e32 v51, 0x80000000, v72
	v_mov_b32_e32 v50, v73
	v_pk_mul_f32 v[50:51], v[50:51], v[74:75] op_sel:[0,1]
	v_mov_b32_e32 v80, v59
	v_pk_fma_f32 v[50:51], v[72:73], v[74:75], v[50:51] op_sel_hi:[1,0,1]
	v_xor_b32_e32 v72, 0x80000000, v79
	v_mov_b32_e32 v73, v78
	v_pk_mul_f32 v[72:73], v[20:21], v[72:73] op_sel_hi:[0,1]
	v_pk_fma_f32 v[72:73], v[18:19], v[78:79], v[72:73]
	v_xor_b32_e32 v75, 0x80000000, v64
	v_mov_b32_e32 v74, v65
	v_pk_mul_f32 v[74:75], v[74:75], v[72:73] op_sel:[0,1]
	v_xor_b32_e32 v79, 0x80000000, v66
	v_pk_fma_f32 v[64:65], v[64:65], v[72:73], v[74:75] op_sel_hi:[1,0,1]
	v_xor_b32_e32 v74, 0x80000000, v61
	v_mov_b32_e32 v75, v60
	v_mov_b32_e32 v78, v67
	v_pk_mul_f32 v[74:75], v[20:21], v[74:75] op_sel_hi:[0,1]
	v_pk_mul_f32 v[78:79], v[78:79], v[60:61] op_sel:[0,1]
	v_pk_fma_f32 v[74:75], v[18:19], v[60:61], v[74:75]
	v_pk_fma_f32 v[60:61], v[66:67], v[60:61], v[78:79] op_sel_hi:[1,0,1]
	v_xor_b32_e32 v66, 0x80000000, v73
	v_mov_b32_e32 v67, v72
	v_pk_mul_f32 v[66:67], v[20:21], v[66:67] op_sel_hi:[0,1]
	v_pk_fma_f32 v[66:67], v[18:19], v[72:73], v[66:67]
	v_xor_b32_e32 v73, 0x80000000, v62
	v_mov_b32_e32 v72, v63
	v_pk_mul_f32 v[72:73], v[72:73], v[66:67] op_sel:[0,1]
	v_xor_b32_e32 v79, 0x80000000, v76
	v_pk_fma_f32 v[62:63], v[62:63], v[66:67], v[72:73] op_sel_hi:[1,0,1]
	v_xor_b32_e32 v72, 0x80000000, v75
	v_mov_b32_e32 v73, v74
	v_mov_b32_e32 v78, v77
	v_pk_mul_f32 v[72:73], v[20:21], v[72:73] op_sel_hi:[0,1]
	v_pk_mul_f32 v[78:79], v[78:79], v[74:75] op_sel:[0,1]
	v_pk_fma_f32 v[72:73], v[18:19], v[74:75], v[72:73]
	v_pk_fma_f32 v[74:75], v[76:77], v[74:75], v[78:79] op_sel_hi:[1,0,1]
	v_xor_b32_e32 v76, 0x80000000, v67
	v_mov_b32_e32 v77, v66
	v_pk_mul_f32 v[76:77], v[20:21], v[76:77] op_sel_hi:[0,1]
	v_xor_b32_e32 v78, 0x80000000, v73
	v_mov_b32_e32 v79, v72
	v_pk_fma_f32 v[66:67], v[18:19], v[66:67], v[76:77]
	v_pk_mul_f32 v[78:79], v[20:21], v[78:79] op_sel_hi:[0,1]
	v_pk_mul_f32 v[80:81], v[80:81], v[72:73] op_sel:[0,1]
	v_xor_b32_e32 v77, 0x80000000, v88
	v_mov_b32_e32 v76, v89
	v_pk_fma_f32 v[78:79], v[18:19], v[72:73], v[78:79]
	v_pk_fma_f32 v[58:59], v[58:59], v[72:73], v[80:81] op_sel_hi:[1,0,1]
	v_xor_b32_e32 v72, 0x80000000, v67
	v_mov_b32_e32 v73, v66
	v_pk_mul_f32 v[76:77], v[76:77], v[66:67] op_sel:[0,1]
	v_pk_mul_f32 v[72:73], v[20:21], v[72:73] op_sel_hi:[0,1]
	v_pk_fma_f32 v[76:77], v[88:89], v[66:67], v[76:77] op_sel_hi:[1,0,1]
	v_pk_fma_f32 v[66:67], v[18:19], v[66:67], v[72:73]
	v_xor_b32_e32 v73, 0x80000000, v54
	v_mov_b32_e32 v72, v55
	v_pk_mul_f32 v[72:73], v[72:73], v[66:67] op_sel:[0,1]
	v_xor_b32_e32 v81, 0x80000000, v56
	v_pk_fma_f32 v[54:55], v[54:55], v[66:67], v[72:73] op_sel_hi:[1,0,1]
	v_xor_b32_e32 v72, 0x80000000, v79
	v_mov_b32_e32 v73, v78
	v_mov_b32_e32 v80, v57
	v_pk_mul_f32 v[72:73], v[20:21], v[72:73] op_sel_hi:[0,1]
	v_pk_mul_f32 v[80:81], v[80:81], v[78:79] op_sel:[0,1]
	v_pk_fma_f32 v[72:73], v[18:19], v[78:79], v[72:73]
	v_pk_fma_f32 v[56:57], v[56:57], v[78:79], v[80:81] op_sel_hi:[1,0,1]
	v_xor_b32_e32 v78, 0x80000000, v67
	v_mov_b32_e32 v79, v66
	v_pk_mul_f32 v[78:79], v[20:21], v[78:79] op_sel_hi:[0,1]
	v_pk_fma_f32 v[66:67], v[18:19], v[66:67], v[78:79]
	v_xor_b32_e32 v79, 0x80000000, v40
	v_mov_b32_e32 v78, v41
	v_pk_mul_f32 v[78:79], v[78:79], v[66:67] op_sel:[0,1]
	v_xor_b32_e32 v81, 0x80000000, v46
	v_pk_fma_f32 v[40:41], v[40:41], v[66:67], v[78:79] op_sel_hi:[1,0,1]
	v_xor_b32_e32 v78, 0x80000000, v73
	v_mov_b32_e32 v79, v72
	v_mov_b32_e32 v80, v47
	v_pk_mul_f32 v[78:79], v[20:21], v[78:79] op_sel_hi:[0,1]
	v_pk_mul_f32 v[80:81], v[80:81], v[72:73] op_sel:[0,1]
	v_pk_fma_f32 v[78:79], v[18:19], v[72:73], v[78:79]
	v_pk_fma_f32 v[46:47], v[46:47], v[72:73], v[80:81] op_sel_hi:[1,0,1]
	v_xor_b32_e32 v72, 0x80000000, v67
	v_mov_b32_e32 v73, v66
	v_pk_mul_f32 v[72:73], v[20:21], v[72:73] op_sel_hi:[0,1]
	v_pk_fma_f32 v[66:67], v[18:19], v[66:67], v[72:73]
	v_xor_b32_e32 v73, 0x80000000, v38
	v_mov_b32_e32 v72, v39
	v_pk_add_f32 v[44:45], v[82:83], v[84:85] neg_lo:[0,1] neg_hi:[0,1]
	v_pk_mul_f32 v[72:73], v[72:73], v[66:67] op_sel:[0,1]
	v_xor_b32_e32 v81, 0x80000000, v44
	v_pk_fma_f32 v[38:39], v[38:39], v[66:67], v[72:73] op_sel_hi:[1,0,1]
	v_xor_b32_e32 v72, 0x80000000, v79
	v_mov_b32_e32 v73, v78
	v_mov_b32_e32 v80, v45
	v_pk_mul_f32 v[72:73], v[20:21], v[72:73] op_sel_hi:[0,1]
	v_pk_mul_f32 v[80:81], v[80:81], v[78:79] op_sel:[0,1]
	v_pk_fma_f32 v[72:73], v[18:19], v[78:79], v[72:73]
	v_pk_fma_f32 v[44:45], v[44:45], v[78:79], v[80:81] op_sel_hi:[1,0,1]
	v_xor_b32_e32 v78, 0x80000000, v67
	v_mov_b32_e32 v79, v66
	v_pk_mul_f32 v[78:79], v[20:21], v[78:79] op_sel_hi:[0,1]
	v_pk_fma_f32 v[66:67], v[18:19], v[66:67], v[78:79]
	v_xor_b32_e32 v79, 0x80000000, v28
	v_mov_b32_e32 v78, v29
	v_pk_mul_f32 v[78:79], v[78:79], v[66:67] op_sel:[0,1]
	v_xor_b32_e32 v81, 0x80000000, v30
	v_pk_fma_f32 v[28:29], v[28:29], v[66:67], v[78:79] op_sel_hi:[1,0,1]
	v_xor_b32_e32 v78, 0x80000000, v73
	v_mov_b32_e32 v79, v72
	v_mov_b32_e32 v80, v31
	v_pk_mul_f32 v[78:79], v[20:21], v[78:79] op_sel_hi:[0,1]
	v_pk_mul_f32 v[80:81], v[80:81], v[72:73] op_sel:[0,1]
	v_pk_fma_f32 v[78:79], v[18:19], v[72:73], v[78:79]
	v_pk_fma_f32 v[30:31], v[30:31], v[72:73], v[80:81] op_sel_hi:[1,0,1]
	v_xor_b32_e32 v72, 0x80000000, v67
	v_mov_b32_e32 v73, v66
	v_pk_mul_f32 v[72:73], v[20:21], v[72:73] op_sel_hi:[0,1]
	v_pk_fma_f32 v[66:67], v[18:19], v[66:67], v[72:73]
	v_xor_b32_e32 v73, 0x80000000, v22
	v_mov_b32_e32 v72, v23
	v_pk_mul_f32 v[72:73], v[72:73], v[66:67] op_sel:[0,1]
	v_xor_b32_e32 v81, 0x80000000, v24
	v_pk_fma_f32 v[22:23], v[22:23], v[66:67], v[72:73] op_sel_hi:[1,0,1]
	v_xor_b32_e32 v72, 0x80000000, v79
	v_mov_b32_e32 v73, v78
	v_mov_b32_e32 v80, v25
	v_pk_mul_f32 v[72:73], v[20:21], v[72:73] op_sel_hi:[0,1]
	v_pk_mul_f32 v[80:81], v[80:81], v[78:79] op_sel:[0,1]
	v_pk_fma_f32 v[72:73], v[18:19], v[78:79], v[72:73]
	v_pk_fma_f32 v[24:25], v[24:25], v[78:79], v[80:81] op_sel_hi:[1,0,1]
	v_xor_b32_e32 v78, 0x80000000, v67
	v_mov_b32_e32 v79, v66
	v_pk_mul_f32 v[78:79], v[20:21], v[78:79] op_sel_hi:[0,1]
	v_pk_fma_f32 v[66:67], v[18:19], v[66:67], v[78:79]
	v_xor_b32_e32 v79, 0x80000000, v6
	v_mov_b32_e32 v78, v7
	v_pk_mul_f32 v[78:79], v[78:79], v[66:67] op_sel:[0,1]
	v_xor_b32_e32 v81, 0x80000000, v10
	v_pk_fma_f32 v[6:7], v[6:7], v[66:67], v[78:79] op_sel_hi:[1,0,1]
	v_xor_b32_e32 v78, 0x80000000, v73
	v_mov_b32_e32 v79, v72
	v_mov_b32_e32 v80, v11
	v_pk_mul_f32 v[78:79], v[20:21], v[78:79] op_sel_hi:[0,1]
	v_pk_mul_f32 v[80:81], v[80:81], v[72:73] op_sel:[0,1]
	v_pk_fma_f32 v[78:79], v[18:19], v[72:73], v[78:79]
	v_pk_fma_f32 v[10:11], v[10:11], v[72:73], v[80:81] op_sel_hi:[1,0,1]
	v_xor_b32_e32 v72, 0x80000000, v67
	v_mov_b32_e32 v73, v66
	v_pk_mul_f32 v[72:73], v[20:21], v[72:73] op_sel_hi:[0,1]
	v_pk_fma_f32 v[18:19], v[18:19], v[66:67], v[72:73]
	v_xor_b32_e32 v67, 0x80000000, v4
	v_mov_b32_e32 v66, v5
	v_pk_add_f32 v[12:13], v[12:13], v[86:87] neg_lo:[0,1] neg_hi:[0,1]
	v_pk_mul_f32 v[66:67], v[66:67], v[18:19] op_sel:[0,1]
	s_nop 0
	v_pk_fma_f32 v[4:5], v[4:5], v[18:19], v[66:67] op_sel_hi:[1,0,1]
	v_xor_b32_e32 v19, 0x80000000, v12
	v_mov_b32_e32 v18, v13
	v_pk_mul_f32 v[18:19], v[18:19], v[78:79] op_sel:[0,1]
	s_nop 0
	v_pk_fma_f32 v[12:13], v[12:13], v[78:79], v[18:19] op_sel_hi:[1,0,1]
	v_lshrrev_b32_e32 v18, 5, v21
	v_bitop3_b32 v18, v18, v21, 15 bitop3:0x6c
	v_lshlrev_b32_e32 v18, 3, v18
	v_bfe_u32 v19, v21, 5, 4
	v_add_u32_e32 v20, 16, v18
	ds_write_b64 v20, v[2:3]
	v_bitop3_b32 v2, v19, v21, 16 bitop3:0x36
	v_lshl_add_u32 v2, v2, 3, 16
	v_add_u32_e32 v3, s47, v18
	ds_write_b64 v2, v[76:77] offset:4096
	ds_write_b64 v20, v[48:49] offset:8192
	ds_write_b64 v2, v[28:29] offset:12288
	ds_write_b64 v20, v[34:35] offset:16384
	ds_write_b64 v2, v[40:41] offset:20480
	ds_write_b64 v20, v[64:65] offset:24576
	ds_write_b64 v2, v[6:7] offset:28672
	ds_write_b64 v20, v[16:17] offset:32768
	ds_write_b64 v2, v[54:55] offset:36864
	ds_write_b64 v20, v[52:53] offset:40960
	ds_write_b64 v2, v[22:23] offset:45056
	ds_write_b64 v20, v[36:37] offset:49152
	ds_write_b64 v2, v[38:39] offset:53248
	ds_write_b64 v20, v[62:63] offset:57344
	ds_write_b64 v2, v[4:5] offset:61440
	ds_write_b64 v3, v[8:9]
	v_add_u32_e32 v3, 0x11000, v2
	ds_write_b64 v3, v[58:59]
	v_add_u32_e32 v3, 0x12000, v20
	ds_write_b64 v3, v[42:43]
	v_add_u32_e32 v3, 0x13000, v2
	ds_write_b64 v3, v[30:31]
	v_add_u32_e32 v3, 0x14000, v20
	ds_write_b64 v3, v[26:27]
	v_add_u32_e32 v3, 0x15000, v2
	ds_write_b64 v3, v[46:47]
	v_add_u32_e32 v3, 0x16000, v20
	ds_write_b64 v3, v[60:61]
	v_add_u32_e32 v3, 0x17000, v2
	ds_write_b64 v3, v[10:11]
	v_add_u32_e32 v3, 0x18000, v20
	ds_write_b64 v3, v[14:15]
	v_add_u32_e32 v3, 0x19000, v2
	ds_write_b64 v3, v[56:57]
	v_add_u32_e32 v3, 0x1a000, v20
	ds_write_b64 v3, v[50:51]
	v_add_u32_e32 v3, 0x1b000, v2
	ds_write_b64 v3, v[24:25]
	v_add_u32_e32 v3, 0x1c000, v20
	ds_write_b64 v3, v[32:33]
	v_add_u32_e32 v3, 0x1d000, v2
	ds_write_b64 v3, v[44:45]
	v_add_u32_e32 v3, 0x1e000, v20
	v_add_u32_e32 v2, 0x1f000, v2
	v_mov_b32_e32 v11, v146
	ds_write_b64 v3, v[74:75]
	ds_write_b64 v2, v[12:13]
	s_waitcnt lgkmcnt(0)
	s_barrier
	s_nop 0
	v_lshlrev_b32_e32 v2, 5, v11
	v_and_b32_e32 v2, 0xfffffe00, v2
	v_and_or_b32 v3, v11, 16, v2
	v_bitop3_b32 v2, v2, 16, v11 bitop3:0x34
	v_bitop3_b32 v12, v11, 2, 15 bitop3:0x6c
	v_bitop3_b32 v22, v11, 4, 15 bitop3:0x6c
	v_bitop3_b32 v30, v11, 6, 15 bitop3:0x6c
	v_bitop3_b32 v38, v11, 8, 15 bitop3:0x6c
	v_and_b32_e32 v10, 15, v11
	v_lshl_add_u32 v18, v3, 3, 16
	v_lshl_add_u32 v87, v2, 3, 16
	v_lshlrev_b32_e32 v12, 3, v12
	v_lshlrev_b32_e32 v22, 3, v22
	v_lshlrev_b32_e32 v30, 3, v30
	v_lshlrev_b32_e32 v38, 3, v38
	v_lshlrev_b32_e32 v3, 3, v10
	v_bitop3_b32 v2, v11, 1, 15 bitop3:0x6c
	v_add_u32_e32 v57, v18, v12
	v_add_u32_e32 v58, v87, v12
	v_bitop3_b32 v12, v11, 3, 15 bitop3:0x6c
	v_add_u32_e32 v61, v18, v22
	v_add_u32_e32 v62, v87, v22
	v_bitop3_b32 v22, v11, 5, 15 bitop3:0x6c
	v_add_u32_e32 v65, v18, v30
	v_add_u32_e32 v66, v87, v30
	v_bitop3_b32 v30, v11, 7, 15 bitop3:0x6c
	v_add_u32_e32 v72, v18, v38
	v_add_u32_e32 v73, v87, v38
	v_bitop3_b32 v38, v11, 9, 15 bitop3:0x6c
	v_add_u32_e32 v19, v18, v3
	v_lshlrev_b32_e32 v2, 3, v2
	v_lshlrev_b32_e32 v12, 3, v12
	v_lshlrev_b32_e32 v22, 3, v22
	v_lshlrev_b32_e32 v30, 3, v30
	v_lshlrev_b32_e32 v38, 3, v38
	v_add_u32_e32 v54, v87, v3
	v_add_u32_e32 v55, v18, v2
	v_add_u32_e32 v56, v87, v2
	ds_read_b64 v[2:3], v19
	ds_read_b64 v[4:5], v54
	ds_read_b64 v[6:7], v55 offset:256
	ds_read_b64 v[8:9], v56 offset:256
	v_add_u32_e32 v59, v18, v12
	v_add_u32_e32 v60, v87, v12
	ds_read_b64 v[12:13], v57 offset:512
	ds_read_b64 v[14:15], v58 offset:512
	ds_read_b64 v[16:17], v59 offset:768
	ds_read_b64 v[20:21], v60 offset:768
	v_add_u32_e32 v63, v18, v22
	v_add_u32_e32 v64, v87, v22
	ds_read_b64 v[22:23], v61 offset:1024
	ds_read_b64 v[24:25], v62 offset:1024
	ds_read_b64 v[26:27], v63 offset:1280
	ds_read_b64 v[28:29], v64 offset:1280
	v_add_u32_e32 v67, v18, v30
	v_add_u32_e32 v71, v87, v30
	ds_read_b64 v[30:31], v65 offset:1536
	ds_read_b64 v[32:33], v66 offset:1536
	ds_read_b64 v[34:35], v67 offset:1792
	ds_read_b64 v[36:37], v71 offset:1792
	v_add_u32_e32 v74, v18, v38
	v_add_u32_e32 v75, v87, v38
	ds_read_b64 v[38:39], v72 offset:2048
	ds_read_b64 v[40:41], v73 offset:2048
	ds_read_b64 v[42:43], v74 offset:2304
	ds_read_b64 v[44:45], v75 offset:2304
	v_bitop3_b32 v46, v11, 10, 15 bitop3:0x6c
	s_waitcnt lgkmcnt(3)
	v_pk_add_f32 v[104:105], v[2:3], v[38:39]
	v_pk_add_f32 v[2:3], v[2:3], v[38:39] neg_lo:[0,1] neg_hi:[0,1]
	s_waitcnt lgkmcnt(2)
	v_pk_add_f32 v[38:39], v[4:5], v[40:41]
	v_pk_add_f32 v[4:5], v[4:5], v[40:41] neg_lo:[0,1] neg_hi:[0,1]
	v_lshlrev_b32_e32 v46, 3, v46
	v_xor_b32_e32 v41, 0x80000000, v4
	v_mov_b32_e32 v40, v5
	v_pk_mul_f32 v[40:41], v[40:41], s[58:59] op_sel_hi:[1,0]
	v_add_u32_e32 v76, v18, v46
	v_pk_fma_f32 v[4:5], v[4:5], s[46:47], v[40:41] op_sel_hi:[1,0,1]
	s_waitcnt lgkmcnt(1)
	v_pk_add_f32 v[40:41], v[6:7], v[42:43]
	v_pk_add_f32 v[6:7], v[6:7], v[42:43] neg_lo:[0,1] neg_hi:[0,1]
	v_add_u32_e32 v77, v87, v46
	v_xor_b32_e32 v43, 0x80000000, v6
	v_mov_b32_e32 v42, v7
	v_bitop3_b32 v46, v11, 11, 15 bitop3:0x6c
	v_pk_mul_f32 v[42:43], v[42:43], s[62:63] op_sel_hi:[1,0]
	v_lshlrev_b32_e32 v46, 3, v46
	v_pk_fma_f32 v[6:7], v[6:7], s[60:61], v[42:43] op_sel_hi:[1,0,1]
	s_waitcnt lgkmcnt(0)
	v_pk_add_f32 v[42:43], v[8:9], v[44:45]
	v_pk_add_f32 v[8:9], v[8:9], v[44:45] neg_lo:[0,1] neg_hi:[0,1]
	v_add_u32_e32 v78, v18, v46
	v_add_u32_e32 v79, v87, v46
	ds_read_b64 v[46:47], v76 offset:2560
	ds_read_b64 v[48:49], v77 offset:2560
	ds_read_b64 v[50:51], v78 offset:2816
	ds_read_b64 v[52:53], v79 offset:2816
	v_xor_b32_e32 v45, 0x80000000, v8
	v_mov_b32_e32 v44, v9
	v_pk_mul_f32 v[44:45], v[44:45], s[66:67] op_sel_hi:[1,0]
	v_bitop3_b32 v80, v11, 12, 15 bitop3:0x6c
	v_pk_fma_f32 v[8:9], v[8:9], s[64:65], v[44:45] op_sel_hi:[1,0,1]
	s_waitcnt lgkmcnt(3)
	v_pk_add_f32 v[44:45], v[12:13], v[46:47]
	v_pk_add_f32 v[12:13], v[12:13], v[46:47] neg_lo:[0,1] neg_hi:[0,1]
	v_lshlrev_b32_e32 v81, 3, v80
	v_xor_b32_e32 v47, 0x80000000, v12
	v_mov_b32_e32 v46, v13
	v_pk_mul_f32 v[46:47], v[46:47], s[70:71] op_sel_hi:[1,0]
	v_bitop3_b32 v82, v11, 13, 15 bitop3:0x6c
	v_pk_fma_f32 v[12:13], v[12:13], s[70:71], v[46:47] op_sel_hi:[1,0,1]
	s_waitcnt lgkmcnt(2)
	v_pk_add_f32 v[46:47], v[14:15], v[48:49]
	v_pk_add_f32 v[14:15], v[14:15], v[48:49] neg_lo:[0,1] neg_hi:[0,1]
	v_add_u32_e32 v80, v18, v81
	v_xor_b32_e32 v49, 0x80000000, v14
	v_mov_b32_e32 v48, v15
	v_pk_mul_f32 v[48:49], v[48:49], s[64:65] op_sel_hi:[1,0]
	v_lshlrev_b32_e32 v83, 3, v82
	v_pk_fma_f32 v[14:15], v[14:15], s[66:67], v[48:49] op_sel_hi:[1,0,1]
	s_waitcnt lgkmcnt(1)
	v_pk_add_f32 v[48:49], v[16:17], v[50:51]
	v_pk_add_f32 v[16:17], v[16:17], v[50:51] neg_lo:[0,1] neg_hi:[0,1]
	v_add_u32_e32 v81, v87, v81
	v_xor_b32_e32 v51, 0x80000000, v16
	v_mov_b32_e32 v50, v17
	v_pk_mul_f32 v[50:51], v[50:51], s[60:61] op_sel_hi:[1,0]
	v_add_u32_e32 v82, v18, v83
	v_pk_fma_f32 v[16:17], v[16:17], s[62:63], v[50:51] op_sel_hi:[1,0,1]
	s_waitcnt lgkmcnt(0)
	v_pk_add_f32 v[50:51], v[20:21], v[52:53]
	v_pk_add_f32 v[20:21], v[20:21], v[52:53] neg_lo:[0,1] neg_hi:[0,1]
	v_add_u32_e32 v83, v87, v83
	ds_read_b64 v[88:89], v80 offset:3072
	ds_read_b64 v[90:91], v81 offset:3072
	ds_read_b64 v[92:93], v82 offset:3328
	ds_read_b64 v[94:95], v83 offset:3328
	v_xor_b32_e32 v53, 0x80000000, v20
	v_mov_b32_e32 v52, v21
	v_pk_mul_f32 v[52:53], v[52:53], s[46:47] op_sel_hi:[1,0]
	v_bitop3_b32 v84, v11, 14, 15 bitop3:0x6c
	v_pk_fma_f32 v[20:21], v[20:21], s[58:59], v[52:53] op_sel_hi:[1,0,1]
	s_waitcnt lgkmcnt(3)
	v_pk_add_f32 v[52:53], v[22:23], v[88:89]
	v_pk_add_f32 v[22:23], v[22:23], v[88:89] neg_lo:[0,1] neg_hi:[0,1]
	v_lshlrev_b32_e32 v85, 3, v84
	v_xor_b32_e32 v89, 0x80000000, v22
	v_mov_b32_e32 v88, v23
	s_waitcnt lgkmcnt(2)
	v_pk_add_f32 v[22:23], v[24:25], v[90:91]
	v_pk_add_f32 v[24:25], v[24:25], v[90:91] neg_lo:[0,1] neg_hi:[0,1]
	v_bitop3_b32 v11, v11, 15, v11 bitop3:0xc
	v_pk_mul_f32 v[90:91], v[24:25], s[58:59] op_sel_hi:[1,0]
	v_xor_b32_e32 v107, 0x80000000, v24
	v_mov_b32_e32 v106, v25
	v_pk_fma_f32 v[24:25], v[106:107], s[46:47], v[90:91] op_sel_hi:[1,0,1] neg_lo:[0,0,1] neg_hi:[0,0,1]
	s_waitcnt lgkmcnt(1)
	v_pk_add_f32 v[90:91], v[26:27], v[92:93]
	v_pk_add_f32 v[26:27], v[26:27], v[92:93] neg_lo:[0,1] neg_hi:[0,1]
	v_add_u32_e32 v84, v18, v85
	v_lshlrev_b32_e32 v11, 3, v11
	v_pk_mul_f32 v[92:93], v[26:27], s[62:63] op_sel_hi:[1,0]
	v_xor_b32_e32 v107, 0x80000000, v26
	v_mov_b32_e32 v106, v27
	v_add_u32_e32 v85, v87, v85
	v_add_u32_e32 v86, v18, v11
	v_add_u32_e32 v87, v87, v11
	ds_read_b64 v[96:97], v84 offset:3584
	ds_read_b64 v[98:99], v85 offset:3584
	ds_read_b64 v[100:101], v86 offset:3840
	ds_read_b64 v[102:103], v87 offset:3840
	v_pk_fma_f32 v[26:27], v[106:107], s[60:61], v[92:93] op_sel_hi:[1,0,1] neg_lo:[0,0,1] neg_hi:[0,0,1]
	s_waitcnt lgkmcnt(4)
	v_pk_add_f32 v[92:93], v[28:29], v[94:95]
	v_pk_add_f32 v[28:29], v[28:29], v[94:95] neg_lo:[0,1] neg_hi:[0,1]
	s_nop 0
	v_pk_mul_f32 v[94:95], v[28:29], s[66:67] op_sel_hi:[1,0]
	v_xor_b32_e32 v107, 0x80000000, v28
	v_mov_b32_e32 v106, v29
	v_pk_fma_f32 v[28:29], v[106:107], s[64:65], v[94:95] op_sel_hi:[1,0,1] neg_lo:[0,0,1] neg_hi:[0,0,1]
	s_waitcnt lgkmcnt(3)
	v_pk_add_f32 v[94:95], v[30:31], v[96:97]
	v_pk_add_f32 v[30:31], v[30:31], v[96:97] neg_lo:[0,1] neg_hi:[0,1]
	v_cvt_f32_i32_e32 v10, v10
	v_pk_mul_f32 v[96:97], v[30:31], s[70:71] op_sel_hi:[1,0]
	v_xor_b32_e32 v107, 0x80000000, v30
	v_mov_b32_e32 v106, v31
	v_pk_fma_f32 v[30:31], v[106:107], s[70:71], v[96:97] op_sel_hi:[1,0,1] neg_lo:[0,0,1] neg_hi:[0,0,1]
	s_waitcnt lgkmcnt(2)
	v_pk_add_f32 v[96:97], v[32:33], v[98:99]
	v_pk_add_f32 v[32:33], v[32:33], v[98:99] neg_lo:[0,1] neg_hi:[0,1]
	v_mul_f32_e32 v10, 0x3b000000, v10
	v_pk_mul_f32 v[98:99], v[32:33], s[64:65] op_sel_hi:[1,0]
	v_xor_b32_e32 v107, 0x80000000, v32
	v_mov_b32_e32 v106, v33
	v_pk_fma_f32 v[32:33], v[106:107], s[66:67], v[98:99] op_sel_hi:[1,0,1] neg_lo:[0,0,1] neg_hi:[0,0,1]
	s_waitcnt lgkmcnt(1)
	v_pk_add_f32 v[98:99], v[34:35], v[100:101]
	v_pk_add_f32 v[34:35], v[34:35], v[100:101] neg_lo:[0,1] neg_hi:[0,1]
	s_nop 0
	v_pk_mul_f32 v[100:101], v[34:35], s[60:61] op_sel_hi:[1,0]
	v_xor_b32_e32 v107, 0x80000000, v34
	v_mov_b32_e32 v106, v35
	v_pk_fma_f32 v[34:35], v[106:107], s[62:63], v[100:101] op_sel_hi:[1,0,1] neg_lo:[0,0,1] neg_hi:[0,0,1]
	s_waitcnt lgkmcnt(0)
	v_pk_add_f32 v[100:101], v[36:37], v[102:103]
	v_pk_add_f32 v[36:37], v[36:37], v[102:103] neg_lo:[0,1] neg_hi:[0,1]
	s_nop 0
	v_pk_mul_f32 v[102:103], v[36:37], s[46:47] op_sel_hi:[1,0]
	v_xor_b32_e32 v107, 0x80000000, v36
	v_mov_b32_e32 v106, v37
	v_pk_fma_f32 v[36:37], v[106:107], s[58:59], v[102:103] op_sel_hi:[1,0,1] neg_lo:[0,0,1] neg_hi:[0,0,1]
	v_pk_add_f32 v[102:103], v[104:105], v[52:53]
	v_pk_add_f32 v[52:53], v[104:105], v[52:53] neg_lo:[0,1] neg_hi:[0,1]
	v_pk_add_f32 v[104:105], v[38:39], v[22:23]
	v_pk_add_f32 v[22:23], v[38:39], v[22:23] neg_lo:[0,1] neg_hi:[0,1]
	s_nop 0
	v_xor_b32_e32 v39, 0x80000000, v22
	v_mov_b32_e32 v38, v23
	v_pk_mul_f32 v[38:39], v[38:39], s[62:63] op_sel_hi:[1,0]
	s_nop 0
	v_pk_fma_f32 v[22:23], v[22:23], s[60:61], v[38:39] op_sel_hi:[1,0,1]
	v_pk_add_f32 v[38:39], v[40:41], v[90:91]
	v_pk_add_f32 v[40:41], v[40:41], v[90:91] neg_lo:[0,1] neg_hi:[0,1]
	s_nop 0
	v_xor_b32_e32 v91, 0x80000000, v40
	v_mov_b32_e32 v90, v41
	v_pk_mul_f32 v[90:91], v[90:91], s[70:71] op_sel_hi:[1,0]
	s_nop 0
	v_pk_fma_f32 v[40:41], v[40:41], s[70:71], v[90:91] op_sel_hi:[1,0,1]
	v_pk_add_f32 v[90:91], v[42:43], v[92:93]
	v_pk_add_f32 v[42:43], v[42:43], v[92:93] neg_lo:[0,1] neg_hi:[0,1]
	s_nop 0
	v_xor_b32_e32 v93, 0x80000000, v42
	v_mov_b32_e32 v92, v43
	v_pk_mul_f32 v[92:93], v[92:93], s[60:61] op_sel_hi:[1,0]
	s_nop 0
	v_pk_fma_f32 v[42:43], v[42:43], s[62:63], v[92:93] op_sel_hi:[1,0,1]
	v_pk_add_f32 v[92:93], v[44:45], v[94:95]
	v_pk_add_f32 v[44:45], v[44:45], v[94:95] neg_lo:[0,1] neg_hi:[0,1]
	s_nop 0
	v_xor_b32_e32 v95, 0x80000000, v44
	v_mov_b32_e32 v94, v45
	v_pk_add_f32 v[44:45], v[46:47], v[96:97]
	v_pk_add_f32 v[46:47], v[46:47], v[96:97] neg_lo:[0,1] neg_hi:[0,1]
	s_nop 0
	v_pk_mul_f32 v[96:97], v[46:47], s[62:63] op_sel_hi:[1,0]
	v_xor_b32_e32 v107, 0x80000000, v46
	v_mov_b32_e32 v106, v47
	v_pk_fma_f32 v[46:47], v[106:107], s[60:61], v[96:97] op_sel_hi:[1,0,1] neg_lo:[0,0,1] neg_hi:[0,0,1]
	v_pk_add_f32 v[96:97], v[48:49], v[98:99]
	v_pk_add_f32 v[48:49], v[48:49], v[98:99] neg_lo:[0,1] neg_hi:[0,1]
	s_nop 0
	v_pk_mul_f32 v[98:99], v[48:49], s[70:71] op_sel_hi:[1,0]
	v_xor_b32_e32 v107, 0x80000000, v48
	v_mov_b32_e32 v106, v49
	v_pk_fma_f32 v[48:49], v[106:107], s[70:71], v[98:99] op_sel_hi:[1,0,1] neg_lo:[0,0,1] neg_hi:[0,0,1]
	v_pk_add_f32 v[98:99], v[50:51], v[100:101]
	v_pk_add_f32 v[50:51], v[50:51], v[100:101] neg_lo:[0,1] neg_hi:[0,1]
	s_nop 0
	v_pk_mul_f32 v[100:101], v[50:51], s[60:61] op_sel_hi:[1,0]
	v_xor_b32_e32 v107, 0x80000000, v50
	v_mov_b32_e32 v106, v51
	v_pk_fma_f32 v[50:51], v[106:107], s[62:63], v[100:101] op_sel_hi:[1,0,1] neg_lo:[0,0,1] neg_hi:[0,0,1]
	v_pk_add_f32 v[100:101], v[2:3], v[88:89]
	v_pk_add_f32 v[2:3], v[2:3], v[88:89] neg_lo:[0,1] neg_hi:[0,1]
	v_pk_add_f32 v[88:89], v[4:5], v[24:25]
	v_pk_add_f32 v[4:5], v[4:5], v[24:25] neg_lo:[0,1] neg_hi:[0,1]
	s_nop 0
	v_xor_b32_e32 v25, 0x80000000, v4
	v_mov_b32_e32 v24, v5
	v_pk_mul_f32 v[24:25], v[24:25], s[62:63] op_sel_hi:[1,0]
	s_nop 0
	v_pk_fma_f32 v[4:5], v[4:5], s[60:61], v[24:25] op_sel_hi:[1,0,1]
	v_pk_add_f32 v[24:25], v[6:7], v[26:27]
	v_pk_add_f32 v[6:7], v[6:7], v[26:27] neg_lo:[0,1] neg_hi:[0,1]
	s_nop 0
	v_xor_b32_e32 v27, 0x80000000, v6
	v_mov_b32_e32 v26, v7
	v_pk_mul_f32 v[26:27], v[26:27], s[70:71] op_sel_hi:[1,0]
	s_nop 0
	v_pk_fma_f32 v[6:7], v[6:7], s[70:71], v[26:27] op_sel_hi:[1,0,1]
	v_pk_add_f32 v[26:27], v[8:9], v[28:29]
	v_pk_add_f32 v[8:9], v[8:9], v[28:29] neg_lo:[0,1] neg_hi:[0,1]
	s_nop 0
	v_xor_b32_e32 v29, 0x80000000, v8
	v_mov_b32_e32 v28, v9
	v_pk_mul_f32 v[28:29], v[28:29], s[60:61] op_sel_hi:[1,0]
	s_nop 0
	v_pk_fma_f32 v[8:9], v[8:9], s[62:63], v[28:29] op_sel_hi:[1,0,1]
	v_pk_add_f32 v[28:29], v[12:13], v[30:31]
	v_pk_add_f32 v[12:13], v[12:13], v[30:31] neg_lo:[0,1] neg_hi:[0,1]
	s_nop 0
	v_xor_b32_e32 v31, 0x80000000, v12
	v_mov_b32_e32 v30, v13
	v_pk_add_f32 v[12:13], v[14:15], v[32:33]
	v_pk_add_f32 v[14:15], v[14:15], v[32:33] neg_lo:[0,1] neg_hi:[0,1]
	s_nop 0
	v_pk_mul_f32 v[32:33], v[14:15], s[62:63] op_sel_hi:[1,0]
	v_xor_b32_e32 v107, 0x80000000, v14
	v_mov_b32_e32 v106, v15
	v_pk_fma_f32 v[14:15], v[106:107], s[60:61], v[32:33] op_sel_hi:[1,0,1] neg_lo:[0,0,1] neg_hi:[0,0,1]
	v_pk_add_f32 v[32:33], v[16:17], v[34:35]
	v_pk_add_f32 v[16:17], v[16:17], v[34:35] neg_lo:[0,1] neg_hi:[0,1]
	s_nop 0
	v_pk_mul_f32 v[34:35], v[16:17], s[70:71] op_sel_hi:[1,0]
	v_xor_b32_e32 v107, 0x80000000, v16
	v_mov_b32_e32 v106, v17
	v_pk_fma_f32 v[16:17], v[106:107], s[70:71], v[34:35] op_sel_hi:[1,0,1] neg_lo:[0,0,1] neg_hi:[0,0,1]
	v_pk_add_f32 v[34:35], v[20:21], v[36:37]
	v_pk_add_f32 v[20:21], v[20:21], v[36:37] neg_lo:[0,1] neg_hi:[0,1]
	s_nop 0
	v_pk_mul_f32 v[36:37], v[20:21], s[60:61] op_sel_hi:[1,0]
	v_xor_b32_e32 v107, 0x80000000, v20
	v_mov_b32_e32 v106, v21
	v_pk_fma_f32 v[20:21], v[106:107], s[62:63], v[36:37] op_sel_hi:[1,0,1] neg_lo:[0,0,1] neg_hi:[0,0,1]
	v_pk_add_f32 v[36:37], v[102:103], v[92:93]
	v_pk_add_f32 v[92:93], v[102:103], v[92:93] neg_lo:[0,1] neg_hi:[0,1]
	v_pk_add_f32 v[102:103], v[104:105], v[44:45]
	v_pk_add_f32 v[44:45], v[104:105], v[44:45] neg_lo:[0,1] neg_hi:[0,1]
	s_nop 0
	v_xor_b32_e32 v105, 0x80000000, v44
	v_mov_b32_e32 v104, v45
	v_pk_mul_f32 v[104:105], v[104:105], s[70:71] op_sel_hi:[1,0]
	s_nop 0
	v_pk_fma_f32 v[44:45], v[44:45], s[70:71], v[104:105] op_sel_hi:[1,0,1]
	v_pk_add_f32 v[104:105], v[38:39], v[96:97]
	v_pk_add_f32 v[38:39], v[38:39], v[96:97] neg_lo:[0,1] neg_hi:[0,1]
	s_nop 0
	v_xor_b32_e32 v97, 0x80000000, v38
	v_mov_b32_e32 v96, v39
	v_pk_add_f32 v[38:39], v[90:91], v[98:99]
	v_pk_add_f32 v[90:91], v[90:91], v[98:99] neg_lo:[0,1] neg_hi:[0,1]
	s_nop 0
	v_pk_mul_f32 v[98:99], v[90:91], s[70:71] op_sel_hi:[1,0]
	v_xor_b32_e32 v107, 0x80000000, v90
	v_mov_b32_e32 v106, v91
	v_pk_fma_f32 v[90:91], v[106:107], s[70:71], v[98:99] op_sel_hi:[1,0,1] neg_lo:[0,0,1] neg_hi:[0,0,1]
	v_pk_add_f32 v[98:99], v[52:53], v[94:95]
	v_pk_add_f32 v[52:53], v[52:53], v[94:95] neg_lo:[0,1] neg_hi:[0,1]
	v_pk_add_f32 v[94:95], v[22:23], v[46:47]
	v_pk_add_f32 v[22:23], v[22:23], v[46:47] neg_lo:[0,1] neg_hi:[0,1]
	s_nop 0
	v_xor_b32_e32 v47, 0x80000000, v22
	v_mov_b32_e32 v46, v23
	v_pk_mul_f32 v[46:47], v[46:47], s[70:71] op_sel_hi:[1,0]
	s_nop 0
	v_pk_fma_f32 v[22:23], v[22:23], s[70:71], v[46:47] op_sel_hi:[1,0,1]
	v_pk_add_f32 v[46:47], v[40:41], v[48:49]
	v_pk_add_f32 v[40:41], v[40:41], v[48:49] neg_lo:[0,1] neg_hi:[0,1]
	s_nop 0
	v_xor_b32_e32 v49, 0x80000000, v40
	v_mov_b32_e32 v48, v41
	v_pk_add_f32 v[40:41], v[42:43], v[50:51]
	v_pk_add_f32 v[42:43], v[42:43], v[50:51] neg_lo:[0,1] neg_hi:[0,1]
	s_nop 0
	v_pk_mul_f32 v[50:51], v[42:43], s[70:71] op_sel_hi:[1,0]
	v_xor_b32_e32 v107, 0x80000000, v42
	v_mov_b32_e32 v106, v43
	v_pk_fma_f32 v[42:43], v[106:107], s[70:71], v[50:51] op_sel_hi:[1,0,1] neg_lo:[0,0,1] neg_hi:[0,0,1]
	v_pk_add_f32 v[50:51], v[100:101], v[28:29]
	v_pk_add_f32 v[28:29], v[100:101], v[28:29] neg_lo:[0,1] neg_hi:[0,1]
	v_pk_add_f32 v[100:101], v[88:89], v[12:13]
	v_pk_add_f32 v[12:13], v[88:89], v[12:13] neg_lo:[0,1] neg_hi:[0,1]
	s_nop 0
	v_xor_b32_e32 v89, 0x80000000, v12
	v_mov_b32_e32 v88, v13
	v_pk_mul_f32 v[88:89], v[88:89], s[70:71] op_sel_hi:[1,0]
	s_nop 0
	v_pk_fma_f32 v[12:13], v[12:13], s[70:71], v[88:89] op_sel_hi:[1,0,1]
	v_pk_add_f32 v[88:89], v[24:25], v[32:33]
	v_pk_add_f32 v[24:25], v[24:25], v[32:33] neg_lo:[0,1] neg_hi:[0,1]
	v_pk_add_f32 v[108:109], v[50:51], v[88:89]
	v_xor_b32_e32 v33, 0x80000000, v24
	v_mov_b32_e32 v32, v25
	v_pk_add_f32 v[24:25], v[26:27], v[34:35]
	v_pk_add_f32 v[26:27], v[26:27], v[34:35] neg_lo:[0,1] neg_hi:[0,1]
	v_pk_add_f32 v[50:51], v[50:51], v[88:89] neg_lo:[0,1] neg_hi:[0,1]
	v_pk_mul_f32 v[34:35], v[26:27], s[70:71] op_sel_hi:[1,0]
	v_xor_b32_e32 v107, 0x80000000, v26
	v_mov_b32_e32 v106, v27
	v_pk_fma_f32 v[26:27], v[106:107], s[70:71], v[34:35] op_sel_hi:[1,0,1] neg_lo:[0,0,1] neg_hi:[0,0,1]
	v_pk_add_f32 v[34:35], v[2:3], v[30:31]
	v_pk_add_f32 v[2:3], v[2:3], v[30:31] neg_lo:[0,1] neg_hi:[0,1]
	v_pk_add_f32 v[30:31], v[4:5], v[14:15]
	v_pk_add_f32 v[4:5], v[4:5], v[14:15] neg_lo:[0,1] neg_hi:[0,1]
	v_pk_add_f32 v[110:111], v[12:13], v[26:27]
	v_xor_b32_e32 v15, 0x80000000, v4
	v_mov_b32_e32 v14, v5
	v_pk_mul_f32 v[14:15], v[14:15], s[70:71] op_sel_hi:[1,0]
	v_pk_add_f32 v[12:13], v[12:13], v[26:27] neg_lo:[0,1] neg_hi:[0,1]
	v_pk_fma_f32 v[4:5], v[4:5], s[70:71], v[14:15] op_sel_hi:[1,0,1]
	v_pk_add_f32 v[14:15], v[6:7], v[16:17]
	v_pk_add_f32 v[6:7], v[6:7], v[16:17] neg_lo:[0,1] neg_hi:[0,1]
	v_pk_add_f32 v[88:89], v[100:101], v[24:25]
	v_xor_b32_e32 v17, 0x80000000, v6
	v_mov_b32_e32 v16, v7
	v_pk_add_f32 v[6:7], v[8:9], v[20:21]
	v_pk_add_f32 v[8:9], v[8:9], v[20:21] neg_lo:[0,1] neg_hi:[0,1]
	v_xor_b32_e32 v113, 0x80000000, v12
	v_pk_mul_f32 v[20:21], v[8:9], s[70:71] op_sel_hi:[1,0]
	v_xor_b32_e32 v107, 0x80000000, v8
	v_mov_b32_e32 v106, v9
	v_pk_fma_f32 v[8:9], v[106:107], s[70:71], v[20:21] op_sel_hi:[1,0,1] neg_lo:[0,0,1] neg_hi:[0,0,1]
	v_pk_add_f32 v[20:21], v[36:37], v[104:105]
	v_pk_add_f32 v[36:37], v[36:37], v[104:105] neg_lo:[0,1] neg_hi:[0,1]
	v_pk_add_f32 v[104:105], v[102:103], v[38:39]
	v_pk_add_f32 v[38:39], v[102:103], v[38:39] neg_lo:[0,1] neg_hi:[0,1]
	v_pk_add_f32 v[106:107], v[52:53], v[48:49]
	v_xor_b32_e32 v103, 0x80000000, v38
	v_mov_b32_e32 v102, v39
	v_pk_add_f32 v[38:39], v[92:93], v[96:97]
	v_pk_add_f32 v[92:93], v[92:93], v[96:97] neg_lo:[0,1] neg_hi:[0,1]
	v_pk_add_f32 v[96:97], v[44:45], v[90:91]
	v_pk_add_f32 v[44:45], v[44:45], v[90:91] neg_lo:[0,1] neg_hi:[0,1]
	v_pk_add_f32 v[48:49], v[52:53], v[48:49] neg_lo:[0,1] neg_hi:[0,1]
	v_pk_add_f32 v[52:53], v[22:23], v[42:43]
	v_pk_add_f32 v[22:23], v[22:23], v[42:43] neg_lo:[0,1] neg_hi:[0,1]
	v_xor_b32_e32 v91, 0x80000000, v44
	v_mov_b32_e32 v90, v45
	v_pk_add_f32 v[44:45], v[98:99], v[46:47]
	v_pk_add_f32 v[46:47], v[98:99], v[46:47] neg_lo:[0,1] neg_hi:[0,1]
	v_pk_add_f32 v[98:99], v[94:95], v[40:41]
	v_pk_add_f32 v[40:41], v[94:95], v[40:41] neg_lo:[0,1] neg_hi:[0,1]
	v_xor_b32_e32 v43, 0x80000000, v22
	v_mov_b32_e32 v42, v23
	v_pk_add_f32 v[22:23], v[100:101], v[24:25] neg_lo:[0,1] neg_hi:[0,1]
	v_xor_b32_e32 v95, 0x80000000, v40
	v_mov_b32_e32 v94, v41
	v_xor_b32_e32 v25, 0x80000000, v22
	v_mov_b32_e32 v24, v23
	v_pk_add_f32 v[100:101], v[28:29], v[32:33]
	v_pk_add_f32 v[32:33], v[28:29], v[32:33] neg_lo:[0,1] neg_hi:[0,1]
	v_mov_b32_e32 v112, v13
	v_pk_add_f32 v[12:13], v[34:35], v[14:15]
	v_pk_add_f32 v[14:15], v[34:35], v[14:15] neg_lo:[0,1] neg_hi:[0,1]
	v_pk_add_f32 v[34:35], v[30:31], v[6:7]
	v_pk_add_f32 v[6:7], v[30:31], v[6:7] neg_lo:[0,1] neg_hi:[0,1]
	v_pk_add_f32 v[114:115], v[2:3], v[16:17]
	v_pk_add_f32 v[16:17], v[2:3], v[16:17] neg_lo:[0,1] neg_hi:[0,1]
	v_pk_add_f32 v[2:3], v[4:5], v[8:9] neg_lo:[0,1] neg_hi:[0,1]
	v_xor_b32_e32 v31, 0x80000000, v6
	v_mov_b32_e32 v30, v7
	v_pk_add_f32 v[116:117], v[4:5], v[8:9]
	v_xor_b32_e32 v119, 0x80000000, v2
	v_mov_b32_e32 v118, v3
	v_pk_add_f32 v[2:3], v[20:21], v[104:105]
	v_pk_add_f32 v[104:105], v[20:21], v[104:105] neg_lo:[0,1] neg_hi:[0,1]
	v_pk_add_f32 v[120:121], v[36:37], v[102:103]
	v_pk_add_f32 v[26:27], v[36:37], v[102:103] neg_lo:[0,1] neg_hi:[0,1]
	v_pk_add_f32 v[36:37], v[38:39], v[96:97]
	v_pk_add_f32 v[40:41], v[38:39], v[96:97] neg_lo:[0,1] neg_hi:[0,1]
	v_pk_add_f32 v[96:97], v[92:93], v[90:91]
	v_pk_add_f32 v[6:7], v[92:93], v[90:91] neg_lo:[0,1] neg_hi:[0,1]
	v_pk_add_f32 v[20:21], v[44:45], v[98:99]
	v_pk_add_f32 v[90:91], v[44:45], v[98:99] neg_lo:[0,1] neg_hi:[0,1]
	v_pk_add_f32 v[92:93], v[46:47], v[94:95]
	v_pk_add_f32 v[22:23], v[46:47], v[94:95] neg_lo:[0,1] neg_hi:[0,1]
	v_pk_add_f32 v[46:47], v[106:107], v[52:53]
	v_pk_add_f32 v[38:39], v[106:107], v[52:53] neg_lo:[0,1] neg_hi:[0,1]
	v_pk_add_f32 v[52:53], v[50:51], v[24:25]
	v_pk_add_f32 v[28:29], v[50:51], v[24:25] neg_lo:[0,1] neg_hi:[0,1]
	v_pk_add_f32 v[50:51], v[100:101], v[110:111]
	v_pk_add_f32 v[44:45], v[100:101], v[110:111] neg_lo:[0,1] neg_hi:[0,1]
	v_pk_add_f32 v[98:99], v[32:33], v[112:113]
	v_pk_add_f32 v[8:9], v[32:33], v[112:113] neg_lo:[0,1] neg_hi:[0,1]
	v_pk_add_f32 v[32:33], v[12:13], v[34:35]
	v_pk_add_f32 v[100:101], v[12:13], v[34:35] neg_lo:[0,1] neg_hi:[0,1]
	v_cos_f32_e32 v12, v10
	v_sin_f32_e32 v13, v10
	v_pk_add_f32 v[94:95], v[48:49], v[42:43]
	v_pk_add_f32 v[4:5], v[48:49], v[42:43] neg_lo:[0,1] neg_hi:[0,1]
	v_pk_add_f32 v[48:49], v[108:109], v[88:89]
	v_pk_add_f32 v[102:103], v[14:15], v[30:31]
	v_pk_add_f32 v[24:25], v[14:15], v[30:31] neg_lo:[0,1] neg_hi:[0,1]
	v_pk_add_f32 v[106:107], v[16:17], v[118:119]
	v_pk_add_f32 v[10:11], v[16:17], v[118:119] neg_lo:[0,1] neg_hi:[0,1]
	v_pk_mul_f32 v[14:15], v[12:13], v[12:13]
	v_add_f32_e32 v16, v12, v12
	v_pk_add_f32 v[88:89], v[108:109], v[88:89] neg_lo:[0,1] neg_hi:[0,1]
	v_mul_f32_e32 v18, v13, v16
	v_pk_add_f32 v[16:17], v[14:15], v[14:15] op_sel:[0,1] op_sel_hi:[0,1] neg_lo:[0,1] neg_hi:[0,1]
	v_xor_b32_e32 v14, 0x80000000, v13
	v_mov_b32_e32 v15, v12
	v_xor_b32_e32 v31, 0x80000000, v48
	v_mov_b32_e32 v30, v49
	v_mov_b32_e32 v108, v13
	v_pk_mul_f32 v[14:15], v[14:15], v[18:19] op_sel_hi:[1,0]
	v_pk_mul_f32 v[30:31], v[108:109], v[30:31] op_sel_hi:[0,1]
	v_pk_fma_f32 v[14:15], v[12:13], v[16:17], v[14:15]
	v_pk_fma_f32 v[12:13], v[12:13], v[48:49], v[30:31] op_sel_hi:[0,1,1]
	v_pk_mul_f32 v[30:31], v[18:19], s[48:49] op_sel_hi:[0,1]
	v_pk_fma_f32 v[30:31], v[16:17], s[40:41], v[30:31]
	v_xor_b32_e32 v49, 0x80000000, v20
	v_mov_b32_e32 v48, v21
	v_pk_mul_f32 v[48:49], v[30:31], v[48:49] op_sel:[1,0]
	v_xor_b32_e32 v109, 0x80000000, v32
	v_pk_fma_f32 v[20:21], v[20:21], v[30:31], v[48:49] op_sel_hi:[1,0,1]
	v_xor_b32_e32 v48, 0x80000000, v15
	v_mov_b32_e32 v49, v14
	v_mov_b32_e32 v108, v33
	v_pk_mul_f32 v[48:49], v[18:19], v[48:49] op_sel_hi:[0,1]
	v_pk_mul_f32 v[108:109], v[14:15], v[108:109] op_sel:[1,0]
	v_pk_fma_f32 v[48:49], v[16:17], v[14:15], v[48:49]
	v_pk_fma_f32 v[14:15], v[14:15], v[32:33], v[108:109] op_sel_hi:[0,1,1]
	v_xor_b32_e32 v32, 0x80000000, v31
	v_mov_b32_e32 v33, v30
	v_pk_mul_f32 v[32:33], v[18:19], v[32:33] op_sel_hi:[0,1]
	v_pk_fma_f32 v[108:109], v[16:17], v[30:31], v[32:33]
	v_xor_b32_e32 v31, 0x80000000, v36
	v_mov_b32_e32 v30, v37
	v_pk_mul_f32 v[30:31], v[30:31], v[108:109] op_sel:[0,1]
	v_pk_add_f32 v[34:35], v[114:115], v[116:117]
	v_pk_fma_f32 v[32:33], v[36:37], v[108:109], v[30:31] op_sel_hi:[1,0,1]
	v_xor_b32_e32 v30, 0x80000000, v49
	v_mov_b32_e32 v31, v48
	v_pk_mul_f32 v[30:31], v[18:19], v[30:31] op_sel_hi:[0,1]
	v_pk_fma_f32 v[110:111], v[16:17], v[48:49], v[30:31]
	v_xor_b32_e32 v31, 0x80000000, v50
	v_mov_b32_e32 v30, v51
	v_xor_b32_e32 v36, 0x80000000, v109
	v_mov_b32_e32 v37, v108
	v_pk_mul_f32 v[30:31], v[48:49], v[30:31] op_sel:[1,0]
	v_pk_mul_f32 v[36:37], v[18:19], v[36:37] op_sel_hi:[0,1]
	v_pk_fma_f32 v[30:31], v[50:51], v[48:49], v[30:31] op_sel_hi:[1,0,1]
	v_pk_fma_f32 v[48:49], v[16:17], v[108:109], v[36:37]
	v_xor_b32_e32 v37, 0x80000000, v46
	v_mov_b32_e32 v36, v47
	v_pk_mul_f32 v[36:37], v[36:37], v[48:49] op_sel:[0,1]
	v_xor_b32_e32 v51, 0x80000000, v34
	v_pk_fma_f32 v[36:37], v[46:47], v[48:49], v[36:37] op_sel_hi:[1,0,1]
	v_xor_b32_e32 v46, 0x80000000, v111
	v_mov_b32_e32 v47, v110
	v_mov_b32_e32 v50, v35
	v_pk_mul_f32 v[46:47], v[18:19], v[46:47] op_sel_hi:[0,1]
	v_pk_mul_f32 v[50:51], v[110:111], v[50:51] op_sel:[1,0]
	v_pk_fma_f32 v[46:47], v[16:17], v[110:111], v[46:47]
	v_pk_fma_f32 v[34:35], v[34:35], v[110:111], v[50:51] op_sel_hi:[1,0,1]
	v_xor_b32_e32 v50, 0x80000000, v49
	v_mov_b32_e32 v51, v48
	v_pk_mul_f32 v[50:51], v[18:19], v[50:51] op_sel_hi:[0,1]
	v_xor_b32_e32 v108, 0x80000000, v47
	v_mov_b32_e32 v109, v46
	v_xor_b32_e32 v111, 0x80000000, v52
	v_mov_b32_e32 v110, v53
	v_pk_fma_f32 v[50:51], v[16:17], v[48:49], v[50:51]
	v_pk_mul_f32 v[108:109], v[18:19], v[108:109] op_sel_hi:[0,1]
	v_pk_mul_f32 v[110:111], v[110:111], v[46:47] op_sel:[0,1]
	v_xor_b32_e32 v49, 0x80000000, v120
	v_mov_b32_e32 v48, v121
	v_pk_fma_f32 v[108:109], v[16:17], v[46:47], v[108:109]
	v_pk_fma_f32 v[46:47], v[52:53], v[46:47], v[110:111] op_sel_hi:[1,0,1]
	v_xor_b32_e32 v52, 0x80000000, v51
	v_mov_b32_e32 v53, v50
	v_pk_mul_f32 v[48:49], v[48:49], v[50:51] op_sel:[0,1]
	v_pk_mul_f32 v[52:53], v[18:19], v[52:53] op_sel_hi:[0,1]
	v_pk_fma_f32 v[48:49], v[120:121], v[50:51], v[48:49] op_sel_hi:[1,0,1]
	v_pk_fma_f32 v[110:111], v[16:17], v[50:51], v[52:53]
	v_xor_b32_e32 v51, 0x80000000, v92
	v_mov_b32_e32 v50, v93
	v_pk_mul_f32 v[50:51], v[50:51], v[110:111] op_sel:[0,1]
	v_pk_add_f32 v[42:43], v[114:115], v[116:117] neg_lo:[0,1] neg_hi:[0,1]
	v_pk_fma_f32 v[52:53], v[92:93], v[110:111], v[50:51] op_sel_hi:[1,0,1]
	v_xor_b32_e32 v50, 0x80000000, v109
	v_mov_b32_e32 v51, v108
	v_pk_mul_f32 v[50:51], v[18:19], v[50:51] op_sel_hi:[0,1]
	v_pk_fma_f32 v[92:93], v[16:17], v[108:109], v[50:51]
	v_xor_b32_e32 v51, 0x80000000, v102
	v_mov_b32_e32 v50, v103
	v_pk_mul_f32 v[50:51], v[50:51], v[108:109] op_sel:[0,1]
	s_nop 0
	v_pk_fma_f32 v[50:51], v[102:103], v[108:109], v[50:51] op_sel_hi:[1,0,1]
	v_xor_b32_e32 v102, 0x80000000, v111
	v_mov_b32_e32 v103, v110
	v_pk_mul_f32 v[102:103], v[18:19], v[102:103] op_sel_hi:[0,1]
	v_pk_fma_f32 v[102:103], v[16:17], v[110:111], v[102:103]
	v_xor_b32_e32 v109, 0x80000000, v96
	v_mov_b32_e32 v108, v97
	v_pk_mul_f32 v[108:109], v[108:109], v[102:103] op_sel:[0,1]
	v_xor_b32_e32 v111, 0x80000000, v98
	v_pk_fma_f32 v[96:97], v[96:97], v[102:103], v[108:109] op_sel_hi:[1,0,1]
	v_xor_b32_e32 v108, 0x80000000, v93
	v_mov_b32_e32 v109, v92
	v_mov_b32_e32 v110, v99
	v_pk_mul_f32 v[108:109], v[18:19], v[108:109] op_sel_hi:[0,1]
	v_pk_mul_f32 v[110:111], v[110:111], v[92:93] op_sel:[0,1]
	v_pk_fma_f32 v[108:109], v[16:17], v[92:93], v[108:109]
	v_pk_fma_f32 v[92:93], v[98:99], v[92:93], v[110:111] op_sel_hi:[1,0,1]
	v_xor_b32_e32 v98, 0x80000000, v103
	v_mov_b32_e32 v99, v102
	v_pk_mul_f32 v[98:99], v[18:19], v[98:99] op_sel_hi:[0,1]
	v_pk_fma_f32 v[98:99], v[16:17], v[102:103], v[98:99]
	v_xor_b32_e32 v103, 0x80000000, v94
	v_mov_b32_e32 v102, v95
	v_pk_mul_f32 v[102:103], v[102:103], v[98:99] op_sel:[0,1]
	v_xor_b32_e32 v111, 0x80000000, v106
	v_pk_fma_f32 v[94:95], v[94:95], v[98:99], v[102:103] op_sel_hi:[1,0,1]
	v_xor_b32_e32 v102, 0x80000000, v109
	v_mov_b32_e32 v103, v108
	v_mov_b32_e32 v110, v107
	v_pk_mul_f32 v[102:103], v[18:19], v[102:103] op_sel_hi:[0,1]
	v_pk_mul_f32 v[110:111], v[110:111], v[108:109] op_sel:[0,1]
	v_pk_fma_f32 v[102:103], v[16:17], v[108:109], v[102:103]
	v_pk_fma_f32 v[106:107], v[106:107], v[108:109], v[110:111] op_sel_hi:[1,0,1]
	v_xor_b32_e32 v108, 0x80000000, v99
	v_mov_b32_e32 v109, v98
	v_pk_mul_f32 v[108:109], v[18:19], v[108:109] op_sel_hi:[0,1]
	v_pk_fma_f32 v[98:99], v[16:17], v[98:99], v[108:109]
	v_xor_b32_e32 v109, 0x80000000, v104
	v_mov_b32_e32 v108, v105
	v_pk_mul_f32 v[108:109], v[108:109], v[98:99] op_sel:[0,1]
	v_xor_b32_e32 v111, 0x80000000, v88
	v_pk_fma_f32 v[104:105], v[104:105], v[98:99], v[108:109] op_sel_hi:[1,0,1]
	v_xor_b32_e32 v108, 0x80000000, v103
	v_mov_b32_e32 v109, v102
	v_mov_b32_e32 v110, v89
	v_pk_mul_f32 v[108:109], v[18:19], v[108:109] op_sel_hi:[0,1]
	v_pk_mul_f32 v[110:111], v[110:111], v[102:103] op_sel:[0,1]
	v_pk_fma_f32 v[108:109], v[16:17], v[102:103], v[108:109]
	v_pk_fma_f32 v[88:89], v[88:89], v[102:103], v[110:111] op_sel_hi:[1,0,1]
	v_xor_b32_e32 v102, 0x80000000, v99
	v_mov_b32_e32 v103, v98
	v_pk_mul_f32 v[102:103], v[18:19], v[102:103] op_sel_hi:[0,1]
	v_pk_fma_f32 v[98:99], v[16:17], v[98:99], v[102:103]
	v_xor_b32_e32 v103, 0x80000000, v90
	v_mov_b32_e32 v102, v91
	v_pk_mul_f32 v[102:103], v[102:103], v[98:99] op_sel:[0,1]
	v_xor_b32_e32 v111, 0x80000000, v100
	v_pk_fma_f32 v[90:91], v[90:91], v[98:99], v[102:103] op_sel_hi:[1,0,1]
	v_xor_b32_e32 v102, 0x80000000, v109
	v_mov_b32_e32 v103, v108
	v_mov_b32_e32 v110, v101
	v_pk_mul_f32 v[102:103], v[18:19], v[102:103] op_sel_hi:[0,1]
	v_pk_mul_f32 v[110:111], v[110:111], v[108:109] op_sel:[0,1]
	v_pk_fma_f32 v[102:103], v[16:17], v[108:109], v[102:103]
	v_pk_fma_f32 v[100:101], v[100:101], v[108:109], v[110:111] op_sel_hi:[1,0,1]
	v_xor_b32_e32 v108, 0x80000000, v99
	v_mov_b32_e32 v109, v98
	v_pk_mul_f32 v[108:109], v[18:19], v[108:109] op_sel_hi:[0,1]
	v_pk_fma_f32 v[98:99], v[16:17], v[98:99], v[108:109]
	v_xor_b32_e32 v109, 0x80000000, v40
	v_mov_b32_e32 v108, v41
	v_pk_mul_f32 v[108:109], v[108:109], v[98:99] op_sel:[0,1]
	v_xor_b32_e32 v111, 0x80000000, v44
	v_pk_fma_f32 v[40:41], v[40:41], v[98:99], v[108:109] op_sel_hi:[1,0,1]
	v_xor_b32_e32 v108, 0x80000000, v103
	v_mov_b32_e32 v109, v102
	v_mov_b32_e32 v110, v45
	v_pk_mul_f32 v[108:109], v[18:19], v[108:109] op_sel_hi:[0,1]
	v_pk_mul_f32 v[110:111], v[110:111], v[102:103] op_sel:[0,1]
	v_pk_fma_f32 v[108:109], v[16:17], v[102:103], v[108:109]
	v_pk_fma_f32 v[44:45], v[44:45], v[102:103], v[110:111] op_sel_hi:[1,0,1]
	v_xor_b32_e32 v102, 0x80000000, v99
	v_mov_b32_e32 v103, v98
	v_pk_mul_f32 v[102:103], v[18:19], v[102:103] op_sel_hi:[0,1]
	v_pk_fma_f32 v[98:99], v[16:17], v[98:99], v[102:103]
	v_xor_b32_e32 v103, 0x80000000, v38
	v_mov_b32_e32 v102, v39
	v_pk_mul_f32 v[102:103], v[102:103], v[98:99] op_sel:[0,1]
	v_xor_b32_e32 v111, 0x80000000, v42
	v_pk_fma_f32 v[38:39], v[38:39], v[98:99], v[102:103] op_sel_hi:[1,0,1]
	v_xor_b32_e32 v102, 0x80000000, v109
	v_mov_b32_e32 v103, v108
	v_mov_b32_e32 v110, v43
	v_pk_mul_f32 v[102:103], v[18:19], v[102:103] op_sel_hi:[0,1]
	v_pk_mul_f32 v[110:111], v[110:111], v[108:109] op_sel:[0,1]
	v_pk_fma_f32 v[102:103], v[16:17], v[108:109], v[102:103]
	v_pk_fma_f32 v[42:43], v[42:43], v[108:109], v[110:111] op_sel_hi:[1,0,1]
	v_xor_b32_e32 v108, 0x80000000, v99
	v_mov_b32_e32 v109, v98
	v_pk_mul_f32 v[108:109], v[18:19], v[108:109] op_sel_hi:[0,1]
	v_pk_fma_f32 v[98:99], v[16:17], v[98:99], v[108:109]
	v_xor_b32_e32 v109, 0x80000000, v26
	v_mov_b32_e32 v108, v27
	v_pk_mul_f32 v[108:109], v[108:109], v[98:99] op_sel:[0,1]
	v_xor_b32_e32 v111, 0x80000000, v28
	v_pk_fma_f32 v[26:27], v[26:27], v[98:99], v[108:109] op_sel_hi:[1,0,1]
	v_xor_b32_e32 v108, 0x80000000, v103
	v_mov_b32_e32 v109, v102
	v_mov_b32_e32 v110, v29
	v_pk_mul_f32 v[108:109], v[18:19], v[108:109] op_sel_hi:[0,1]
	v_pk_mul_f32 v[110:111], v[110:111], v[102:103] op_sel:[0,1]
	v_pk_fma_f32 v[108:109], v[16:17], v[102:103], v[108:109]
	v_pk_fma_f32 v[28:29], v[28:29], v[102:103], v[110:111] op_sel_hi:[1,0,1]
	v_xor_b32_e32 v102, 0x80000000, v99
	v_mov_b32_e32 v103, v98
	v_pk_mul_f32 v[102:103], v[18:19], v[102:103] op_sel_hi:[0,1]
	v_pk_fma_f32 v[98:99], v[16:17], v[98:99], v[102:103]
	v_xor_b32_e32 v103, 0x80000000, v22
	v_mov_b32_e32 v102, v23
	v_pk_mul_f32 v[102:103], v[102:103], v[98:99] op_sel:[0,1]
	v_xor_b32_e32 v111, 0x80000000, v24
	v_pk_fma_f32 v[22:23], v[22:23], v[98:99], v[102:103] op_sel_hi:[1,0,1]
	v_xor_b32_e32 v102, 0x80000000, v109
	v_mov_b32_e32 v103, v108
	v_mov_b32_e32 v110, v25
	v_pk_mul_f32 v[102:103], v[18:19], v[102:103] op_sel_hi:[0,1]
	v_pk_mul_f32 v[110:111], v[110:111], v[108:109] op_sel:[0,1]
	v_pk_fma_f32 v[102:103], v[16:17], v[108:109], v[102:103]
	v_pk_fma_f32 v[24:25], v[24:25], v[108:109], v[110:111] op_sel_hi:[1,0,1]
	v_xor_b32_e32 v108, 0x80000000, v99
	v_mov_b32_e32 v109, v98
	v_pk_mul_f32 v[108:109], v[18:19], v[108:109] op_sel_hi:[0,1]
	v_pk_fma_f32 v[98:99], v[16:17], v[98:99], v[108:109]
	v_xor_b32_e32 v109, 0x80000000, v6
	v_mov_b32_e32 v108, v7
	v_pk_mul_f32 v[108:109], v[108:109], v[98:99] op_sel:[0,1]
	v_xor_b32_e32 v111, 0x80000000, v8
	v_pk_fma_f32 v[6:7], v[6:7], v[98:99], v[108:109] op_sel_hi:[1,0,1]
	v_xor_b32_e32 v108, 0x80000000, v103
	v_mov_b32_e32 v109, v102
	v_mov_b32_e32 v110, v9
	v_pk_mul_f32 v[108:109], v[18:19], v[108:109] op_sel_hi:[0,1]
	v_pk_mul_f32 v[110:111], v[110:111], v[102:103] op_sel:[0,1]
	v_pk_fma_f32 v[108:109], v[16:17], v[102:103], v[108:109]
	v_pk_fma_f32 v[8:9], v[8:9], v[102:103], v[110:111] op_sel_hi:[1,0,1]
	v_xor_b32_e32 v102, 0x80000000, v99
	v_mov_b32_e32 v103, v98
	v_pk_mul_f32 v[102:103], v[18:19], v[102:103] op_sel_hi:[0,1]
	v_pk_fma_f32 v[16:17], v[16:17], v[98:99], v[102:103]
	v_xor_b32_e32 v99, 0x80000000, v4
	v_mov_b32_e32 v98, v5
	v_pk_mul_f32 v[98:99], v[98:99], v[16:17] op_sel:[0,1]
	s_nop 0
	v_pk_fma_f32 v[4:5], v[4:5], v[16:17], v[98:99] op_sel_hi:[1,0,1]
	v_xor_b32_e32 v17, 0x80000000, v10
	v_mov_b32_e32 v16, v11
	v_pk_mul_f32 v[16:17], v[16:17], v[108:109] op_sel:[0,1]
	s_nop 0
	v_pk_fma_f32 v[10:11], v[10:11], v[108:109], v[16:17] op_sel_hi:[1,0,1]
	ds_write_b64 v19, v[2:3]
	ds_write_b64 v54, v[104:105]
	ds_write_b64 v55, v[48:49] offset:256
	ds_write_b64 v56, v[26:27] offset:256
	ds_write_b64 v57, v[32:33] offset:512
	ds_write_b64 v58, v[40:41] offset:512
	ds_write_b64 v59, v[96:97] offset:768
	ds_write_b64 v60, v[6:7] offset:768
	ds_write_b64 v61, v[20:21] offset:1024
	ds_write_b64 v62, v[90:91] offset:1024
	ds_write_b64 v63, v[52:53] offset:1280
	ds_write_b64 v64, v[22:23] offset:1280
	ds_write_b64 v65, v[36:37] offset:1536
	ds_write_b64 v66, v[38:39] offset:1536
	ds_write_b64 v67, v[94:95] offset:1792
	ds_write_b64 v71, v[4:5] offset:1792
	ds_write_b64 v72, v[12:13] offset:2048
	ds_write_b64 v73, v[88:89] offset:2048
	ds_write_b64 v74, v[46:47] offset:2304
	ds_write_b64 v75, v[28:29] offset:2304
	ds_write_b64 v76, v[30:31] offset:2560
	ds_write_b64 v77, v[44:45] offset:2560
	ds_write_b64 v78, v[92:93] offset:2816
	ds_write_b64 v79, v[8:9] offset:2816
	ds_write_b64 v80, v[14:15] offset:3072
	ds_write_b64 v81, v[100:101] offset:3072
	ds_write_b64 v82, v[50:51] offset:3328
	ds_write_b64 v83, v[24:25] offset:3328
	ds_write_b64 v84, v[34:35] offset:3584
	ds_write_b64 v85, v[42:43] offset:3584
	ds_write_b64 v86, v[106:107] offset:3840
	ds_write_b64 v87, v[10:11] offset:3840
	v_mov_b32_e32 v2, v146
	s_waitcnt lgkmcnt(0)
	s_barrier
	s_nop 0
	v_lshlrev_b32_e32 v34, 4, v2
	v_lshrrev_b32_e32 v35, 1, v2
	v_bitop3_b32 v3, v35, v34, 16 bitop3:0x6c
	v_lshl_add_u32 v26, v3, 3, 16
	v_bitop3_b32 v3, v35, 1, 15 bitop3:0x6c
	v_bitop3_b32 v11, v35, 5, 15 bitop3:0x6c
	v_bitop3_b32 v19, v35, 9, 15 bitop3:0x6c
	v_lshlrev_b32_e32 v37, 3, v3
	v_bitop3_b32 v3, v35, 2, 15 bitop3:0x6c
	v_lshlrev_b32_e32 v45, 3, v11
	v_bitop3_b32 v11, v35, 6, 15 bitop3:0x6c
	v_lshlrev_b32_e32 v49, 3, v19
	v_bitop3_b32 v19, v35, 10, 15 bitop3:0x6c
	v_bitop3_b32 v29, v35, 14, 15 bitop3:0x6c
	v_add_u32_e32 v34, 0x2000, v34
	v_bfe_u32 v2, v2, 1, 4
	v_lshlrev_b32_e32 v38, 3, v3
	v_bitop3_b32 v3, v35, 3, 15 bitop3:0x6c
	v_bitop3_b32 v10, v35, 4, 15 bitop3:0x6c
	v_lshlrev_b32_e32 v46, 3, v11
	v_bitop3_b32 v11, v35, 7, 15 bitop3:0x6c
	v_bitop3_b32 v18, v35, 8, 15 bitop3:0x6c
	v_lshlrev_b32_e32 v50, 3, v19
	v_bitop3_b32 v19, v35, 11, 15 bitop3:0x6c
	v_bitop3_b32 v27, v35, 12, 15 bitop3:0x6c
	v_bitop3_b32 v28, v35, 13, 15 bitop3:0x6c
	v_lshlrev_b32_e32 v54, 3, v29
	v_bitop3_b32 v29, v35, 15, v35 bitop3:0xc
	v_bitop3_b32 v34, v34, v35, 16 bitop3:0x78
	v_lshlrev_b32_e32 v36, 3, v2
	v_lshlrev_b32_e32 v39, 3, v3
	v_lshlrev_b32_e32 v44, 3, v10
	v_lshlrev_b32_e32 v47, 3, v11
	v_lshlrev_b32_e32 v48, 3, v18
	v_lshlrev_b32_e32 v51, 3, v19
	v_lshlrev_b32_e32 v52, 3, v27
	v_lshlrev_b32_e32 v53, 3, v28
	v_lshlrev_b32_e32 v55, 3, v29
	v_lshl_add_u32 v34, v34, 3, 16
	v_add_u32_e32 v2, v26, v36
	v_add_u32_e32 v4, v26, v37
	v_add_u32_e32 v6, v26, v38
	v_add_u32_e32 v8, v26, v39
	v_add_u32_e32 v10, v26, v44
	v_add_u32_e32 v12, v26, v45
	v_add_u32_e32 v14, v26, v46
	v_add_u32_e32 v16, v26, v47
	v_add_u32_e32 v18, v26, v48
	v_add_u32_e32 v20, v26, v49
	v_add_u32_e32 v22, v26, v50
	v_add_u32_e32 v24, v26, v51
	v_add_u32_e32 v27, v26, v52
	v_add_u32_e32 v28, v26, v53
	v_add_u32_e32 v30, v26, v54
	v_add_u32_e32 v32, v26, v55
	v_add_u32_e32 v35, v34, v36
	v_add_u32_e32 v40, v34, v37
	v_add_u32_e32 v41, v34, v38
	v_add_u32_e32 v42, v34, v39
	ds_read_b64 v[2:3], v2
	ds_read_b64 v[4:5], v4
	ds_read_b64 v[6:7], v6
	ds_read_b64 v[8:9], v8
	ds_read_b64 v[10:11], v10
	ds_read_b64 v[12:13], v12
	ds_read_b64 v[14:15], v14
	ds_read_b64 v[16:17], v16
	ds_read_b64 v[18:19], v18
	ds_read_b64 v[20:21], v20
	ds_read_b64 v[22:23], v22
	ds_read_b64 v[24:25], v24
	ds_read_b64 v[26:27], v27
	ds_read_b64 v[28:29], v28
	ds_read_b64 v[30:31], v30
	ds_read_b64 v[32:33], v32
	ds_read_b64 v[36:37], v35
	ds_read_b64 v[38:39], v40
	ds_read_b64 v[40:41], v41
	ds_read_b64 v[42:43], v42
	v_add_u32_e32 v35, v34, v44
	v_add_u32_e32 v44, v34, v45
	v_add_u32_e32 v45, v34, v46
	v_add_u32_e32 v46, v34, v47
	ds_read_b64 v[72:73], v35
	ds_read_b64 v[74:75], v44
	ds_read_b64 v[76:77], v45
	ds_read_b64 v[78:79], v46
	v_add_u32_e32 v35, v34, v48
	v_add_u32_e32 v44, v34, v49
	v_add_u32_e32 v45, v34, v50
	v_add_u32_e32 v46, v34, v51
	ds_read_b64 v[80:81], v35
	ds_read_b64 v[82:83], v44
	ds_read_b64 v[84:85], v45
	ds_read_b64 v[86:87], v46
	v_add_u32_e32 v35, v34, v52
	v_add_u32_e32 v44, v34, v53
	v_add_u32_e32 v45, v34, v54
	v_add_u32_e32 v34, v34, v55
	ds_read_b64 v[88:89], v35
	ds_read_b64 v[90:91], v44
	ds_read_b64 v[92:93], v45
	ds_read_b64 v[94:95], v34
	s_waitcnt lgkmcnt(14)
	v_pk_add_f32 v[34:35], v[2:3], v[18:19]
	v_pk_add_f32 v[2:3], v[2:3], v[18:19] neg_lo:[0,1] neg_hi:[0,1]
	v_pk_add_f32 v[18:19], v[4:5], v[20:21]
	v_pk_add_f32 v[4:5], v[4:5], v[20:21] neg_lo:[0,1] neg_hi:[0,1]
	s_nop 0
	v_xor_b32_e32 v21, 0x80000000, v4
	v_mov_b32_e32 v20, v5
	v_pk_mul_f32 v[20:21], v[20:21], s[62:63] op_sel_hi:[1,0]
	s_nop 0
	v_pk_fma_f32 v[4:5], v[4:5], s[60:61], v[20:21] op_sel_hi:[1,0,1]
	v_pk_add_f32 v[20:21], v[6:7], v[22:23]
	v_pk_add_f32 v[6:7], v[6:7], v[22:23] neg_lo:[0,1] neg_hi:[0,1]
	s_nop 0
	v_xor_b32_e32 v23, 0x80000000, v6
	v_mov_b32_e32 v22, v7
	v_pk_mul_f32 v[22:23], v[22:23], s[70:71] op_sel_hi:[1,0]
	s_nop 0
	v_pk_fma_f32 v[6:7], v[6:7], s[70:71], v[22:23] op_sel_hi:[1,0,1]
	v_pk_add_f32 v[22:23], v[8:9], v[24:25]
	v_pk_add_f32 v[8:9], v[8:9], v[24:25] neg_lo:[0,1] neg_hi:[0,1]
	s_nop 0
	v_xor_b32_e32 v25, 0x80000000, v8
	v_mov_b32_e32 v24, v9
	v_pk_mul_f32 v[24:25], v[24:25], s[60:61] op_sel_hi:[1,0]
	s_nop 0
	v_pk_fma_f32 v[8:9], v[8:9], s[62:63], v[24:25] op_sel_hi:[1,0,1]
	v_pk_add_f32 v[24:25], v[10:11], v[26:27]
	v_pk_add_f32 v[10:11], v[10:11], v[26:27] neg_lo:[0,1] neg_hi:[0,1]
	s_nop 0
	v_xor_b32_e32 v27, 0x80000000, v10
	v_mov_b32_e32 v26, v11
	v_pk_add_f32 v[10:11], v[12:13], v[28:29]
	v_pk_add_f32 v[12:13], v[12:13], v[28:29] neg_lo:[0,1] neg_hi:[0,1]
	s_nop 0
	v_pk_mul_f32 v[28:29], v[12:13], s[62:63] op_sel_hi:[1,0]
	v_xor_b32_e32 v45, 0x80000000, v12
	v_mov_b32_e32 v44, v13
	v_pk_fma_f32 v[12:13], v[44:45], s[60:61], v[28:29] op_sel_hi:[1,0,1] neg_lo:[0,0,1] neg_hi:[0,0,1]
	v_pk_add_f32 v[28:29], v[14:15], v[30:31]
	v_pk_add_f32 v[14:15], v[14:15], v[30:31] neg_lo:[0,1] neg_hi:[0,1]
	s_nop 0
	v_pk_mul_f32 v[30:31], v[14:15], s[70:71] op_sel_hi:[1,0]
	v_xor_b32_e32 v45, 0x80000000, v14
	v_mov_b32_e32 v44, v15
	v_pk_fma_f32 v[14:15], v[44:45], s[70:71], v[30:31] op_sel_hi:[1,0,1] neg_lo:[0,0,1] neg_hi:[0,0,1]
	v_pk_add_f32 v[30:31], v[16:17], v[32:33]
	v_pk_add_f32 v[16:17], v[16:17], v[32:33] neg_lo:[0,1] neg_hi:[0,1]
	s_nop 0
	v_pk_mul_f32 v[32:33], v[16:17], s[60:61] op_sel_hi:[1,0]
	v_xor_b32_e32 v45, 0x80000000, v16
	v_mov_b32_e32 v44, v17
	v_pk_fma_f32 v[16:17], v[44:45], s[62:63], v[32:33] op_sel_hi:[1,0,1] neg_lo:[0,0,1] neg_hi:[0,0,1]
	v_pk_add_f32 v[32:33], v[34:35], v[24:25]
	v_pk_add_f32 v[24:25], v[34:35], v[24:25] neg_lo:[0,1] neg_hi:[0,1]
	v_pk_add_f32 v[34:35], v[18:19], v[10:11]
	v_pk_add_f32 v[10:11], v[18:19], v[10:11] neg_lo:[0,1] neg_hi:[0,1]
	s_nop 0
	v_xor_b32_e32 v19, 0x80000000, v10
	v_mov_b32_e32 v18, v11
	v_pk_mul_f32 v[18:19], v[18:19], s[70:71] op_sel_hi:[1,0]
	s_nop 0
	v_pk_fma_f32 v[10:11], v[10:11], s[70:71], v[18:19] op_sel_hi:[1,0,1]
	v_pk_add_f32 v[18:19], v[20:21], v[28:29]
	v_pk_add_f32 v[20:21], v[20:21], v[28:29] neg_lo:[0,1] neg_hi:[0,1]
	s_nop 0
	v_xor_b32_e32 v29, 0x80000000, v20
	v_mov_b32_e32 v28, v21
	v_pk_add_f32 v[20:21], v[22:23], v[30:31]
	v_pk_add_f32 v[22:23], v[22:23], v[30:31] neg_lo:[0,1] neg_hi:[0,1]
	s_nop 0
	v_pk_mul_f32 v[30:31], v[22:23], s[70:71] op_sel_hi:[1,0]
	v_xor_b32_e32 v45, 0x80000000, v22
	v_mov_b32_e32 v44, v23
	v_pk_fma_f32 v[22:23], v[44:45], s[70:71], v[30:31] op_sel_hi:[1,0,1] neg_lo:[0,0,1] neg_hi:[0,0,1]
	v_pk_add_f32 v[30:31], v[2:3], v[26:27]
	v_pk_add_f32 v[2:3], v[2:3], v[26:27] neg_lo:[0,1] neg_hi:[0,1]
	v_pk_add_f32 v[26:27], v[4:5], v[12:13]
	v_pk_add_f32 v[4:5], v[4:5], v[12:13] neg_lo:[0,1] neg_hi:[0,1]
	s_nop 0
	v_xor_b32_e32 v13, 0x80000000, v4
	v_mov_b32_e32 v12, v5
	v_pk_mul_f32 v[12:13], v[12:13], s[70:71] op_sel_hi:[1,0]
	s_nop 0
	v_pk_fma_f32 v[4:5], v[4:5], s[70:71], v[12:13] op_sel_hi:[1,0,1]
	v_pk_add_f32 v[12:13], v[6:7], v[14:15]
	v_pk_add_f32 v[6:7], v[6:7], v[14:15] neg_lo:[0,1] neg_hi:[0,1]
	s_nop 0
	v_xor_b32_e32 v15, 0x80000000, v6
	v_mov_b32_e32 v14, v7
	v_pk_add_f32 v[6:7], v[8:9], v[16:17]
	v_pk_add_f32 v[8:9], v[8:9], v[16:17] neg_lo:[0,1] neg_hi:[0,1]
	s_nop 0
	v_pk_mul_f32 v[16:17], v[8:9], s[70:71] op_sel_hi:[1,0]
	v_xor_b32_e32 v45, 0x80000000, v8
	v_mov_b32_e32 v44, v9
	v_pk_fma_f32 v[8:9], v[44:45], s[70:71], v[16:17] op_sel_hi:[1,0,1] neg_lo:[0,0,1] neg_hi:[0,0,1]
	v_pk_add_f32 v[16:17], v[32:33], v[18:19]
	v_pk_add_f32 v[18:19], v[32:33], v[18:19] neg_lo:[0,1] neg_hi:[0,1]
	v_pk_add_f32 v[32:33], v[34:35], v[20:21]
	v_pk_add_f32 v[20:21], v[34:35], v[20:21] neg_lo:[0,1] neg_hi:[0,1]
	v_pk_add_f32 v[66:67], v[16:17], v[32:33]
	v_xor_b32_e32 v35, 0x80000000, v20
	v_mov_b32_e32 v34, v21
	v_pk_add_f32 v[20:21], v[24:25], v[28:29]
	v_pk_add_f32 v[24:25], v[24:25], v[28:29] neg_lo:[0,1] neg_hi:[0,1]
	v_pk_add_f32 v[28:29], v[10:11], v[22:23]
	v_pk_add_f32 v[10:11], v[10:11], v[22:23] neg_lo:[0,1] neg_hi:[0,1]
	v_pk_add_f32 v[58:59], v[20:21], v[28:29]
	v_xor_b32_e32 v23, 0x80000000, v10
	v_mov_b32_e32 v22, v11
	v_pk_add_f32 v[10:11], v[30:31], v[12:13]
	v_pk_add_f32 v[12:13], v[30:31], v[12:13] neg_lo:[0,1] neg_hi:[0,1]
	v_pk_add_f32 v[30:31], v[26:27], v[6:7]
	v_pk_add_f32 v[6:7], v[26:27], v[6:7] neg_lo:[0,1] neg_hi:[0,1]
	v_pk_add_f32 v[54:55], v[24:25], v[22:23]
	v_xor_b32_e32 v27, 0x80000000, v6
	v_mov_b32_e32 v26, v7
	v_pk_add_f32 v[6:7], v[2:3], v[14:15]
	v_pk_add_f32 v[2:3], v[2:3], v[14:15] neg_lo:[0,1] neg_hi:[0,1]
	v_pk_add_f32 v[14:15], v[4:5], v[8:9]
	v_pk_add_f32 v[4:5], v[4:5], v[8:9] neg_lo:[0,1] neg_hi:[0,1]
	v_pk_add_f32 v[52:53], v[24:25], v[22:23] neg_lo:[0,1] neg_hi:[0,1]
	v_xor_b32_e32 v9, 0x80000000, v4
	v_mov_b32_e32 v8, v5
	v_pk_add_f32 v[50:51], v[10:11], v[30:31]
	v_pk_add_f32 v[48:49], v[10:11], v[30:31] neg_lo:[0,1] neg_hi:[0,1]
	v_pk_add_f32 v[46:47], v[12:13], v[26:27]
	v_pk_add_f32 v[44:45], v[12:13], v[26:27] neg_lo:[0,1] neg_hi:[0,1]
	v_pk_add_f32 v[30:31], v[2:3], v[8:9]
	v_pk_add_f32 v[26:27], v[2:3], v[8:9] neg_lo:[0,1] neg_hi:[0,1]
	s_waitcnt lgkmcnt(6)
	v_pk_add_f32 v[8:9], v[38:39], v[82:83] neg_lo:[0,1] neg_hi:[0,1]
	s_waitcnt lgkmcnt(2)
	v_pk_add_f32 v[24:25], v[74:75], v[90:91] neg_lo:[0,1] neg_hi:[0,1]
	v_pk_add_f32 v[56:57], v[20:21], v[28:29] neg_lo:[0,1] neg_hi:[0,1]
	v_pk_add_f32 v[2:3], v[36:37], v[80:81]
	v_pk_add_f32 v[4:5], v[36:37], v[80:81] neg_lo:[0,1] neg_hi:[0,1]
	v_xor_b32_e32 v11, 0x80000000, v8
	v_mov_b32_e32 v10, v9
	v_pk_mul_f32 v[28:29], v[24:25], s[62:63] op_sel_hi:[1,0]
	v_xor_b32_e32 v37, 0x80000000, v24
	v_mov_b32_e32 v36, v25
	v_pk_add_f32 v[64:65], v[16:17], v[32:33] neg_lo:[0,1] neg_hi:[0,1]
	v_pk_mul_f32 v[10:11], v[10:11], s[62:63] op_sel_hi:[1,0]
	v_pk_add_f32 v[12:13], v[40:41], v[84:85] neg_lo:[0,1] neg_hi:[0,1]
	v_pk_add_f32 v[16:17], v[42:43], v[86:87] neg_lo:[0,1] neg_hi:[0,1]
	v_pk_fma_f32 v[24:25], v[36:37], s[60:61], v[28:29] op_sel_hi:[1,0,1] neg_lo:[0,0,1] neg_hi:[0,0,1]
	s_waitcnt lgkmcnt(1)
	v_pk_add_f32 v[36:37], v[76:77], v[92:93] neg_lo:[0,1] neg_hi:[0,1]
	v_pk_add_f32 v[62:63], v[18:19], v[34:35]
	v_pk_add_f32 v[60:61], v[18:19], v[34:35] neg_lo:[0,1] neg_hi:[0,1]
	v_pk_add_f32 v[34:35], v[6:7], v[14:15]
	v_pk_add_f32 v[32:33], v[6:7], v[14:15] neg_lo:[0,1] neg_hi:[0,1]
	v_pk_add_f32 v[6:7], v[38:39], v[82:83]
	v_pk_fma_f32 v[8:9], v[8:9], s[60:61], v[10:11] op_sel_hi:[1,0,1]
	v_pk_add_f32 v[10:11], v[40:41], v[84:85]
	v_xor_b32_e32 v15, 0x80000000, v12
	v_mov_b32_e32 v14, v13
	v_xor_b32_e32 v19, 0x80000000, v16
	v_mov_b32_e32 v18, v17
	v_pk_mul_f32 v[38:39], v[36:37], s[70:71] op_sel_hi:[1,0]
	v_xor_b32_e32 v41, 0x80000000, v36
	v_mov_b32_e32 v40, v37
	v_pk_mul_f32 v[14:15], v[14:15], s[70:71] op_sel_hi:[1,0]
	v_pk_mul_f32 v[18:19], v[18:19], s[60:61] op_sel_hi:[1,0]
	v_pk_add_f32 v[20:21], v[72:73], v[88:89] neg_lo:[0,1] neg_hi:[0,1]
	v_pk_fma_f32 v[36:37], v[40:41], s[70:71], v[38:39] op_sel_hi:[1,0,1] neg_lo:[0,0,1] neg_hi:[0,0,1]
	s_waitcnt lgkmcnt(0)
	v_pk_add_f32 v[40:41], v[78:79], v[94:95] neg_lo:[0,1] neg_hi:[0,1]
	v_pk_fma_f32 v[12:13], v[12:13], s[70:71], v[14:15] op_sel_hi:[1,0,1]
	v_pk_add_f32 v[14:15], v[42:43], v[86:87]
	v_pk_fma_f32 v[16:17], v[16:17], s[62:63], v[18:19] op_sel_hi:[1,0,1]
	v_pk_add_f32 v[18:19], v[72:73], v[88:89]
	v_xor_b32_e32 v23, 0x80000000, v20
	v_mov_b32_e32 v22, v21
	v_pk_add_f32 v[20:21], v[74:75], v[90:91]
	v_pk_mul_f32 v[42:43], v[40:41], s[60:61] op_sel_hi:[1,0]
	v_xor_b32_e32 v73, 0x80000000, v40
	v_mov_b32_e32 v72, v41
	v_pk_fma_f32 v[40:41], v[72:73], s[62:63], v[42:43] op_sel_hi:[1,0,1] neg_lo:[0,0,1] neg_hi:[0,0,1]
	v_pk_add_f32 v[42:43], v[2:3], v[18:19]
	v_pk_add_f32 v[2:3], v[2:3], v[18:19] neg_lo:[0,1] neg_hi:[0,1]
	v_pk_add_f32 v[18:19], v[6:7], v[20:21]
	v_pk_add_f32 v[6:7], v[6:7], v[20:21] neg_lo:[0,1] neg_hi:[0,1]
	v_pk_add_f32 v[28:29], v[76:77], v[92:93]
	v_xor_b32_e32 v21, 0x80000000, v6
	v_mov_b32_e32 v20, v7
	v_pk_mul_f32 v[20:21], v[20:21], s[70:71] op_sel_hi:[1,0]
	v_pk_add_f32 v[38:39], v[78:79], v[94:95]
	v_pk_fma_f32 v[6:7], v[6:7], s[70:71], v[20:21] op_sel_hi:[1,0,1]
	v_pk_add_f32 v[20:21], v[10:11], v[28:29]
	v_pk_add_f32 v[10:11], v[10:11], v[28:29] neg_lo:[0,1] neg_hi:[0,1]
	s_nop 0
	v_xor_b32_e32 v29, 0x80000000, v10
	v_mov_b32_e32 v28, v11
	v_pk_add_f32 v[10:11], v[14:15], v[38:39]
	v_pk_add_f32 v[14:15], v[14:15], v[38:39] neg_lo:[0,1] neg_hi:[0,1]
	s_nop 0
	v_pk_mul_f32 v[38:39], v[14:15], s[70:71] op_sel_hi:[1,0]
	v_xor_b32_e32 v73, 0x80000000, v14
	v_mov_b32_e32 v72, v15
	v_pk_fma_f32 v[14:15], v[72:73], s[70:71], v[38:39] op_sel_hi:[1,0,1] neg_lo:[0,0,1] neg_hi:[0,0,1]
	v_pk_add_f32 v[38:39], v[4:5], v[22:23]
	v_pk_add_f32 v[4:5], v[4:5], v[22:23] neg_lo:[0,1] neg_hi:[0,1]
	v_pk_add_f32 v[22:23], v[8:9], v[24:25]
	v_pk_add_f32 v[8:9], v[8:9], v[24:25] neg_lo:[0,1] neg_hi:[0,1]
	s_nop 0
	v_xor_b32_e32 v25, 0x80000000, v8
	v_mov_b32_e32 v24, v9
	v_pk_mul_f32 v[24:25], v[24:25], s[70:71] op_sel_hi:[1,0]
	s_nop 0
	v_pk_fma_f32 v[8:9], v[8:9], s[70:71], v[24:25] op_sel_hi:[1,0,1]
	v_pk_add_f32 v[24:25], v[12:13], v[36:37]
	v_pk_add_f32 v[12:13], v[12:13], v[36:37] neg_lo:[0,1] neg_hi:[0,1]
	v_pk_add_f32 v[74:75], v[38:39], v[24:25] neg_lo:[0,1] neg_hi:[0,1]
	v_xor_b32_e32 v37, 0x80000000, v12
	v_mov_b32_e32 v36, v13
	v_pk_add_f32 v[12:13], v[16:17], v[40:41]
	v_pk_add_f32 v[16:17], v[16:17], v[40:41] neg_lo:[0,1] neg_hi:[0,1]
	v_pk_add_f32 v[76:77], v[22:23], v[12:13]
	v_pk_mul_f32 v[40:41], v[16:17], s[70:71] op_sel_hi:[1,0]
	v_xor_b32_e32 v73, 0x80000000, v16
	v_mov_b32_e32 v72, v17
	v_pk_fma_f32 v[16:17], v[72:73], s[70:71], v[40:41] op_sel_hi:[1,0,1] neg_lo:[0,0,1] neg_hi:[0,0,1]
	v_pk_add_f32 v[72:73], v[18:19], v[10:11]
	v_pk_add_f32 v[10:11], v[18:19], v[10:11] neg_lo:[0,1] neg_hi:[0,1]
	v_pk_add_f32 v[12:13], v[22:23], v[12:13] neg_lo:[0,1] neg_hi:[0,1]
	v_xor_b32_e32 v19, 0x80000000, v10
	v_mov_b32_e32 v18, v11
	v_pk_add_f32 v[10:11], v[2:3], v[28:29]
	v_pk_add_f32 v[2:3], v[2:3], v[28:29] neg_lo:[0,1] neg_hi:[0,1]
	v_pk_add_f32 v[28:29], v[6:7], v[14:15]
	v_pk_add_f32 v[6:7], v[6:7], v[14:15] neg_lo:[0,1] neg_hi:[0,1]
	v_pk_add_f32 v[22:23], v[10:11], v[28:29] neg_lo:[0,1] neg_hi:[0,1]
	v_xor_b32_e32 v15, 0x80000000, v6
	v_mov_b32_e32 v14, v7
	v_pk_add_f32 v[6:7], v[38:39], v[24:25]
	v_pk_add_f32 v[24:25], v[10:11], v[28:29]
	v_mov_b32_e32 v28, v146
	v_pk_add_f32 v[40:41], v[42:43], v[20:21]
	v_pk_add_f32 v[20:21], v[42:43], v[20:21] neg_lo:[0,1] neg_hi:[0,1]
	v_lshlrev_b32_e32 v71, 4, v28
	v_lshrrev_b32_e32 v29, 1, v28
	v_pk_add_f32 v[42:43], v[40:41], v[72:73]
	v_pk_add_f32 v[40:41], v[40:41], v[72:73] neg_lo:[0,1] neg_hi:[0,1]
	v_bfe_u32 v28, v28, 1, 4
	v_bitop3_b32 v72, v29, v71, 16 bitop3:0x6c
	v_lshl_add_u32 v72, v72, 3, 16
	v_lshlrev_b32_e32 v28, 3, v28
	v_add_u32_e32 v73, v72, v28
	ds_write_b64 v73, v[66:67]
	v_bitop3_b32 v73, v29, 1, 15 bitop3:0x6c
	v_xor_b32_e32 v79, 0x80000000, v12
	v_mov_b32_e32 v78, v13
	v_lshlrev_b32_e32 v73, 3, v73
	v_pk_add_f32 v[12:13], v[74:75], v[78:79]
	v_pk_add_f32 v[10:11], v[74:75], v[78:79] neg_lo:[0,1] neg_hi:[0,1]
	v_add_u32_e32 v74, v72, v73
	ds_write_b64 v74, v[64:65]
	v_bitop3_b32 v74, v29, 2, 15 bitop3:0x6c
	v_lshlrev_b32_e32 v74, 3, v74
	v_add_u32_e32 v75, v72, v74
	ds_write_b64 v75, v[62:63]
	v_bitop3_b32 v75, v29, 3, 15 bitop3:0x6c
	v_lshlrev_b32_e32 v75, 3, v75
	v_pk_add_f32 v[80:81], v[4:5], v[36:37]
	v_pk_add_f32 v[82:83], v[4:5], v[36:37] neg_lo:[0,1] neg_hi:[0,1]
	v_pk_add_f32 v[4:5], v[8:9], v[16:17]
	v_pk_add_f32 v[8:9], v[8:9], v[16:17] neg_lo:[0,1] neg_hi:[0,1]
	v_pk_add_f32 v[38:39], v[20:21], v[18:19]
	v_pk_add_f32 v[36:37], v[20:21], v[18:19] neg_lo:[0,1] neg_hi:[0,1]
	v_pk_add_f32 v[20:21], v[2:3], v[14:15]
	v_pk_add_f32 v[18:19], v[2:3], v[14:15] neg_lo:[0,1] neg_hi:[0,1]
	v_pk_add_f32 v[16:17], v[6:7], v[76:77]
	v_pk_add_f32 v[14:15], v[6:7], v[76:77] neg_lo:[0,1] neg_hi:[0,1]
	v_add_u32_e32 v76, v72, v75
	ds_write_b64 v76, v[60:61]
	v_bitop3_b32 v76, v29, 4, 15 bitop3:0x6c
	v_lshlrev_b32_e32 v76, 3, v76
	v_add_u32_e32 v77, v72, v76
	ds_write_b64 v77, v[58:59]
	v_bitop3_b32 v77, v29, 5, 15 bitop3:0x6c
	v_lshlrev_b32_e32 v77, 3, v77
	v_add_u32_e32 v78, v72, v77
	ds_write_b64 v78, v[56:57]
	v_bitop3_b32 v78, v29, 6, 15 bitop3:0x6c
	v_lshlrev_b32_e32 v78, 3, v78
	v_add_u32_e32 v79, v72, v78
	ds_write_b64 v79, v[54:55]
	v_bitop3_b32 v79, v29, 7, 15 bitop3:0x6c
	v_lshlrev_b32_e32 v79, 3, v79
	v_xor_b32_e32 v85, 0x80000000, v8
	v_mov_b32_e32 v84, v9
	v_pk_add_f32 v[8:9], v[80:81], v[4:5]
	v_pk_add_f32 v[6:7], v[80:81], v[4:5] neg_lo:[0,1] neg_hi:[0,1]
	v_add_u32_e32 v80, v72, v79
	ds_write_b64 v80, v[52:53]
	v_bitop3_b32 v80, v29, 8, 15 bitop3:0x6c
	v_lshlrev_b32_e32 v80, 3, v80
	v_add_u32_e32 v81, v72, v80
	ds_write_b64 v81, v[50:51]
	v_bitop3_b32 v81, v29, 9, 15 bitop3:0x6c
	v_lshlrev_b32_e32 v81, 3, v81
	v_pk_add_f32 v[4:5], v[82:83], v[84:85]
	v_pk_add_f32 v[2:3], v[82:83], v[84:85] neg_lo:[0,1] neg_hi:[0,1]
	v_add_u32_e32 v82, v72, v81
	ds_write_b64 v82, v[48:49]
	v_bitop3_b32 v82, v29, 10, 15 bitop3:0x6c
	v_lshlrev_b32_e32 v82, 3, v82
	v_add_u32_e32 v83, v72, v82
	ds_write_b64 v83, v[46:47]
	v_bitop3_b32 v83, v29, 11, 15 bitop3:0x6c
	v_lshlrev_b32_e32 v83, 3, v83
	v_add_u32_e32 v84, v72, v83
	ds_write_b64 v84, v[44:45]
	v_bitop3_b32 v84, v29, 12, 15 bitop3:0x6c
	v_lshlrev_b32_e32 v84, 3, v84
	v_add_u32_e32 v85, v72, v84
	ds_write_b64 v85, v[34:35]
	v_bitop3_b32 v85, v29, 13, 15 bitop3:0x6c
	v_lshlrev_b32_e32 v85, 3, v85
	v_add_u32_e32 v86, v72, v85
	ds_write_b64 v86, v[32:33]
	v_bitop3_b32 v86, v29, 14, 15 bitop3:0x6c
	v_lshlrev_b32_e32 v86, 3, v86
	v_add_u32_e32 v87, v72, v86
	v_add_u32_e32 v88, 0x2000, v71
	ds_write_b64 v87, v[30:31]
	v_bitop3_b32 v87, v29, 15, v29 bitop3:0xc
	v_bitop3_b32 v29, v88, v29, 16 bitop3:0x78
	v_lshlrev_b32_e32 v87, 3, v87
	v_lshl_add_u32 v29, v29, 3, 16
	v_add_u32_e32 v72, v72, v87
	v_add_u32_e32 v28, v29, v28
	ds_write_b64 v72, v[26:27]
	ds_write_b64 v28, v[42:43]
	v_add_u32_e32 v28, v29, v73
	ds_write_b64 v28, v[40:41]
	v_add_u32_e32 v28, v29, v74
	ds_write_b64 v28, v[38:39]
	v_add_u32_e32 v28, v29, v75
	ds_write_b64 v28, v[36:37]
	v_add_u32_e32 v28, v29, v76
	ds_write_b64 v28, v[24:25]
	v_add_u32_e32 v28, v29, v77
	ds_write_b64 v28, v[22:23]
	v_add_u32_e32 v28, v29, v78
	ds_write_b64 v28, v[20:21]
	v_add_u32_e32 v28, v29, v79
	ds_write_b64 v28, v[18:19]
	v_add_u32_e32 v28, v29, v80
	ds_write_b64 v28, v[16:17]
	v_add_u32_e32 v28, v29, v81
	ds_write_b64 v28, v[14:15]
	v_add_u32_e32 v28, v29, v82
	v_or_b32_e32 v72, 1, v71
	ds_write_b64 v28, v[12:13]
	v_add_u32_e32 v28, v29, v83
	v_bfrev_b32_e32 v72, v72
	ds_write_b64 v28, v[10:11]
	v_add_u32_e32 v28, v29, v84
	v_lshrrev_b32_e32 v72, 18, v72
	ds_write_b64 v28, v[8:9]
	v_add_u32_e32 v28, v29, v85
	v_sub_u32_e32 v72, 0, v72
	ds_write_b64 v28, v[6:7]
	v_add_u32_e32 v28, v29, v86
	v_and_b32_e32 v72, 0x3fff, v72
	ds_write_b64 v28, v[4:5]
	v_add_u32_e32 v28, v29, v87
	v_bfrev_b32_e32 v72, v72
	ds_write_b64 v28, v[2:3]
	v_lshl_add_u64 v[28:29], v[0:1], 2, s[0:1]
	v_bfrev_b32_e32 v0, v71
	v_lshrrev_b32_e32 v73, 18, v72
	v_lshrrev_b32_e32 v72, 23, v72
	v_lshrrev_b32_e32 v0, 18, v0
	v_bitop3_b32 v72, v72, v73, 31 bitop3:0x6c
	v_or_b32_e32 v73, 2, v71
	v_sub_u32_e32 v0, 0, v0
	v_bfrev_b32_e32 v73, v73
	v_and_b32_e32 v0, 0x3fff, v0
	v_lshrrev_b32_e32 v73, 18, v73
	v_bfrev_b32_e32 v0, v0
	v_sub_u32_e32 v73, 0, v73
	v_lshrrev_b32_e32 v1, 18, v0
	v_lshrrev_b32_e32 v0, 23, v0
	v_and_b32_e32 v74, 0x3fff, v73
	v_bitop3_b32 v0, v0, v1, 31 bitop3:0x6c
	v_bfrev_b32_e32 v74, v74
	v_and_b32_e32 v73, 0x1fff, v73
	v_lshl_add_u32 v0, v0, 3, 16
	v_lshrrev_b32_e32 v75, 18, v74
	v_lshrrev_b32_e32 v74, 23, v74
	v_bfrev_b32_e32 v73, v73
	s_waitcnt lgkmcnt(0)
	s_barrier
	ds_read_b64 v[0:1], v0
	v_bitop3_b32 v74, v74, v75, 31 bitop3:0x6c
	v_lshrrev_b32_e32 v75, 18, v73
	v_lshrrev_b32_e32 v73, 23, v73
	v_bitop3_b32 v73, v73, v75, 31 bitop3:0x6c
	v_lshl_add_u32 v72, v72, 3, 16
	v_lshl_add_u32 v74, v74, 3, 16
	v_lshl_add_u32 v76, v73, 3, 16
	ds_read_b64 v[72:73], v72
	ds_read_b64 v[74:75], v74
	ds_read_b64 v[76:77], v76
	s_waitcnt lgkmcnt(3)
	v_pk_add_f32 v[78:79], v[66:67], v[0:1]
	v_sub_f32_e32 v1, v67, v1
	v_sub_f32_e32 v0, v0, v66
	v_mul_f32_e32 v67, 0.5, v1
	v_mul_f32_e32 v66, 0.5, v0
	s_waitcnt lgkmcnt(2)
	v_pk_add_f32 v[0:1], v[64:65], v[72:73]
	v_mul_f32_e32 v78, 0.5, v78
	v_mul_f32_e32 v80, 0.5, v0
	v_sub_f32_e32 v0, v65, v73
	v_mul_f32_e32 v65, 0.5, v0
	v_sub_f32_e32 v0, v72, v64
	v_mul_f32_e32 v73, 0.5, v1
	v_mul_f32_e32 v64, 0.5, v0
	s_waitcnt lgkmcnt(1)
	v_pk_add_f32 v[0:1], v[62:63], v[74:75]
	s_mov_b32 s0, 0x10000
	v_mul_f32_e32 v72, 0.5, v0
	v_sub_f32_e32 v0, v63, v75
	v_mul_f32_e32 v75, 0.5, v0
	v_sub_f32_e32 v0, v74, v62
	v_mul_f32_e32 v81, 0.5, v1
	v_mul_f32_e32 v74, 0.5, v0
	s_waitcnt lgkmcnt(0)
	v_pk_add_f32 v[0:1], v[60:61], v[76:77]
	v_sub_f32_e32 v61, v61, v77
	v_mul_f32_e32 v0, 0.5, v0
	v_mul_f32_e32 v61, 0.5, v61
	v_sub_f32_e32 v60, v76, v60
	v_mul_f32_e32 v79, 0.5, v79
	v_mul_f32_e32 v1, 0.5, v1
	v_mul_f32_e32 v76, 0.5, v60
	v_cvt_pk_f16_f32 v63, v0, v61
	v_cvt_pk_f16_f32 v62, v72, v75
	v_cvt_pk_f16_f32 v61, v80, v65
	v_cvt_pk_f16_f32 v60, v78, v67
	v_add_co_u32_e32 v0, vcc, s0, v28
	global_store_dwordx4 v[28:29], v[60:63], off offset:-4096
	s_lshl_b64 s[0:1], s[68:69], 13
	s_add_u32 s92, s0, 0xc00000
	v_cvt_pk_f16_f32 v63, v1, v76
	v_cvt_pk_f16_f32 v62, v81, v74
	v_cvt_pk_f16_f32 v61, v73, v64
	v_cvt_pk_f16_f32 v60, v79, v66
	v_addc_co_u32_e32 v1, vcc, 0, v29, vcc
	global_store_dwordx4 v[0:1], v[60:63], off offset:-4096
	s_addc_u32 s93, s1, 0
	s_add_u32 s94, s56, s10
	v_or_b32_e32 v60, 4, v71
	v_bfrev_b32_e32 v60, v60
	v_lshrrev_b32_e32 v60, 18, v60
	v_sub_u32_e32 v62, 0, v60
	v_and_b32_e32 v63, 0x1fff, v62
	v_bfrev_b32_e32 v63, v63
	v_lshrrev_b32_e32 v64, 18, v63
	v_lshrrev_b32_e32 v63, 23, v63
	v_bitop3_b32 v63, v63, v64, 31 bitop3:0x6c
	v_or_b32_e32 v64, 6, v71
	v_bfrev_b32_e32 v64, v64
	v_and_b32_e32 v60, 0x3fff, v62
	v_lshrrev_b32_e32 v64, 18, v64
	v_bfrev_b32_e32 v60, v60
	v_sub_u32_e32 v64, 0, v64
	v_lshrrev_b32_e32 v61, 18, v60
	v_lshrrev_b32_e32 v60, 23, v60
	v_and_b32_e32 v64, 0x2fff, v64
	v_bitop3_b32 v60, v60, v61, 31 bitop3:0x6c
	v_bfrev_b32_e32 v64, v64
	v_and_b32_e32 v62, 0xfff, v62
	v_lshl_add_u32 v60, v60, 3, 16
	v_lshrrev_b32_e32 v65, 18, v64
	v_lshrrev_b32_e32 v64, 23, v64
	v_bfrev_b32_e32 v62, v62
	ds_read_b64 v[60:61], v60
	v_bitop3_b32 v64, v64, v65, 31 bitop3:0x6c
	v_lshrrev_b32_e32 v65, 18, v62
	v_lshrrev_b32_e32 v62, 23, v62
	v_bitop3_b32 v62, v62, v65, 31 bitop3:0x6c
	v_lshl_add_u32 v63, v63, 3, 16
	v_lshl_add_u32 v64, v64, 3, 16
	v_lshl_add_u32 v66, v62, 3, 16
	ds_read_b64 v[62:63], v63
	ds_read_b64 v[64:65], v64
	ds_read_b64 v[66:67], v66
	s_waitcnt lgkmcnt(3)
	v_pk_add_f32 v[72:73], v[58:59], v[60:61]
	v_sub_f32_e32 v59, v59, v61
	v_sub_f32_e32 v58, v60, v58
	v_mul_f32_e32 v61, 0.5, v59
	v_mul_f32_e32 v60, 0.5, v58
	s_waitcnt lgkmcnt(2)
	v_pk_add_f32 v[58:59], v[56:57], v[62:63]
	v_sub_f32_e32 v57, v57, v63
	v_sub_f32_e32 v56, v62, v56
	v_mul_f32_e32 v63, 0.5, v57
	v_mul_f32_e32 v62, 0.5, v56
	s_waitcnt lgkmcnt(1)
	v_pk_add_f32 v[56:57], v[54:55], v[64:65]
	v_sub_f32_e32 v55, v55, v65
	v_sub_f32_e32 v54, v64, v54
	v_mul_f32_e32 v65, 0.5, v55
	v_mul_f32_e32 v64, 0.5, v54
	s_waitcnt lgkmcnt(0)
	v_pk_add_f32 v[54:55], v[52:53], v[66:67]
	v_sub_f32_e32 v53, v53, v67
	v_mul_f32_e32 v72, 0.5, v72
	v_mul_f32_e32 v58, 0.5, v58
	v_mul_f32_e32 v56, 0.5, v56
	v_mul_f32_e32 v54, 0.5, v54
	v_mul_f32_e32 v53, 0.5, v53
	v_sub_f32_e32 v52, v66, v52
	v_mul_f32_e32 v73, 0.5, v73
	v_mul_f32_e32 v59, 0.5, v59
	v_mul_f32_e32 v57, 0.5, v57
	v_mul_f32_e32 v67, 0.5, v55
	v_mul_f32_e32 v66, 0.5, v52
	v_cvt_pk_f16_f32 v55, v54, v53
	v_cvt_pk_f16_f32 v54, v56, v65
	v_cvt_pk_f16_f32 v53, v58, v63
	v_cvt_pk_f16_f32 v52, v72, v61
	global_store_dwordx4 v[28:29], v[52:55], off offset:-3072
	s_addc_u32 s95, s57, s11
	s_lshl_b64 s[0:1], s[68:69], 14
	v_cvt_pk_f16_f32 v55, v67, v66
	v_cvt_pk_f16_f32 v54, v57, v64
	v_cvt_pk_f16_f32 v53, v59, v62
	v_cvt_pk_f16_f32 v52, v73, v60
	global_store_dwordx4 v[0:1], v[52:55], off offset:-3072
	s_add_u32 s12, s26, s0
	s_addc_u32 s13, s27, s1
	v_or_b32_e32 v52, 8, v71
	v_bfrev_b32_e32 v52, v52
	v_lshrrev_b32_e32 v52, 18, v52
	v_sub_u32_e32 v62, 0, v52
	v_and_b32_e32 v54, 0x1fff, v62
	v_bfrev_b32_e32 v54, v54
	v_lshrrev_b32_e32 v55, 18, v54
	v_lshrrev_b32_e32 v54, 23, v54
	v_bitop3_b32 v54, v54, v55, 31 bitop3:0x6c
	v_or_b32_e32 v55, 10, v71
	v_bfrev_b32_e32 v55, v55
	v_lshrrev_b32_e32 v55, 18, v55
	v_sub_u32_e32 v55, 0, v55
	v_and_b32_e32 v55, 0x2fff, v55
	v_and_b32_e32 v52, 0x3fff, v62
	v_bfrev_b32_e32 v55, v55
	v_bfrev_b32_e32 v52, v52
	v_lshrrev_b32_e32 v56, 18, v55
	v_lshrrev_b32_e32 v55, 23, v55
	v_lshrrev_b32_e32 v53, 18, v52
	v_lshrrev_b32_e32 v52, 23, v52
	v_bitop3_b32 v55, v55, v56, 31 bitop3:0x6c
	v_bitop3_b32 v52, v52, v53, 31 bitop3:0x6c
	v_lshl_add_u32 v56, v55, 3, 16
	v_and_b32_e32 v55, 0xfff, v62
	v_lshl_add_u32 v52, v52, 3, 16
	v_bfrev_b32_e32 v55, v55
	ds_read_b64 v[52:53], v52
	v_lshrrev_b32_e32 v57, 18, v55
	v_lshrrev_b32_e32 v55, 23, v55
	v_bitop3_b32 v55, v55, v57, 31 bitop3:0x6c
	v_lshl_add_u32 v54, v54, 3, 16
	v_lshl_add_u32 v58, v55, 3, 16
	ds_read_b64 v[54:55], v54
	ds_read_b64 v[56:57], v56
	ds_read_b64 v[58:59], v58
	s_waitcnt lgkmcnt(3)
	v_pk_add_f32 v[60:61], v[50:51], v[52:53]
	v_sub_f32_e32 v51, v51, v53
	v_sub_f32_e32 v50, v52, v50
	v_mul_f32_e32 v53, 0.5, v51
	v_mul_f32_e32 v52, 0.5, v50
	s_waitcnt lgkmcnt(2)
	v_pk_add_f32 v[50:51], v[48:49], v[54:55]
	v_sub_f32_e32 v49, v49, v55
	v_sub_f32_e32 v48, v54, v48
	v_mul_f32_e32 v55, 0.5, v49
	v_mul_f32_e32 v54, 0.5, v48
	s_waitcnt lgkmcnt(1)
	v_pk_add_f32 v[48:49], v[46:47], v[56:57]
	v_sub_f32_e32 v47, v47, v57
	v_sub_f32_e32 v46, v56, v46
	v_mul_f32_e32 v57, 0.5, v47
	v_mul_f32_e32 v56, 0.5, v46
	s_waitcnt lgkmcnt(0)
	v_pk_add_f32 v[46:47], v[44:45], v[58:59]
	v_sub_f32_e32 v45, v45, v59
	v_mul_f32_e32 v60, 0.5, v60
	v_mul_f32_e32 v50, 0.5, v50
	v_mul_f32_e32 v48, 0.5, v48
	v_mul_f32_e32 v46, 0.5, v46
	v_mul_f32_e32 v45, 0.5, v45
	v_sub_f32_e32 v44, v58, v44
	v_mul_f32_e32 v61, 0.5, v61
	v_mul_f32_e32 v51, 0.5, v51
	v_mul_f32_e32 v49, 0.5, v49
	v_mul_f32_e32 v59, 0.5, v47
	v_mul_f32_e32 v58, 0.5, v44
	v_cvt_pk_f16_f32 v47, v46, v45
	v_cvt_pk_f16_f32 v46, v48, v57
	v_cvt_pk_f16_f32 v45, v50, v55
	v_cvt_pk_f16_f32 v44, v60, v53
	global_store_dwordx4 v[28:29], v[44:47], off offset:-2048
	s_add_u32 s14, s30, s0
	s_addc_u32 s15, s31, s1
	v_cvt_pk_f16_f32 v47, v59, v58
	v_cvt_pk_f16_f32 v46, v49, v56
	v_cvt_pk_f16_f32 v45, v51, v54
	v_cvt_pk_f16_f32 v44, v61, v52
	global_store_dwordx4 v[0:1], v[44:47], off offset:-2048
	v_cmp_lt_i32_e32 vcc, s25, v146
	v_add_u32_e32 v55, 0xe00, v146
	v_or_b32_e32 v44, 12, v71
	v_bfrev_b32_e32 v44, v44
	v_lshrrev_b32_e32 v44, 18, v44
	v_sub_u32_e32 v46, 0, v44
	v_and_b32_e32 v44, 0x37ff, v46
	v_and_b32_e32 v46, 0x17ff, v46
	v_bfrev_b32_e32 v46, v46
	v_lshrrev_b32_e32 v47, 18, v46
	v_lshrrev_b32_e32 v46, 23, v46
	v_bitop3_b32 v46, v46, v47, 31 bitop3:0x6c
	v_or_b32_e32 v47, 14, v71
	v_bfrev_b32_e32 v47, v47
	v_lshrrev_b32_e32 v47, 18, v47
	v_sub_u32_e32 v47, 0, v47
	v_and_b32_e32 v47, 0x27ff, v47
	v_bfrev_b32_e32 v47, v47
	v_bfrev_b32_e32 v44, v44
	v_lshrrev_b32_e32 v48, 18, v47
	v_lshrrev_b32_e32 v47, 23, v47
	v_lshrrev_b32_e32 v45, 18, v44
	v_lshrrev_b32_e32 v44, 23, v44
	v_bitop3_b32 v47, v47, v48, 31 bitop3:0x6c
	v_bitop3_b32 v44, v44, v45, 31 bitop3:0x6c
	v_lshl_add_u32 v48, v47, 3, 16
	v_and_b32_e32 v47, 0x7ff, v62
	v_lshl_add_u32 v44, v44, 3, 16
	v_bfrev_b32_e32 v47, v47
	ds_read_b64 v[44:45], v44
	v_lshrrev_b32_e32 v49, 18, v47
	v_lshrrev_b32_e32 v47, 23, v47
	v_bitop3_b32 v47, v47, v49, 31 bitop3:0x6c
	v_lshl_add_u32 v46, v46, 3, 16
	v_lshl_add_u32 v50, v47, 3, 16
	ds_read_b64 v[46:47], v46
	ds_read_b64 v[48:49], v48
	ds_read_b64 v[50:51], v50
	s_waitcnt lgkmcnt(3)
	v_pk_add_f32 v[52:53], v[34:35], v[44:45]
	v_sub_f32_e32 v35, v35, v45
	v_sub_f32_e32 v34, v44, v34
	v_mul_f32_e32 v45, 0.5, v35
	v_mul_f32_e32 v44, 0.5, v34
	s_waitcnt lgkmcnt(2)
	v_pk_add_f32 v[34:35], v[32:33], v[46:47]
	v_sub_f32_e32 v33, v33, v47
	v_sub_f32_e32 v32, v46, v32
	v_mul_f32_e32 v47, 0.5, v33
	v_mul_f32_e32 v46, 0.5, v32
	s_waitcnt lgkmcnt(1)
	v_pk_add_f32 v[32:33], v[30:31], v[48:49]
	v_sub_f32_e32 v31, v31, v49
	v_sub_f32_e32 v30, v48, v30
	v_mul_f32_e32 v49, 0.5, v31
	v_mul_f32_e32 v48, 0.5, v30
	s_waitcnt lgkmcnt(0)
	v_pk_add_f32 v[30:31], v[26:27], v[50:51]
	v_sub_f32_e32 v27, v27, v51
	v_mul_f32_e32 v52, 0.5, v52
	v_mul_f32_e32 v34, 0.5, v34
	v_mul_f32_e32 v32, 0.5, v32
	v_mul_f32_e32 v30, 0.5, v30
	v_mul_f32_e32 v27, 0.5, v27
	v_sub_f32_e32 v26, v50, v26
	v_mul_f32_e32 v53, 0.5, v53
	v_mul_f32_e32 v35, 0.5, v35
	v_mul_f32_e32 v54, 0.5, v33
	v_mul_f32_e32 v51, 0.5, v31
	v_mul_f32_e32 v26, 0.5, v26
	v_cvt_pk_f16_f32 v33, v30, v27
	v_cvt_pk_f16_f32 v32, v32, v49
	v_cvt_pk_f16_f32 v31, v34, v47
	v_cvt_pk_f16_f32 v30, v52, v45
	global_store_dwordx4 v[28:29], v[30:33], off offset:-1024
	v_add_u32_e32 v52, 0x800, v146
	s_nop 0
	v_cvt_pk_f16_f32 v33, v51, v26
	v_cvt_pk_f16_f32 v32, v54, v48
	v_cvt_pk_f16_f32 v31, v35, v46
	v_cvt_pk_f16_f32 v30, v53, v44
	global_store_dwordx4 v[0:1], v[30:33], off offset:-1024
	v_bfrev_b32_e32 v26, v88
	v_lshrrev_b32_e32 v26, 18, v26
	v_add_u32_e32 v30, 0x2001, v71
	v_bfrev_b32_e32 v30, v30
	v_lshrrev_b32_e32 v30, 18, v30
	v_sub_u32_e32 v30, 0, v30
	v_and_b32_e32 v30, 0x3fff, v30
	v_bfrev_b32_e32 v30, v30
	v_lshrrev_b32_e32 v31, 18, v30
	v_lshrrev_b32_e32 v30, 23, v30
	v_bitop3_b32 v30, v30, v31, 31 bitop3:0x6c
	v_add_u32_e32 v31, 0x2002, v71
	v_bfrev_b32_e32 v31, v31
	v_lshrrev_b32_e32 v31, 18, v31
	v_sub_u32_e32 v31, 0, v31
	v_and_b32_e32 v31, 0x3fff, v31
	v_bfrev_b32_e32 v31, v31
	v_lshrrev_b32_e32 v32, 18, v31
	v_lshrrev_b32_e32 v31, 23, v31
	v_bitop3_b32 v31, v31, v32, 31 bitop3:0x6c
	v_sub_u32_e32 v26, 0, v26
	v_lshl_add_u32 v32, v31, 3, 16
	v_add_u32_e32 v31, 0x2003, v71
	v_and_b32_e32 v26, 0x3fff, v26
	v_bfrev_b32_e32 v31, v31
	v_bfrev_b32_e32 v26, v26
	v_lshrrev_b32_e32 v31, 18, v31
	v_lshrrev_b32_e32 v27, 18, v26
	v_lshrrev_b32_e32 v26, 23, v26
	v_sub_u32_e32 v31, 0, v31
	v_bitop3_b32 v26, v26, v27, 31 bitop3:0x6c
	v_and_b32_e32 v31, 0x1fff, v31
	v_lshl_add_u32 v26, v26, 3, 16
	v_bfrev_b32_e32 v31, v31
	ds_read_b64 v[26:27], v26
	v_lshrrev_b32_e32 v33, 18, v31
	v_lshrrev_b32_e32 v31, 23, v31
	v_bitop3_b32 v31, v31, v33, 31 bitop3:0x6c
	v_lshl_add_u32 v30, v30, 3, 16
	v_lshl_add_u32 v34, v31, 3, 16
	ds_read_b64 v[30:31], v30
	ds_read_b64 v[32:33], v32
	ds_read_b64 v[34:35], v34
	s_waitcnt lgkmcnt(3)
	v_pk_add_f32 v[44:45], v[42:43], v[26:27]
	v_sub_f32_e32 v27, v43, v27
	v_sub_f32_e32 v26, v26, v42
	v_mul_f32_e32 v43, 0.5, v27
	v_mul_f32_e32 v42, 0.5, v26
	s_waitcnt lgkmcnt(2)
	v_pk_add_f32 v[26:27], v[40:41], v[30:31]
	v_mul_f32_e32 v44, 0.5, v44
	v_mul_f32_e32 v46, 0.5, v26
	v_sub_f32_e32 v26, v41, v31
	v_mul_f32_e32 v31, 0.5, v26
	v_sub_f32_e32 v26, v30, v40
	v_mul_f32_e32 v41, 0.5, v27
	v_mul_f32_e32 v40, 0.5, v26
	s_waitcnt lgkmcnt(1)
	v_pk_add_f32 v[26:27], v[38:39], v[32:33]
	v_mul_f32_e32 v45, 0.5, v45
	v_mul_f32_e32 v30, 0.5, v26
	v_sub_f32_e32 v26, v39, v33
	v_mul_f32_e32 v39, 0.5, v26
	v_sub_f32_e32 v26, v32, v38
	v_mul_f32_e32 v47, 0.5, v27
	v_mul_f32_e32 v38, 0.5, v26
	s_waitcnt lgkmcnt(0)
	v_pk_add_f32 v[26:27], v[36:37], v[34:35]
	v_sub_f32_e32 v32, v37, v35
	v_mul_f32_e32 v26, 0.5, v26
	v_mul_f32_e32 v32, 0.5, v32
	v_sub_f32_e32 v33, v34, v36
	v_mul_f32_e32 v27, 0.5, v27
	v_mul_f32_e32 v34, 0.5, v33
	v_cvt_pk_f16_f32 v33, v26, v32
	v_cvt_pk_f16_f32 v32, v30, v39
	v_cvt_pk_f16_f32 v31, v46, v31
	v_cvt_pk_f16_f32 v30, v44, v43
	global_store_dwordx4 v[28:29], v[30:33], off
	v_add_u32_e32 v26, 0x2004, v71
	v_bfrev_b32_e32 v26, v26
	v_cvt_pk_f16_f32 v33, v27, v34
	v_cvt_pk_f16_f32 v32, v47, v38
	v_cvt_pk_f16_f32 v31, v41, v40
	v_cvt_pk_f16_f32 v30, v45, v42
	global_store_dwordx4 v[0:1], v[30:33], off
	v_lshrrev_b32_e32 v26, 18, v26
	v_sub_u32_e32 v26, 0, v26
	v_add_u32_e32 v30, 0x2005, v71
	v_bfrev_b32_e32 v30, v30
	v_lshrrev_b32_e32 v30, 18, v30
	v_sub_u32_e32 v30, 0, v30
	v_and_b32_e32 v30, 0x1fff, v30
	v_bfrev_b32_e32 v30, v30
	v_lshrrev_b32_e32 v31, 18, v30
	v_lshrrev_b32_e32 v30, 23, v30
	v_bitop3_b32 v30, v30, v31, 31 bitop3:0x6c
	v_add_u32_e32 v31, 0x2006, v71
	v_bfrev_b32_e32 v31, v31
	v_lshrrev_b32_e32 v31, 18, v31
	v_sub_u32_e32 v31, 0, v31
	v_and_b32_e32 v31, 0x2fff, v31
	v_bfrev_b32_e32 v31, v31
	v_lshrrev_b32_e32 v32, 18, v31
	v_lshrrev_b32_e32 v31, 23, v31
	v_bitop3_b32 v31, v31, v32, 31 bitop3:0x6c
	v_lshl_add_u32 v32, v31, 3, 16
	v_add_u32_e32 v31, 0x2007, v71
	v_and_b32_e32 v26, 0x3fff, v26
	v_bfrev_b32_e32 v31, v31
	v_bfrev_b32_e32 v26, v26
	v_lshrrev_b32_e32 v31, 18, v31
	v_lshrrev_b32_e32 v27, 18, v26
	v_lshrrev_b32_e32 v26, 23, v26
	v_sub_u32_e32 v31, 0, v31
	v_bitop3_b32 v26, v26, v27, 31 bitop3:0x6c
	v_and_b32_e32 v31, 0xfff, v31
	v_lshl_add_u32 v26, v26, 3, 16
	v_bfrev_b32_e32 v31, v31
	ds_read_b64 v[26:27], v26
	v_lshrrev_b32_e32 v33, 18, v31
	v_lshrrev_b32_e32 v31, 23, v31
	v_bitop3_b32 v31, v31, v33, 31 bitop3:0x6c
	v_lshl_add_u32 v30, v30, 3, 16
	v_lshl_add_u32 v34, v31, 3, 16
	ds_read_b64 v[30:31], v30
	ds_read_b64 v[32:33], v32
	ds_read_b64 v[34:35], v34
	s_waitcnt lgkmcnt(3)
	v_pk_add_f32 v[36:37], v[24:25], v[26:27]
	v_sub_f32_e32 v25, v25, v27
	v_sub_f32_e32 v24, v26, v24
	v_mul_f32_e32 v27, 0.5, v25
	v_mul_f32_e32 v26, 0.5, v24
	s_waitcnt lgkmcnt(2)
	v_pk_add_f32 v[24:25], v[22:23], v[30:31]
	v_sub_f32_e32 v23, v23, v31
	v_sub_f32_e32 v22, v30, v22
	v_mul_f32_e32 v31, 0.5, v23
	v_mul_f32_e32 v30, 0.5, v22
	s_waitcnt lgkmcnt(1)
	v_pk_add_f32 v[22:23], v[20:21], v[32:33]
	v_sub_f32_e32 v21, v21, v33
	v_sub_f32_e32 v20, v32, v20
	v_mul_f32_e32 v33, 0.5, v21
	v_mul_f32_e32 v32, 0.5, v20
	s_waitcnt lgkmcnt(0)
	v_pk_add_f32 v[20:21], v[18:19], v[34:35]
	v_sub_f32_e32 v19, v19, v35
	v_mul_f32_e32 v36, 0.5, v36
	v_mul_f32_e32 v24, 0.5, v24
	v_mul_f32_e32 v22, 0.5, v22
	v_mul_f32_e32 v20, 0.5, v20
	v_mul_f32_e32 v19, 0.5, v19
	v_sub_f32_e32 v18, v34, v18
	v_mul_f32_e32 v37, 0.5, v37
	v_mul_f32_e32 v25, 0.5, v25
	v_mul_f32_e32 v23, 0.5, v23
	v_mul_f32_e32 v35, 0.5, v21
	v_mul_f32_e32 v34, 0.5, v18
	v_cvt_pk_f16_f32 v21, v20, v19
	v_cvt_pk_f16_f32 v20, v22, v33
	v_cvt_pk_f16_f32 v19, v24, v31
	v_cvt_pk_f16_f32 v18, v36, v27
	global_store_dwordx4 v[28:29], v[18:21], off offset:1024
	v_add_u32_e32 v53, 0xa00, v146
	v_add_u32_e32 v54, 0xc00, v146
	v_cvt_pk_f16_f32 v21, v35, v34
	v_cvt_pk_f16_f32 v20, v23, v32
	v_cvt_pk_f16_f32 v19, v25, v30
	v_cvt_pk_f16_f32 v18, v37, v26
	global_store_dwordx4 v[0:1], v[18:21], off offset:1024
	v_add_u32_e32 v47, 0x1000, v146
	v_add_u32_e32 v46, 0x1200, v146
	v_add_u32_e32 v20, 0x2009, v71
	v_bfrev_b32_e32 v20, v20
	v_lshrrev_b32_e32 v20, 18, v20
	v_sub_u32_e32 v20, 0, v20
	v_and_b32_e32 v20, 0x1fff, v20
	v_bfrev_b32_e32 v20, v20
	v_lshrrev_b32_e32 v21, 18, v20
	v_lshrrev_b32_e32 v20, 23, v20
	v_bitop3_b32 v20, v20, v21, 31 bitop3:0x6c
	v_add_u32_e32 v21, 0x200a, v71
	v_bfrev_b32_e32 v21, v21
	v_lshrrev_b32_e32 v21, 18, v21
	v_sub_u32_e32 v21, 0, v21
	v_and_b32_e32 v21, 0x2fff, v21
	v_add_u32_e32 v18, 0x2008, v71
	v_bfrev_b32_e32 v21, v21
	v_bfrev_b32_e32 v18, v18
	v_lshrrev_b32_e32 v22, 18, v21
	v_lshrrev_b32_e32 v21, 23, v21
	v_lshrrev_b32_e32 v18, 18, v18
	v_bitop3_b32 v21, v21, v22, 31 bitop3:0x6c
	v_sub_u32_e32 v18, 0, v18
	v_lshl_add_u32 v22, v21, 3, 16
	v_add_u32_e32 v21, 0x200b, v71
	v_and_b32_e32 v18, 0x3fff, v18
	v_bfrev_b32_e32 v21, v21
	v_bfrev_b32_e32 v18, v18
	v_lshrrev_b32_e32 v21, 18, v21
	v_lshrrev_b32_e32 v19, 18, v18
	v_lshrrev_b32_e32 v18, 23, v18
	v_sub_u32_e32 v21, 0, v21
	v_bitop3_b32 v18, v18, v19, 31 bitop3:0x6c
	v_and_b32_e32 v21, 0xfff, v21
	v_lshl_add_u32 v18, v18, 3, 16
	v_bfrev_b32_e32 v21, v21
	ds_read_b64 v[18:19], v18
	v_lshrrev_b32_e32 v23, 18, v21
	v_lshrrev_b32_e32 v21, 23, v21
	v_bitop3_b32 v21, v21, v23, 31 bitop3:0x6c
	v_lshl_add_u32 v20, v20, 3, 16
	v_lshl_add_u32 v24, v21, 3, 16
	ds_read_b64 v[20:21], v20
	ds_read_b64 v[22:23], v22
	ds_read_b64 v[24:25], v24
	s_waitcnt lgkmcnt(3)
	v_pk_add_f32 v[26:27], v[16:17], v[18:19]
	v_sub_f32_e32 v17, v17, v19
	v_sub_f32_e32 v16, v18, v16
	v_mul_f32_e32 v19, 0.5, v17
	v_mul_f32_e32 v18, 0.5, v16
	s_waitcnt lgkmcnt(2)
	v_pk_add_f32 v[16:17], v[14:15], v[20:21]
	v_sub_f32_e32 v15, v15, v21
	v_sub_f32_e32 v14, v20, v14
	v_mul_f32_e32 v21, 0.5, v15
	v_mul_f32_e32 v20, 0.5, v14
	s_waitcnt lgkmcnt(1)
	v_pk_add_f32 v[14:15], v[12:13], v[22:23]
	v_sub_f32_e32 v13, v13, v23
	v_sub_f32_e32 v12, v22, v12
	v_mul_f32_e32 v23, 0.5, v13
	v_mul_f32_e32 v22, 0.5, v12
	s_waitcnt lgkmcnt(0)
	v_pk_add_f32 v[12:13], v[10:11], v[24:25]
	v_sub_f32_e32 v11, v11, v25
	v_mul_f32_e32 v26, 0.5, v26
	v_mul_f32_e32 v16, 0.5, v16
	v_mul_f32_e32 v14, 0.5, v14
	v_mul_f32_e32 v12, 0.5, v12
	v_mul_f32_e32 v11, 0.5, v11
	v_sub_f32_e32 v10, v24, v10
	v_mul_f32_e32 v27, 0.5, v27
	v_mul_f32_e32 v17, 0.5, v17
	v_mul_f32_e32 v15, 0.5, v15
	v_mul_f32_e32 v25, 0.5, v13
	v_mul_f32_e32 v24, 0.5, v10
	v_cvt_pk_f16_f32 v13, v12, v11
	v_cvt_pk_f16_f32 v12, v14, v23
	v_cvt_pk_f16_f32 v11, v16, v21
	v_cvt_pk_f16_f32 v10, v26, v19
	global_store_dwordx4 v[28:29], v[10:13], off offset:2048
	v_add_u32_e32 v26, 0x1600, v146
	s_nop 0
	v_cvt_pk_f16_f32 v13, v25, v24
	v_cvt_pk_f16_f32 v12, v15, v22
	v_cvt_pk_f16_f32 v11, v17, v20
	v_cvt_pk_f16_f32 v10, v27, v18
	global_store_dwordx4 v[0:1], v[10:13], off offset:2048
	v_add_u32_e32 v27, 0x1400, v146
	s_nop 0
	v_add_u32_e32 v12, 0x200d, v71
	v_bfrev_b32_e32 v12, v12
	v_lshrrev_b32_e32 v12, 18, v12
	v_sub_u32_e32 v12, 0, v12
	v_and_b32_e32 v12, 0x17ff, v12
	v_bfrev_b32_e32 v12, v12
	v_lshrrev_b32_e32 v13, 18, v12
	v_lshrrev_b32_e32 v12, 23, v12
	v_bitop3_b32 v12, v12, v13, 31 bitop3:0x6c
	v_add_u32_e32 v13, 0x200e, v71
	v_bfrev_b32_e32 v13, v13
	v_lshrrev_b32_e32 v13, 18, v13
	v_sub_u32_e32 v13, 0, v13
	v_and_b32_e32 v13, 0x27ff, v13
	v_add_u32_e32 v10, 0x200c, v71
	v_bfrev_b32_e32 v13, v13
	v_bfrev_b32_e32 v10, v10
	v_lshrrev_b32_e32 v14, 18, v13
	v_lshrrev_b32_e32 v13, 23, v13
	v_lshrrev_b32_e32 v10, 18, v10
	v_bitop3_b32 v13, v13, v14, 31 bitop3:0x6c
	v_sub_u32_e32 v10, 0, v10
	v_lshl_add_u32 v14, v13, 3, 16
	v_add_u32_e32 v13, 0x200f, v71
	v_and_b32_e32 v10, 0x37ff, v10
	v_bfrev_b32_e32 v13, v13
	v_bfrev_b32_e32 v10, v10
	v_lshrrev_b32_e32 v13, 18, v13
	v_lshrrev_b32_e32 v11, 18, v10
	v_lshrrev_b32_e32 v10, 23, v10
	v_sub_u32_e32 v13, 0, v13
	v_bitop3_b32 v10, v10, v11, 31 bitop3:0x6c
	v_and_b32_e32 v13, 0x7ff, v13
	v_lshl_add_u32 v10, v10, 3, 16
	v_bfrev_b32_e32 v13, v13
	ds_read_b64 v[10:11], v10
	v_lshrrev_b32_e32 v15, 18, v13
	v_lshrrev_b32_e32 v13, 23, v13
	v_bitop3_b32 v13, v13, v15, 31 bitop3:0x6c
	v_lshl_add_u32 v12, v12, 3, 16
	v_lshl_add_u32 v16, v13, 3, 16
	ds_read_b64 v[12:13], v12
	ds_read_b64 v[14:15], v14
	ds_read_b64 v[16:17], v16
	s_waitcnt lgkmcnt(3)
	v_pk_add_f32 v[18:19], v[8:9], v[10:11]
	v_sub_f32_e32 v9, v9, v11
	v_sub_f32_e32 v8, v10, v8
	v_mul_f32_e32 v11, 0.5, v9
	v_mul_f32_e32 v10, 0.5, v8
	s_waitcnt lgkmcnt(2)
	v_pk_add_f32 v[8:9], v[6:7], v[12:13]
	v_sub_f32_e32 v7, v7, v13
	v_sub_f32_e32 v6, v12, v6
	v_mul_f32_e32 v13, 0.5, v7
	v_mul_f32_e32 v12, 0.5, v6
	s_waitcnt lgkmcnt(1)
	v_pk_add_f32 v[6:7], v[4:5], v[14:15]
	v_sub_f32_e32 v5, v5, v15
	v_sub_f32_e32 v4, v14, v4
	v_mul_f32_e32 v15, 0.5, v5
	v_mul_f32_e32 v14, 0.5, v4
	s_waitcnt lgkmcnt(0)
	v_pk_add_f32 v[4:5], v[2:3], v[16:17]
	v_sub_f32_e32 v3, v3, v17
	v_mul_f32_e32 v18, 0.5, v18
	v_mul_f32_e32 v8, 0.5, v8
	v_mul_f32_e32 v6, 0.5, v6
	v_mul_f32_e32 v4, 0.5, v4
	v_mul_f32_e32 v3, 0.5, v3
	v_sub_f32_e32 v2, v16, v2
	v_mul_f32_e32 v19, 0.5, v19
	v_mul_f32_e32 v9, 0.5, v9
	v_mul_f32_e32 v7, 0.5, v7
	v_mul_f32_e32 v17, 0.5, v5
	v_mul_f32_e32 v16, 0.5, v2
	v_cvt_pk_f16_f32 v5, v4, v3
	v_cvt_pk_f16_f32 v4, v6, v15
	v_cvt_pk_f16_f32 v3, v8, v13
	v_cvt_pk_f16_f32 v2, v18, v11
	global_store_dwordx4 v[28:29], v[2:5], off offset:3072
	s_nop 1
	v_cvt_pk_f16_f32 v5, v17, v16
	v_cvt_pk_f16_f32 v4, v7, v14
	v_cvt_pk_f16_f32 v3, v9, v12
	v_cvt_pk_f16_f32 v2, v19, v10
	global_store_dwordx4 v[0:1], v[2:5], off offset:3072
	global_load_dword v2, v153, s[90:91] offset:2048
	global_load_dword v0, v154, s[90:91]
	global_load_dword v6, v145, s[90:91]
	global_load_dword v4, v145, s[94:95]
	v_lshlrev_b32_e32 v8, 1, v146
	v_max_i32_e32 v12, 1, v146
	v_add_u32_e32 v13, 0x1e00, v146
	v_cmp_lt_i32_e32 vcc, 0, v146
	v_add_u32_e32 v9, 0x1000, v8
	v_add_u32_e32 v10, 0x2000, v8
	v_add_u32_e32 v11, 0x3000, v8
	v_lshlrev_b32_e32 v12, 1, v12
	v_cndmask_b32_e64 v14, 0, 1.0, vcc
	v_cmp_gt_i32_e32 vcc, 0x1fff, v13
	v_min_i32_e32 v13, 0x1ffe, v13
	v_lshlrev_b32_e32 v13, 1, v13
	s_nop 0
	v_cndmask_b32_e64 v15, 0, 1.0, vcc
	global_load_ushort v163, v12, s[12:13] offset:-2
	global_load_ushort v164, v8, s[12:13]
	global_load_ushort v165, v8, s[12:13] offset:2
	global_load_ushort v166, v12, s[14:15] offset:-2
	global_load_ushort v167, v8, s[14:15]
	global_load_ushort v168, v8, s[14:15] offset:2
	global_load_ushort v169, v8, s[12:13] offset:1022
	global_load_ushort v170, v8, s[12:13] offset:1024
	global_load_ushort v171, v8, s[12:13] offset:1026
	global_load_ushort v172, v8, s[14:15] offset:1022
	global_load_ushort v173, v8, s[14:15] offset:1024
	global_load_ushort v174, v8, s[14:15] offset:1026
	global_load_ushort v175, v8, s[12:13] offset:2046
	global_load_ushort v176, v8, s[12:13] offset:2048
	global_load_ushort v177, v8, s[12:13] offset:2050
	global_load_ushort v178, v8, s[14:15] offset:2046
	global_load_ushort v179, v8, s[14:15] offset:2048
	global_load_ushort v180, v8, s[14:15] offset:2050
	global_load_ushort v181, v8, s[12:13] offset:3070
	global_load_ushort v182, v8, s[12:13] offset:3072
	global_load_ushort v183, v8, s[12:13] offset:3074
	global_load_ushort v184, v8, s[14:15] offset:3070
	global_load_ushort v185, v8, s[14:15] offset:3072
	global_load_ushort v186, v8, s[14:15] offset:3074
	global_load_ushort v187, v9, s[12:13] offset:-2
	global_load_ushort v188, v9, s[12:13]
	global_load_ushort v189, v9, s[12:13] offset:2
	global_load_ushort v190, v9, s[14:15] offset:-2
	global_load_ushort v191, v9, s[14:15]
	global_load_ushort v192, v9, s[14:15] offset:2
	global_load_ushort v193, v9, s[12:13] offset:1022
	global_load_ushort v194, v9, s[12:13] offset:1024
	global_load_ushort v195, v9, s[12:13] offset:1026
	global_load_ushort v196, v9, s[14:15] offset:1022
	global_load_ushort v197, v9, s[14:15] offset:1024
	global_load_ushort v198, v9, s[14:15] offset:1026
	global_load_ushort v199, v9, s[12:13] offset:2046
	global_load_ushort v200, v9, s[12:13] offset:2048
	global_load_ushort v201, v9, s[12:13] offset:2050
	global_load_ushort v202, v9, s[14:15] offset:2046
	global_load_ushort v203, v9, s[14:15] offset:2048
	global_load_ushort v204, v9, s[14:15] offset:2050
	global_load_ushort v205, v9, s[12:13] offset:3070
	global_load_ushort v206, v9, s[12:13] offset:3072
	global_load_ushort v207, v9, s[12:13] offset:3074
	global_load_ushort v208, v9, s[14:15] offset:3070
	global_load_ushort v209, v9, s[14:15] offset:3072
	global_load_ushort v210, v9, s[14:15] offset:3074
	global_load_ushort v211, v10, s[12:13] offset:-2
	global_load_ushort v212, v10, s[12:13]
	global_load_ushort v213, v10, s[12:13] offset:2
	global_load_ushort v221, v10, s[14:15] offset:-2
	global_load_ushort v222, v10, s[14:15]
	global_load_ushort v223, v10, s[14:15] offset:2
	global_load_ushort v224, v10, s[12:13] offset:1022
	global_load_ushort v225, v10, s[12:13] offset:1024
	global_load_ushort v226, v10, s[12:13] offset:1026
	global_load_ushort v227, v10, s[14:15] offset:1022
	global_load_ushort v228, v10, s[14:15] offset:1024
	global_load_ushort v229, v10, s[14:15] offset:1026
	global_load_ushort v230, v10, s[12:13] offset:2046
	global_load_ushort v231, v10, s[12:13] offset:2048
	global_load_ushort v232, v10, s[12:13] offset:2050
	global_load_ushort v233, v10, s[14:15] offset:2046
	global_load_ushort v234, v10, s[14:15] offset:2048
	global_load_ushort v235, v10, s[14:15] offset:2050
	global_load_ushort v236, v10, s[12:13] offset:3070
	global_load_ushort v237, v10, s[12:13] offset:3072
	global_load_ushort v238, v10, s[12:13] offset:3074
	global_load_ushort v239, v10, s[14:15] offset:3070
	global_load_ushort v240, v10, s[14:15] offset:3072
	global_load_ushort v241, v10, s[14:15] offset:3074
	global_load_ushort v242, v11, s[12:13] offset:-2
	global_load_ushort v243, v11, s[12:13]
	global_load_ushort v244, v11, s[12:13] offset:2
	global_load_ushort v245, v11, s[14:15] offset:-2
	global_load_ushort v246, v11, s[14:15]
	global_load_ushort v247, v11, s[14:15] offset:2
	global_load_ushort v248, v11, s[12:13] offset:1022
	global_load_ushort v249, v11, s[12:13] offset:1024
	global_load_ushort v250, v11, s[12:13] offset:1026
	global_load_ushort v251, v11, s[14:15] offset:1022
	global_load_ushort v253, v11, s[14:15] offset:1024
	global_load_ushort v254, v11, s[14:15] offset:1026
	global_load_ushort v255, v11, s[12:13] offset:2046
	global_load_ushort v1, v11, s[12:13] offset:2048
	global_load_ushort v3, v11, s[12:13] offset:2050
	global_load_ushort v5, v11, s[14:15] offset:2046
	global_load_ushort v7, v11, s[14:15] offset:2048
	global_load_ushort v16, v11, s[14:15] offset:2050
	global_load_ushort v17, v11, s[12:13] offset:3070
	global_load_ushort v18, v11, s[12:13] offset:3072
	global_load_ushort v19, v13, s[12:13] offset:2
	global_load_ushort v20, v11, s[14:15] offset:3070
	global_load_ushort v21, v11, s[14:15] offset:3072
	global_load_ushort v22, v13, s[14:15] offset:2
	s_waitcnt vmcnt(48)
	v_lshlrev_b32_e32 v163, 16, v163
	v_lshlrev_b32_e32 v164, 16, v164
	v_lshlrev_b32_e32 v165, 16, v165
	v_mul_f32_e32 v163, v14, v163
	v_mul_f32_e32 v163, v6, v163
	v_fmac_f32_e32 v163, v2, v164
	v_fmac_f32_e32 v163, v0, v165
	v_add_f32_e32 v32, v4, v163
	v_lshlrev_b32_e32 v166, 16, v166
	v_lshlrev_b32_e32 v167, 16, v167
	v_lshlrev_b32_e32 v168, 16, v168
	v_mul_f32_e32 v166, v14, v166
	v_mul_f32_e32 v166, v6, v166
	v_fmac_f32_e32 v166, v2, v167
	v_fmac_f32_e32 v166, v0, v168
	v_add_f32_e32 v34, v4, v166
	v_lshlrev_b32_e32 v169, 16, v169
	v_lshlrev_b32_e32 v170, 16, v170
	v_lshlrev_b32_e32 v171, 16, v171
	v_mul_f32_e32 v169, v6, v169
	v_fmac_f32_e32 v169, v2, v170
	v_fmac_f32_e32 v169, v0, v171
	v_add_f32_e32 v33, v4, v169
	v_lshlrev_b32_e32 v172, 16, v172
	v_lshlrev_b32_e32 v173, 16, v173
	v_lshlrev_b32_e32 v174, 16, v174
	v_mul_f32_e32 v172, v6, v172
	v_fmac_f32_e32 v172, v2, v173
	v_fmac_f32_e32 v172, v0, v174
	v_add_f32_e32 v35, v4, v172
	v_lshlrev_b32_e32 v175, 16, v175
	v_lshlrev_b32_e32 v176, 16, v176
	v_lshlrev_b32_e32 v177, 16, v177
	v_mul_f32_e32 v175, v6, v175
	v_fmac_f32_e32 v175, v2, v176
	v_fmac_f32_e32 v175, v0, v177
	v_add_f32_e32 v37, v4, v175
	v_lshlrev_b32_e32 v178, 16, v178
	v_lshlrev_b32_e32 v179, 16, v179
	v_lshlrev_b32_e32 v180, 16, v180
	v_mul_f32_e32 v178, v6, v178
	v_fmac_f32_e32 v178, v2, v179
	v_fmac_f32_e32 v178, v0, v180
	v_add_f32_e32 v31, v4, v178
	v_lshlrev_b32_e32 v181, 16, v181
	v_lshlrev_b32_e32 v182, 16, v182
	v_lshlrev_b32_e32 v183, 16, v183
	v_mul_f32_e32 v181, v6, v181
	v_fmac_f32_e32 v181, v2, v182
	v_fmac_f32_e32 v181, v0, v183
	v_add_f32_e32 v36, v4, v181
	v_lshlrev_b32_e32 v184, 16, v184
	v_lshlrev_b32_e32 v185, 16, v185
	v_lshlrev_b32_e32 v186, 16, v186
	v_mul_f32_e32 v184, v6, v184
	v_fmac_f32_e32 v184, v2, v185
	v_fmac_f32_e32 v184, v0, v186
	v_add_f32_e32 v30, v4, v184
	v_lshlrev_b32_e32 v187, 16, v187
	v_lshlrev_b32_e32 v188, 16, v188
	v_lshlrev_b32_e32 v189, 16, v189
	v_mul_f32_e32 v187, v6, v187
	v_fmac_f32_e32 v187, v2, v188
	v_fmac_f32_e32 v187, v0, v189
	v_add_f32_e32 v39, v4, v187
	v_lshlrev_b32_e32 v190, 16, v190
	v_lshlrev_b32_e32 v191, 16, v191
	v_lshlrev_b32_e32 v192, 16, v192
	v_mul_f32_e32 v190, v6, v190
	v_fmac_f32_e32 v190, v2, v191
	v_fmac_f32_e32 v190, v0, v192
	v_add_f32_e32 v41, v4, v190
	v_lshlrev_b32_e32 v193, 16, v193
	v_lshlrev_b32_e32 v194, 16, v194
	v_lshlrev_b32_e32 v195, 16, v195
	v_mul_f32_e32 v193, v6, v193
	v_fmac_f32_e32 v193, v2, v194
	v_fmac_f32_e32 v193, v0, v195
	v_add_f32_e32 v38, v4, v193
	v_lshlrev_b32_e32 v196, 16, v196
	v_lshlrev_b32_e32 v197, 16, v197
	v_lshlrev_b32_e32 v198, 16, v198
	v_mul_f32_e32 v196, v6, v196
	v_fmac_f32_e32 v196, v2, v197
	v_fmac_f32_e32 v196, v0, v198
	v_add_f32_e32 v40, v4, v196
	v_lshlrev_b32_e32 v199, 16, v199
	v_lshlrev_b32_e32 v200, 16, v200
	v_lshlrev_b32_e32 v201, 16, v201
	v_mul_f32_e32 v199, v6, v199
	v_fmac_f32_e32 v199, v2, v200
	v_fmac_f32_e32 v199, v0, v201
	v_add_f32_e32 v43, v4, v199
	v_lshlrev_b32_e32 v202, 16, v202
	v_lshlrev_b32_e32 v203, 16, v203
	v_lshlrev_b32_e32 v204, 16, v204
	v_mul_f32_e32 v202, v6, v202
	v_fmac_f32_e32 v202, v2, v203
	v_fmac_f32_e32 v202, v0, v204
	v_add_f32_e32 v45, v4, v202
	v_lshlrev_b32_e32 v205, 16, v205
	v_lshlrev_b32_e32 v206, 16, v206
	v_lshlrev_b32_e32 v207, 16, v207
	v_mul_f32_e32 v205, v6, v205
	v_fmac_f32_e32 v205, v2, v206
	v_fmac_f32_e32 v205, v0, v207
	v_add_f32_e32 v42, v4, v205
	v_lshlrev_b32_e32 v208, 16, v208
	v_lshlrev_b32_e32 v209, 16, v209
	v_lshlrev_b32_e32 v210, 16, v210
	v_mul_f32_e32 v208, v6, v208
	v_fmac_f32_e32 v208, v2, v209
	v_fmac_f32_e32 v208, v0, v210
	v_add_f32_e32 v44, v4, v208
	s_waitcnt vmcnt(0)
	v_lshlrev_b32_e32 v211, 16, v211
	v_lshlrev_b32_e32 v212, 16, v212
	v_lshlrev_b32_e32 v213, 16, v213
	v_mul_f32_e32 v211, v6, v211
	v_fmac_f32_e32 v211, v2, v212
	v_fmac_f32_e32 v211, v0, v213
	v_add_f32_e32 v47, v4, v211
	v_lshlrev_b32_e32 v221, 16, v221
	v_lshlrev_b32_e32 v222, 16, v222
	v_lshlrev_b32_e32 v223, 16, v223
	v_mul_f32_e32 v221, v6, v221
	v_fmac_f32_e32 v221, v2, v222
	v_fmac_f32_e32 v221, v0, v223
	v_add_f32_e32 v49, v4, v221
	v_lshlrev_b32_e32 v224, 16, v224
	v_lshlrev_b32_e32 v225, 16, v225
	v_lshlrev_b32_e32 v226, 16, v226
	v_mul_f32_e32 v224, v6, v224
	v_fmac_f32_e32 v224, v2, v225
	v_fmac_f32_e32 v224, v0, v226
	v_add_f32_e32 v46, v4, v224
	v_lshlrev_b32_e32 v227, 16, v227
	v_lshlrev_b32_e32 v228, 16, v228
	v_lshlrev_b32_e32 v229, 16, v229
	v_mul_f32_e32 v227, v6, v227
	v_fmac_f32_e32 v227, v2, v228
	v_fmac_f32_e32 v227, v0, v229
	v_add_f32_e32 v48, v4, v227
	v_lshlrev_b32_e32 v230, 16, v230
	v_lshlrev_b32_e32 v231, 16, v231
	v_lshlrev_b32_e32 v232, 16, v232
	v_mul_f32_e32 v230, v6, v230
	v_fmac_f32_e32 v230, v2, v231
	v_fmac_f32_e32 v230, v0, v232
	v_add_f32_e32 v51, v4, v230
	v_lshlrev_b32_e32 v233, 16, v233
	v_lshlrev_b32_e32 v234, 16, v234
	v_lshlrev_b32_e32 v235, 16, v235
	v_mul_f32_e32 v233, v6, v233
	v_fmac_f32_e32 v233, v2, v234
	v_fmac_f32_e32 v233, v0, v235
	v_add_f32_e32 v53, v4, v233
	v_lshlrev_b32_e32 v236, 16, v236
	v_lshlrev_b32_e32 v237, 16, v237
	v_lshlrev_b32_e32 v238, 16, v238
	v_mul_f32_e32 v236, v6, v236
	v_fmac_f32_e32 v236, v2, v237
	v_fmac_f32_e32 v236, v0, v238
	v_add_f32_e32 v50, v4, v236
	v_lshlrev_b32_e32 v239, 16, v239
	v_lshlrev_b32_e32 v240, 16, v240
	v_lshlrev_b32_e32 v241, 16, v241
	v_mul_f32_e32 v239, v6, v239
	v_fmac_f32_e32 v239, v2, v240
	v_fmac_f32_e32 v239, v0, v241
	v_add_f32_e32 v52, v4, v239
	v_lshlrev_b32_e32 v242, 16, v242
	v_lshlrev_b32_e32 v243, 16, v243
	v_lshlrev_b32_e32 v244, 16, v244
	v_mul_f32_e32 v242, v6, v242
	v_fmac_f32_e32 v242, v2, v243
	v_fmac_f32_e32 v242, v0, v244
	v_add_f32_e32 v55, v4, v242
	v_lshlrev_b32_e32 v245, 16, v245
	v_lshlrev_b32_e32 v246, 16, v246
	v_lshlrev_b32_e32 v247, 16, v247
	v_mul_f32_e32 v245, v6, v245
	v_fmac_f32_e32 v245, v2, v246
	v_fmac_f32_e32 v245, v0, v247
	v_add_f32_e32 v57, v4, v245
	v_lshlrev_b32_e32 v248, 16, v248
	v_lshlrev_b32_e32 v249, 16, v249
	v_lshlrev_b32_e32 v250, 16, v250
	v_mul_f32_e32 v248, v6, v248
	v_fmac_f32_e32 v248, v2, v249
	v_fmac_f32_e32 v248, v0, v250
	v_add_f32_e32 v54, v4, v248
	v_lshlrev_b32_e32 v251, 16, v251
	v_lshlrev_b32_e32 v253, 16, v253
	v_lshlrev_b32_e32 v254, 16, v254
	v_mul_f32_e32 v251, v6, v251
	v_fmac_f32_e32 v251, v2, v253
	v_fmac_f32_e32 v251, v0, v254
	v_add_f32_e32 v56, v4, v251
	v_lshlrev_b32_e32 v255, 16, v255
	v_lshlrev_b32_e32 v1, 16, v1
	v_lshlrev_b32_e32 v3, 16, v3
	v_mul_f32_e32 v255, v6, v255
	v_fmac_f32_e32 v255, v2, v1
	v_fmac_f32_e32 v255, v0, v3
	v_add_f32_e32 v59, v4, v255
	v_lshlrev_b32_e32 v5, 16, v5
	v_lshlrev_b32_e32 v7, 16, v7
	v_lshlrev_b32_e32 v16, 16, v16
	v_mul_f32_e32 v5, v6, v5
	v_fmac_f32_e32 v5, v2, v7
	v_fmac_f32_e32 v5, v0, v16
	v_add_f32_e32 v61, v4, v5
	v_lshlrev_b32_e32 v17, 16, v17
	v_lshlrev_b32_e32 v18, 16, v18
	v_lshlrev_b32_e32 v19, 16, v19
	v_mul_f32_e32 v19, v15, v19
	v_mul_f32_e32 v17, v6, v17
	v_fmac_f32_e32 v17, v2, v18
	v_fmac_f32_e32 v17, v0, v19
	v_add_f32_e32 v58, v4, v17
	v_lshlrev_b32_e32 v20, 16, v20
	v_lshlrev_b32_e32 v21, 16, v21
	v_lshlrev_b32_e32 v22, 16, v22
	v_mul_f32_e32 v22, v15, v22
	v_mul_f32_e32 v20, v6, v20
	v_fmac_f32_e32 v20, v2, v21
	v_fmac_f32_e32 v20, v0, v22
	v_add_f32_e32 v60, v4, v20
	v_readlane_b32 s72, v252, 22
	v_readlane_b32 s78, v252, 28
	v_readlane_b32 s79, v252, 29
	s_add_u32 s24, s78, s10
	s_addc_u32 s59, s79, s11
	s_lshl_b64 s[0:1], s[68:69], 1
	v_readlane_b32 s4, v252, 50
	v_readlane_b32 s73, v252, 23
	v_readlane_b32 s74, v252, 24
	v_readlane_b32 s75, v252, 25
	v_readlane_b32 s76, v252, 26
	v_readlane_b32 s77, v252, 27
	v_readlane_b32 s80, v252, 30
	v_readlane_b32 s81, v252, 31
	v_readlane_b32 s82, v252, 32
	v_readlane_b32 s83, v252, 33
	s_add_u32 s96, s4, s0
	v_readlane_b32 s0, v252, 51
	s_movk_i32 s83, 0xea00
	s_movk_i32 s82, 0xdff
	s_movk_i32 s81, 0xee00
	s_movk_i32 s80, 0x13ff
	s_movk_i32 s77, 0xf200
	s_movk_i32 s76, 0x7ff
	s_movk_i32 s73, 0xf000
	s_movk_i32 s72, 0x1ff
	s_movk_i32 s75, 0xfff
	s_movk_i32 s74, 0x1fff
	s_movk_i32 s78, 0xf400
	s_movk_i32 s79, 0x11ff
	s_movk_i32 s69, 0xec00
	s_addc_u32 s97, s0, s1
	s_mov_b64 s[14:15], -1
	v_readlane_b32 s84, v252, 34
	v_readlane_b32 s85, v252, 35
	v_readlane_b32 s86, v252, 36
	v_readlane_b32 s87, v252, 37
	s_branch .LBB0_538

.LBB0_908:
	s_nop 1
	v_lshlrev_b32_e32 v0, 2, v146
	s_add_i32 s79, 16, 0x10000
	v_add_u32_e32 v64, 16, v0
	v_add_u32_e32 v65, s79, v0
	s_waitcnt lgkmcnt(0)
	s_barrier
	ds_read2st64_b32 v[2:3], v64 offset1:8
	ds_read2st64_b32 v[4:5], v65 offset1:8
	ds_read2st64_b32 v[8:9], v64 offset0:16 offset1:24
	ds_read2st64_b32 v[10:11], v65 offset0:16 offset1:24
	ds_read2st64_b32 v[12:13], v64 offset0:32 offset1:40
	ds_read2st64_b32 v[14:15], v65 offset0:32 offset1:40
	s_mov_b32 s47, s40
	s_waitcnt lgkmcnt(5)
	v_mov_b32_e32 v6, v2
	s_waitcnt lgkmcnt(4)
	v_mov_b32_e32 v7, v4
	v_mov_b32_e32 v4, v3
	s_waitcnt lgkmcnt(3)
	v_mov_b32_e32 v2, v8
	s_waitcnt lgkmcnt(2)
	v_mov_b32_e32 v3, v10
	v_mov_b32_e32 v10, v9
	ds_read2st64_b32 v[8:9], v64 offset0:48 offset1:56
	ds_read2st64_b32 v[16:17], v65 offset0:48 offset1:56
	s_waitcnt lgkmcnt(3)
	v_mov_b32_e32 v18, v12
	s_waitcnt lgkmcnt(2)
	v_mov_b32_e32 v19, v14
	v_mov_b32_e32 v14, v13
	s_waitcnt lgkmcnt(1)
	v_mov_b32_e32 v12, v8
	s_waitcnt lgkmcnt(0)
	v_mov_b32_e32 v13, v16
	ds_read2st64_b32 v[20:21], v64 offset0:64 offset1:72
	ds_read2st64_b32 v[22:23], v65 offset0:64 offset1:72
	v_mov_b32_e32 v16, v9
	ds_read2st64_b32 v[8:9], v64 offset0:80 offset1:88
	ds_read2st64_b32 v[24:25], v65 offset0:80 offset1:88
	s_mov_b32 s41, s43
	s_waitcnt lgkmcnt(3)
	v_mov_b32_e32 v26, v20
	s_waitcnt lgkmcnt(2)
	v_mov_b32_e32 v27, v22
	v_mov_b32_e32 v22, v21
	s_waitcnt lgkmcnt(1)
	v_mov_b32_e32 v28, v8
	s_waitcnt lgkmcnt(0)
	v_mov_b32_e32 v29, v24
	ds_read2st64_b32 v[20:21], v64 offset0:96 offset1:104
	ds_read2st64_b32 v[30:31], v65 offset0:96 offset1:104
	v_mov_b32_e32 v24, v9
	ds_read2st64_b32 v[8:9], v64 offset0:112 offset1:120
	ds_read2st64_b32 v[32:33], v65 offset0:112 offset1:120
	v_and_b32_e32 v196, 63, v146
	v_lshlrev_b32_e32 v196, 2, v196
	v_and_b32_e32 v0, 0xffffffc0, v146
	v_lshl_add_u32 v0, v0, 5, v196
	v_add_u32_e32 v0, 0x400, v0
	s_waitcnt lgkmcnt(3)
	v_mov_b32_e32 v34, v20
	s_waitcnt lgkmcnt(2)
	v_mov_b32_e32 v35, v30
	v_mov_b32_e32 v30, v21
	s_waitcnt lgkmcnt(1)
	v_mov_b32_e32 v36, v8
	s_waitcnt lgkmcnt(0)
	v_mov_b32_e32 v37, v32
	ds_read2st64_b32 v[20:21], v64 offset0:128 offset1:136
	ds_read2st64_b32 v[38:39], v65 offset0:128 offset1:136
	v_mov_b32_e32 v32, v9
	ds_read2st64_b32 v[8:9], v64 offset0:144 offset1:152
	ds_read2st64_b32 v[40:41], v65 offset0:144 offset1:152
	v_readlane_b32 s0, v252, 48
	s_waitcnt lgkmcnt(3)
	v_mov_b32_e32 v42, v20
	s_waitcnt lgkmcnt(2)
	v_mov_b32_e32 v43, v38
	v_mov_b32_e32 v38, v21
	s_waitcnt lgkmcnt(1)
	v_mov_b32_e32 v44, v8
	s_waitcnt lgkmcnt(0)
	v_mov_b32_e32 v45, v40
	ds_read2st64_b32 v[20:21], v64 offset0:160 offset1:168
	ds_read2st64_b32 v[46:47], v65 offset0:160 offset1:168
	v_mov_b32_e32 v40, v9
	ds_read2st64_b32 v[8:9], v64 offset0:176 offset1:184
	ds_read2st64_b32 v[48:49], v65 offset0:176 offset1:184
	v_ashrrev_i32_e32 v1, 31, v0
	s_waitcnt lgkmcnt(3)
	v_mov_b32_e32 v50, v20
	s_waitcnt lgkmcnt(2)
	v_mov_b32_e32 v51, v46
	v_mov_b32_e32 v46, v21
	s_waitcnt lgkmcnt(1)
	v_mov_b32_e32 v52, v8
	s_waitcnt lgkmcnt(0)
	v_mov_b32_e32 v53, v48
	ds_read2st64_b32 v[20:21], v64 offset0:192 offset1:200
	ds_read2st64_b32 v[54:55], v65 offset0:192 offset1:200
	v_mov_b32_e32 v48, v9
	ds_read2st64_b32 v[8:9], v64 offset0:208 offset1:216
	ds_read2st64_b32 v[56:57], v65 offset0:208 offset1:216
	v_readlane_b32 s1, v252, 49
	s_waitcnt lgkmcnt(3)
	v_mov_b32_e32 v58, v20
	s_waitcnt lgkmcnt(2)
	v_mov_b32_e32 v59, v54
	v_mov_b32_e32 v54, v21
	s_waitcnt lgkmcnt(1)
	v_mov_b32_e32 v60, v8
	s_waitcnt lgkmcnt(0)
	v_mov_b32_e32 v61, v56
	ds_read2st64_b32 v[20:21], v64 offset0:224 offset1:232
	ds_read2st64_b32 v[62:63], v65 offset0:224 offset1:232
	v_mov_b32_e32 v56, v9
	ds_read2st64_b32 v[8:9], v64 offset0:240 offset1:248
	ds_read2st64_b32 v[64:65], v65 offset0:240 offset1:248
	s_waitcnt lgkmcnt(0)
	v_mov_b32_e32 v66, v20
	v_mov_b32_e32 v67, v62
	v_mov_b32_e32 v72, v8
	v_mov_b32_e32 v73, v64
	v_mov_b32_e32 v64, v9
	v_pk_add_f32 v[8:9], v[6:7], v[42:43]
	v_pk_add_f32 v[6:7], v[6:7], v[42:43] neg_lo:[0,1] neg_hi:[0,1]
	v_pk_add_f32 v[42:43], v[4:5], v[38:39]
	v_pk_add_f32 v[4:5], v[4:5], v[38:39] neg_lo:[0,1] neg_hi:[0,1]
	v_mov_b32_e32 v62, v21
	v_xor_b32_e32 v39, 0x80000000, v4
	v_mov_b32_e32 v38, v5
	v_pk_mul_f32 v[38:39], v[38:39], s[48:49] op_sel_hi:[1,0]
	v_mov_b32_e32 v21, v146
	v_pk_fma_f32 v[4:5], v[4:5], s[44:45], v[38:39] op_sel_hi:[1,0,1]
	v_pk_add_f32 v[38:39], v[2:3], v[44:45]
	v_pk_add_f32 v[2:3], v[2:3], v[44:45] neg_lo:[0,1] neg_hi:[0,1]
	s_barrier
	v_xor_b32_e32 v45, 0x80000000, v2
	v_mov_b32_e32 v44, v3
	v_pk_mul_f32 v[44:45], v[44:45], s[54:55] op_sel_hi:[1,0]
	s_nop 0
	v_pk_fma_f32 v[2:3], v[2:3], s[52:53], v[44:45] op_sel_hi:[1,0,1]
	v_pk_add_f32 v[44:45], v[10:11], v[40:41]
	v_pk_add_f32 v[10:11], v[10:11], v[40:41] neg_lo:[0,1] neg_hi:[0,1]
	s_lshl_b64 s[10:11], s[62:63], 2
	v_xor_b32_e32 v41, 0x80000000, v10
	v_mov_b32_e32 v40, v11
	v_pk_mul_f32 v[40:41], v[40:41], s[58:59] op_sel_hi:[1,0]
	v_add_u32_e32 v70, 0x200, v146
	v_pk_fma_f32 v[10:11], v[10:11], s[56:57], v[40:41] op_sel_hi:[1,0,1]
	v_pk_add_f32 v[40:41], v[18:19], v[50:51]
	v_pk_add_f32 v[18:19], v[18:19], v[50:51] neg_lo:[0,1] neg_hi:[0,1]
	v_ashrrev_i32_e32 v147, 31, v146
	v_xor_b32_e32 v51, 0x80000000, v18
	v_mov_b32_e32 v50, v19
	v_pk_mul_f32 v[50:51], v[50:51], s[60:61] op_sel_hi:[1,0]
	v_add_u32_e32 v69, 0x400, v146
	v_pk_fma_f32 v[18:19], v[18:19], s[60:61], v[50:51] op_sel_hi:[1,0,1]
	v_pk_add_f32 v[50:51], v[14:15], v[46:47]
	v_pk_add_f32 v[14:15], v[14:15], v[46:47] neg_lo:[0,1] neg_hi:[0,1]
	v_add_u32_e32 v68, 0x600, v146
	v_xor_b32_e32 v47, 0x80000000, v14
	v_mov_b32_e32 v46, v15
	v_pk_mul_f32 v[46:47], v[46:47], s[56:57] op_sel_hi:[1,0]
	s_mov_b32 s16, 0
	v_pk_fma_f32 v[14:15], v[14:15], s[58:59], v[46:47] op_sel_hi:[1,0,1]
	v_pk_add_f32 v[46:47], v[12:13], v[52:53]
	v_pk_add_f32 v[12:13], v[12:13], v[52:53] neg_lo:[0,1] neg_hi:[0,1]
	s_nop 0
	v_xor_b32_e32 v53, 0x80000000, v12
	v_mov_b32_e32 v52, v13
	v_pk_mul_f32 v[52:53], v[52:53], s[52:53] op_sel_hi:[1,0]
	s_nop 0
	v_pk_fma_f32 v[12:13], v[12:13], s[54:55], v[52:53] op_sel_hi:[1,0,1]
	v_pk_add_f32 v[52:53], v[16:17], v[48:49]
	v_pk_add_f32 v[16:17], v[16:17], v[48:49] neg_lo:[0,1] neg_hi:[0,1]
	s_nop 0
	v_xor_b32_e32 v49, 0x80000000, v16
	v_mov_b32_e32 v48, v17
	v_pk_mul_f32 v[48:49], v[48:49], s[44:45] op_sel_hi:[1,0]
	s_nop 0
	v_pk_fma_f32 v[16:17], v[16:17], s[48:49], v[48:49] op_sel_hi:[1,0,1]
	v_pk_add_f32 v[48:49], v[26:27], v[58:59]
	v_pk_add_f32 v[26:27], v[26:27], v[58:59] neg_lo:[0,1] neg_hi:[0,1]
	s_nop 0
	v_xor_b32_e32 v59, 0x80000000, v26
	v_mov_b32_e32 v58, v27
	v_pk_add_f32 v[26:27], v[22:23], v[54:55]
	v_pk_add_f32 v[22:23], v[22:23], v[54:55] neg_lo:[0,1] neg_hi:[0,1]
	s_nop 0
	v_pk_mul_f32 v[54:55], v[22:23], s[48:49] op_sel_hi:[1,0]
	v_xor_b32_e32 v75, 0x80000000, v22
	v_mov_b32_e32 v74, v23
	v_pk_fma_f32 v[22:23], v[74:75], s[44:45], v[54:55] op_sel_hi:[1,0,1] neg_lo:[0,0,1] neg_hi:[0,0,1]
	v_pk_add_f32 v[54:55], v[28:29], v[60:61]
	v_pk_add_f32 v[28:29], v[28:29], v[60:61] neg_lo:[0,1] neg_hi:[0,1]
	s_nop 0
	v_pk_mul_f32 v[60:61], v[28:29], s[54:55] op_sel_hi:[1,0]
	v_xor_b32_e32 v75, 0x80000000, v28
	v_mov_b32_e32 v74, v29
	v_pk_fma_f32 v[28:29], v[74:75], s[52:53], v[60:61] op_sel_hi:[1,0,1] neg_lo:[0,0,1] neg_hi:[0,0,1]
	v_pk_add_f32 v[60:61], v[24:25], v[56:57]
	v_pk_add_f32 v[24:25], v[24:25], v[56:57] neg_lo:[0,1] neg_hi:[0,1]
	s_nop 0
	v_pk_mul_f32 v[56:57], v[24:25], s[58:59] op_sel_hi:[1,0]
	v_xor_b32_e32 v75, 0x80000000, v24
	v_mov_b32_e32 v74, v25
	v_pk_fma_f32 v[24:25], v[74:75], s[56:57], v[56:57] op_sel_hi:[1,0,1] neg_lo:[0,0,1] neg_hi:[0,0,1]
	v_pk_add_f32 v[56:57], v[34:35], v[66:67]
	v_pk_add_f32 v[34:35], v[34:35], v[66:67] neg_lo:[0,1] neg_hi:[0,1]
	s_nop 0
	v_pk_mul_f32 v[66:67], v[34:35], s[60:61] op_sel_hi:[1,0]
	v_xor_b32_e32 v75, 0x80000000, v34
	v_mov_b32_e32 v74, v35
	v_pk_fma_f32 v[34:35], v[74:75], s[60:61], v[66:67] op_sel_hi:[1,0,1] neg_lo:[0,0,1] neg_hi:[0,0,1]
	v_pk_add_f32 v[66:67], v[30:31], v[62:63]
	v_pk_add_f32 v[30:31], v[30:31], v[62:63] neg_lo:[0,1] neg_hi:[0,1]
	s_nop 0
	v_pk_mul_f32 v[62:63], v[30:31], s[56:57] op_sel_hi:[1,0]
	v_xor_b32_e32 v75, 0x80000000, v30
	v_mov_b32_e32 v74, v31
	v_pk_fma_f32 v[30:31], v[74:75], s[58:59], v[62:63] op_sel_hi:[1,0,1] neg_lo:[0,0,1] neg_hi:[0,0,1]
	v_pk_add_f32 v[62:63], v[36:37], v[72:73]
	v_pk_add_f32 v[36:37], v[36:37], v[72:73] neg_lo:[0,1] neg_hi:[0,1]
	s_nop 0
	v_pk_mul_f32 v[72:73], v[36:37], s[52:53] op_sel_hi:[1,0]
	v_xor_b32_e32 v75, 0x80000000, v36
	v_mov_b32_e32 v74, v37
	v_pk_fma_f32 v[36:37], v[74:75], s[54:55], v[72:73] op_sel_hi:[1,0,1] neg_lo:[0,0,1] neg_hi:[0,0,1]
	v_pk_add_f32 v[72:73], v[32:33], v[64:65]
	v_pk_add_f32 v[32:33], v[32:33], v[64:65] neg_lo:[0,1] neg_hi:[0,1]
	s_nop 0
	v_pk_mul_f32 v[64:65], v[32:33], s[44:45] op_sel_hi:[1,0]
	v_xor_b32_e32 v75, 0x80000000, v32
	v_mov_b32_e32 v74, v33
	v_pk_fma_f32 v[32:33], v[74:75], s[48:49], v[64:65] op_sel_hi:[1,0,1] neg_lo:[0,0,1] neg_hi:[0,0,1]
	v_pk_add_f32 v[64:65], v[8:9], v[48:49]
	v_pk_add_f32 v[8:9], v[8:9], v[48:49] neg_lo:[0,1] neg_hi:[0,1]
	v_pk_add_f32 v[48:49], v[42:43], v[26:27]
	v_pk_add_f32 v[26:27], v[42:43], v[26:27] neg_lo:[0,1] neg_hi:[0,1]
	s_nop 0
	v_xor_b32_e32 v43, 0x80000000, v26
	v_mov_b32_e32 v42, v27
	v_pk_mul_f32 v[42:43], v[42:43], s[54:55] op_sel_hi:[1,0]
	s_nop 0
	v_pk_fma_f32 v[26:27], v[26:27], s[52:53], v[42:43] op_sel_hi:[1,0,1]
	v_pk_add_f32 v[42:43], v[38:39], v[54:55]
	v_pk_add_f32 v[38:39], v[38:39], v[54:55] neg_lo:[0,1] neg_hi:[0,1]
	s_nop 0
	v_xor_b32_e32 v55, 0x80000000, v38
	v_mov_b32_e32 v54, v39
	v_pk_mul_f32 v[54:55], v[54:55], s[60:61] op_sel_hi:[1,0]
	s_nop 0
	v_pk_fma_f32 v[38:39], v[38:39], s[60:61], v[54:55] op_sel_hi:[1,0,1]
	v_pk_add_f32 v[54:55], v[44:45], v[60:61]
	v_pk_add_f32 v[44:45], v[44:45], v[60:61] neg_lo:[0,1] neg_hi:[0,1]
	s_nop 0
	v_xor_b32_e32 v61, 0x80000000, v44
	v_mov_b32_e32 v60, v45
	v_pk_mul_f32 v[60:61], v[60:61], s[52:53] op_sel_hi:[1,0]
	s_nop 0
	v_pk_fma_f32 v[44:45], v[44:45], s[54:55], v[60:61] op_sel_hi:[1,0,1]
	v_pk_add_f32 v[60:61], v[40:41], v[56:57]
	v_pk_add_f32 v[40:41], v[40:41], v[56:57] neg_lo:[0,1] neg_hi:[0,1]
	s_nop 0
	v_xor_b32_e32 v57, 0x80000000, v40
	v_mov_b32_e32 v56, v41
	v_pk_add_f32 v[40:41], v[50:51], v[66:67]
	v_pk_add_f32 v[50:51], v[50:51], v[66:67] neg_lo:[0,1] neg_hi:[0,1]
	s_nop 0
	v_pk_mul_f32 v[66:67], v[50:51], s[54:55] op_sel_hi:[1,0]
	v_xor_b32_e32 v75, 0x80000000, v50
	v_mov_b32_e32 v74, v51
	v_pk_fma_f32 v[50:51], v[74:75], s[52:53], v[66:67] op_sel_hi:[1,0,1] neg_lo:[0,0,1] neg_hi:[0,0,1]
	v_pk_add_f32 v[66:67], v[46:47], v[62:63]
	v_pk_add_f32 v[46:47], v[46:47], v[62:63] neg_lo:[0,1] neg_hi:[0,1]
	s_nop 0
	v_pk_mul_f32 v[62:63], v[46:47], s[60:61] op_sel_hi:[1,0]
	v_xor_b32_e32 v75, 0x80000000, v46
	v_mov_b32_e32 v74, v47
	v_pk_fma_f32 v[46:47], v[74:75], s[60:61], v[62:63] op_sel_hi:[1,0,1] neg_lo:[0,0,1] neg_hi:[0,0,1]
	v_pk_add_f32 v[62:63], v[52:53], v[72:73]
	v_pk_add_f32 v[52:53], v[52:53], v[72:73] neg_lo:[0,1] neg_hi:[0,1]
	s_nop 0
	v_pk_mul_f32 v[72:73], v[52:53], s[52:53] op_sel_hi:[1,0]
	v_xor_b32_e32 v75, 0x80000000, v52
	v_mov_b32_e32 v74, v53
	v_pk_fma_f32 v[52:53], v[74:75], s[54:55], v[72:73] op_sel_hi:[1,0,1] neg_lo:[0,0,1] neg_hi:[0,0,1]
	v_pk_add_f32 v[72:73], v[6:7], v[58:59]
	v_pk_add_f32 v[6:7], v[6:7], v[58:59] neg_lo:[0,1] neg_hi:[0,1]
	v_pk_add_f32 v[58:59], v[4:5], v[22:23]
	v_pk_add_f32 v[4:5], v[4:5], v[22:23] neg_lo:[0,1] neg_hi:[0,1]
	s_nop 0
	v_xor_b32_e32 v23, 0x80000000, v4
	v_mov_b32_e32 v22, v5
	v_pk_mul_f32 v[22:23], v[22:23], s[54:55] op_sel_hi:[1,0]
	s_nop 0
	v_pk_fma_f32 v[4:5], v[4:5], s[52:53], v[22:23] op_sel_hi:[1,0,1]
	v_pk_add_f32 v[22:23], v[2:3], v[28:29]
	v_pk_add_f32 v[2:3], v[2:3], v[28:29] neg_lo:[0,1] neg_hi:[0,1]
	s_nop 0
	v_xor_b32_e32 v29, 0x80000000, v2
	v_mov_b32_e32 v28, v3
	v_pk_mul_f32 v[28:29], v[28:29], s[60:61] op_sel_hi:[1,0]
	s_nop 0
	v_pk_fma_f32 v[2:3], v[2:3], s[60:61], v[28:29] op_sel_hi:[1,0,1]
	v_pk_add_f32 v[28:29], v[10:11], v[24:25]
	v_pk_add_f32 v[10:11], v[10:11], v[24:25] neg_lo:[0,1] neg_hi:[0,1]
	s_nop 0
	v_xor_b32_e32 v25, 0x80000000, v10
	v_mov_b32_e32 v24, v11
	v_pk_mul_f32 v[24:25], v[24:25], s[52:53] op_sel_hi:[1,0]
	s_nop 0
	v_pk_fma_f32 v[10:11], v[10:11], s[54:55], v[24:25] op_sel_hi:[1,0,1]
	v_pk_add_f32 v[24:25], v[18:19], v[34:35]
	v_pk_add_f32 v[18:19], v[18:19], v[34:35] neg_lo:[0,1] neg_hi:[0,1]
	s_nop 0
	v_xor_b32_e32 v35, 0x80000000, v18
	v_mov_b32_e32 v34, v19
	v_pk_add_f32 v[18:19], v[14:15], v[30:31]
	v_pk_add_f32 v[14:15], v[14:15], v[30:31] neg_lo:[0,1] neg_hi:[0,1]
	s_nop 0
	v_pk_mul_f32 v[30:31], v[14:15], s[54:55] op_sel_hi:[1,0]
	v_xor_b32_e32 v75, 0x80000000, v14
	v_mov_b32_e32 v74, v15
	v_pk_fma_f32 v[14:15], v[74:75], s[52:53], v[30:31] op_sel_hi:[1,0,1] neg_lo:[0,0,1] neg_hi:[0,0,1]
	v_pk_add_f32 v[30:31], v[12:13], v[36:37]
	v_pk_add_f32 v[12:13], v[12:13], v[36:37] neg_lo:[0,1] neg_hi:[0,1]
	s_nop 0
	v_pk_mul_f32 v[36:37], v[12:13], s[60:61] op_sel_hi:[1,0]
	v_xor_b32_e32 v75, 0x80000000, v12
	v_mov_b32_e32 v74, v13
	v_pk_fma_f32 v[12:13], v[74:75], s[60:61], v[36:37] op_sel_hi:[1,0,1] neg_lo:[0,0,1] neg_hi:[0,0,1]
	v_pk_add_f32 v[36:37], v[16:17], v[32:33]
	v_pk_add_f32 v[16:17], v[16:17], v[32:33] neg_lo:[0,1] neg_hi:[0,1]
	s_nop 0
	v_pk_mul_f32 v[32:33], v[16:17], s[52:53] op_sel_hi:[1,0]
	v_xor_b32_e32 v75, 0x80000000, v16
	v_mov_b32_e32 v74, v17
	v_pk_fma_f32 v[16:17], v[74:75], s[54:55], v[32:33] op_sel_hi:[1,0,1] neg_lo:[0,0,1] neg_hi:[0,0,1]
	v_pk_add_f32 v[32:33], v[64:65], v[60:61]
	v_pk_add_f32 v[60:61], v[64:65], v[60:61] neg_lo:[0,1] neg_hi:[0,1]
	v_pk_add_f32 v[64:65], v[48:49], v[40:41]
	v_pk_add_f32 v[40:41], v[48:49], v[40:41] neg_lo:[0,1] neg_hi:[0,1]
	s_nop 0
	v_xor_b32_e32 v49, 0x80000000, v40
	v_mov_b32_e32 v48, v41
	v_pk_mul_f32 v[48:49], v[48:49], s[60:61] op_sel_hi:[1,0]
	s_nop 0
	v_pk_fma_f32 v[40:41], v[40:41], s[60:61], v[48:49] op_sel_hi:[1,0,1]
	v_pk_add_f32 v[48:49], v[42:43], v[66:67]
	v_pk_add_f32 v[42:43], v[42:43], v[66:67] neg_lo:[0,1] neg_hi:[0,1]
	s_nop 0
	v_xor_b32_e32 v67, 0x80000000, v42
	v_mov_b32_e32 v66, v43
	v_pk_add_f32 v[42:43], v[54:55], v[62:63]
	v_pk_add_f32 v[54:55], v[54:55], v[62:63] neg_lo:[0,1] neg_hi:[0,1]
	s_nop 0
	v_pk_mul_f32 v[62:63], v[54:55], s[60:61] op_sel_hi:[1,0]
	v_xor_b32_e32 v75, 0x80000000, v54
	v_mov_b32_e32 v74, v55
	v_pk_fma_f32 v[54:55], v[74:75], s[60:61], v[62:63] op_sel_hi:[1,0,1] neg_lo:[0,0,1] neg_hi:[0,0,1]
	v_pk_add_f32 v[62:63], v[8:9], v[56:57]
	v_pk_add_f32 v[8:9], v[8:9], v[56:57] neg_lo:[0,1] neg_hi:[0,1]
	v_pk_add_f32 v[56:57], v[26:27], v[50:51]
	v_pk_add_f32 v[26:27], v[26:27], v[50:51] neg_lo:[0,1] neg_hi:[0,1]
	s_nop 0
	v_xor_b32_e32 v51, 0x80000000, v26
	v_mov_b32_e32 v50, v27
	v_pk_mul_f32 v[50:51], v[50:51], s[60:61] op_sel_hi:[1,0]
	s_nop 0
	v_pk_fma_f32 v[26:27], v[26:27], s[60:61], v[50:51] op_sel_hi:[1,0,1]
	v_pk_add_f32 v[50:51], v[38:39], v[46:47]
	v_pk_add_f32 v[38:39], v[38:39], v[46:47] neg_lo:[0,1] neg_hi:[0,1]
	s_nop 0
	v_xor_b32_e32 v47, 0x80000000, v38
	v_mov_b32_e32 v46, v39
	v_pk_add_f32 v[38:39], v[44:45], v[52:53]
	v_pk_add_f32 v[44:45], v[44:45], v[52:53] neg_lo:[0,1] neg_hi:[0,1]
	s_nop 0
	v_pk_mul_f32 v[52:53], v[44:45], s[60:61] op_sel_hi:[1,0]
	v_xor_b32_e32 v75, 0x80000000, v44
	v_mov_b32_e32 v74, v45
	v_pk_fma_f32 v[44:45], v[74:75], s[60:61], v[52:53] op_sel_hi:[1,0,1] neg_lo:[0,0,1] neg_hi:[0,0,1]
	v_pk_add_f32 v[52:53], v[72:73], v[24:25]
	v_pk_add_f32 v[24:25], v[72:73], v[24:25] neg_lo:[0,1] neg_hi:[0,1]
	v_pk_add_f32 v[72:73], v[58:59], v[18:19]
	v_pk_add_f32 v[18:19], v[58:59], v[18:19] neg_lo:[0,1] neg_hi:[0,1]
	s_nop 0
	v_xor_b32_e32 v59, 0x80000000, v18
	v_mov_b32_e32 v58, v19
	v_pk_mul_f32 v[58:59], v[58:59], s[60:61] op_sel_hi:[1,0]
	s_nop 0
	v_pk_fma_f32 v[18:19], v[18:19], s[60:61], v[58:59] op_sel_hi:[1,0,1]
	v_pk_add_f32 v[58:59], v[22:23], v[30:31]
	v_pk_add_f32 v[22:23], v[22:23], v[30:31] neg_lo:[0,1] neg_hi:[0,1]
	s_nop 0
	v_xor_b32_e32 v31, 0x80000000, v22
	v_mov_b32_e32 v30, v23
	v_pk_add_f32 v[22:23], v[28:29], v[36:37]
	v_pk_add_f32 v[28:29], v[28:29], v[36:37] neg_lo:[0,1] neg_hi:[0,1]
	v_pk_add_f32 v[76:77], v[24:25], v[30:31]
	v_pk_mul_f32 v[36:37], v[28:29], s[60:61] op_sel_hi:[1,0]
	v_xor_b32_e32 v75, 0x80000000, v28
	v_mov_b32_e32 v74, v29
	v_pk_fma_f32 v[28:29], v[74:75], s[60:61], v[36:37] op_sel_hi:[1,0,1] neg_lo:[0,0,1] neg_hi:[0,0,1]
	v_pk_add_f32 v[36:37], v[6:7], v[34:35]
	v_pk_add_f32 v[6:7], v[6:7], v[34:35] neg_lo:[0,1] neg_hi:[0,1]
	v_pk_add_f32 v[34:35], v[4:5], v[14:15]
	v_pk_add_f32 v[4:5], v[4:5], v[14:15] neg_lo:[0,1] neg_hi:[0,1]
	v_pk_add_f32 v[78:79], v[18:19], v[28:29]
	v_xor_b32_e32 v15, 0x80000000, v4
	v_mov_b32_e32 v14, v5
	v_pk_mul_f32 v[14:15], v[14:15], s[60:61] op_sel_hi:[1,0]
	v_pk_add_f32 v[18:19], v[18:19], v[28:29] neg_lo:[0,1] neg_hi:[0,1]
	v_pk_fma_f32 v[4:5], v[4:5], s[60:61], v[14:15] op_sel_hi:[1,0,1]
	v_pk_add_f32 v[14:15], v[2:3], v[12:13]
	v_pk_add_f32 v[2:3], v[2:3], v[12:13] neg_lo:[0,1] neg_hi:[0,1]
	v_xor_b32_e32 v81, 0x80000000, v18
	v_xor_b32_e32 v13, 0x80000000, v2
	v_mov_b32_e32 v12, v3
	v_pk_add_f32 v[2:3], v[10:11], v[16:17]
	v_pk_add_f32 v[10:11], v[10:11], v[16:17] neg_lo:[0,1] neg_hi:[0,1]
	v_mov_b32_e32 v80, v19
	v_pk_mul_f32 v[16:17], v[10:11], s[60:61] op_sel_hi:[1,0]
	v_xor_b32_e32 v75, 0x80000000, v10
	v_mov_b32_e32 v74, v11
	v_pk_fma_f32 v[10:11], v[74:75], s[60:61], v[16:17] op_sel_hi:[1,0,1] neg_lo:[0,0,1] neg_hi:[0,0,1]
	v_pk_add_f32 v[74:75], v[62:63], v[50:51]
	v_pk_add_f32 v[50:51], v[62:63], v[50:51] neg_lo:[0,1] neg_hi:[0,1]
	v_pk_add_f32 v[62:63], v[56:57], v[38:39]
	v_pk_add_f32 v[38:39], v[56:57], v[38:39] neg_lo:[0,1] neg_hi:[0,1]
	v_pk_add_f32 v[16:17], v[32:33], v[48:49]
	v_pk_add_f32 v[32:33], v[32:33], v[48:49] neg_lo:[0,1] neg_hi:[0,1]
	v_pk_add_f32 v[48:49], v[64:65], v[42:43]
	v_pk_add_f32 v[42:43], v[64:65], v[42:43] neg_lo:[0,1] neg_hi:[0,1]
	v_xor_b32_e32 v57, 0x80000000, v38
	v_mov_b32_e32 v56, v39
	v_pk_add_f32 v[38:39], v[8:9], v[46:47]
	v_pk_add_f32 v[8:9], v[8:9], v[46:47] neg_lo:[0,1] neg_hi:[0,1]
	v_pk_add_f32 v[46:47], v[26:27], v[44:45]
	v_pk_add_f32 v[26:27], v[26:27], v[44:45] neg_lo:[0,1] neg_hi:[0,1]
	v_xor_b32_e32 v65, 0x80000000, v42
	v_mov_b32_e32 v64, v43
	v_pk_add_f32 v[42:43], v[60:61], v[66:67]
	v_pk_add_f32 v[60:61], v[60:61], v[66:67] neg_lo:[0,1] neg_hi:[0,1]
	v_pk_add_f32 v[66:67], v[40:41], v[54:55]
	v_pk_add_f32 v[40:41], v[40:41], v[54:55] neg_lo:[0,1] neg_hi:[0,1]
	v_xor_b32_e32 v45, 0x80000000, v26
	v_mov_b32_e32 v44, v27
	v_pk_add_f32 v[26:27], v[52:53], v[58:59]
	v_pk_add_f32 v[52:53], v[52:53], v[58:59] neg_lo:[0,1] neg_hi:[0,1]
	v_pk_add_f32 v[58:59], v[72:73], v[22:23]
	v_pk_add_f32 v[22:23], v[72:73], v[22:23] neg_lo:[0,1] neg_hi:[0,1]
	v_pk_add_f32 v[18:19], v[36:37], v[14:15]
	v_pk_add_f32 v[14:15], v[36:37], v[14:15] neg_lo:[0,1] neg_hi:[0,1]
	v_pk_add_f32 v[36:37], v[34:35], v[2:3]
	v_pk_add_f32 v[2:3], v[34:35], v[2:3] neg_lo:[0,1] neg_hi:[0,1]
	v_xor_b32_e32 v55, 0x80000000, v40
	v_mov_b32_e32 v54, v41
	v_xor_b32_e32 v73, 0x80000000, v22
	v_mov_b32_e32 v72, v23
	v_xor_b32_e32 v35, 0x80000000, v2
	v_mov_b32_e32 v34, v3
	v_pk_add_f32 v[2:3], v[4:5], v[10:11] neg_lo:[0,1] neg_hi:[0,1]
	v_pk_add_f32 v[24:25], v[24:25], v[30:31] neg_lo:[0,1] neg_hi:[0,1]
	v_pk_add_f32 v[82:83], v[6:7], v[12:13]
	v_pk_add_f32 v[12:13], v[6:7], v[12:13] neg_lo:[0,1] neg_hi:[0,1]
	v_xor_b32_e32 v87, 0x80000000, v2
	v_mov_b32_e32 v86, v3
	v_pk_add_f32 v[2:3], v[16:17], v[48:49]
	v_pk_add_f32 v[88:89], v[16:17], v[48:49] neg_lo:[0,1] neg_hi:[0,1]
	v_pk_add_f32 v[48:49], v[32:33], v[64:65]
	v_pk_add_f32 v[28:29], v[32:33], v[64:65] neg_lo:[0,1] neg_hi:[0,1]
	v_pk_add_f32 v[64:65], v[60:61], v[54:55]
	v_pk_add_f32 v[6:7], v[60:61], v[54:55] neg_lo:[0,1] neg_hi:[0,1]
	v_pk_add_f32 v[60:61], v[50:51], v[56:57]
	v_pk_add_f32 v[22:23], v[50:51], v[56:57] neg_lo:[0,1] neg_hi:[0,1]
	v_pk_add_f32 v[50:51], v[52:53], v[72:73]
	v_pk_add_f32 v[30:31], v[52:53], v[72:73] neg_lo:[0,1] neg_hi:[0,1]
	v_pk_add_f32 v[52:53], v[18:19], v[36:37]
	v_pk_add_f32 v[56:57], v[18:19], v[36:37] neg_lo:[0,1] neg_hi:[0,1]
	v_mov_b32_e32 v18, v21
	v_pk_add_f32 v[84:85], v[4:5], v[10:11]
	v_cvt_f32_i32_e32 v18, v18
	v_pk_add_f32 v[32:33], v[42:43], v[66:67]
	v_pk_add_f32 v[40:41], v[42:43], v[66:67] neg_lo:[0,1] neg_hi:[0,1]
	v_pk_add_f32 v[66:67], v[24:25], v[80:81]
	v_pk_add_f32 v[10:11], v[24:25], v[80:81] neg_lo:[0,1] neg_hi:[0,1]
	v_pk_add_f32 v[72:73], v[14:15], v[34:35]
	v_pk_add_f32 v[24:25], v[14:15], v[34:35] neg_lo:[0,1] neg_hi:[0,1]
	v_mul_f32_e32 v15, 0x38800000, v18
	v_cos_f32_e32 v14, v15
	v_sin_f32_e32 v15, v15
	v_pk_add_f32 v[16:17], v[74:75], v[62:63]
	v_pk_add_f32 v[54:55], v[74:75], v[62:63] neg_lo:[0,1] neg_hi:[0,1]
	v_pk_add_f32 v[62:63], v[8:9], v[44:45]
	v_pk_add_f32 v[4:5], v[8:9], v[44:45] neg_lo:[0,1] neg_hi:[0,1]
	v_pk_add_f32 v[8:9], v[26:27], v[58:59]
	v_add_f32_e32 v20, v14, v14
	v_pk_add_f32 v[42:43], v[38:39], v[46:47]
	v_pk_add_f32 v[38:39], v[38:39], v[46:47] neg_lo:[0,1] neg_hi:[0,1]
	v_pk_add_f32 v[58:59], v[26:27], v[58:59] neg_lo:[0,1] neg_hi:[0,1]
	v_pk_add_f32 v[26:27], v[76:77], v[78:79]
	v_pk_add_f32 v[46:47], v[76:77], v[78:79] neg_lo:[0,1] neg_hi:[0,1]
	v_pk_mul_f32 v[18:19], v[14:15], v[14:15]
	v_mul_f32_e32 v20, v15, v20
	v_xor_b32_e32 v34, 0x80000000, v15
	v_mov_b32_e32 v35, v14
	v_xor_b32_e32 v37, 0x80000000, v8
	v_mov_b32_e32 v36, v9
	v_mov_b32_e32 v78, v15
	v_pk_add_f32 v[18:19], v[18:19], v[18:19] op_sel:[0,1] op_sel_hi:[0,1] neg_lo:[0,1] neg_hi:[0,1]
	v_pk_mul_f32 v[34:35], v[34:35], v[20:21] op_sel_hi:[1,0]
	v_pk_mul_f32 v[36:37], v[78:79], v[36:37] op_sel_hi:[0,1]
	v_pk_fma_f32 v[34:35], v[14:15], v[18:19], v[34:35]
	v_pk_fma_f32 v[8:9], v[14:15], v[8:9], v[36:37] op_sel_hi:[0,1,1]
	v_pk_mul_f32 v[14:15], v[20:21], s[46:47] op_sel_hi:[0,1]
	v_pk_fma_f32 v[36:37], v[18:19], s[40:41], v[14:15]
	v_xor_b32_e32 v15, 0x80000000, v16
	v_mov_b32_e32 v14, v17
	v_pk_mul_f32 v[14:15], v[14:15], v[36:37] op_sel:[0,1]
	v_pk_add_f32 v[74:75], v[82:83], v[84:85]
	v_pk_fma_f32 v[16:17], v[16:17], v[36:37], v[14:15] op_sel_hi:[1,0,1]
	v_xor_b32_e32 v14, 0x80000000, v35
	v_mov_b32_e32 v15, v34
	v_pk_mul_f32 v[14:15], v[20:21], v[14:15] op_sel_hi:[0,1]
	v_pk_fma_f32 v[78:79], v[18:19], v[34:35], v[14:15]
	v_xor_b32_e32 v15, 0x80000000, v52
	v_mov_b32_e32 v14, v53
	v_pk_mul_f32 v[14:15], v[34:35], v[14:15] op_sel:[1,0]
	v_pk_add_f32 v[76:77], v[12:13], v[86:87]
	v_pk_fma_f32 v[14:15], v[34:35], v[52:53], v[14:15] op_sel_hi:[0,1,1]
	v_xor_b32_e32 v34, 0x80000000, v37
	v_mov_b32_e32 v35, v36
	v_pk_mul_f32 v[34:35], v[20:21], v[34:35] op_sel_hi:[0,1]
	v_xor_b32_e32 v53, 0x80000000, v26
	v_mov_b32_e32 v52, v27
	v_pk_fma_f32 v[36:37], v[18:19], v[36:37], v[34:35]
	v_xor_b32_e32 v35, 0x80000000, v32
	v_mov_b32_e32 v34, v33
	v_pk_mul_f32 v[52:53], v[52:53], v[78:79] op_sel:[0,1]
	v_pk_mul_f32 v[34:35], v[34:35], v[36:37] op_sel:[0,1]
	v_pk_fma_f32 v[26:27], v[26:27], v[78:79], v[52:53] op_sel_hi:[1,0,1]
	v_xor_b32_e32 v52, 0x80000000, v37
	v_mov_b32_e32 v53, v36
	v_pk_fma_f32 v[34:35], v[32:33], v[36:37], v[34:35] op_sel_hi:[1,0,1]
	v_xor_b32_e32 v32, 0x80000000, v79
	v_mov_b32_e32 v33, v78
	v_pk_mul_f32 v[52:53], v[20:21], v[52:53] op_sel_hi:[0,1]
	v_pk_mul_f32 v[32:33], v[20:21], v[32:33] op_sel_hi:[0,1]
	v_pk_fma_f32 v[52:53], v[18:19], v[36:37], v[52:53]
	v_xor_b32_e32 v37, 0x80000000, v42
	v_mov_b32_e32 v36, v43
	v_pk_fma_f32 v[32:33], v[18:19], v[78:79], v[32:33]
	v_pk_mul_f32 v[36:37], v[36:37], v[52:53] op_sel:[0,1]
	v_xor_b32_e32 v79, 0x80000000, v74
	v_pk_fma_f32 v[36:37], v[42:43], v[52:53], v[36:37] op_sel_hi:[1,0,1]
	v_xor_b32_e32 v42, 0x80000000, v33
	v_mov_b32_e32 v43, v32
	v_mov_b32_e32 v78, v75
	v_pk_mul_f32 v[42:43], v[20:21], v[42:43] op_sel_hi:[0,1]
	v_pk_mul_f32 v[78:79], v[78:79], v[32:33] op_sel:[0,1]
	v_pk_fma_f32 v[42:43], v[18:19], v[32:33], v[42:43]
	v_pk_fma_f32 v[32:33], v[74:75], v[32:33], v[78:79] op_sel_hi:[1,0,1]
	v_xor_b32_e32 v74, 0x80000000, v53
	v_mov_b32_e32 v75, v52
	v_pk_mul_f32 v[74:75], v[20:21], v[74:75] op_sel_hi:[0,1]
	v_pk_fma_f32 v[52:53], v[18:19], v[52:53], v[74:75]
	v_xor_b32_e32 v75, 0x80000000, v48
	v_mov_b32_e32 v74, v49
	v_pk_mul_f32 v[74:75], v[74:75], v[52:53] op_sel:[0,1]
	v_xor_b32_e32 v79, 0x80000000, v50
	v_pk_fma_f32 v[48:49], v[48:49], v[52:53], v[74:75] op_sel_hi:[1,0,1]
	v_xor_b32_e32 v74, 0x80000000, v43
	v_mov_b32_e32 v75, v42
	v_mov_b32_e32 v78, v51
	v_pk_mul_f32 v[74:75], v[20:21], v[74:75] op_sel_hi:[0,1]
	v_pk_mul_f32 v[78:79], v[78:79], v[42:43] op_sel:[0,1]
	v_pk_fma_f32 v[74:75], v[18:19], v[42:43], v[74:75]
	v_pk_fma_f32 v[42:43], v[50:51], v[42:43], v[78:79] op_sel_hi:[1,0,1]
	v_xor_b32_e32 v50, 0x80000000, v53
	v_mov_b32_e32 v51, v52
	v_pk_mul_f32 v[50:51], v[20:21], v[50:51] op_sel_hi:[0,1]
	v_pk_fma_f32 v[78:79], v[18:19], v[52:53], v[50:51]
	v_xor_b32_e32 v51, 0x80000000, v60
	v_mov_b32_e32 v50, v61
	v_pk_mul_f32 v[50:51], v[50:51], v[78:79] op_sel:[0,1]
	v_xor_b32_e32 v81, 0x80000000, v58
	v_pk_fma_f32 v[52:53], v[60:61], v[78:79], v[50:51] op_sel_hi:[1,0,1]
	v_xor_b32_e32 v50, 0x80000000, v75
	v_mov_b32_e32 v51, v74
	v_pk_mul_f32 v[50:51], v[20:21], v[50:51] op_sel_hi:[0,1]
	v_pk_fma_f32 v[60:61], v[18:19], v[74:75], v[50:51]
	v_xor_b32_e32 v51, 0x80000000, v72
	v_mov_b32_e32 v50, v73
	v_pk_mul_f32 v[50:51], v[50:51], v[74:75] op_sel:[0,1]
	v_mov_b32_e32 v80, v59
	v_pk_fma_f32 v[50:51], v[72:73], v[74:75], v[50:51] op_sel_hi:[1,0,1]
	v_xor_b32_e32 v72, 0x80000000, v79
	v_mov_b32_e32 v73, v78
	v_pk_mul_f32 v[72:73], v[20:21], v[72:73] op_sel_hi:[0,1]
	v_pk_fma_f32 v[72:73], v[18:19], v[78:79], v[72:73]
	v_xor_b32_e32 v75, 0x80000000, v64
	v_mov_b32_e32 v74, v65
	v_pk_mul_f32 v[74:75], v[74:75], v[72:73] op_sel:[0,1]
	v_xor_b32_e32 v79, 0x80000000, v66
	v_pk_fma_f32 v[64:65], v[64:65], v[72:73], v[74:75] op_sel_hi:[1,0,1]
	v_xor_b32_e32 v74, 0x80000000, v61
	v_mov_b32_e32 v75, v60
	v_mov_b32_e32 v78, v67
	v_pk_mul_f32 v[74:75], v[20:21], v[74:75] op_sel_hi:[0,1]
	v_pk_mul_f32 v[78:79], v[78:79], v[60:61] op_sel:[0,1]
	v_pk_fma_f32 v[74:75], v[18:19], v[60:61], v[74:75]
	v_pk_fma_f32 v[60:61], v[66:67], v[60:61], v[78:79] op_sel_hi:[1,0,1]
	v_xor_b32_e32 v66, 0x80000000, v73
	v_mov_b32_e32 v67, v72
	v_pk_mul_f32 v[66:67], v[20:21], v[66:67] op_sel_hi:[0,1]
	v_pk_fma_f32 v[66:67], v[18:19], v[72:73], v[66:67]
	v_xor_b32_e32 v73, 0x80000000, v62
	v_mov_b32_e32 v72, v63
	v_pk_mul_f32 v[72:73], v[72:73], v[66:67] op_sel:[0,1]
	v_xor_b32_e32 v79, 0x80000000, v76
	v_pk_fma_f32 v[62:63], v[62:63], v[66:67], v[72:73] op_sel_hi:[1,0,1]
	v_xor_b32_e32 v72, 0x80000000, v75
	v_mov_b32_e32 v73, v74
	v_mov_b32_e32 v78, v77
	v_pk_mul_f32 v[72:73], v[20:21], v[72:73] op_sel_hi:[0,1]
	v_pk_mul_f32 v[78:79], v[78:79], v[74:75] op_sel:[0,1]
	v_pk_fma_f32 v[72:73], v[18:19], v[74:75], v[72:73]
	v_pk_fma_f32 v[74:75], v[76:77], v[74:75], v[78:79] op_sel_hi:[1,0,1]
	v_xor_b32_e32 v76, 0x80000000, v67
	v_mov_b32_e32 v77, v66
	v_pk_mul_f32 v[76:77], v[20:21], v[76:77] op_sel_hi:[0,1]
	v_xor_b32_e32 v78, 0x80000000, v73
	v_mov_b32_e32 v79, v72
	v_pk_fma_f32 v[66:67], v[18:19], v[66:67], v[76:77]
	v_pk_mul_f32 v[78:79], v[20:21], v[78:79] op_sel_hi:[0,1]
	v_pk_mul_f32 v[80:81], v[80:81], v[72:73] op_sel:[0,1]
	v_xor_b32_e32 v77, 0x80000000, v88
	v_mov_b32_e32 v76, v89
	v_pk_fma_f32 v[78:79], v[18:19], v[72:73], v[78:79]
	v_pk_fma_f32 v[58:59], v[58:59], v[72:73], v[80:81] op_sel_hi:[1,0,1]
	v_xor_b32_e32 v72, 0x80000000, v67
	v_mov_b32_e32 v73, v66
	v_pk_mul_f32 v[76:77], v[76:77], v[66:67] op_sel:[0,1]
	v_pk_mul_f32 v[72:73], v[20:21], v[72:73] op_sel_hi:[0,1]
	v_pk_fma_f32 v[76:77], v[88:89], v[66:67], v[76:77] op_sel_hi:[1,0,1]
	v_pk_fma_f32 v[66:67], v[18:19], v[66:67], v[72:73]
	v_xor_b32_e32 v73, 0x80000000, v54
	v_mov_b32_e32 v72, v55
	v_pk_mul_f32 v[72:73], v[72:73], v[66:67] op_sel:[0,1]
	v_xor_b32_e32 v81, 0x80000000, v56
	v_pk_fma_f32 v[54:55], v[54:55], v[66:67], v[72:73] op_sel_hi:[1,0,1]
	v_xor_b32_e32 v72, 0x80000000, v79
	v_mov_b32_e32 v73, v78
	v_mov_b32_e32 v80, v57
	v_pk_mul_f32 v[72:73], v[20:21], v[72:73] op_sel_hi:[0,1]
	v_pk_mul_f32 v[80:81], v[80:81], v[78:79] op_sel:[0,1]
	v_pk_fma_f32 v[72:73], v[18:19], v[78:79], v[72:73]
	v_pk_fma_f32 v[56:57], v[56:57], v[78:79], v[80:81] op_sel_hi:[1,0,1]
	v_xor_b32_e32 v78, 0x80000000, v67
	v_mov_b32_e32 v79, v66
	v_pk_mul_f32 v[78:79], v[20:21], v[78:79] op_sel_hi:[0,1]
	v_pk_fma_f32 v[66:67], v[18:19], v[66:67], v[78:79]
	v_xor_b32_e32 v79, 0x80000000, v40
	v_mov_b32_e32 v78, v41
	v_pk_mul_f32 v[78:79], v[78:79], v[66:67] op_sel:[0,1]
	v_xor_b32_e32 v81, 0x80000000, v46
	v_pk_fma_f32 v[40:41], v[40:41], v[66:67], v[78:79] op_sel_hi:[1,0,1]
	v_xor_b32_e32 v78, 0x80000000, v73
	v_mov_b32_e32 v79, v72
	v_mov_b32_e32 v80, v47
	v_pk_mul_f32 v[78:79], v[20:21], v[78:79] op_sel_hi:[0,1]
	v_pk_mul_f32 v[80:81], v[80:81], v[72:73] op_sel:[0,1]
	v_pk_fma_f32 v[78:79], v[18:19], v[72:73], v[78:79]
	v_pk_fma_f32 v[46:47], v[46:47], v[72:73], v[80:81] op_sel_hi:[1,0,1]
	v_xor_b32_e32 v72, 0x80000000, v67
	v_mov_b32_e32 v73, v66
	v_pk_mul_f32 v[72:73], v[20:21], v[72:73] op_sel_hi:[0,1]
	v_pk_fma_f32 v[66:67], v[18:19], v[66:67], v[72:73]
	v_xor_b32_e32 v73, 0x80000000, v38
	v_mov_b32_e32 v72, v39
	v_pk_add_f32 v[44:45], v[82:83], v[84:85] neg_lo:[0,1] neg_hi:[0,1]
	v_pk_mul_f32 v[72:73], v[72:73], v[66:67] op_sel:[0,1]
	v_xor_b32_e32 v81, 0x80000000, v44
	v_pk_fma_f32 v[38:39], v[38:39], v[66:67], v[72:73] op_sel_hi:[1,0,1]
	v_xor_b32_e32 v72, 0x80000000, v79
	v_mov_b32_e32 v73, v78
	v_mov_b32_e32 v80, v45
	v_pk_mul_f32 v[72:73], v[20:21], v[72:73] op_sel_hi:[0,1]
	v_pk_mul_f32 v[80:81], v[80:81], v[78:79] op_sel:[0,1]
	v_pk_fma_f32 v[72:73], v[18:19], v[78:79], v[72:73]
	v_pk_fma_f32 v[44:45], v[44:45], v[78:79], v[80:81] op_sel_hi:[1,0,1]
	v_xor_b32_e32 v78, 0x80000000, v67
	v_mov_b32_e32 v79, v66
	v_pk_mul_f32 v[78:79], v[20:21], v[78:79] op_sel_hi:[0,1]
	v_pk_fma_f32 v[66:67], v[18:19], v[66:67], v[78:79]
	v_xor_b32_e32 v79, 0x80000000, v28
	v_mov_b32_e32 v78, v29
	v_pk_mul_f32 v[78:79], v[78:79], v[66:67] op_sel:[0,1]
	v_xor_b32_e32 v81, 0x80000000, v30
	v_pk_fma_f32 v[28:29], v[28:29], v[66:67], v[78:79] op_sel_hi:[1,0,1]
	v_xor_b32_e32 v78, 0x80000000, v73
	v_mov_b32_e32 v79, v72
	v_mov_b32_e32 v80, v31
	v_pk_mul_f32 v[78:79], v[20:21], v[78:79] op_sel_hi:[0,1]
	v_pk_mul_f32 v[80:81], v[80:81], v[72:73] op_sel:[0,1]
	v_pk_fma_f32 v[78:79], v[18:19], v[72:73], v[78:79]
	v_pk_fma_f32 v[30:31], v[30:31], v[72:73], v[80:81] op_sel_hi:[1,0,1]
	v_xor_b32_e32 v72, 0x80000000, v67
	v_mov_b32_e32 v73, v66
	v_pk_mul_f32 v[72:73], v[20:21], v[72:73] op_sel_hi:[0,1]
	v_pk_fma_f32 v[66:67], v[18:19], v[66:67], v[72:73]
	v_xor_b32_e32 v73, 0x80000000, v22
	v_mov_b32_e32 v72, v23
	v_pk_mul_f32 v[72:73], v[72:73], v[66:67] op_sel:[0,1]
	v_xor_b32_e32 v81, 0x80000000, v24
	v_pk_fma_f32 v[22:23], v[22:23], v[66:67], v[72:73] op_sel_hi:[1,0,1]
	v_xor_b32_e32 v72, 0x80000000, v79
	v_mov_b32_e32 v73, v78
	v_mov_b32_e32 v80, v25
	v_pk_mul_f32 v[72:73], v[20:21], v[72:73] op_sel_hi:[0,1]
	v_pk_mul_f32 v[80:81], v[80:81], v[78:79] op_sel:[0,1]
	v_pk_fma_f32 v[72:73], v[18:19], v[78:79], v[72:73]
	v_pk_fma_f32 v[24:25], v[24:25], v[78:79], v[80:81] op_sel_hi:[1,0,1]
	v_xor_b32_e32 v78, 0x80000000, v67
	v_mov_b32_e32 v79, v66
	v_pk_mul_f32 v[78:79], v[20:21], v[78:79] op_sel_hi:[0,1]
	v_pk_fma_f32 v[66:67], v[18:19], v[66:67], v[78:79]
	v_xor_b32_e32 v79, 0x80000000, v6
	v_mov_b32_e32 v78, v7
	v_pk_mul_f32 v[78:79], v[78:79], v[66:67] op_sel:[0,1]
	v_xor_b32_e32 v81, 0x80000000, v10
	v_pk_fma_f32 v[6:7], v[6:7], v[66:67], v[78:79] op_sel_hi:[1,0,1]
	v_xor_b32_e32 v78, 0x80000000, v73
	v_mov_b32_e32 v79, v72
	v_mov_b32_e32 v80, v11
	v_pk_mul_f32 v[78:79], v[20:21], v[78:79] op_sel_hi:[0,1]
	v_pk_mul_f32 v[80:81], v[80:81], v[72:73] op_sel:[0,1]
	v_pk_fma_f32 v[78:79], v[18:19], v[72:73], v[78:79]
	v_pk_fma_f32 v[10:11], v[10:11], v[72:73], v[80:81] op_sel_hi:[1,0,1]
	v_xor_b32_e32 v72, 0x80000000, v67
	v_mov_b32_e32 v73, v66
	v_pk_mul_f32 v[72:73], v[20:21], v[72:73] op_sel_hi:[0,1]
	v_pk_fma_f32 v[18:19], v[18:19], v[66:67], v[72:73]
	v_xor_b32_e32 v67, 0x80000000, v4
	v_mov_b32_e32 v66, v5
	v_pk_add_f32 v[12:13], v[12:13], v[86:87] neg_lo:[0,1] neg_hi:[0,1]
	v_pk_mul_f32 v[66:67], v[66:67], v[18:19] op_sel:[0,1]
	s_nop 0
	v_pk_fma_f32 v[4:5], v[4:5], v[18:19], v[66:67] op_sel_hi:[1,0,1]
	v_xor_b32_e32 v19, 0x80000000, v12
	v_mov_b32_e32 v18, v13
	v_pk_mul_f32 v[18:19], v[18:19], v[78:79] op_sel:[0,1]
	s_nop 0
	v_pk_fma_f32 v[12:13], v[12:13], v[78:79], v[18:19] op_sel_hi:[1,0,1]
	v_lshrrev_b32_e32 v18, 5, v21
	v_bitop3_b32 v18, v18, v21, 15 bitop3:0x6c
	v_lshlrev_b32_e32 v18, 3, v18
	v_bfe_u32 v19, v21, 5, 4
	v_add_u32_e32 v20, 16, v18
	ds_write_b64 v20, v[2:3]
	v_bitop3_b32 v2, v19, v21, 16 bitop3:0x36
	v_lshl_add_u32 v2, v2, 3, 16
	v_add_u32_e32 v3, s79, v18
	ds_write_b64 v2, v[76:77] offset:4096
	ds_write_b64 v20, v[48:49] offset:8192
	ds_write_b64 v2, v[28:29] offset:12288
	ds_write_b64 v20, v[34:35] offset:16384
	ds_write_b64 v2, v[40:41] offset:20480
	ds_write_b64 v20, v[64:65] offset:24576
	ds_write_b64 v2, v[6:7] offset:28672
	ds_write_b64 v20, v[16:17] offset:32768
	ds_write_b64 v2, v[54:55] offset:36864
	ds_write_b64 v20, v[52:53] offset:40960
	ds_write_b64 v2, v[22:23] offset:45056
	ds_write_b64 v20, v[36:37] offset:49152
	ds_write_b64 v2, v[38:39] offset:53248
	ds_write_b64 v20, v[62:63] offset:57344
	ds_write_b64 v2, v[4:5] offset:61440
	ds_write_b64 v3, v[8:9]
	v_add_u32_e32 v3, 0x11000, v2
	ds_write_b64 v3, v[58:59]
	v_add_u32_e32 v3, 0x12000, v20
	ds_write_b64 v3, v[42:43]
	v_add_u32_e32 v3, 0x13000, v2
	ds_write_b64 v3, v[30:31]
	v_add_u32_e32 v3, 0x14000, v20
	ds_write_b64 v3, v[26:27]
	v_add_u32_e32 v3, 0x15000, v2
	ds_write_b64 v3, v[46:47]
	v_add_u32_e32 v3, 0x16000, v20
	ds_write_b64 v3, v[60:61]
	v_add_u32_e32 v3, 0x17000, v2
	ds_write_b64 v3, v[10:11]
	v_add_u32_e32 v3, 0x18000, v20
	ds_write_b64 v3, v[14:15]
	v_add_u32_e32 v3, 0x19000, v2
	ds_write_b64 v3, v[56:57]
	v_add_u32_e32 v3, 0x1a000, v20
	ds_write_b64 v3, v[50:51]
	v_add_u32_e32 v3, 0x1b000, v2
	ds_write_b64 v3, v[24:25]
	v_add_u32_e32 v3, 0x1c000, v20
	ds_write_b64 v3, v[32:33]
	v_add_u32_e32 v3, 0x1d000, v2
	ds_write_b64 v3, v[44:45]
	v_add_u32_e32 v3, 0x1e000, v20
	v_add_u32_e32 v2, 0x1f000, v2
	v_mov_b32_e32 v11, v146
	ds_write_b64 v3, v[74:75]
	ds_write_b64 v2, v[12:13]
	s_waitcnt lgkmcnt(0)
	s_barrier
	s_nop 0
	v_lshlrev_b32_e32 v2, 5, v11
	v_and_b32_e32 v2, 0xfffffe00, v2
	v_and_or_b32 v3, v11, 16, v2
	v_bitop3_b32 v2, v2, 16, v11 bitop3:0x34
	v_bitop3_b32 v12, v11, 2, 15 bitop3:0x6c
	v_bitop3_b32 v22, v11, 4, 15 bitop3:0x6c
	v_bitop3_b32 v30, v11, 6, 15 bitop3:0x6c
	v_bitop3_b32 v38, v11, 8, 15 bitop3:0x6c
	v_and_b32_e32 v10, 15, v11
	v_lshl_add_u32 v18, v3, 3, 16
	v_lshl_add_u32 v87, v2, 3, 16
	v_lshlrev_b32_e32 v12, 3, v12
	v_lshlrev_b32_e32 v22, 3, v22
	v_lshlrev_b32_e32 v30, 3, v30
	v_lshlrev_b32_e32 v38, 3, v38
	v_lshlrev_b32_e32 v3, 3, v10
	v_bitop3_b32 v2, v11, 1, 15 bitop3:0x6c
	v_add_u32_e32 v57, v18, v12
	v_add_u32_e32 v58, v87, v12
	v_bitop3_b32 v12, v11, 3, 15 bitop3:0x6c
	v_add_u32_e32 v61, v18, v22
	v_add_u32_e32 v62, v87, v22
	v_bitop3_b32 v22, v11, 5, 15 bitop3:0x6c
	v_add_u32_e32 v65, v18, v30
	v_add_u32_e32 v66, v87, v30
	v_bitop3_b32 v30, v11, 7, 15 bitop3:0x6c
	v_add_u32_e32 v72, v18, v38
	v_add_u32_e32 v73, v87, v38
	v_bitop3_b32 v38, v11, 9, 15 bitop3:0x6c
	v_add_u32_e32 v19, v18, v3
	v_lshlrev_b32_e32 v2, 3, v2
	v_lshlrev_b32_e32 v12, 3, v12
	v_lshlrev_b32_e32 v22, 3, v22
	v_lshlrev_b32_e32 v30, 3, v30
	v_lshlrev_b32_e32 v38, 3, v38
	v_add_u32_e32 v54, v87, v3
	v_add_u32_e32 v55, v18, v2
	v_add_u32_e32 v56, v87, v2
	ds_read_b64 v[2:3], v19
	ds_read_b64 v[4:5], v54
	ds_read_b64 v[6:7], v55 offset:256
	ds_read_b64 v[8:9], v56 offset:256
	v_add_u32_e32 v59, v18, v12
	v_add_u32_e32 v60, v87, v12
	ds_read_b64 v[12:13], v57 offset:512
	ds_read_b64 v[14:15], v58 offset:512
	ds_read_b64 v[16:17], v59 offset:768
	ds_read_b64 v[20:21], v60 offset:768
	v_add_u32_e32 v63, v18, v22
	v_add_u32_e32 v64, v87, v22
	ds_read_b64 v[22:23], v61 offset:1024
	ds_read_b64 v[24:25], v62 offset:1024
	ds_read_b64 v[26:27], v63 offset:1280
	ds_read_b64 v[28:29], v64 offset:1280
	v_add_u32_e32 v67, v18, v30
	v_add_u32_e32 v71, v87, v30
	ds_read_b64 v[30:31], v65 offset:1536
	ds_read_b64 v[32:33], v66 offset:1536
	ds_read_b64 v[34:35], v67 offset:1792
	ds_read_b64 v[36:37], v71 offset:1792
	v_add_u32_e32 v74, v18, v38
	v_add_u32_e32 v75, v87, v38
	ds_read_b64 v[38:39], v72 offset:2048
	ds_read_b64 v[40:41], v73 offset:2048
	ds_read_b64 v[42:43], v74 offset:2304
	ds_read_b64 v[44:45], v75 offset:2304
	v_bitop3_b32 v46, v11, 10, 15 bitop3:0x6c
	s_waitcnt lgkmcnt(3)
	v_pk_add_f32 v[104:105], v[2:3], v[38:39]
	v_pk_add_f32 v[2:3], v[2:3], v[38:39] neg_lo:[0,1] neg_hi:[0,1]
	s_waitcnt lgkmcnt(2)
	v_pk_add_f32 v[38:39], v[4:5], v[40:41]
	v_pk_add_f32 v[4:5], v[4:5], v[40:41] neg_lo:[0,1] neg_hi:[0,1]
	v_lshlrev_b32_e32 v46, 3, v46
	v_xor_b32_e32 v41, 0x80000000, v4
	v_mov_b32_e32 v40, v5
	v_pk_mul_f32 v[40:41], v[40:41], s[48:49] op_sel_hi:[1,0]
	v_add_u32_e32 v76, v18, v46
	v_pk_fma_f32 v[4:5], v[4:5], s[44:45], v[40:41] op_sel_hi:[1,0,1]
	s_waitcnt lgkmcnt(1)
	v_pk_add_f32 v[40:41], v[6:7], v[42:43]
	v_pk_add_f32 v[6:7], v[6:7], v[42:43] neg_lo:[0,1] neg_hi:[0,1]
	v_add_u32_e32 v77, v87, v46
	v_xor_b32_e32 v43, 0x80000000, v6
	v_mov_b32_e32 v42, v7
	v_bitop3_b32 v46, v11, 11, 15 bitop3:0x6c
	v_pk_mul_f32 v[42:43], v[42:43], s[54:55] op_sel_hi:[1,0]
	v_lshlrev_b32_e32 v46, 3, v46
	v_pk_fma_f32 v[6:7], v[6:7], s[52:53], v[42:43] op_sel_hi:[1,0,1]
	s_waitcnt lgkmcnt(0)
	v_pk_add_f32 v[42:43], v[8:9], v[44:45]
	v_pk_add_f32 v[8:9], v[8:9], v[44:45] neg_lo:[0,1] neg_hi:[0,1]
	v_add_u32_e32 v78, v18, v46
	v_add_u32_e32 v79, v87, v46
	ds_read_b64 v[46:47], v76 offset:2560
	ds_read_b64 v[48:49], v77 offset:2560
	ds_read_b64 v[50:51], v78 offset:2816
	ds_read_b64 v[52:53], v79 offset:2816
	v_xor_b32_e32 v45, 0x80000000, v8
	v_mov_b32_e32 v44, v9
	v_pk_mul_f32 v[44:45], v[44:45], s[58:59] op_sel_hi:[1,0]
	v_bitop3_b32 v80, v11, 12, 15 bitop3:0x6c
	v_pk_fma_f32 v[8:9], v[8:9], s[56:57], v[44:45] op_sel_hi:[1,0,1]
	s_waitcnt lgkmcnt(3)
	v_pk_add_f32 v[44:45], v[12:13], v[46:47]
	v_pk_add_f32 v[12:13], v[12:13], v[46:47] neg_lo:[0,1] neg_hi:[0,1]
	v_lshlrev_b32_e32 v81, 3, v80
	v_xor_b32_e32 v47, 0x80000000, v12
	v_mov_b32_e32 v46, v13
	v_pk_mul_f32 v[46:47], v[46:47], s[60:61] op_sel_hi:[1,0]
	v_bitop3_b32 v82, v11, 13, 15 bitop3:0x6c
	v_pk_fma_f32 v[12:13], v[12:13], s[60:61], v[46:47] op_sel_hi:[1,0,1]
	s_waitcnt lgkmcnt(2)
	v_pk_add_f32 v[46:47], v[14:15], v[48:49]
	v_pk_add_f32 v[14:15], v[14:15], v[48:49] neg_lo:[0,1] neg_hi:[0,1]
	v_add_u32_e32 v80, v18, v81
	v_xor_b32_e32 v49, 0x80000000, v14
	v_mov_b32_e32 v48, v15
	v_pk_mul_f32 v[48:49], v[48:49], s[56:57] op_sel_hi:[1,0]
	v_lshlrev_b32_e32 v83, 3, v82
	v_pk_fma_f32 v[14:15], v[14:15], s[58:59], v[48:49] op_sel_hi:[1,0,1]
	s_waitcnt lgkmcnt(1)
	v_pk_add_f32 v[48:49], v[16:17], v[50:51]
	v_pk_add_f32 v[16:17], v[16:17], v[50:51] neg_lo:[0,1] neg_hi:[0,1]
	v_add_u32_e32 v81, v87, v81
	v_xor_b32_e32 v51, 0x80000000, v16
	v_mov_b32_e32 v50, v17
	v_pk_mul_f32 v[50:51], v[50:51], s[52:53] op_sel_hi:[1,0]
	v_add_u32_e32 v82, v18, v83
	v_pk_fma_f32 v[16:17], v[16:17], s[54:55], v[50:51] op_sel_hi:[1,0,1]
	s_waitcnt lgkmcnt(0)
	v_pk_add_f32 v[50:51], v[20:21], v[52:53]
	v_pk_add_f32 v[20:21], v[20:21], v[52:53] neg_lo:[0,1] neg_hi:[0,1]
	v_add_u32_e32 v83, v87, v83
	ds_read_b64 v[88:89], v80 offset:3072
	ds_read_b64 v[90:91], v81 offset:3072
	ds_read_b64 v[92:93], v82 offset:3328
	ds_read_b64 v[94:95], v83 offset:3328
	v_xor_b32_e32 v53, 0x80000000, v20
	v_mov_b32_e32 v52, v21
	v_pk_mul_f32 v[52:53], v[52:53], s[44:45] op_sel_hi:[1,0]
	v_bitop3_b32 v84, v11, 14, 15 bitop3:0x6c
	v_pk_fma_f32 v[20:21], v[20:21], s[48:49], v[52:53] op_sel_hi:[1,0,1]
	s_waitcnt lgkmcnt(3)
	v_pk_add_f32 v[52:53], v[22:23], v[88:89]
	v_pk_add_f32 v[22:23], v[22:23], v[88:89] neg_lo:[0,1] neg_hi:[0,1]
	v_lshlrev_b32_e32 v85, 3, v84
	v_xor_b32_e32 v89, 0x80000000, v22
	v_mov_b32_e32 v88, v23
	s_waitcnt lgkmcnt(2)
	v_pk_add_f32 v[22:23], v[24:25], v[90:91]
	v_pk_add_f32 v[24:25], v[24:25], v[90:91] neg_lo:[0,1] neg_hi:[0,1]
	v_bitop3_b32 v11, v11, 15, v11 bitop3:0xc
	v_pk_mul_f32 v[90:91], v[24:25], s[48:49] op_sel_hi:[1,0]
	v_xor_b32_e32 v107, 0x80000000, v24
	v_mov_b32_e32 v106, v25
	v_pk_fma_f32 v[24:25], v[106:107], s[44:45], v[90:91] op_sel_hi:[1,0,1] neg_lo:[0,0,1] neg_hi:[0,0,1]
	s_waitcnt lgkmcnt(1)
	v_pk_add_f32 v[90:91], v[26:27], v[92:93]
	v_pk_add_f32 v[26:27], v[26:27], v[92:93] neg_lo:[0,1] neg_hi:[0,1]
	v_add_u32_e32 v84, v18, v85
	v_lshlrev_b32_e32 v11, 3, v11
	v_pk_mul_f32 v[92:93], v[26:27], s[54:55] op_sel_hi:[1,0]
	v_xor_b32_e32 v107, 0x80000000, v26
	v_mov_b32_e32 v106, v27
	v_add_u32_e32 v85, v87, v85
	v_add_u32_e32 v86, v18, v11
	v_add_u32_e32 v87, v87, v11
	ds_read_b64 v[96:97], v84 offset:3584
	ds_read_b64 v[98:99], v85 offset:3584
	ds_read_b64 v[100:101], v86 offset:3840
	ds_read_b64 v[102:103], v87 offset:3840
	v_pk_fma_f32 v[26:27], v[106:107], s[52:53], v[92:93] op_sel_hi:[1,0,1] neg_lo:[0,0,1] neg_hi:[0,0,1]
	s_waitcnt lgkmcnt(4)
	v_pk_add_f32 v[92:93], v[28:29], v[94:95]
	v_pk_add_f32 v[28:29], v[28:29], v[94:95] neg_lo:[0,1] neg_hi:[0,1]
	s_nop 0
	v_pk_mul_f32 v[94:95], v[28:29], s[58:59] op_sel_hi:[1,0]
	v_xor_b32_e32 v107, 0x80000000, v28
	v_mov_b32_e32 v106, v29
	v_pk_fma_f32 v[28:29], v[106:107], s[56:57], v[94:95] op_sel_hi:[1,0,1] neg_lo:[0,0,1] neg_hi:[0,0,1]
	s_waitcnt lgkmcnt(3)
	v_pk_add_f32 v[94:95], v[30:31], v[96:97]
	v_pk_add_f32 v[30:31], v[30:31], v[96:97] neg_lo:[0,1] neg_hi:[0,1]
	v_cvt_f32_i32_e32 v10, v10
	v_pk_mul_f32 v[96:97], v[30:31], s[60:61] op_sel_hi:[1,0]
	v_xor_b32_e32 v107, 0x80000000, v30
	v_mov_b32_e32 v106, v31
	v_pk_fma_f32 v[30:31], v[106:107], s[60:61], v[96:97] op_sel_hi:[1,0,1] neg_lo:[0,0,1] neg_hi:[0,0,1]
	s_waitcnt lgkmcnt(2)
	v_pk_add_f32 v[96:97], v[32:33], v[98:99]
	v_pk_add_f32 v[32:33], v[32:33], v[98:99] neg_lo:[0,1] neg_hi:[0,1]
	v_mul_f32_e32 v10, 0x3b000000, v10
	v_pk_mul_f32 v[98:99], v[32:33], s[56:57] op_sel_hi:[1,0]
	v_xor_b32_e32 v107, 0x80000000, v32
	v_mov_b32_e32 v106, v33
	v_pk_fma_f32 v[32:33], v[106:107], s[58:59], v[98:99] op_sel_hi:[1,0,1] neg_lo:[0,0,1] neg_hi:[0,0,1]
	s_waitcnt lgkmcnt(1)
	v_pk_add_f32 v[98:99], v[34:35], v[100:101]
	v_pk_add_f32 v[34:35], v[34:35], v[100:101] neg_lo:[0,1] neg_hi:[0,1]
	s_nop 0
	v_pk_mul_f32 v[100:101], v[34:35], s[52:53] op_sel_hi:[1,0]
	v_xor_b32_e32 v107, 0x80000000, v34
	v_mov_b32_e32 v106, v35
	v_pk_fma_f32 v[34:35], v[106:107], s[54:55], v[100:101] op_sel_hi:[1,0,1] neg_lo:[0,0,1] neg_hi:[0,0,1]
	s_waitcnt lgkmcnt(0)
	v_pk_add_f32 v[100:101], v[36:37], v[102:103]
	v_pk_add_f32 v[36:37], v[36:37], v[102:103] neg_lo:[0,1] neg_hi:[0,1]
	s_nop 0
	v_pk_mul_f32 v[102:103], v[36:37], s[44:45] op_sel_hi:[1,0]
	v_xor_b32_e32 v107, 0x80000000, v36
	v_mov_b32_e32 v106, v37
	v_pk_fma_f32 v[36:37], v[106:107], s[48:49], v[102:103] op_sel_hi:[1,0,1] neg_lo:[0,0,1] neg_hi:[0,0,1]
	v_pk_add_f32 v[102:103], v[104:105], v[52:53]
	v_pk_add_f32 v[52:53], v[104:105], v[52:53] neg_lo:[0,1] neg_hi:[0,1]
	v_pk_add_f32 v[104:105], v[38:39], v[22:23]
	v_pk_add_f32 v[22:23], v[38:39], v[22:23] neg_lo:[0,1] neg_hi:[0,1]
	s_nop 0
	v_xor_b32_e32 v39, 0x80000000, v22
	v_mov_b32_e32 v38, v23
	v_pk_mul_f32 v[38:39], v[38:39], s[54:55] op_sel_hi:[1,0]
	s_nop 0
	v_pk_fma_f32 v[22:23], v[22:23], s[52:53], v[38:39] op_sel_hi:[1,0,1]
	v_pk_add_f32 v[38:39], v[40:41], v[90:91]
	v_pk_add_f32 v[40:41], v[40:41], v[90:91] neg_lo:[0,1] neg_hi:[0,1]
	s_nop 0
	v_xor_b32_e32 v91, 0x80000000, v40
	v_mov_b32_e32 v90, v41
	v_pk_mul_f32 v[90:91], v[90:91], s[60:61] op_sel_hi:[1,0]
	s_nop 0
	v_pk_fma_f32 v[40:41], v[40:41], s[60:61], v[90:91] op_sel_hi:[1,0,1]
	v_pk_add_f32 v[90:91], v[42:43], v[92:93]
	v_pk_add_f32 v[42:43], v[42:43], v[92:93] neg_lo:[0,1] neg_hi:[0,1]
	s_nop 0
	v_xor_b32_e32 v93, 0x80000000, v42
	v_mov_b32_e32 v92, v43
	v_pk_mul_f32 v[92:93], v[92:93], s[52:53] op_sel_hi:[1,0]
	s_nop 0
	v_pk_fma_f32 v[42:43], v[42:43], s[54:55], v[92:93] op_sel_hi:[1,0,1]
	v_pk_add_f32 v[92:93], v[44:45], v[94:95]
	v_pk_add_f32 v[44:45], v[44:45], v[94:95] neg_lo:[0,1] neg_hi:[0,1]
	s_nop 0
	v_xor_b32_e32 v95, 0x80000000, v44
	v_mov_b32_e32 v94, v45
	v_pk_add_f32 v[44:45], v[46:47], v[96:97]
	v_pk_add_f32 v[46:47], v[46:47], v[96:97] neg_lo:[0,1] neg_hi:[0,1]
	s_nop 0
	v_pk_mul_f32 v[96:97], v[46:47], s[54:55] op_sel_hi:[1,0]
	v_xor_b32_e32 v107, 0x80000000, v46
	v_mov_b32_e32 v106, v47
	v_pk_fma_f32 v[46:47], v[106:107], s[52:53], v[96:97] op_sel_hi:[1,0,1] neg_lo:[0,0,1] neg_hi:[0,0,1]
	v_pk_add_f32 v[96:97], v[48:49], v[98:99]
	v_pk_add_f32 v[48:49], v[48:49], v[98:99] neg_lo:[0,1] neg_hi:[0,1]
	s_nop 0
	v_pk_mul_f32 v[98:99], v[48:49], s[60:61] op_sel_hi:[1,0]
	v_xor_b32_e32 v107, 0x80000000, v48
	v_mov_b32_e32 v106, v49
	v_pk_fma_f32 v[48:49], v[106:107], s[60:61], v[98:99] op_sel_hi:[1,0,1] neg_lo:[0,0,1] neg_hi:[0,0,1]
	v_pk_add_f32 v[98:99], v[50:51], v[100:101]
	v_pk_add_f32 v[50:51], v[50:51], v[100:101] neg_lo:[0,1] neg_hi:[0,1]
	s_nop 0
	v_pk_mul_f32 v[100:101], v[50:51], s[52:53] op_sel_hi:[1,0]
	v_xor_b32_e32 v107, 0x80000000, v50
	v_mov_b32_e32 v106, v51
	v_pk_fma_f32 v[50:51], v[106:107], s[54:55], v[100:101] op_sel_hi:[1,0,1] neg_lo:[0,0,1] neg_hi:[0,0,1]
	v_pk_add_f32 v[100:101], v[2:3], v[88:89]
	v_pk_add_f32 v[2:3], v[2:3], v[88:89] neg_lo:[0,1] neg_hi:[0,1]
	v_pk_add_f32 v[88:89], v[4:5], v[24:25]
	v_pk_add_f32 v[4:5], v[4:5], v[24:25] neg_lo:[0,1] neg_hi:[0,1]
	s_nop 0
	v_xor_b32_e32 v25, 0x80000000, v4
	v_mov_b32_e32 v24, v5
	v_pk_mul_f32 v[24:25], v[24:25], s[54:55] op_sel_hi:[1,0]
	s_nop 0
	v_pk_fma_f32 v[4:5], v[4:5], s[52:53], v[24:25] op_sel_hi:[1,0,1]
	v_pk_add_f32 v[24:25], v[6:7], v[26:27]
	v_pk_add_f32 v[6:7], v[6:7], v[26:27] neg_lo:[0,1] neg_hi:[0,1]
	s_nop 0
	v_xor_b32_e32 v27, 0x80000000, v6
	v_mov_b32_e32 v26, v7
	v_pk_mul_f32 v[26:27], v[26:27], s[60:61] op_sel_hi:[1,0]
	s_nop 0
	v_pk_fma_f32 v[6:7], v[6:7], s[60:61], v[26:27] op_sel_hi:[1,0,1]
	v_pk_add_f32 v[26:27], v[8:9], v[28:29]
	v_pk_add_f32 v[8:9], v[8:9], v[28:29] neg_lo:[0,1] neg_hi:[0,1]
	s_nop 0
	v_xor_b32_e32 v29, 0x80000000, v8
	v_mov_b32_e32 v28, v9
	v_pk_mul_f32 v[28:29], v[28:29], s[52:53] op_sel_hi:[1,0]
	s_nop 0
	v_pk_fma_f32 v[8:9], v[8:9], s[54:55], v[28:29] op_sel_hi:[1,0,1]
	v_pk_add_f32 v[28:29], v[12:13], v[30:31]
	v_pk_add_f32 v[12:13], v[12:13], v[30:31] neg_lo:[0,1] neg_hi:[0,1]
	s_nop 0
	v_xor_b32_e32 v31, 0x80000000, v12
	v_mov_b32_e32 v30, v13
	v_pk_add_f32 v[12:13], v[14:15], v[32:33]
	v_pk_add_f32 v[14:15], v[14:15], v[32:33] neg_lo:[0,1] neg_hi:[0,1]
	s_nop 0
	v_pk_mul_f32 v[32:33], v[14:15], s[54:55] op_sel_hi:[1,0]
	v_xor_b32_e32 v107, 0x80000000, v14
	v_mov_b32_e32 v106, v15
	v_pk_fma_f32 v[14:15], v[106:107], s[52:53], v[32:33] op_sel_hi:[1,0,1] neg_lo:[0,0,1] neg_hi:[0,0,1]
	v_pk_add_f32 v[32:33], v[16:17], v[34:35]
	v_pk_add_f32 v[16:17], v[16:17], v[34:35] neg_lo:[0,1] neg_hi:[0,1]
	s_nop 0
	v_pk_mul_f32 v[34:35], v[16:17], s[60:61] op_sel_hi:[1,0]
	v_xor_b32_e32 v107, 0x80000000, v16
	v_mov_b32_e32 v106, v17
	v_pk_fma_f32 v[16:17], v[106:107], s[60:61], v[34:35] op_sel_hi:[1,0,1] neg_lo:[0,0,1] neg_hi:[0,0,1]
	v_pk_add_f32 v[34:35], v[20:21], v[36:37]
	v_pk_add_f32 v[20:21], v[20:21], v[36:37] neg_lo:[0,1] neg_hi:[0,1]
	s_nop 0
	v_pk_mul_f32 v[36:37], v[20:21], s[52:53] op_sel_hi:[1,0]
	v_xor_b32_e32 v107, 0x80000000, v20
	v_mov_b32_e32 v106, v21
	v_pk_fma_f32 v[20:21], v[106:107], s[54:55], v[36:37] op_sel_hi:[1,0,1] neg_lo:[0,0,1] neg_hi:[0,0,1]
	v_pk_add_f32 v[36:37], v[102:103], v[92:93]
	v_pk_add_f32 v[92:93], v[102:103], v[92:93] neg_lo:[0,1] neg_hi:[0,1]
	v_pk_add_f32 v[102:103], v[104:105], v[44:45]
	v_pk_add_f32 v[44:45], v[104:105], v[44:45] neg_lo:[0,1] neg_hi:[0,1]
	s_nop 0
	v_xor_b32_e32 v105, 0x80000000, v44
	v_mov_b32_e32 v104, v45
	v_pk_mul_f32 v[104:105], v[104:105], s[60:61] op_sel_hi:[1,0]
	s_nop 0
	v_pk_fma_f32 v[44:45], v[44:45], s[60:61], v[104:105] op_sel_hi:[1,0,1]
	v_pk_add_f32 v[104:105], v[38:39], v[96:97]
	v_pk_add_f32 v[38:39], v[38:39], v[96:97] neg_lo:[0,1] neg_hi:[0,1]
	s_nop 0
	v_xor_b32_e32 v97, 0x80000000, v38
	v_mov_b32_e32 v96, v39
	v_pk_add_f32 v[38:39], v[90:91], v[98:99]
	v_pk_add_f32 v[90:91], v[90:91], v[98:99] neg_lo:[0,1] neg_hi:[0,1]
	s_nop 0
	v_pk_mul_f32 v[98:99], v[90:91], s[60:61] op_sel_hi:[1,0]
	v_xor_b32_e32 v107, 0x80000000, v90
	v_mov_b32_e32 v106, v91
	v_pk_fma_f32 v[90:91], v[106:107], s[60:61], v[98:99] op_sel_hi:[1,0,1] neg_lo:[0,0,1] neg_hi:[0,0,1]
	v_pk_add_f32 v[98:99], v[52:53], v[94:95]
	v_pk_add_f32 v[52:53], v[52:53], v[94:95] neg_lo:[0,1] neg_hi:[0,1]
	v_pk_add_f32 v[94:95], v[22:23], v[46:47]
	v_pk_add_f32 v[22:23], v[22:23], v[46:47] neg_lo:[0,1] neg_hi:[0,1]
	s_nop 0
	v_xor_b32_e32 v47, 0x80000000, v22
	v_mov_b32_e32 v46, v23
	v_pk_mul_f32 v[46:47], v[46:47], s[60:61] op_sel_hi:[1,0]
	s_nop 0
	v_pk_fma_f32 v[22:23], v[22:23], s[60:61], v[46:47] op_sel_hi:[1,0,1]
	v_pk_add_f32 v[46:47], v[40:41], v[48:49]
	v_pk_add_f32 v[40:41], v[40:41], v[48:49] neg_lo:[0,1] neg_hi:[0,1]
	s_nop 0
	v_xor_b32_e32 v49, 0x80000000, v40
	v_mov_b32_e32 v48, v41
	v_pk_add_f32 v[40:41], v[42:43], v[50:51]
	v_pk_add_f32 v[42:43], v[42:43], v[50:51] neg_lo:[0,1] neg_hi:[0,1]
	s_nop 0
	v_pk_mul_f32 v[50:51], v[42:43], s[60:61] op_sel_hi:[1,0]
	v_xor_b32_e32 v107, 0x80000000, v42
	v_mov_b32_e32 v106, v43
	v_pk_fma_f32 v[42:43], v[106:107], s[60:61], v[50:51] op_sel_hi:[1,0,1] neg_lo:[0,0,1] neg_hi:[0,0,1]
	v_pk_add_f32 v[50:51], v[100:101], v[28:29]
	v_pk_add_f32 v[28:29], v[100:101], v[28:29] neg_lo:[0,1] neg_hi:[0,1]
	v_pk_add_f32 v[100:101], v[88:89], v[12:13]
	v_pk_add_f32 v[12:13], v[88:89], v[12:13] neg_lo:[0,1] neg_hi:[0,1]
	s_nop 0
	v_xor_b32_e32 v89, 0x80000000, v12
	v_mov_b32_e32 v88, v13
	v_pk_mul_f32 v[88:89], v[88:89], s[60:61] op_sel_hi:[1,0]
	s_nop 0
	v_pk_fma_f32 v[12:13], v[12:13], s[60:61], v[88:89] op_sel_hi:[1,0,1]
	v_pk_add_f32 v[88:89], v[24:25], v[32:33]
	v_pk_add_f32 v[24:25], v[24:25], v[32:33] neg_lo:[0,1] neg_hi:[0,1]
	v_pk_add_f32 v[108:109], v[50:51], v[88:89]
	v_xor_b32_e32 v33, 0x80000000, v24
	v_mov_b32_e32 v32, v25
	v_pk_add_f32 v[24:25], v[26:27], v[34:35]
	v_pk_add_f32 v[26:27], v[26:27], v[34:35] neg_lo:[0,1] neg_hi:[0,1]
	v_pk_add_f32 v[50:51], v[50:51], v[88:89] neg_lo:[0,1] neg_hi:[0,1]
	v_pk_mul_f32 v[34:35], v[26:27], s[60:61] op_sel_hi:[1,0]
	v_xor_b32_e32 v107, 0x80000000, v26
	v_mov_b32_e32 v106, v27
	v_pk_fma_f32 v[26:27], v[106:107], s[60:61], v[34:35] op_sel_hi:[1,0,1] neg_lo:[0,0,1] neg_hi:[0,0,1]
	v_pk_add_f32 v[34:35], v[2:3], v[30:31]
	v_pk_add_f32 v[2:3], v[2:3], v[30:31] neg_lo:[0,1] neg_hi:[0,1]
	v_pk_add_f32 v[30:31], v[4:5], v[14:15]
	v_pk_add_f32 v[4:5], v[4:5], v[14:15] neg_lo:[0,1] neg_hi:[0,1]
	v_pk_add_f32 v[110:111], v[12:13], v[26:27]
	v_xor_b32_e32 v15, 0x80000000, v4
	v_mov_b32_e32 v14, v5
	v_pk_mul_f32 v[14:15], v[14:15], s[60:61] op_sel_hi:[1,0]
	v_pk_add_f32 v[12:13], v[12:13], v[26:27] neg_lo:[0,1] neg_hi:[0,1]
	v_pk_fma_f32 v[4:5], v[4:5], s[60:61], v[14:15] op_sel_hi:[1,0,1]
	v_pk_add_f32 v[14:15], v[6:7], v[16:17]
	v_pk_add_f32 v[6:7], v[6:7], v[16:17] neg_lo:[0,1] neg_hi:[0,1]
	v_pk_add_f32 v[88:89], v[100:101], v[24:25]
	v_xor_b32_e32 v17, 0x80000000, v6
	v_mov_b32_e32 v16, v7
	v_pk_add_f32 v[6:7], v[8:9], v[20:21]
	v_pk_add_f32 v[8:9], v[8:9], v[20:21] neg_lo:[0,1] neg_hi:[0,1]
	v_xor_b32_e32 v113, 0x80000000, v12
	v_pk_mul_f32 v[20:21], v[8:9], s[60:61] op_sel_hi:[1,0]
	v_xor_b32_e32 v107, 0x80000000, v8
	v_mov_b32_e32 v106, v9
	v_pk_fma_f32 v[8:9], v[106:107], s[60:61], v[20:21] op_sel_hi:[1,0,1] neg_lo:[0,0,1] neg_hi:[0,0,1]
	v_pk_add_f32 v[20:21], v[36:37], v[104:105]
	v_pk_add_f32 v[36:37], v[36:37], v[104:105] neg_lo:[0,1] neg_hi:[0,1]
	v_pk_add_f32 v[104:105], v[102:103], v[38:39]
	v_pk_add_f32 v[38:39], v[102:103], v[38:39] neg_lo:[0,1] neg_hi:[0,1]
	v_pk_add_f32 v[106:107], v[52:53], v[48:49]
	v_xor_b32_e32 v103, 0x80000000, v38
	v_mov_b32_e32 v102, v39
	v_pk_add_f32 v[38:39], v[92:93], v[96:97]
	v_pk_add_f32 v[92:93], v[92:93], v[96:97] neg_lo:[0,1] neg_hi:[0,1]
	v_pk_add_f32 v[96:97], v[44:45], v[90:91]
	v_pk_add_f32 v[44:45], v[44:45], v[90:91] neg_lo:[0,1] neg_hi:[0,1]
	v_pk_add_f32 v[48:49], v[52:53], v[48:49] neg_lo:[0,1] neg_hi:[0,1]
	v_pk_add_f32 v[52:53], v[22:23], v[42:43]
	v_pk_add_f32 v[22:23], v[22:23], v[42:43] neg_lo:[0,1] neg_hi:[0,1]
	v_xor_b32_e32 v91, 0x80000000, v44
	v_mov_b32_e32 v90, v45
	v_pk_add_f32 v[44:45], v[98:99], v[46:47]
	v_pk_add_f32 v[46:47], v[98:99], v[46:47] neg_lo:[0,1] neg_hi:[0,1]
	v_pk_add_f32 v[98:99], v[94:95], v[40:41]
	v_pk_add_f32 v[40:41], v[94:95], v[40:41] neg_lo:[0,1] neg_hi:[0,1]
	v_xor_b32_e32 v43, 0x80000000, v22
	v_mov_b32_e32 v42, v23
	v_pk_add_f32 v[22:23], v[100:101], v[24:25] neg_lo:[0,1] neg_hi:[0,1]
	v_xor_b32_e32 v95, 0x80000000, v40
	v_mov_b32_e32 v94, v41
	v_xor_b32_e32 v25, 0x80000000, v22
	v_mov_b32_e32 v24, v23
	v_pk_add_f32 v[100:101], v[28:29], v[32:33]
	v_pk_add_f32 v[32:33], v[28:29], v[32:33] neg_lo:[0,1] neg_hi:[0,1]
	v_mov_b32_e32 v112, v13
	v_pk_add_f32 v[12:13], v[34:35], v[14:15]
	v_pk_add_f32 v[14:15], v[34:35], v[14:15] neg_lo:[0,1] neg_hi:[0,1]
	v_pk_add_f32 v[34:35], v[30:31], v[6:7]
	v_pk_add_f32 v[6:7], v[30:31], v[6:7] neg_lo:[0,1] neg_hi:[0,1]
	v_pk_add_f32 v[114:115], v[2:3], v[16:17]
	v_pk_add_f32 v[16:17], v[2:3], v[16:17] neg_lo:[0,1] neg_hi:[0,1]
	v_pk_add_f32 v[2:3], v[4:5], v[8:9] neg_lo:[0,1] neg_hi:[0,1]
	v_xor_b32_e32 v31, 0x80000000, v6
	v_mov_b32_e32 v30, v7
	v_pk_add_f32 v[116:117], v[4:5], v[8:9]
	v_xor_b32_e32 v119, 0x80000000, v2
	v_mov_b32_e32 v118, v3
	v_pk_add_f32 v[2:3], v[20:21], v[104:105]
	v_pk_add_f32 v[104:105], v[20:21], v[104:105] neg_lo:[0,1] neg_hi:[0,1]
	v_pk_add_f32 v[120:121], v[36:37], v[102:103]
	v_pk_add_f32 v[26:27], v[36:37], v[102:103] neg_lo:[0,1] neg_hi:[0,1]
	v_pk_add_f32 v[36:37], v[38:39], v[96:97]
	v_pk_add_f32 v[40:41], v[38:39], v[96:97] neg_lo:[0,1] neg_hi:[0,1]
	v_pk_add_f32 v[96:97], v[92:93], v[90:91]
	v_pk_add_f32 v[6:7], v[92:93], v[90:91] neg_lo:[0,1] neg_hi:[0,1]
	v_pk_add_f32 v[20:21], v[44:45], v[98:99]
	v_pk_add_f32 v[90:91], v[44:45], v[98:99] neg_lo:[0,1] neg_hi:[0,1]
	v_pk_add_f32 v[92:93], v[46:47], v[94:95]
	v_pk_add_f32 v[22:23], v[46:47], v[94:95] neg_lo:[0,1] neg_hi:[0,1]
	v_pk_add_f32 v[46:47], v[106:107], v[52:53]
	v_pk_add_f32 v[38:39], v[106:107], v[52:53] neg_lo:[0,1] neg_hi:[0,1]
	v_pk_add_f32 v[52:53], v[50:51], v[24:25]
	v_pk_add_f32 v[28:29], v[50:51], v[24:25] neg_lo:[0,1] neg_hi:[0,1]
	v_pk_add_f32 v[50:51], v[100:101], v[110:111]
	v_pk_add_f32 v[44:45], v[100:101], v[110:111] neg_lo:[0,1] neg_hi:[0,1]
	v_pk_add_f32 v[98:99], v[32:33], v[112:113]
	v_pk_add_f32 v[8:9], v[32:33], v[112:113] neg_lo:[0,1] neg_hi:[0,1]
	v_pk_add_f32 v[32:33], v[12:13], v[34:35]
	v_pk_add_f32 v[100:101], v[12:13], v[34:35] neg_lo:[0,1] neg_hi:[0,1]
	v_cos_f32_e32 v12, v10
	v_sin_f32_e32 v13, v10
	v_pk_add_f32 v[94:95], v[48:49], v[42:43]
	v_pk_add_f32 v[4:5], v[48:49], v[42:43] neg_lo:[0,1] neg_hi:[0,1]
	v_pk_add_f32 v[48:49], v[108:109], v[88:89]
	v_pk_add_f32 v[102:103], v[14:15], v[30:31]
	v_pk_add_f32 v[24:25], v[14:15], v[30:31] neg_lo:[0,1] neg_hi:[0,1]
	v_pk_add_f32 v[106:107], v[16:17], v[118:119]
	v_pk_add_f32 v[10:11], v[16:17], v[118:119] neg_lo:[0,1] neg_hi:[0,1]
	v_pk_mul_f32 v[14:15], v[12:13], v[12:13]
	v_add_f32_e32 v16, v12, v12
	v_pk_add_f32 v[88:89], v[108:109], v[88:89] neg_lo:[0,1] neg_hi:[0,1]
	v_mul_f32_e32 v18, v13, v16
	v_pk_add_f32 v[16:17], v[14:15], v[14:15] op_sel:[0,1] op_sel_hi:[0,1] neg_lo:[0,1] neg_hi:[0,1]
	v_xor_b32_e32 v14, 0x80000000, v13
	v_mov_b32_e32 v15, v12
	v_xor_b32_e32 v31, 0x80000000, v48
	v_mov_b32_e32 v30, v49
	v_mov_b32_e32 v108, v13
	v_pk_mul_f32 v[14:15], v[14:15], v[18:19] op_sel_hi:[1,0]
	v_pk_mul_f32 v[30:31], v[108:109], v[30:31] op_sel_hi:[0,1]
	v_pk_fma_f32 v[14:15], v[12:13], v[16:17], v[14:15]
	v_pk_fma_f32 v[12:13], v[12:13], v[48:49], v[30:31] op_sel_hi:[0,1,1]
	v_pk_mul_f32 v[30:31], v[18:19], s[46:47] op_sel_hi:[0,1]
	v_pk_fma_f32 v[30:31], v[16:17], s[40:41], v[30:31]
	v_xor_b32_e32 v49, 0x80000000, v20
	v_mov_b32_e32 v48, v21
	v_pk_mul_f32 v[48:49], v[30:31], v[48:49] op_sel:[1,0]
	v_xor_b32_e32 v109, 0x80000000, v32
	v_pk_fma_f32 v[20:21], v[20:21], v[30:31], v[48:49] op_sel_hi:[1,0,1]
	v_xor_b32_e32 v48, 0x80000000, v15
	v_mov_b32_e32 v49, v14
	v_mov_b32_e32 v108, v33
	v_pk_mul_f32 v[48:49], v[18:19], v[48:49] op_sel_hi:[0,1]
	v_pk_mul_f32 v[108:109], v[14:15], v[108:109] op_sel:[1,0]
	v_pk_fma_f32 v[48:49], v[16:17], v[14:15], v[48:49]
	v_pk_fma_f32 v[14:15], v[14:15], v[32:33], v[108:109] op_sel_hi:[0,1,1]
	v_xor_b32_e32 v32, 0x80000000, v31
	v_mov_b32_e32 v33, v30
	v_pk_mul_f32 v[32:33], v[18:19], v[32:33] op_sel_hi:[0,1]
	v_pk_fma_f32 v[108:109], v[16:17], v[30:31], v[32:33]
	v_xor_b32_e32 v31, 0x80000000, v36
	v_mov_b32_e32 v30, v37
	v_pk_mul_f32 v[30:31], v[30:31], v[108:109] op_sel:[0,1]
	v_pk_add_f32 v[34:35], v[114:115], v[116:117]
	v_pk_fma_f32 v[32:33], v[36:37], v[108:109], v[30:31] op_sel_hi:[1,0,1]
	v_xor_b32_e32 v30, 0x80000000, v49
	v_mov_b32_e32 v31, v48
	v_pk_mul_f32 v[30:31], v[18:19], v[30:31] op_sel_hi:[0,1]
	v_pk_fma_f32 v[110:111], v[16:17], v[48:49], v[30:31]
	v_xor_b32_e32 v31, 0x80000000, v50
	v_mov_b32_e32 v30, v51
	v_xor_b32_e32 v36, 0x80000000, v109
	v_mov_b32_e32 v37, v108
	v_pk_mul_f32 v[30:31], v[48:49], v[30:31] op_sel:[1,0]
	v_pk_mul_f32 v[36:37], v[18:19], v[36:37] op_sel_hi:[0,1]
	v_pk_fma_f32 v[30:31], v[50:51], v[48:49], v[30:31] op_sel_hi:[1,0,1]
	v_pk_fma_f32 v[48:49], v[16:17], v[108:109], v[36:37]
	v_xor_b32_e32 v37, 0x80000000, v46
	v_mov_b32_e32 v36, v47
	v_pk_mul_f32 v[36:37], v[36:37], v[48:49] op_sel:[0,1]
	v_xor_b32_e32 v51, 0x80000000, v34
	v_pk_fma_f32 v[36:37], v[46:47], v[48:49], v[36:37] op_sel_hi:[1,0,1]
	v_xor_b32_e32 v46, 0x80000000, v111
	v_mov_b32_e32 v47, v110
	v_mov_b32_e32 v50, v35
	v_pk_mul_f32 v[46:47], v[18:19], v[46:47] op_sel_hi:[0,1]
	v_pk_mul_f32 v[50:51], v[110:111], v[50:51] op_sel:[1,0]
	v_pk_fma_f32 v[46:47], v[16:17], v[110:111], v[46:47]
	v_pk_fma_f32 v[34:35], v[34:35], v[110:111], v[50:51] op_sel_hi:[1,0,1]
	v_xor_b32_e32 v50, 0x80000000, v49
	v_mov_b32_e32 v51, v48
	v_pk_mul_f32 v[50:51], v[18:19], v[50:51] op_sel_hi:[0,1]
	v_xor_b32_e32 v108, 0x80000000, v47
	v_mov_b32_e32 v109, v46
	v_xor_b32_e32 v111, 0x80000000, v52
	v_mov_b32_e32 v110, v53
	v_pk_fma_f32 v[50:51], v[16:17], v[48:49], v[50:51]
	v_pk_mul_f32 v[108:109], v[18:19], v[108:109] op_sel_hi:[0,1]
	v_pk_mul_f32 v[110:111], v[110:111], v[46:47] op_sel:[0,1]
	v_xor_b32_e32 v49, 0x80000000, v120
	v_mov_b32_e32 v48, v121
	v_pk_fma_f32 v[108:109], v[16:17], v[46:47], v[108:109]
	v_pk_fma_f32 v[46:47], v[52:53], v[46:47], v[110:111] op_sel_hi:[1,0,1]
	v_xor_b32_e32 v52, 0x80000000, v51
	v_mov_b32_e32 v53, v50
	v_pk_mul_f32 v[48:49], v[48:49], v[50:51] op_sel:[0,1]
	v_pk_mul_f32 v[52:53], v[18:19], v[52:53] op_sel_hi:[0,1]
	v_pk_fma_f32 v[48:49], v[120:121], v[50:51], v[48:49] op_sel_hi:[1,0,1]
	v_pk_fma_f32 v[110:111], v[16:17], v[50:51], v[52:53]
	v_xor_b32_e32 v51, 0x80000000, v92
	v_mov_b32_e32 v50, v93
	v_pk_mul_f32 v[50:51], v[50:51], v[110:111] op_sel:[0,1]
	v_pk_add_f32 v[42:43], v[114:115], v[116:117] neg_lo:[0,1] neg_hi:[0,1]
	v_pk_fma_f32 v[52:53], v[92:93], v[110:111], v[50:51] op_sel_hi:[1,0,1]
	v_xor_b32_e32 v50, 0x80000000, v109
	v_mov_b32_e32 v51, v108
	v_pk_mul_f32 v[50:51], v[18:19], v[50:51] op_sel_hi:[0,1]
	v_pk_fma_f32 v[92:93], v[16:17], v[108:109], v[50:51]
	v_xor_b32_e32 v51, 0x80000000, v102
	v_mov_b32_e32 v50, v103
	v_pk_mul_f32 v[50:51], v[50:51], v[108:109] op_sel:[0,1]
	s_nop 0
	v_pk_fma_f32 v[50:51], v[102:103], v[108:109], v[50:51] op_sel_hi:[1,0,1]
	v_xor_b32_e32 v102, 0x80000000, v111
	v_mov_b32_e32 v103, v110
	v_pk_mul_f32 v[102:103], v[18:19], v[102:103] op_sel_hi:[0,1]
	v_pk_fma_f32 v[102:103], v[16:17], v[110:111], v[102:103]
	v_xor_b32_e32 v109, 0x80000000, v96
	v_mov_b32_e32 v108, v97
	v_pk_mul_f32 v[108:109], v[108:109], v[102:103] op_sel:[0,1]
	v_xor_b32_e32 v111, 0x80000000, v98
	v_pk_fma_f32 v[96:97], v[96:97], v[102:103], v[108:109] op_sel_hi:[1,0,1]
	v_xor_b32_e32 v108, 0x80000000, v93
	v_mov_b32_e32 v109, v92
	v_mov_b32_e32 v110, v99
	v_pk_mul_f32 v[108:109], v[18:19], v[108:109] op_sel_hi:[0,1]
	v_pk_mul_f32 v[110:111], v[110:111], v[92:93] op_sel:[0,1]
	v_pk_fma_f32 v[108:109], v[16:17], v[92:93], v[108:109]
	v_pk_fma_f32 v[92:93], v[98:99], v[92:93], v[110:111] op_sel_hi:[1,0,1]
	v_xor_b32_e32 v98, 0x80000000, v103
	v_mov_b32_e32 v99, v102
	v_pk_mul_f32 v[98:99], v[18:19], v[98:99] op_sel_hi:[0,1]
	v_pk_fma_f32 v[98:99], v[16:17], v[102:103], v[98:99]
	v_xor_b32_e32 v103, 0x80000000, v94
	v_mov_b32_e32 v102, v95
	v_pk_mul_f32 v[102:103], v[102:103], v[98:99] op_sel:[0,1]
	v_xor_b32_e32 v111, 0x80000000, v106
	v_pk_fma_f32 v[94:95], v[94:95], v[98:99], v[102:103] op_sel_hi:[1,0,1]
	v_xor_b32_e32 v102, 0x80000000, v109
	v_mov_b32_e32 v103, v108
	v_mov_b32_e32 v110, v107
	v_pk_mul_f32 v[102:103], v[18:19], v[102:103] op_sel_hi:[0,1]
	v_pk_mul_f32 v[110:111], v[110:111], v[108:109] op_sel:[0,1]
	v_pk_fma_f32 v[102:103], v[16:17], v[108:109], v[102:103]
	v_pk_fma_f32 v[106:107], v[106:107], v[108:109], v[110:111] op_sel_hi:[1,0,1]
	v_xor_b32_e32 v108, 0x80000000, v99
	v_mov_b32_e32 v109, v98
	v_pk_mul_f32 v[108:109], v[18:19], v[108:109] op_sel_hi:[0,1]
	v_pk_fma_f32 v[98:99], v[16:17], v[98:99], v[108:109]
	v_xor_b32_e32 v109, 0x80000000, v104
	v_mov_b32_e32 v108, v105
	v_pk_mul_f32 v[108:109], v[108:109], v[98:99] op_sel:[0,1]
	v_xor_b32_e32 v111, 0x80000000, v88
	v_pk_fma_f32 v[104:105], v[104:105], v[98:99], v[108:109] op_sel_hi:[1,0,1]
	v_xor_b32_e32 v108, 0x80000000, v103
	v_mov_b32_e32 v109, v102
	v_mov_b32_e32 v110, v89
	v_pk_mul_f32 v[108:109], v[18:19], v[108:109] op_sel_hi:[0,1]
	v_pk_mul_f32 v[110:111], v[110:111], v[102:103] op_sel:[0,1]
	v_pk_fma_f32 v[108:109], v[16:17], v[102:103], v[108:109]
	v_pk_fma_f32 v[88:89], v[88:89], v[102:103], v[110:111] op_sel_hi:[1,0,1]
	v_xor_b32_e32 v102, 0x80000000, v99
	v_mov_b32_e32 v103, v98
	v_pk_mul_f32 v[102:103], v[18:19], v[102:103] op_sel_hi:[0,1]
	v_pk_fma_f32 v[98:99], v[16:17], v[98:99], v[102:103]
	v_xor_b32_e32 v103, 0x80000000, v90
	v_mov_b32_e32 v102, v91
	v_pk_mul_f32 v[102:103], v[102:103], v[98:99] op_sel:[0,1]
	v_xor_b32_e32 v111, 0x80000000, v100
	v_pk_fma_f32 v[90:91], v[90:91], v[98:99], v[102:103] op_sel_hi:[1,0,1]
	v_xor_b32_e32 v102, 0x80000000, v109
	v_mov_b32_e32 v103, v108
	v_mov_b32_e32 v110, v101
	v_pk_mul_f32 v[102:103], v[18:19], v[102:103] op_sel_hi:[0,1]
	v_pk_mul_f32 v[110:111], v[110:111], v[108:109] op_sel:[0,1]
	v_pk_fma_f32 v[102:103], v[16:17], v[108:109], v[102:103]
	v_pk_fma_f32 v[100:101], v[100:101], v[108:109], v[110:111] op_sel_hi:[1,0,1]
	v_xor_b32_e32 v108, 0x80000000, v99
	v_mov_b32_e32 v109, v98
	v_pk_mul_f32 v[108:109], v[18:19], v[108:109] op_sel_hi:[0,1]
	v_pk_fma_f32 v[98:99], v[16:17], v[98:99], v[108:109]
	v_xor_b32_e32 v109, 0x80000000, v40
	v_mov_b32_e32 v108, v41
	v_pk_mul_f32 v[108:109], v[108:109], v[98:99] op_sel:[0,1]
	v_xor_b32_e32 v111, 0x80000000, v44
	v_pk_fma_f32 v[40:41], v[40:41], v[98:99], v[108:109] op_sel_hi:[1,0,1]
	v_xor_b32_e32 v108, 0x80000000, v103
	v_mov_b32_e32 v109, v102
	v_mov_b32_e32 v110, v45
	v_pk_mul_f32 v[108:109], v[18:19], v[108:109] op_sel_hi:[0,1]
	v_pk_mul_f32 v[110:111], v[110:111], v[102:103] op_sel:[0,1]
	v_pk_fma_f32 v[108:109], v[16:17], v[102:103], v[108:109]
	v_pk_fma_f32 v[44:45], v[44:45], v[102:103], v[110:111] op_sel_hi:[1,0,1]
	v_xor_b32_e32 v102, 0x80000000, v99
	v_mov_b32_e32 v103, v98
	v_pk_mul_f32 v[102:103], v[18:19], v[102:103] op_sel_hi:[0,1]
	v_pk_fma_f32 v[98:99], v[16:17], v[98:99], v[102:103]
	v_xor_b32_e32 v103, 0x80000000, v38
	v_mov_b32_e32 v102, v39
	v_pk_mul_f32 v[102:103], v[102:103], v[98:99] op_sel:[0,1]
	v_xor_b32_e32 v111, 0x80000000, v42
	v_pk_fma_f32 v[38:39], v[38:39], v[98:99], v[102:103] op_sel_hi:[1,0,1]
	v_xor_b32_e32 v102, 0x80000000, v109
	v_mov_b32_e32 v103, v108
	v_mov_b32_e32 v110, v43
	v_pk_mul_f32 v[102:103], v[18:19], v[102:103] op_sel_hi:[0,1]
	v_pk_mul_f32 v[110:111], v[110:111], v[108:109] op_sel:[0,1]
	v_pk_fma_f32 v[102:103], v[16:17], v[108:109], v[102:103]
	v_pk_fma_f32 v[42:43], v[42:43], v[108:109], v[110:111] op_sel_hi:[1,0,1]
	v_xor_b32_e32 v108, 0x80000000, v99
	v_mov_b32_e32 v109, v98
	v_pk_mul_f32 v[108:109], v[18:19], v[108:109] op_sel_hi:[0,1]
	v_pk_fma_f32 v[98:99], v[16:17], v[98:99], v[108:109]
	v_xor_b32_e32 v109, 0x80000000, v26
	v_mov_b32_e32 v108, v27
	v_pk_mul_f32 v[108:109], v[108:109], v[98:99] op_sel:[0,1]
	v_xor_b32_e32 v111, 0x80000000, v28
	v_pk_fma_f32 v[26:27], v[26:27], v[98:99], v[108:109] op_sel_hi:[1,0,1]
	v_xor_b32_e32 v108, 0x80000000, v103
	v_mov_b32_e32 v109, v102
	v_mov_b32_e32 v110, v29
	v_pk_mul_f32 v[108:109], v[18:19], v[108:109] op_sel_hi:[0,1]
	v_pk_mul_f32 v[110:111], v[110:111], v[102:103] op_sel:[0,1]
	v_pk_fma_f32 v[108:109], v[16:17], v[102:103], v[108:109]
	v_pk_fma_f32 v[28:29], v[28:29], v[102:103], v[110:111] op_sel_hi:[1,0,1]
	v_xor_b32_e32 v102, 0x80000000, v99
	v_mov_b32_e32 v103, v98
	v_pk_mul_f32 v[102:103], v[18:19], v[102:103] op_sel_hi:[0,1]
	v_pk_fma_f32 v[98:99], v[16:17], v[98:99], v[102:103]
	v_xor_b32_e32 v103, 0x80000000, v22
	v_mov_b32_e32 v102, v23
	v_pk_mul_f32 v[102:103], v[102:103], v[98:99] op_sel:[0,1]
	v_xor_b32_e32 v111, 0x80000000, v24
	v_pk_fma_f32 v[22:23], v[22:23], v[98:99], v[102:103] op_sel_hi:[1,0,1]
	v_xor_b32_e32 v102, 0x80000000, v109
	v_mov_b32_e32 v103, v108
	v_mov_b32_e32 v110, v25
	v_pk_mul_f32 v[102:103], v[18:19], v[102:103] op_sel_hi:[0,1]
	v_pk_mul_f32 v[110:111], v[110:111], v[108:109] op_sel:[0,1]
	v_pk_fma_f32 v[102:103], v[16:17], v[108:109], v[102:103]
	v_pk_fma_f32 v[24:25], v[24:25], v[108:109], v[110:111] op_sel_hi:[1,0,1]
	v_xor_b32_e32 v108, 0x80000000, v99
	v_mov_b32_e32 v109, v98
	v_pk_mul_f32 v[108:109], v[18:19], v[108:109] op_sel_hi:[0,1]
	v_pk_fma_f32 v[98:99], v[16:17], v[98:99], v[108:109]
	v_xor_b32_e32 v109, 0x80000000, v6
	v_mov_b32_e32 v108, v7
	v_pk_mul_f32 v[108:109], v[108:109], v[98:99] op_sel:[0,1]
	v_xor_b32_e32 v111, 0x80000000, v8
	v_pk_fma_f32 v[6:7], v[6:7], v[98:99], v[108:109] op_sel_hi:[1,0,1]
	v_xor_b32_e32 v108, 0x80000000, v103
	v_mov_b32_e32 v109, v102
	v_mov_b32_e32 v110, v9
	v_pk_mul_f32 v[108:109], v[18:19], v[108:109] op_sel_hi:[0,1]
	v_pk_mul_f32 v[110:111], v[110:111], v[102:103] op_sel:[0,1]
	v_pk_fma_f32 v[108:109], v[16:17], v[102:103], v[108:109]
	v_pk_fma_f32 v[8:9], v[8:9], v[102:103], v[110:111] op_sel_hi:[1,0,1]
	v_xor_b32_e32 v102, 0x80000000, v99
	v_mov_b32_e32 v103, v98
	v_pk_mul_f32 v[102:103], v[18:19], v[102:103] op_sel_hi:[0,1]
	v_pk_fma_f32 v[16:17], v[16:17], v[98:99], v[102:103]
	v_xor_b32_e32 v99, 0x80000000, v4
	v_mov_b32_e32 v98, v5
	v_pk_mul_f32 v[98:99], v[98:99], v[16:17] op_sel:[0,1]
	s_nop 0
	v_pk_fma_f32 v[4:5], v[4:5], v[16:17], v[98:99] op_sel_hi:[1,0,1]
	v_xor_b32_e32 v17, 0x80000000, v10
	v_mov_b32_e32 v16, v11
	v_pk_mul_f32 v[16:17], v[16:17], v[108:109] op_sel:[0,1]
	s_nop 0
	v_pk_fma_f32 v[10:11], v[10:11], v[108:109], v[16:17] op_sel_hi:[1,0,1]
	ds_write_b64 v19, v[2:3]
	ds_write_b64 v54, v[104:105]
	ds_write_b64 v55, v[48:49] offset:256
	ds_write_b64 v56, v[26:27] offset:256
	ds_write_b64 v57, v[32:33] offset:512
	ds_write_b64 v58, v[40:41] offset:512
	ds_write_b64 v59, v[96:97] offset:768
	ds_write_b64 v60, v[6:7] offset:768
	ds_write_b64 v61, v[20:21] offset:1024
	ds_write_b64 v62, v[90:91] offset:1024
	ds_write_b64 v63, v[52:53] offset:1280
	ds_write_b64 v64, v[22:23] offset:1280
	ds_write_b64 v65, v[36:37] offset:1536
	ds_write_b64 v66, v[38:39] offset:1536
	ds_write_b64 v67, v[94:95] offset:1792
	ds_write_b64 v71, v[4:5] offset:1792
	ds_write_b64 v72, v[12:13] offset:2048
	ds_write_b64 v73, v[88:89] offset:2048
	ds_write_b64 v74, v[46:47] offset:2304
	ds_write_b64 v75, v[28:29] offset:2304
	ds_write_b64 v76, v[30:31] offset:2560
	ds_write_b64 v77, v[44:45] offset:2560
	ds_write_b64 v78, v[92:93] offset:2816
	ds_write_b64 v79, v[8:9] offset:2816
	ds_write_b64 v80, v[14:15] offset:3072
	ds_write_b64 v81, v[100:101] offset:3072
	ds_write_b64 v82, v[50:51] offset:3328
	ds_write_b64 v83, v[24:25] offset:3328
	ds_write_b64 v84, v[34:35] offset:3584
	ds_write_b64 v85, v[42:43] offset:3584
	ds_write_b64 v86, v[106:107] offset:3840
	ds_write_b64 v87, v[10:11] offset:3840
	v_mov_b32_e32 v2, v146
	s_waitcnt lgkmcnt(0)
	s_barrier
	s_nop 0
	v_lshlrev_b32_e32 v34, 4, v2
	v_lshrrev_b32_e32 v35, 1, v2
	v_bitop3_b32 v3, v35, v34, 16 bitop3:0x6c
	v_lshl_add_u32 v26, v3, 3, 16
	v_bitop3_b32 v3, v35, 1, 15 bitop3:0x6c
	v_bitop3_b32 v11, v35, 5, 15 bitop3:0x6c
	v_bitop3_b32 v19, v35, 9, 15 bitop3:0x6c
	v_lshlrev_b32_e32 v37, 3, v3
	v_bitop3_b32 v3, v35, 2, 15 bitop3:0x6c
	v_lshlrev_b32_e32 v45, 3, v11
	v_bitop3_b32 v11, v35, 6, 15 bitop3:0x6c
	v_lshlrev_b32_e32 v49, 3, v19
	v_bitop3_b32 v19, v35, 10, 15 bitop3:0x6c
	v_bitop3_b32 v29, v35, 14, 15 bitop3:0x6c
	v_add_u32_e32 v34, 0x2000, v34
	v_bfe_u32 v2, v2, 1, 4
	v_lshlrev_b32_e32 v38, 3, v3
	v_bitop3_b32 v3, v35, 3, 15 bitop3:0x6c
	v_bitop3_b32 v10, v35, 4, 15 bitop3:0x6c
	v_lshlrev_b32_e32 v46, 3, v11
	v_bitop3_b32 v11, v35, 7, 15 bitop3:0x6c
	v_bitop3_b32 v18, v35, 8, 15 bitop3:0x6c
	v_lshlrev_b32_e32 v50, 3, v19
	v_bitop3_b32 v19, v35, 11, 15 bitop3:0x6c
	v_bitop3_b32 v27, v35, 12, 15 bitop3:0x6c
	v_bitop3_b32 v28, v35, 13, 15 bitop3:0x6c
	v_lshlrev_b32_e32 v54, 3, v29
	v_bitop3_b32 v29, v35, 15, v35 bitop3:0xc
	v_bitop3_b32 v34, v34, v35, 16 bitop3:0x78
	v_lshlrev_b32_e32 v36, 3, v2
	v_lshlrev_b32_e32 v39, 3, v3
	v_lshlrev_b32_e32 v44, 3, v10
	v_lshlrev_b32_e32 v47, 3, v11
	v_lshlrev_b32_e32 v48, 3, v18
	v_lshlrev_b32_e32 v51, 3, v19
	v_lshlrev_b32_e32 v52, 3, v27
	v_lshlrev_b32_e32 v53, 3, v28
	v_lshlrev_b32_e32 v55, 3, v29
	v_lshl_add_u32 v34, v34, 3, 16
	v_add_u32_e32 v2, v26, v36
	v_add_u32_e32 v4, v26, v37
	v_add_u32_e32 v6, v26, v38
	v_add_u32_e32 v8, v26, v39
	v_add_u32_e32 v10, v26, v44
	v_add_u32_e32 v12, v26, v45
	v_add_u32_e32 v14, v26, v46
	v_add_u32_e32 v16, v26, v47
	v_add_u32_e32 v18, v26, v48
	v_add_u32_e32 v20, v26, v49
	v_add_u32_e32 v22, v26, v50
	v_add_u32_e32 v24, v26, v51
	v_add_u32_e32 v27, v26, v52
	v_add_u32_e32 v28, v26, v53
	v_add_u32_e32 v30, v26, v54
	v_add_u32_e32 v32, v26, v55
	v_add_u32_e32 v35, v34, v36
	v_add_u32_e32 v40, v34, v37
	v_add_u32_e32 v41, v34, v38
	v_add_u32_e32 v42, v34, v39
	ds_read_b64 v[2:3], v2
	ds_read_b64 v[4:5], v4
	ds_read_b64 v[6:7], v6
	ds_read_b64 v[8:9], v8
	ds_read_b64 v[10:11], v10
	ds_read_b64 v[12:13], v12
	ds_read_b64 v[14:15], v14
	ds_read_b64 v[16:17], v16
	ds_read_b64 v[18:19], v18
	ds_read_b64 v[20:21], v20
	ds_read_b64 v[22:23], v22
	ds_read_b64 v[24:25], v24
	ds_read_b64 v[26:27], v27
	ds_read_b64 v[28:29], v28
	ds_read_b64 v[30:31], v30
	ds_read_b64 v[32:33], v32
	ds_read_b64 v[36:37], v35
	ds_read_b64 v[38:39], v40
	ds_read_b64 v[40:41], v41
	ds_read_b64 v[42:43], v42
	v_add_u32_e32 v35, v34, v44
	v_add_u32_e32 v44, v34, v45
	v_add_u32_e32 v45, v34, v46
	v_add_u32_e32 v46, v34, v47
	ds_read_b64 v[72:73], v35
	ds_read_b64 v[74:75], v44
	ds_read_b64 v[76:77], v45
	ds_read_b64 v[78:79], v46
	v_add_u32_e32 v35, v34, v48
	v_add_u32_e32 v44, v34, v49
	v_add_u32_e32 v45, v34, v50
	v_add_u32_e32 v46, v34, v51
	ds_read_b64 v[80:81], v35
	ds_read_b64 v[82:83], v44
	ds_read_b64 v[84:85], v45
	ds_read_b64 v[86:87], v46
	v_add_u32_e32 v35, v34, v52
	v_add_u32_e32 v44, v34, v53
	v_add_u32_e32 v45, v34, v54
	v_add_u32_e32 v34, v34, v55
	ds_read_b64 v[88:89], v35
	ds_read_b64 v[90:91], v44
	ds_read_b64 v[92:93], v45
	ds_read_b64 v[94:95], v34
	s_waitcnt lgkmcnt(14)
	v_pk_add_f32 v[34:35], v[2:3], v[18:19]
	v_pk_add_f32 v[2:3], v[2:3], v[18:19] neg_lo:[0,1] neg_hi:[0,1]
	v_pk_add_f32 v[18:19], v[4:5], v[20:21]
	v_pk_add_f32 v[4:5], v[4:5], v[20:21] neg_lo:[0,1] neg_hi:[0,1]
	s_nop 0
	v_xor_b32_e32 v21, 0x80000000, v4
	v_mov_b32_e32 v20, v5
	v_pk_mul_f32 v[20:21], v[20:21], s[54:55] op_sel_hi:[1,0]
	s_nop 0
	v_pk_fma_f32 v[4:5], v[4:5], s[52:53], v[20:21] op_sel_hi:[1,0,1]
	v_pk_add_f32 v[20:21], v[6:7], v[22:23]
	v_pk_add_f32 v[6:7], v[6:7], v[22:23] neg_lo:[0,1] neg_hi:[0,1]
	s_nop 0
	v_xor_b32_e32 v23, 0x80000000, v6
	v_mov_b32_e32 v22, v7
	v_pk_mul_f32 v[22:23], v[22:23], s[60:61] op_sel_hi:[1,0]
	s_nop 0
	v_pk_fma_f32 v[6:7], v[6:7], s[60:61], v[22:23] op_sel_hi:[1,0,1]
	v_pk_add_f32 v[22:23], v[8:9], v[24:25]
	v_pk_add_f32 v[8:9], v[8:9], v[24:25] neg_lo:[0,1] neg_hi:[0,1]
	s_nop 0
	v_xor_b32_e32 v25, 0x80000000, v8
	v_mov_b32_e32 v24, v9
	v_pk_mul_f32 v[24:25], v[24:25], s[52:53] op_sel_hi:[1,0]
	s_nop 0
	v_pk_fma_f32 v[8:9], v[8:9], s[54:55], v[24:25] op_sel_hi:[1,0,1]
	v_pk_add_f32 v[24:25], v[10:11], v[26:27]
	v_pk_add_f32 v[10:11], v[10:11], v[26:27] neg_lo:[0,1] neg_hi:[0,1]
	s_nop 0
	v_xor_b32_e32 v27, 0x80000000, v10
	v_mov_b32_e32 v26, v11
	v_pk_add_f32 v[10:11], v[12:13], v[28:29]
	v_pk_add_f32 v[12:13], v[12:13], v[28:29] neg_lo:[0,1] neg_hi:[0,1]
	s_nop 0
	v_pk_mul_f32 v[28:29], v[12:13], s[54:55] op_sel_hi:[1,0]
	v_xor_b32_e32 v45, 0x80000000, v12
	v_mov_b32_e32 v44, v13
	v_pk_fma_f32 v[12:13], v[44:45], s[52:53], v[28:29] op_sel_hi:[1,0,1] neg_lo:[0,0,1] neg_hi:[0,0,1]
	v_pk_add_f32 v[28:29], v[14:15], v[30:31]
	v_pk_add_f32 v[14:15], v[14:15], v[30:31] neg_lo:[0,1] neg_hi:[0,1]
	s_nop 0
	v_pk_mul_f32 v[30:31], v[14:15], s[60:61] op_sel_hi:[1,0]
	v_xor_b32_e32 v45, 0x80000000, v14
	v_mov_b32_e32 v44, v15
	v_pk_fma_f32 v[14:15], v[44:45], s[60:61], v[30:31] op_sel_hi:[1,0,1] neg_lo:[0,0,1] neg_hi:[0,0,1]
	v_pk_add_f32 v[30:31], v[16:17], v[32:33]
	v_pk_add_f32 v[16:17], v[16:17], v[32:33] neg_lo:[0,1] neg_hi:[0,1]
	s_nop 0
	v_pk_mul_f32 v[32:33], v[16:17], s[52:53] op_sel_hi:[1,0]
	v_xor_b32_e32 v45, 0x80000000, v16
	v_mov_b32_e32 v44, v17
	v_pk_fma_f32 v[16:17], v[44:45], s[54:55], v[32:33] op_sel_hi:[1,0,1] neg_lo:[0,0,1] neg_hi:[0,0,1]
	v_pk_add_f32 v[32:33], v[34:35], v[24:25]
	v_pk_add_f32 v[24:25], v[34:35], v[24:25] neg_lo:[0,1] neg_hi:[0,1]
	v_pk_add_f32 v[34:35], v[18:19], v[10:11]
	v_pk_add_f32 v[10:11], v[18:19], v[10:11] neg_lo:[0,1] neg_hi:[0,1]
	s_nop 0
	v_xor_b32_e32 v19, 0x80000000, v10
	v_mov_b32_e32 v18, v11
	v_pk_mul_f32 v[18:19], v[18:19], s[60:61] op_sel_hi:[1,0]
	s_nop 0
	v_pk_fma_f32 v[10:11], v[10:11], s[60:61], v[18:19] op_sel_hi:[1,0,1]
	v_pk_add_f32 v[18:19], v[20:21], v[28:29]
	v_pk_add_f32 v[20:21], v[20:21], v[28:29] neg_lo:[0,1] neg_hi:[0,1]
	s_nop 0
	v_xor_b32_e32 v29, 0x80000000, v20
	v_mov_b32_e32 v28, v21
	v_pk_add_f32 v[20:21], v[22:23], v[30:31]
	v_pk_add_f32 v[22:23], v[22:23], v[30:31] neg_lo:[0,1] neg_hi:[0,1]
	s_nop 0
	v_pk_mul_f32 v[30:31], v[22:23], s[60:61] op_sel_hi:[1,0]
	v_xor_b32_e32 v45, 0x80000000, v22
	v_mov_b32_e32 v44, v23
	v_pk_fma_f32 v[22:23], v[44:45], s[60:61], v[30:31] op_sel_hi:[1,0,1] neg_lo:[0,0,1] neg_hi:[0,0,1]
	v_pk_add_f32 v[30:31], v[2:3], v[26:27]
	v_pk_add_f32 v[2:3], v[2:3], v[26:27] neg_lo:[0,1] neg_hi:[0,1]
	v_pk_add_f32 v[26:27], v[4:5], v[12:13]
	v_pk_add_f32 v[4:5], v[4:5], v[12:13] neg_lo:[0,1] neg_hi:[0,1]
	s_nop 0
	v_xor_b32_e32 v13, 0x80000000, v4
	v_mov_b32_e32 v12, v5
	v_pk_mul_f32 v[12:13], v[12:13], s[60:61] op_sel_hi:[1,0]
	s_nop 0
	v_pk_fma_f32 v[4:5], v[4:5], s[60:61], v[12:13] op_sel_hi:[1,0,1]
	v_pk_add_f32 v[12:13], v[6:7], v[14:15]
	v_pk_add_f32 v[6:7], v[6:7], v[14:15] neg_lo:[0,1] neg_hi:[0,1]
	s_nop 0
	v_xor_b32_e32 v15, 0x80000000, v6
	v_mov_b32_e32 v14, v7
	v_pk_add_f32 v[6:7], v[8:9], v[16:17]
	v_pk_add_f32 v[8:9], v[8:9], v[16:17] neg_lo:[0,1] neg_hi:[0,1]
	s_nop 0
	v_pk_mul_f32 v[16:17], v[8:9], s[60:61] op_sel_hi:[1,0]
	v_xor_b32_e32 v45, 0x80000000, v8
	v_mov_b32_e32 v44, v9
	v_pk_fma_f32 v[8:9], v[44:45], s[60:61], v[16:17] op_sel_hi:[1,0,1] neg_lo:[0,0,1] neg_hi:[0,0,1]
	v_pk_add_f32 v[16:17], v[32:33], v[18:19]
	v_pk_add_f32 v[18:19], v[32:33], v[18:19] neg_lo:[0,1] neg_hi:[0,1]
	v_pk_add_f32 v[32:33], v[34:35], v[20:21]
	v_pk_add_f32 v[20:21], v[34:35], v[20:21] neg_lo:[0,1] neg_hi:[0,1]
	v_pk_add_f32 v[66:67], v[16:17], v[32:33]
	v_xor_b32_e32 v35, 0x80000000, v20
	v_mov_b32_e32 v34, v21
	v_pk_add_f32 v[20:21], v[24:25], v[28:29]
	v_pk_add_f32 v[24:25], v[24:25], v[28:29] neg_lo:[0,1] neg_hi:[0,1]
	v_pk_add_f32 v[28:29], v[10:11], v[22:23]
	v_pk_add_f32 v[10:11], v[10:11], v[22:23] neg_lo:[0,1] neg_hi:[0,1]
	v_pk_add_f32 v[58:59], v[20:21], v[28:29]
	v_xor_b32_e32 v23, 0x80000000, v10
	v_mov_b32_e32 v22, v11
	v_pk_add_f32 v[10:11], v[30:31], v[12:13]
	v_pk_add_f32 v[12:13], v[30:31], v[12:13] neg_lo:[0,1] neg_hi:[0,1]
	v_pk_add_f32 v[30:31], v[26:27], v[6:7]
	v_pk_add_f32 v[6:7], v[26:27], v[6:7] neg_lo:[0,1] neg_hi:[0,1]
	v_pk_add_f32 v[54:55], v[24:25], v[22:23]
	v_xor_b32_e32 v27, 0x80000000, v6
	v_mov_b32_e32 v26, v7
	v_pk_add_f32 v[6:7], v[2:3], v[14:15]
	v_pk_add_f32 v[2:3], v[2:3], v[14:15] neg_lo:[0,1] neg_hi:[0,1]
	v_pk_add_f32 v[14:15], v[4:5], v[8:9]
	v_pk_add_f32 v[4:5], v[4:5], v[8:9] neg_lo:[0,1] neg_hi:[0,1]
	v_pk_add_f32 v[52:53], v[24:25], v[22:23] neg_lo:[0,1] neg_hi:[0,1]
	v_xor_b32_e32 v9, 0x80000000, v4
	v_mov_b32_e32 v8, v5
	v_pk_add_f32 v[50:51], v[10:11], v[30:31]
	v_pk_add_f32 v[48:49], v[10:11], v[30:31] neg_lo:[0,1] neg_hi:[0,1]
	v_pk_add_f32 v[46:47], v[12:13], v[26:27]
	v_pk_add_f32 v[44:45], v[12:13], v[26:27] neg_lo:[0,1] neg_hi:[0,1]
	v_pk_add_f32 v[30:31], v[2:3], v[8:9]
	v_pk_add_f32 v[26:27], v[2:3], v[8:9] neg_lo:[0,1] neg_hi:[0,1]
	s_waitcnt lgkmcnt(6)
	v_pk_add_f32 v[8:9], v[38:39], v[82:83] neg_lo:[0,1] neg_hi:[0,1]
	s_waitcnt lgkmcnt(2)
	v_pk_add_f32 v[24:25], v[74:75], v[90:91] neg_lo:[0,1] neg_hi:[0,1]
	v_pk_add_f32 v[56:57], v[20:21], v[28:29] neg_lo:[0,1] neg_hi:[0,1]
	v_pk_add_f32 v[2:3], v[36:37], v[80:81]
	v_pk_add_f32 v[4:5], v[36:37], v[80:81] neg_lo:[0,1] neg_hi:[0,1]
	v_xor_b32_e32 v11, 0x80000000, v8
	v_mov_b32_e32 v10, v9
	v_pk_mul_f32 v[28:29], v[24:25], s[54:55] op_sel_hi:[1,0]
	v_xor_b32_e32 v37, 0x80000000, v24
	v_mov_b32_e32 v36, v25
	v_pk_add_f32 v[64:65], v[16:17], v[32:33] neg_lo:[0,1] neg_hi:[0,1]
	v_pk_mul_f32 v[10:11], v[10:11], s[54:55] op_sel_hi:[1,0]
	v_pk_add_f32 v[12:13], v[40:41], v[84:85] neg_lo:[0,1] neg_hi:[0,1]
	v_pk_add_f32 v[16:17], v[42:43], v[86:87] neg_lo:[0,1] neg_hi:[0,1]
	v_pk_fma_f32 v[24:25], v[36:37], s[52:53], v[28:29] op_sel_hi:[1,0,1] neg_lo:[0,0,1] neg_hi:[0,0,1]
	s_waitcnt lgkmcnt(1)
	v_pk_add_f32 v[36:37], v[76:77], v[92:93] neg_lo:[0,1] neg_hi:[0,1]
	v_pk_add_f32 v[62:63], v[18:19], v[34:35]
	v_pk_add_f32 v[60:61], v[18:19], v[34:35] neg_lo:[0,1] neg_hi:[0,1]
	v_pk_add_f32 v[34:35], v[6:7], v[14:15]
	v_pk_add_f32 v[32:33], v[6:7], v[14:15] neg_lo:[0,1] neg_hi:[0,1]
	v_pk_add_f32 v[6:7], v[38:39], v[82:83]
	v_pk_fma_f32 v[8:9], v[8:9], s[52:53], v[10:11] op_sel_hi:[1,0,1]
	v_pk_add_f32 v[10:11], v[40:41], v[84:85]
	v_xor_b32_e32 v15, 0x80000000, v12
	v_mov_b32_e32 v14, v13
	v_xor_b32_e32 v19, 0x80000000, v16
	v_mov_b32_e32 v18, v17
	v_pk_mul_f32 v[38:39], v[36:37], s[60:61] op_sel_hi:[1,0]
	v_xor_b32_e32 v41, 0x80000000, v36
	v_mov_b32_e32 v40, v37
	v_pk_mul_f32 v[14:15], v[14:15], s[60:61] op_sel_hi:[1,0]
	v_pk_mul_f32 v[18:19], v[18:19], s[52:53] op_sel_hi:[1,0]
	v_pk_add_f32 v[20:21], v[72:73], v[88:89] neg_lo:[0,1] neg_hi:[0,1]
	v_pk_fma_f32 v[36:37], v[40:41], s[60:61], v[38:39] op_sel_hi:[1,0,1] neg_lo:[0,0,1] neg_hi:[0,0,1]
	s_waitcnt lgkmcnt(0)
	v_pk_add_f32 v[40:41], v[78:79], v[94:95] neg_lo:[0,1] neg_hi:[0,1]
	v_pk_fma_f32 v[12:13], v[12:13], s[60:61], v[14:15] op_sel_hi:[1,0,1]
	v_pk_add_f32 v[14:15], v[42:43], v[86:87]
	v_pk_fma_f32 v[16:17], v[16:17], s[54:55], v[18:19] op_sel_hi:[1,0,1]
	v_pk_add_f32 v[18:19], v[72:73], v[88:89]
	v_xor_b32_e32 v23, 0x80000000, v20
	v_mov_b32_e32 v22, v21
	v_pk_add_f32 v[20:21], v[74:75], v[90:91]
	v_pk_mul_f32 v[42:43], v[40:41], s[52:53] op_sel_hi:[1,0]
	v_xor_b32_e32 v73, 0x80000000, v40
	v_mov_b32_e32 v72, v41
	v_pk_fma_f32 v[40:41], v[72:73], s[54:55], v[42:43] op_sel_hi:[1,0,1] neg_lo:[0,0,1] neg_hi:[0,0,1]
	v_pk_add_f32 v[42:43], v[2:3], v[18:19]
	v_pk_add_f32 v[2:3], v[2:3], v[18:19] neg_lo:[0,1] neg_hi:[0,1]
	v_pk_add_f32 v[18:19], v[6:7], v[20:21]
	v_pk_add_f32 v[6:7], v[6:7], v[20:21] neg_lo:[0,1] neg_hi:[0,1]
	v_pk_add_f32 v[28:29], v[76:77], v[92:93]
	v_xor_b32_e32 v21, 0x80000000, v6
	v_mov_b32_e32 v20, v7
	v_pk_mul_f32 v[20:21], v[20:21], s[60:61] op_sel_hi:[1,0]
	v_pk_add_f32 v[38:39], v[78:79], v[94:95]
	v_pk_fma_f32 v[6:7], v[6:7], s[60:61], v[20:21] op_sel_hi:[1,0,1]
	v_pk_add_f32 v[20:21], v[10:11], v[28:29]
	v_pk_add_f32 v[10:11], v[10:11], v[28:29] neg_lo:[0,1] neg_hi:[0,1]
	s_nop 0
	v_xor_b32_e32 v29, 0x80000000, v10
	v_mov_b32_e32 v28, v11
	v_pk_add_f32 v[10:11], v[14:15], v[38:39]
	v_pk_add_f32 v[14:15], v[14:15], v[38:39] neg_lo:[0,1] neg_hi:[0,1]
	s_nop 0
	v_pk_mul_f32 v[38:39], v[14:15], s[60:61] op_sel_hi:[1,0]
	v_xor_b32_e32 v73, 0x80000000, v14
	v_mov_b32_e32 v72, v15
	v_pk_fma_f32 v[14:15], v[72:73], s[60:61], v[38:39] op_sel_hi:[1,0,1] neg_lo:[0,0,1] neg_hi:[0,0,1]
	v_pk_add_f32 v[38:39], v[4:5], v[22:23]
	v_pk_add_f32 v[4:5], v[4:5], v[22:23] neg_lo:[0,1] neg_hi:[0,1]
	v_pk_add_f32 v[22:23], v[8:9], v[24:25]
	v_pk_add_f32 v[8:9], v[8:9], v[24:25] neg_lo:[0,1] neg_hi:[0,1]
	s_nop 0
	v_xor_b32_e32 v25, 0x80000000, v8
	v_mov_b32_e32 v24, v9
	v_pk_mul_f32 v[24:25], v[24:25], s[60:61] op_sel_hi:[1,0]
	s_nop 0
	v_pk_fma_f32 v[8:9], v[8:9], s[60:61], v[24:25] op_sel_hi:[1,0,1]
	v_pk_add_f32 v[24:25], v[12:13], v[36:37]
	v_pk_add_f32 v[12:13], v[12:13], v[36:37] neg_lo:[0,1] neg_hi:[0,1]
	v_pk_add_f32 v[74:75], v[38:39], v[24:25] neg_lo:[0,1] neg_hi:[0,1]
	v_xor_b32_e32 v37, 0x80000000, v12
	v_mov_b32_e32 v36, v13
	v_pk_add_f32 v[12:13], v[16:17], v[40:41]
	v_pk_add_f32 v[16:17], v[16:17], v[40:41] neg_lo:[0,1] neg_hi:[0,1]
	v_pk_add_f32 v[76:77], v[22:23], v[12:13]
	v_pk_mul_f32 v[40:41], v[16:17], s[60:61] op_sel_hi:[1,0]
	v_xor_b32_e32 v73, 0x80000000, v16
	v_mov_b32_e32 v72, v17
	v_pk_fma_f32 v[16:17], v[72:73], s[60:61], v[40:41] op_sel_hi:[1,0,1] neg_lo:[0,0,1] neg_hi:[0,0,1]
	v_pk_add_f32 v[72:73], v[18:19], v[10:11]
	v_pk_add_f32 v[10:11], v[18:19], v[10:11] neg_lo:[0,1] neg_hi:[0,1]
	v_pk_add_f32 v[12:13], v[22:23], v[12:13] neg_lo:[0,1] neg_hi:[0,1]
	v_xor_b32_e32 v19, 0x80000000, v10
	v_mov_b32_e32 v18, v11
	v_pk_add_f32 v[10:11], v[2:3], v[28:29]
	v_pk_add_f32 v[2:3], v[2:3], v[28:29] neg_lo:[0,1] neg_hi:[0,1]
	v_pk_add_f32 v[28:29], v[6:7], v[14:15]
	v_pk_add_f32 v[6:7], v[6:7], v[14:15] neg_lo:[0,1] neg_hi:[0,1]
	v_pk_add_f32 v[22:23], v[10:11], v[28:29] neg_lo:[0,1] neg_hi:[0,1]
	v_xor_b32_e32 v15, 0x80000000, v6
	v_mov_b32_e32 v14, v7
	v_pk_add_f32 v[6:7], v[38:39], v[24:25]
	v_pk_add_f32 v[24:25], v[10:11], v[28:29]
	v_mov_b32_e32 v28, v146
	v_pk_add_f32 v[40:41], v[42:43], v[20:21]
	v_pk_add_f32 v[20:21], v[42:43], v[20:21] neg_lo:[0,1] neg_hi:[0,1]
	v_lshlrev_b32_e32 v71, 4, v28
	v_lshrrev_b32_e32 v29, 1, v28
	v_pk_add_f32 v[42:43], v[40:41], v[72:73]
	v_pk_add_f32 v[40:41], v[40:41], v[72:73] neg_lo:[0,1] neg_hi:[0,1]
	v_bfe_u32 v28, v28, 1, 4
	v_bitop3_b32 v72, v29, v71, 16 bitop3:0x6c
	v_lshl_add_u32 v72, v72, 3, 16
	v_lshlrev_b32_e32 v28, 3, v28
	v_add_u32_e32 v73, v72, v28
	ds_write_b64 v73, v[66:67]
	v_bitop3_b32 v73, v29, 1, 15 bitop3:0x6c
	v_xor_b32_e32 v79, 0x80000000, v12
	v_mov_b32_e32 v78, v13
	v_lshlrev_b32_e32 v73, 3, v73
	v_pk_add_f32 v[12:13], v[74:75], v[78:79]
	v_pk_add_f32 v[10:11], v[74:75], v[78:79] neg_lo:[0,1] neg_hi:[0,1]
	v_add_u32_e32 v74, v72, v73
	ds_write_b64 v74, v[64:65]
	v_bitop3_b32 v74, v29, 2, 15 bitop3:0x6c
	v_lshlrev_b32_e32 v74, 3, v74
	v_add_u32_e32 v75, v72, v74
	ds_write_b64 v75, v[62:63]
	v_bitop3_b32 v75, v29, 3, 15 bitop3:0x6c
	v_lshlrev_b32_e32 v75, 3, v75
	v_pk_add_f32 v[80:81], v[4:5], v[36:37]
	v_pk_add_f32 v[82:83], v[4:5], v[36:37] neg_lo:[0,1] neg_hi:[0,1]
	v_pk_add_f32 v[4:5], v[8:9], v[16:17]
	v_pk_add_f32 v[8:9], v[8:9], v[16:17] neg_lo:[0,1] neg_hi:[0,1]
	v_pk_add_f32 v[38:39], v[20:21], v[18:19]
	v_pk_add_f32 v[36:37], v[20:21], v[18:19] neg_lo:[0,1] neg_hi:[0,1]
	v_pk_add_f32 v[20:21], v[2:3], v[14:15]
	v_pk_add_f32 v[18:19], v[2:3], v[14:15] neg_lo:[0,1] neg_hi:[0,1]
	v_pk_add_f32 v[16:17], v[6:7], v[76:77]
	v_pk_add_f32 v[14:15], v[6:7], v[76:77] neg_lo:[0,1] neg_hi:[0,1]
	v_add_u32_e32 v76, v72, v75
	ds_write_b64 v76, v[60:61]
	v_bitop3_b32 v76, v29, 4, 15 bitop3:0x6c
	v_lshlrev_b32_e32 v76, 3, v76
	v_add_u32_e32 v77, v72, v76
	ds_write_b64 v77, v[58:59]
	v_bitop3_b32 v77, v29, 5, 15 bitop3:0x6c
	v_lshlrev_b32_e32 v77, 3, v77
	v_add_u32_e32 v78, v72, v77
	ds_write_b64 v78, v[56:57]
	v_bitop3_b32 v78, v29, 6, 15 bitop3:0x6c
	v_lshlrev_b32_e32 v78, 3, v78
	v_add_u32_e32 v79, v72, v78
	ds_write_b64 v79, v[54:55]
	v_bitop3_b32 v79, v29, 7, 15 bitop3:0x6c
	v_lshlrev_b32_e32 v79, 3, v79
	v_xor_b32_e32 v85, 0x80000000, v8
	v_mov_b32_e32 v84, v9
	v_pk_add_f32 v[8:9], v[80:81], v[4:5]
	v_pk_add_f32 v[6:7], v[80:81], v[4:5] neg_lo:[0,1] neg_hi:[0,1]
	v_add_u32_e32 v80, v72, v79
	ds_write_b64 v80, v[52:53]
	v_bitop3_b32 v80, v29, 8, 15 bitop3:0x6c
	v_lshlrev_b32_e32 v80, 3, v80
	v_add_u32_e32 v81, v72, v80
	ds_write_b64 v81, v[50:51]
	v_bitop3_b32 v81, v29, 9, 15 bitop3:0x6c
	v_lshlrev_b32_e32 v81, 3, v81
	v_pk_add_f32 v[4:5], v[82:83], v[84:85]
	v_pk_add_f32 v[2:3], v[82:83], v[84:85] neg_lo:[0,1] neg_hi:[0,1]
	v_add_u32_e32 v82, v72, v81
	ds_write_b64 v82, v[48:49]
	v_bitop3_b32 v82, v29, 10, 15 bitop3:0x6c
	v_lshlrev_b32_e32 v82, 3, v82
	v_add_u32_e32 v83, v72, v82
	ds_write_b64 v83, v[46:47]
	v_bitop3_b32 v83, v29, 11, 15 bitop3:0x6c
	v_lshlrev_b32_e32 v83, 3, v83
	v_add_u32_e32 v84, v72, v83
	ds_write_b64 v84, v[44:45]
	v_bitop3_b32 v84, v29, 12, 15 bitop3:0x6c
	v_lshlrev_b32_e32 v84, 3, v84
	v_add_u32_e32 v85, v72, v84
	ds_write_b64 v85, v[34:35]
	v_bitop3_b32 v85, v29, 13, 15 bitop3:0x6c
	v_lshlrev_b32_e32 v85, 3, v85
	v_add_u32_e32 v86, v72, v85
	ds_write_b64 v86, v[32:33]
	v_bitop3_b32 v86, v29, 14, 15 bitop3:0x6c
	v_lshlrev_b32_e32 v86, 3, v86
	v_add_u32_e32 v87, v72, v86
	v_add_u32_e32 v88, 0x2000, v71
	ds_write_b64 v87, v[30:31]
	v_bitop3_b32 v87, v29, 15, v29 bitop3:0xc
	v_bitop3_b32 v29, v88, v29, 16 bitop3:0x78
	v_lshlrev_b32_e32 v87, 3, v87
	v_lshl_add_u32 v29, v29, 3, 16
	v_add_u32_e32 v72, v72, v87
	v_add_u32_e32 v28, v29, v28
	ds_write_b64 v72, v[26:27]
	ds_write_b64 v28, v[42:43]
	v_add_u32_e32 v28, v29, v73
	ds_write_b64 v28, v[40:41]
	v_add_u32_e32 v28, v29, v74
	ds_write_b64 v28, v[38:39]
	v_add_u32_e32 v28, v29, v75
	ds_write_b64 v28, v[36:37]
	v_add_u32_e32 v28, v29, v76
	ds_write_b64 v28, v[24:25]
	v_add_u32_e32 v28, v29, v77
	ds_write_b64 v28, v[22:23]
	v_add_u32_e32 v28, v29, v78
	ds_write_b64 v28, v[20:21]
	v_add_u32_e32 v28, v29, v79
	ds_write_b64 v28, v[18:19]
	v_add_u32_e32 v28, v29, v80
	ds_write_b64 v28, v[16:17]
	v_add_u32_e32 v28, v29, v81
	ds_write_b64 v28, v[14:15]
	v_add_u32_e32 v28, v29, v82
	v_or_b32_e32 v72, 1, v71
	ds_write_b64 v28, v[12:13]
	v_add_u32_e32 v28, v29, v83
	v_bfrev_b32_e32 v72, v72
	ds_write_b64 v28, v[10:11]
	v_add_u32_e32 v28, v29, v84
	v_lshrrev_b32_e32 v72, 18, v72
	ds_write_b64 v28, v[8:9]
	v_add_u32_e32 v28, v29, v85
	v_sub_u32_e32 v72, 0, v72
	ds_write_b64 v28, v[6:7]
	v_add_u32_e32 v28, v29, v86
	v_and_b32_e32 v72, 0x3fff, v72
	ds_write_b64 v28, v[4:5]
	v_add_u32_e32 v28, v29, v87
	v_bfrev_b32_e32 v72, v72
	ds_write_b64 v28, v[2:3]
	v_lshl_add_u64 v[28:29], v[0:1], 2, s[0:1]
	v_bfrev_b32_e32 v0, v71
	v_lshrrev_b32_e32 v73, 18, v72
	v_lshrrev_b32_e32 v72, 23, v72
	v_lshrrev_b32_e32 v0, 18, v0
	v_bitop3_b32 v72, v72, v73, 31 bitop3:0x6c
	v_or_b32_e32 v73, 2, v71
	v_sub_u32_e32 v0, 0, v0
	v_bfrev_b32_e32 v73, v73
	v_and_b32_e32 v0, 0x3fff, v0
	v_lshrrev_b32_e32 v73, 18, v73
	v_bfrev_b32_e32 v0, v0
	v_sub_u32_e32 v73, 0, v73
	v_lshrrev_b32_e32 v1, 18, v0
	v_lshrrev_b32_e32 v0, 23, v0
	v_and_b32_e32 v74, 0x3fff, v73
	v_bitop3_b32 v0, v0, v1, 31 bitop3:0x6c
	v_bfrev_b32_e32 v74, v74
	v_and_b32_e32 v73, 0x1fff, v73
	v_lshl_add_u32 v0, v0, 3, 16
	v_lshrrev_b32_e32 v75, 18, v74
	v_lshrrev_b32_e32 v74, 23, v74
	v_bfrev_b32_e32 v73, v73
	s_waitcnt lgkmcnt(0)
	s_barrier
	ds_read_b64 v[0:1], v0
	v_bitop3_b32 v74, v74, v75, 31 bitop3:0x6c
	v_lshrrev_b32_e32 v75, 18, v73
	v_lshrrev_b32_e32 v73, 23, v73
	v_bitop3_b32 v73, v73, v75, 31 bitop3:0x6c
	v_lshl_add_u32 v72, v72, 3, 16
	v_lshl_add_u32 v74, v74, 3, 16
	v_lshl_add_u32 v76, v73, 3, 16
	ds_read_b64 v[72:73], v72
	ds_read_b64 v[74:75], v74
	ds_read_b64 v[76:77], v76
	s_waitcnt lgkmcnt(3)
	v_pk_add_f32 v[78:79], v[66:67], v[0:1]
	v_sub_f32_e32 v1, v67, v1
	v_sub_f32_e32 v0, v0, v66
	v_mul_f32_e32 v67, 0.5, v1
	v_mul_f32_e32 v66, 0.5, v0
	s_waitcnt lgkmcnt(2)
	v_pk_add_f32 v[0:1], v[64:65], v[72:73]
	v_mul_f32_e32 v78, 0.5, v78
	v_mul_f32_e32 v80, 0.5, v0
	v_sub_f32_e32 v0, v65, v73
	v_mul_f32_e32 v65, 0.5, v0
	v_sub_f32_e32 v0, v72, v64
	v_mul_f32_e32 v73, 0.5, v1
	v_mul_f32_e32 v64, 0.5, v0
	s_waitcnt lgkmcnt(1)
	v_pk_add_f32 v[0:1], v[62:63], v[74:75]
	s_mov_b32 s0, 0x10000
	v_mul_f32_e32 v72, 0.5, v0
	v_sub_f32_e32 v0, v63, v75
	v_mul_f32_e32 v75, 0.5, v0
	v_sub_f32_e32 v0, v74, v62
	v_mul_f32_e32 v81, 0.5, v1
	v_mul_f32_e32 v74, 0.5, v0
	s_waitcnt lgkmcnt(0)
	v_pk_add_f32 v[0:1], v[60:61], v[76:77]
	v_sub_f32_e32 v61, v61, v77
	v_mul_f32_e32 v0, 0.5, v0
	v_mul_f32_e32 v61, 0.5, v61
	v_sub_f32_e32 v60, v76, v60
	v_mul_f32_e32 v79, 0.5, v79
	v_mul_f32_e32 v1, 0.5, v1
	v_mul_f32_e32 v76, 0.5, v60
	v_cvt_pk_f16_f32 v63, v0, v61
	v_cvt_pk_f16_f32 v62, v72, v75
	v_cvt_pk_f16_f32 v61, v80, v65
	v_cvt_pk_f16_f32 v60, v78, v67
	v_add_co_u32_e32 v0, vcc, s0, v28
	global_store_dwordx4 v[28:29], v[60:63], off offset:-4096
	v_readlane_b32 s0, v252, 50
	s_add_u32 s64, s0, s10
	v_cvt_pk_f16_f32 v63, v1, v76
	v_cvt_pk_f16_f32 v62, v81, v74
	v_cvt_pk_f16_f32 v61, v73, v64
	v_cvt_pk_f16_f32 v60, v79, v66
	v_addc_co_u32_e32 v1, vcc, 0, v29, vcc
	global_store_dwordx4 v[0:1], v[60:63], off offset:-4096
	v_readlane_b32 s0, v252, 51
	s_addc_u32 s65, s0, s11
	v_or_b32_e32 v60, 4, v71
	v_bfrev_b32_e32 v60, v60
	v_lshrrev_b32_e32 v60, 18, v60
	v_sub_u32_e32 v62, 0, v60
	v_and_b32_e32 v63, 0x1fff, v62
	v_bfrev_b32_e32 v63, v63
	v_lshrrev_b32_e32 v64, 18, v63
	v_lshrrev_b32_e32 v63, 23, v63
	v_bitop3_b32 v63, v63, v64, 31 bitop3:0x6c
	v_or_b32_e32 v64, 6, v71
	v_bfrev_b32_e32 v64, v64
	v_and_b32_e32 v60, 0x3fff, v62
	v_lshrrev_b32_e32 v64, 18, v64
	v_bfrev_b32_e32 v60, v60
	v_sub_u32_e32 v64, 0, v64
	v_lshrrev_b32_e32 v61, 18, v60
	v_lshrrev_b32_e32 v60, 23, v60
	v_and_b32_e32 v64, 0x2fff, v64
	v_bitop3_b32 v60, v60, v61, 31 bitop3:0x6c
	v_bfrev_b32_e32 v64, v64
	v_and_b32_e32 v62, 0xfff, v62
	v_lshl_add_u32 v60, v60, 3, 16
	v_lshrrev_b32_e32 v65, 18, v64
	v_lshrrev_b32_e32 v64, 23, v64
	v_bfrev_b32_e32 v62, v62
	ds_read_b64 v[60:61], v60
	v_bitop3_b32 v64, v64, v65, 31 bitop3:0x6c
	v_lshrrev_b32_e32 v65, 18, v62
	v_lshrrev_b32_e32 v62, 23, v62
	v_bitop3_b32 v62, v62, v65, 31 bitop3:0x6c
	v_lshl_add_u32 v63, v63, 3, 16
	v_lshl_add_u32 v64, v64, 3, 16
	v_lshl_add_u32 v66, v62, 3, 16
	ds_read_b64 v[62:63], v63
	ds_read_b64 v[64:65], v64
	ds_read_b64 v[66:67], v66
	s_waitcnt lgkmcnt(3)
	v_pk_add_f32 v[72:73], v[58:59], v[60:61]
	v_sub_f32_e32 v59, v59, v61
	v_sub_f32_e32 v58, v60, v58
	v_mul_f32_e32 v61, 0.5, v59
	v_mul_f32_e32 v60, 0.5, v58
	s_waitcnt lgkmcnt(2)
	v_pk_add_f32 v[58:59], v[56:57], v[62:63]
	v_sub_f32_e32 v57, v57, v63
	v_sub_f32_e32 v56, v62, v56
	v_mul_f32_e32 v63, 0.5, v57
	v_mul_f32_e32 v62, 0.5, v56
	s_waitcnt lgkmcnt(1)
	v_pk_add_f32 v[56:57], v[54:55], v[64:65]
	v_sub_f32_e32 v55, v55, v65
	v_sub_f32_e32 v54, v64, v54
	v_mul_f32_e32 v65, 0.5, v55
	v_mul_f32_e32 v64, 0.5, v54
	s_waitcnt lgkmcnt(0)
	v_pk_add_f32 v[54:55], v[52:53], v[66:67]
	v_sub_f32_e32 v53, v53, v67
	v_mul_f32_e32 v72, 0.5, v72
	v_mul_f32_e32 v58, 0.5, v58
	v_mul_f32_e32 v56, 0.5, v56
	v_mul_f32_e32 v54, 0.5, v54
	v_mul_f32_e32 v53, 0.5, v53
	v_sub_f32_e32 v52, v66, v52
	v_mul_f32_e32 v73, 0.5, v73
	v_mul_f32_e32 v59, 0.5, v59
	v_mul_f32_e32 v57, 0.5, v57
	v_mul_f32_e32 v67, 0.5, v55
	v_mul_f32_e32 v66, 0.5, v52
	v_cvt_pk_f16_f32 v55, v54, v53
	v_cvt_pk_f16_f32 v54, v56, v65
	v_cvt_pk_f16_f32 v53, v58, v63
	v_cvt_pk_f16_f32 v52, v72, v61
	global_store_dwordx4 v[28:29], v[52:55], off offset:-3072
	s_lshl_b64 s[0:1], s[62:63], 13
	s_add_u32 s66, s0, 0xc00000
	v_cvt_pk_f16_f32 v55, v67, v66
	v_cvt_pk_f16_f32 v54, v57, v64
	v_cvt_pk_f16_f32 v53, v59, v62
	v_cvt_pk_f16_f32 v52, v73, v60
	global_store_dwordx4 v[0:1], v[52:55], off offset:-3072
	s_addc_u32 s67, s1, 0
	v_readlane_b32 s0, v252, 6
	v_or_b32_e32 v52, 8, v71
	v_bfrev_b32_e32 v52, v52
	v_lshrrev_b32_e32 v52, 18, v52
	v_sub_u32_e32 v62, 0, v52
	v_and_b32_e32 v54, 0x1fff, v62
	v_bfrev_b32_e32 v54, v54
	v_lshrrev_b32_e32 v55, 18, v54
	v_lshrrev_b32_e32 v54, 23, v54
	v_bitop3_b32 v54, v54, v55, 31 bitop3:0x6c
	v_or_b32_e32 v55, 10, v71
	v_bfrev_b32_e32 v55, v55
	v_lshrrev_b32_e32 v55, 18, v55
	v_sub_u32_e32 v55, 0, v55
	v_and_b32_e32 v55, 0x2fff, v55
	v_and_b32_e32 v52, 0x3fff, v62
	v_bfrev_b32_e32 v55, v55
	v_bfrev_b32_e32 v52, v52
	v_lshrrev_b32_e32 v56, 18, v55
	v_lshrrev_b32_e32 v55, 23, v55
	v_lshrrev_b32_e32 v53, 18, v52
	v_lshrrev_b32_e32 v52, 23, v52
	v_bitop3_b32 v55, v55, v56, 31 bitop3:0x6c
	v_bitop3_b32 v52, v52, v53, 31 bitop3:0x6c
	v_lshl_add_u32 v56, v55, 3, 16
	v_and_b32_e32 v55, 0xfff, v62
	v_lshl_add_u32 v52, v52, 3, 16
	v_bfrev_b32_e32 v55, v55
	ds_read_b64 v[52:53], v52
	v_lshrrev_b32_e32 v57, 18, v55
	v_lshrrev_b32_e32 v55, 23, v55
	v_bitop3_b32 v55, v55, v57, 31 bitop3:0x6c
	v_lshl_add_u32 v54, v54, 3, 16
	v_lshl_add_u32 v58, v55, 3, 16
	ds_read_b64 v[54:55], v54
	ds_read_b64 v[56:57], v56
	ds_read_b64 v[58:59], v58
	s_waitcnt lgkmcnt(3)
	v_pk_add_f32 v[60:61], v[50:51], v[52:53]
	v_sub_f32_e32 v51, v51, v53
	v_sub_f32_e32 v50, v52, v50
	v_mul_f32_e32 v53, 0.5, v51
	v_mul_f32_e32 v52, 0.5, v50
	s_waitcnt lgkmcnt(2)
	v_pk_add_f32 v[50:51], v[48:49], v[54:55]
	v_sub_f32_e32 v49, v49, v55
	v_sub_f32_e32 v48, v54, v48
	v_mul_f32_e32 v55, 0.5, v49
	v_mul_f32_e32 v54, 0.5, v48
	s_waitcnt lgkmcnt(1)
	v_pk_add_f32 v[48:49], v[46:47], v[56:57]
	v_sub_f32_e32 v47, v47, v57
	v_sub_f32_e32 v46, v56, v46
	v_mul_f32_e32 v57, 0.5, v47
	v_mul_f32_e32 v56, 0.5, v46
	s_waitcnt lgkmcnt(0)
	v_pk_add_f32 v[46:47], v[44:45], v[58:59]
	v_sub_f32_e32 v45, v45, v59
	v_mul_f32_e32 v60, 0.5, v60
	v_mul_f32_e32 v50, 0.5, v50
	v_mul_f32_e32 v48, 0.5, v48
	v_mul_f32_e32 v46, 0.5, v46
	v_mul_f32_e32 v45, 0.5, v45
	v_sub_f32_e32 v44, v58, v44
	v_mul_f32_e32 v61, 0.5, v61
	v_mul_f32_e32 v51, 0.5, v51
	v_mul_f32_e32 v49, 0.5, v49
	v_mul_f32_e32 v59, 0.5, v47
	v_mul_f32_e32 v58, 0.5, v44
	v_cvt_pk_f16_f32 v47, v46, v45
	v_cvt_pk_f16_f32 v46, v48, v57
	v_cvt_pk_f16_f32 v45, v50, v55
	v_cvt_pk_f16_f32 v44, v60, v53
	global_store_dwordx4 v[28:29], v[44:47], off offset:-2048
	s_add_u32 s68, s0, s10
	v_readlane_b32 s0, v252, 47
	v_cvt_pk_f16_f32 v47, v59, v58
	v_cvt_pk_f16_f32 v46, v49, v56
	v_cvt_pk_f16_f32 v45, v51, v54
	v_cvt_pk_f16_f32 v44, v61, v52
	global_store_dwordx4 v[0:1], v[44:47], off offset:-2048
	s_addc_u32 s69, s0, s11
	s_lshl_b64 s[0:1], s[62:63], 14
	v_or_b32_e32 v44, 12, v71
	v_bfrev_b32_e32 v44, v44
	v_lshrrev_b32_e32 v44, 18, v44
	v_sub_u32_e32 v46, 0, v44
	v_and_b32_e32 v44, 0x37ff, v46
	v_and_b32_e32 v46, 0x17ff, v46
	v_bfrev_b32_e32 v46, v46
	v_lshrrev_b32_e32 v47, 18, v46
	v_lshrrev_b32_e32 v46, 23, v46
	v_bitop3_b32 v46, v46, v47, 31 bitop3:0x6c
	v_or_b32_e32 v47, 14, v71
	v_bfrev_b32_e32 v47, v47
	v_lshrrev_b32_e32 v47, 18, v47
	v_sub_u32_e32 v47, 0, v47
	v_and_b32_e32 v47, 0x27ff, v47
	v_bfrev_b32_e32 v47, v47
	v_bfrev_b32_e32 v44, v44
	v_lshrrev_b32_e32 v48, 18, v47
	v_lshrrev_b32_e32 v47, 23, v47
	v_lshrrev_b32_e32 v45, 18, v44
	v_lshrrev_b32_e32 v44, 23, v44
	v_bitop3_b32 v47, v47, v48, 31 bitop3:0x6c
	v_bitop3_b32 v44, v44, v45, 31 bitop3:0x6c
	v_lshl_add_u32 v48, v47, 3, 16
	v_and_b32_e32 v47, 0x7ff, v62
	v_lshl_add_u32 v44, v44, 3, 16
	v_bfrev_b32_e32 v47, v47
	ds_read_b64 v[44:45], v44
	v_lshrrev_b32_e32 v49, 18, v47
	v_lshrrev_b32_e32 v47, 23, v47
	v_bitop3_b32 v47, v47, v49, 31 bitop3:0x6c
	v_lshl_add_u32 v46, v46, 3, 16
	v_lshl_add_u32 v50, v47, 3, 16
	ds_read_b64 v[46:47], v46
	ds_read_b64 v[48:49], v48
	ds_read_b64 v[50:51], v50
	s_waitcnt lgkmcnt(3)
	v_pk_add_f32 v[52:53], v[34:35], v[44:45]
	v_sub_f32_e32 v35, v35, v45
	v_sub_f32_e32 v34, v44, v34
	v_mul_f32_e32 v45, 0.5, v35
	v_mul_f32_e32 v44, 0.5, v34
	s_waitcnt lgkmcnt(2)
	v_pk_add_f32 v[34:35], v[32:33], v[46:47]
	v_sub_f32_e32 v33, v33, v47
	v_sub_f32_e32 v32, v46, v32
	v_mul_f32_e32 v47, 0.5, v33
	v_mul_f32_e32 v46, 0.5, v32
	s_waitcnt lgkmcnt(1)
	v_pk_add_f32 v[32:33], v[30:31], v[48:49]
	v_sub_f32_e32 v31, v31, v49
	v_sub_f32_e32 v30, v48, v30
	v_mul_f32_e32 v49, 0.5, v31
	v_mul_f32_e32 v48, 0.5, v30
	s_waitcnt lgkmcnt(0)
	v_pk_add_f32 v[30:31], v[26:27], v[50:51]
	v_sub_f32_e32 v27, v27, v51
	v_mul_f32_e32 v52, 0.5, v52
	v_mul_f32_e32 v34, 0.5, v34
	v_mul_f32_e32 v32, 0.5, v32
	v_mul_f32_e32 v30, 0.5, v30
	v_mul_f32_e32 v27, 0.5, v27
	v_sub_f32_e32 v26, v50, v26
	v_mul_f32_e32 v53, 0.5, v53
	v_mul_f32_e32 v35, 0.5, v35
	v_mul_f32_e32 v54, 0.5, v33
	v_mul_f32_e32 v51, 0.5, v31
	v_mul_f32_e32 v26, 0.5, v26
	v_cvt_pk_f16_f32 v33, v30, v27
	v_cvt_pk_f16_f32 v32, v32, v49
	v_cvt_pk_f16_f32 v31, v34, v47
	v_cvt_pk_f16_f32 v30, v52, v45
	global_store_dwordx4 v[28:29], v[30:33], off offset:-1024
	s_add_u32 s12, s26, s0
	s_addc_u32 s13, s27, s1
	v_cvt_pk_f16_f32 v33, v51, v26
	v_cvt_pk_f16_f32 v32, v54, v48
	v_cvt_pk_f16_f32 v31, v35, v46
	v_cvt_pk_f16_f32 v30, v53, v44
	global_store_dwordx4 v[0:1], v[30:33], off offset:-1024
	v_bfrev_b32_e32 v26, v88
	v_lshrrev_b32_e32 v26, 18, v26
	v_add_u32_e32 v30, 0x2001, v71
	v_bfrev_b32_e32 v30, v30
	v_lshrrev_b32_e32 v30, 18, v30
	v_sub_u32_e32 v30, 0, v30
	v_and_b32_e32 v30, 0x3fff, v30
	v_bfrev_b32_e32 v30, v30
	v_lshrrev_b32_e32 v31, 18, v30
	v_lshrrev_b32_e32 v30, 23, v30
	v_bitop3_b32 v30, v30, v31, 31 bitop3:0x6c
	v_add_u32_e32 v31, 0x2002, v71
	v_bfrev_b32_e32 v31, v31
	v_lshrrev_b32_e32 v31, 18, v31
	v_sub_u32_e32 v31, 0, v31
	v_and_b32_e32 v31, 0x3fff, v31
	v_bfrev_b32_e32 v31, v31
	v_lshrrev_b32_e32 v32, 18, v31
	v_lshrrev_b32_e32 v31, 23, v31
	v_bitop3_b32 v31, v31, v32, 31 bitop3:0x6c
	v_sub_u32_e32 v26, 0, v26
	v_lshl_add_u32 v32, v31, 3, 16
	v_add_u32_e32 v31, 0x2003, v71
	v_and_b32_e32 v26, 0x3fff, v26
	v_bfrev_b32_e32 v31, v31
	v_bfrev_b32_e32 v26, v26
	v_lshrrev_b32_e32 v31, 18, v31
	v_lshrrev_b32_e32 v27, 18, v26
	v_lshrrev_b32_e32 v26, 23, v26
	v_sub_u32_e32 v31, 0, v31
	v_bitop3_b32 v26, v26, v27, 31 bitop3:0x6c
	v_and_b32_e32 v31, 0x1fff, v31
	v_lshl_add_u32 v26, v26, 3, 16
	v_bfrev_b32_e32 v31, v31
	ds_read_b64 v[26:27], v26
	v_lshrrev_b32_e32 v33, 18, v31
	v_lshrrev_b32_e32 v31, 23, v31
	v_bitop3_b32 v31, v31, v33, 31 bitop3:0x6c
	v_lshl_add_u32 v30, v30, 3, 16
	v_lshl_add_u32 v34, v31, 3, 16
	ds_read_b64 v[30:31], v30
	ds_read_b64 v[32:33], v32
	ds_read_b64 v[34:35], v34
	s_waitcnt lgkmcnt(3)
	v_pk_add_f32 v[44:45], v[42:43], v[26:27]
	v_sub_f32_e32 v27, v43, v27
	v_sub_f32_e32 v26, v26, v42
	v_mul_f32_e32 v43, 0.5, v27
	v_mul_f32_e32 v42, 0.5, v26
	s_waitcnt lgkmcnt(2)
	v_pk_add_f32 v[26:27], v[40:41], v[30:31]
	v_mul_f32_e32 v44, 0.5, v44
	v_mul_f32_e32 v46, 0.5, v26
	v_sub_f32_e32 v26, v41, v31
	v_mul_f32_e32 v31, 0.5, v26
	v_sub_f32_e32 v26, v30, v40
	v_mul_f32_e32 v41, 0.5, v27
	v_mul_f32_e32 v40, 0.5, v26
	s_waitcnt lgkmcnt(1)
	v_pk_add_f32 v[26:27], v[38:39], v[32:33]
	v_mul_f32_e32 v45, 0.5, v45
	v_mul_f32_e32 v30, 0.5, v26
	v_sub_f32_e32 v26, v39, v33
	v_mul_f32_e32 v39, 0.5, v26
	v_sub_f32_e32 v26, v32, v38
	v_mul_f32_e32 v47, 0.5, v27
	v_mul_f32_e32 v38, 0.5, v26
	s_waitcnt lgkmcnt(0)
	v_pk_add_f32 v[26:27], v[36:37], v[34:35]
	v_sub_f32_e32 v32, v37, v35
	v_mul_f32_e32 v26, 0.5, v26
	v_mul_f32_e32 v32, 0.5, v32
	v_sub_f32_e32 v33, v34, v36
	v_mul_f32_e32 v27, 0.5, v27
	v_mul_f32_e32 v34, 0.5, v33
	v_cvt_pk_f16_f32 v33, v26, v32
	v_cvt_pk_f16_f32 v32, v30, v39
	v_cvt_pk_f16_f32 v31, v46, v31
	v_cvt_pk_f16_f32 v30, v44, v43
	global_store_dwordx4 v[28:29], v[30:33], off
	v_add_u32_e32 v26, 0x2004, v71
	v_bfrev_b32_e32 v26, v26
	v_cvt_pk_f16_f32 v33, v27, v34
	v_cvt_pk_f16_f32 v32, v47, v38
	v_cvt_pk_f16_f32 v31, v41, v40
	v_cvt_pk_f16_f32 v30, v45, v42
	global_store_dwordx4 v[0:1], v[30:33], off
	v_lshrrev_b32_e32 v26, 18, v26
	v_sub_u32_e32 v26, 0, v26
	v_add_u32_e32 v30, 0x2005, v71
	v_bfrev_b32_e32 v30, v30
	v_lshrrev_b32_e32 v30, 18, v30
	v_sub_u32_e32 v30, 0, v30
	v_and_b32_e32 v30, 0x1fff, v30
	v_bfrev_b32_e32 v30, v30
	v_lshrrev_b32_e32 v31, 18, v30
	v_lshrrev_b32_e32 v30, 23, v30
	v_bitop3_b32 v30, v30, v31, 31 bitop3:0x6c
	v_add_u32_e32 v31, 0x2006, v71
	v_bfrev_b32_e32 v31, v31
	v_lshrrev_b32_e32 v31, 18, v31
	v_sub_u32_e32 v31, 0, v31
	v_and_b32_e32 v31, 0x2fff, v31
	v_bfrev_b32_e32 v31, v31
	v_lshrrev_b32_e32 v32, 18, v31
	v_lshrrev_b32_e32 v31, 23, v31
	v_bitop3_b32 v31, v31, v32, 31 bitop3:0x6c
	v_lshl_add_u32 v32, v31, 3, 16
	v_add_u32_e32 v31, 0x2007, v71
	v_and_b32_e32 v26, 0x3fff, v26
	v_bfrev_b32_e32 v31, v31
	v_bfrev_b32_e32 v26, v26
	v_lshrrev_b32_e32 v31, 18, v31
	v_lshrrev_b32_e32 v27, 18, v26
	v_lshrrev_b32_e32 v26, 23, v26
	v_sub_u32_e32 v31, 0, v31
	v_bitop3_b32 v26, v26, v27, 31 bitop3:0x6c
	v_and_b32_e32 v31, 0xfff, v31
	v_lshl_add_u32 v26, v26, 3, 16
	v_bfrev_b32_e32 v31, v31
	ds_read_b64 v[26:27], v26
	v_lshrrev_b32_e32 v33, 18, v31
	v_lshrrev_b32_e32 v31, 23, v31
	v_bitop3_b32 v31, v31, v33, 31 bitop3:0x6c
	v_lshl_add_u32 v30, v30, 3, 16
	v_lshl_add_u32 v34, v31, 3, 16
	ds_read_b64 v[30:31], v30
	ds_read_b64 v[32:33], v32
	ds_read_b64 v[34:35], v34
	s_waitcnt lgkmcnt(3)
	v_pk_add_f32 v[36:37], v[24:25], v[26:27]
	v_sub_f32_e32 v25, v25, v27
	v_sub_f32_e32 v24, v26, v24
	v_mul_f32_e32 v27, 0.5, v25
	v_mul_f32_e32 v26, 0.5, v24
	s_waitcnt lgkmcnt(2)
	v_pk_add_f32 v[24:25], v[22:23], v[30:31]
	v_sub_f32_e32 v23, v23, v31
	v_sub_f32_e32 v22, v30, v22
	v_mul_f32_e32 v31, 0.5, v23
	v_mul_f32_e32 v30, 0.5, v22
	s_waitcnt lgkmcnt(1)
	v_pk_add_f32 v[22:23], v[20:21], v[32:33]
	v_sub_f32_e32 v21, v21, v33
	v_sub_f32_e32 v20, v32, v20
	v_mul_f32_e32 v33, 0.5, v21
	v_mul_f32_e32 v32, 0.5, v20
	s_waitcnt lgkmcnt(0)
	v_pk_add_f32 v[20:21], v[18:19], v[34:35]
	v_sub_f32_e32 v19, v19, v35
	v_mul_f32_e32 v36, 0.5, v36
	v_mul_f32_e32 v24, 0.5, v24
	v_mul_f32_e32 v22, 0.5, v22
	v_mul_f32_e32 v20, 0.5, v20
	v_mul_f32_e32 v19, 0.5, v19
	v_sub_f32_e32 v18, v34, v18
	v_mul_f32_e32 v37, 0.5, v37
	v_mul_f32_e32 v25, 0.5, v25
	v_mul_f32_e32 v23, 0.5, v23
	v_mul_f32_e32 v35, 0.5, v21
	v_mul_f32_e32 v34, 0.5, v18
	v_cvt_pk_f16_f32 v21, v20, v19
	v_cvt_pk_f16_f32 v20, v22, v33
	v_cvt_pk_f16_f32 v19, v24, v31
	v_cvt_pk_f16_f32 v18, v36, v27
	global_store_dwordx4 v[28:29], v[18:21], off offset:1024
	s_add_u32 s14, s30, s0
	s_addc_u32 s15, s31, s1
	v_cvt_pk_f16_f32 v21, v35, v34
	v_cvt_pk_f16_f32 v20, v23, v32
	v_cvt_pk_f16_f32 v19, v25, v30
	v_cvt_pk_f16_f32 v18, v37, v26
	global_store_dwordx4 v[0:1], v[18:21], off offset:1024
	v_cmp_lt_i32_e32 vcc, s33, v146
	v_add_u32_e32 v52, 0x800, v146
	v_add_u32_e32 v20, 0x2009, v71
	v_bfrev_b32_e32 v20, v20
	v_lshrrev_b32_e32 v20, 18, v20
	v_sub_u32_e32 v20, 0, v20
	v_and_b32_e32 v20, 0x1fff, v20
	v_bfrev_b32_e32 v20, v20
	v_lshrrev_b32_e32 v21, 18, v20
	v_lshrrev_b32_e32 v20, 23, v20
	v_bitop3_b32 v20, v20, v21, 31 bitop3:0x6c
	v_add_u32_e32 v21, 0x200a, v71
	v_bfrev_b32_e32 v21, v21
	v_lshrrev_b32_e32 v21, 18, v21
	v_sub_u32_e32 v21, 0, v21
	v_and_b32_e32 v21, 0x2fff, v21
	v_add_u32_e32 v18, 0x2008, v71
	v_bfrev_b32_e32 v21, v21
	v_bfrev_b32_e32 v18, v18
	v_lshrrev_b32_e32 v22, 18, v21
	v_lshrrev_b32_e32 v21, 23, v21
	v_lshrrev_b32_e32 v18, 18, v18
	v_bitop3_b32 v21, v21, v22, 31 bitop3:0x6c
	v_sub_u32_e32 v18, 0, v18
	v_lshl_add_u32 v22, v21, 3, 16
	v_add_u32_e32 v21, 0x200b, v71
	v_and_b32_e32 v18, 0x3fff, v18
	v_bfrev_b32_e32 v21, v21
	v_bfrev_b32_e32 v18, v18
	v_lshrrev_b32_e32 v21, 18, v21
	v_lshrrev_b32_e32 v19, 18, v18
	v_lshrrev_b32_e32 v18, 23, v18
	v_sub_u32_e32 v21, 0, v21
	v_bitop3_b32 v18, v18, v19, 31 bitop3:0x6c
	v_and_b32_e32 v21, 0xfff, v21
	v_lshl_add_u32 v18, v18, 3, 16
	v_bfrev_b32_e32 v21, v21
	ds_read_b64 v[18:19], v18
	v_lshrrev_b32_e32 v23, 18, v21
	v_lshrrev_b32_e32 v21, 23, v21
	v_bitop3_b32 v21, v21, v23, 31 bitop3:0x6c
	v_lshl_add_u32 v20, v20, 3, 16
	v_lshl_add_u32 v24, v21, 3, 16
	ds_read_b64 v[20:21], v20
	ds_read_b64 v[22:23], v22
	ds_read_b64 v[24:25], v24
	s_waitcnt lgkmcnt(3)
	v_pk_add_f32 v[26:27], v[16:17], v[18:19]
	v_sub_f32_e32 v17, v17, v19
	v_sub_f32_e32 v16, v18, v16
	v_mul_f32_e32 v19, 0.5, v17
	v_mul_f32_e32 v18, 0.5, v16
	s_waitcnt lgkmcnt(2)
	v_pk_add_f32 v[16:17], v[14:15], v[20:21]
	v_sub_f32_e32 v15, v15, v21
	v_sub_f32_e32 v14, v20, v14
	v_mul_f32_e32 v21, 0.5, v15
	v_mul_f32_e32 v20, 0.5, v14
	s_waitcnt lgkmcnt(1)
	v_pk_add_f32 v[14:15], v[12:13], v[22:23]
	v_sub_f32_e32 v13, v13, v23
	v_sub_f32_e32 v12, v22, v12
	v_mul_f32_e32 v23, 0.5, v13
	v_mul_f32_e32 v22, 0.5, v12
	s_waitcnt lgkmcnt(0)
	v_pk_add_f32 v[12:13], v[10:11], v[24:25]
	v_sub_f32_e32 v11, v11, v25
	v_mul_f32_e32 v26, 0.5, v26
	v_mul_f32_e32 v16, 0.5, v16
	v_mul_f32_e32 v14, 0.5, v14
	v_mul_f32_e32 v12, 0.5, v12
	v_mul_f32_e32 v11, 0.5, v11
	v_sub_f32_e32 v10, v24, v10
	v_mul_f32_e32 v27, 0.5, v27
	v_mul_f32_e32 v17, 0.5, v17
	v_mul_f32_e32 v15, 0.5, v15
	v_mul_f32_e32 v25, 0.5, v13
	v_mul_f32_e32 v24, 0.5, v10
	v_cvt_pk_f16_f32 v13, v12, v11
	v_cvt_pk_f16_f32 v12, v14, v23
	v_cvt_pk_f16_f32 v11, v16, v21
	v_cvt_pk_f16_f32 v10, v26, v19
	global_store_dwordx4 v[28:29], v[10:13], off offset:2048
	v_add_u32_e32 v53, 0xa00, v146
	v_add_u32_e32 v54, 0xc00, v146
	v_cvt_pk_f16_f32 v13, v25, v24
	v_cvt_pk_f16_f32 v12, v15, v22
	v_cvt_pk_f16_f32 v11, v17, v20
	v_cvt_pk_f16_f32 v10, v27, v18
	global_store_dwordx4 v[0:1], v[10:13], off offset:2048
	v_add_u32_e32 v55, 0xe00, v146
	v_add_u32_e32 v47, 0x1000, v146
	v_add_u32_e32 v12, 0x200d, v71
	v_bfrev_b32_e32 v12, v12
	v_lshrrev_b32_e32 v12, 18, v12
	v_sub_u32_e32 v12, 0, v12
	v_and_b32_e32 v12, 0x17ff, v12
	v_bfrev_b32_e32 v12, v12
	v_lshrrev_b32_e32 v13, 18, v12
	v_lshrrev_b32_e32 v12, 23, v12
	v_bitop3_b32 v12, v12, v13, 31 bitop3:0x6c
	v_add_u32_e32 v13, 0x200e, v71
	v_bfrev_b32_e32 v13, v13
	v_lshrrev_b32_e32 v13, 18, v13
	v_sub_u32_e32 v13, 0, v13
	v_and_b32_e32 v13, 0x27ff, v13
	v_add_u32_e32 v10, 0x200c, v71
	v_bfrev_b32_e32 v13, v13
	v_bfrev_b32_e32 v10, v10
	v_lshrrev_b32_e32 v14, 18, v13
	v_lshrrev_b32_e32 v13, 23, v13
	v_lshrrev_b32_e32 v10, 18, v10
	v_bitop3_b32 v13, v13, v14, 31 bitop3:0x6c
	v_sub_u32_e32 v10, 0, v10
	v_lshl_add_u32 v14, v13, 3, 16
	v_add_u32_e32 v13, 0x200f, v71
	v_and_b32_e32 v10, 0x37ff, v10
	v_bfrev_b32_e32 v13, v13
	v_bfrev_b32_e32 v10, v10
	v_lshrrev_b32_e32 v13, 18, v13
	v_lshrrev_b32_e32 v11, 18, v10
	v_lshrrev_b32_e32 v10, 23, v10
	v_sub_u32_e32 v13, 0, v13
	v_bitop3_b32 v10, v10, v11, 31 bitop3:0x6c
	v_and_b32_e32 v13, 0x7ff, v13
	v_lshl_add_u32 v10, v10, 3, 16
	v_bfrev_b32_e32 v13, v13
	ds_read_b64 v[10:11], v10
	v_lshrrev_b32_e32 v15, 18, v13
	v_lshrrev_b32_e32 v13, 23, v13
	v_bitop3_b32 v13, v13, v15, 31 bitop3:0x6c
	v_lshl_add_u32 v12, v12, 3, 16
	v_lshl_add_u32 v16, v13, 3, 16
	ds_read_b64 v[12:13], v12
	ds_read_b64 v[14:15], v14
	ds_read_b64 v[16:17], v16
	s_waitcnt lgkmcnt(3)
	v_pk_add_f32 v[18:19], v[8:9], v[10:11]
	v_sub_f32_e32 v9, v9, v11
	v_sub_f32_e32 v8, v10, v8
	v_mul_f32_e32 v11, 0.5, v9
	v_mul_f32_e32 v10, 0.5, v8
	s_waitcnt lgkmcnt(2)
	v_pk_add_f32 v[8:9], v[6:7], v[12:13]
	v_sub_f32_e32 v7, v7, v13
	v_sub_f32_e32 v6, v12, v6
	v_mul_f32_e32 v13, 0.5, v7
	v_mul_f32_e32 v12, 0.5, v6
	s_waitcnt lgkmcnt(1)
	v_pk_add_f32 v[6:7], v[4:5], v[14:15]
	v_sub_f32_e32 v5, v5, v15
	v_sub_f32_e32 v4, v14, v4
	v_mul_f32_e32 v15, 0.5, v5
	v_mul_f32_e32 v14, 0.5, v4
	s_waitcnt lgkmcnt(0)
	v_pk_add_f32 v[4:5], v[2:3], v[16:17]
	v_sub_f32_e32 v3, v3, v17
	v_mul_f32_e32 v18, 0.5, v18
	v_mul_f32_e32 v8, 0.5, v8
	v_mul_f32_e32 v6, 0.5, v6
	v_mul_f32_e32 v4, 0.5, v4
	v_mul_f32_e32 v3, 0.5, v3
	v_sub_f32_e32 v2, v16, v2
	v_mul_f32_e32 v19, 0.5, v19
	v_mul_f32_e32 v9, 0.5, v9
	v_mul_f32_e32 v7, 0.5, v7
	v_mul_f32_e32 v17, 0.5, v5
	v_mul_f32_e32 v16, 0.5, v2
	v_cvt_pk_f16_f32 v5, v4, v3
	v_cvt_pk_f16_f32 v4, v6, v15
	v_cvt_pk_f16_f32 v3, v8, v13
	v_cvt_pk_f16_f32 v2, v18, v11
	global_store_dwordx4 v[28:29], v[2:5], off offset:3072
	v_add_u32_e32 v46, 0x1200, v146
	v_add_u32_e32 v27, 0x1400, v146
	v_cvt_pk_f16_f32 v5, v17, v16
	v_cvt_pk_f16_f32 v4, v7, v14
	v_cvt_pk_f16_f32 v3, v9, v12
	v_cvt_pk_f16_f32 v2, v19, v10
	global_store_dwordx4 v[0:1], v[2:5], off offset:3072
	global_load_dword v2, v151, s[64:65] offset:2048
	global_load_dword v0, v152, s[64:65]
	global_load_dword v6, v145, s[64:65]
	global_load_dword v4, v145, s[68:69]
	v_lshlrev_b32_e32 v8, 1, v146
	v_max_i32_e32 v12, 1, v146
	v_add_u32_e32 v13, 0x1e00, v146
	v_cmp_lt_i32_e32 vcc, 0, v146
	v_add_u32_e32 v9, 0x1000, v8
	v_add_u32_e32 v10, 0x2000, v8
	v_add_u32_e32 v11, 0x3000, v8
	v_lshlrev_b32_e32 v12, 1, v12
	v_cndmask_b32_e64 v14, 0, 1.0, vcc
	v_cmp_gt_i32_e32 vcc, 0x1fff, v13
	v_min_i32_e32 v13, 0x1ffe, v13
	v_lshlrev_b32_e32 v13, 1, v13
	s_nop 0
	v_cndmask_b32_e64 v15, 0, 1.0, vcc
	global_load_ushort v163, v12, s[12:13] offset:-2
	global_load_ushort v164, v8, s[12:13]
	global_load_ushort v165, v8, s[12:13] offset:2
	global_load_ushort v166, v12, s[14:15] offset:-2
	global_load_ushort v167, v8, s[14:15]
	global_load_ushort v168, v8, s[14:15] offset:2
	global_load_ushort v169, v8, s[12:13] offset:1022
	global_load_ushort v170, v8, s[12:13] offset:1024
	global_load_ushort v171, v8, s[12:13] offset:1026
	global_load_ushort v172, v8, s[14:15] offset:1022
	global_load_ushort v173, v8, s[14:15] offset:1024
	global_load_ushort v174, v8, s[14:15] offset:1026
	global_load_ushort v175, v8, s[12:13] offset:2046
	global_load_ushort v176, v8, s[12:13] offset:2048
	global_load_ushort v177, v8, s[12:13] offset:2050
	global_load_ushort v178, v8, s[14:15] offset:2046
	global_load_ushort v179, v8, s[14:15] offset:2048
	global_load_ushort v180, v8, s[14:15] offset:2050
	global_load_ushort v181, v8, s[12:13] offset:3070
	global_load_ushort v182, v8, s[12:13] offset:3072
	global_load_ushort v183, v8, s[12:13] offset:3074
	global_load_ushort v184, v8, s[14:15] offset:3070
	global_load_ushort v185, v8, s[14:15] offset:3072
	global_load_ushort v186, v8, s[14:15] offset:3074
	global_load_ushort v187, v9, s[12:13] offset:-2
	global_load_ushort v188, v9, s[12:13]
	global_load_ushort v189, v9, s[12:13] offset:2
	global_load_ushort v190, v9, s[14:15] offset:-2
	global_load_ushort v191, v9, s[14:15]
	global_load_ushort v192, v9, s[14:15] offset:2
	global_load_ushort v193, v9, s[12:13] offset:1022
	global_load_ushort v194, v9, s[12:13] offset:1024
	global_load_ushort v195, v9, s[12:13] offset:1026
	global_load_ushort v196, v9, s[14:15] offset:1022
	global_load_ushort v197, v9, s[14:15] offset:1024
	global_load_ushort v198, v9, s[14:15] offset:1026
	global_load_ushort v199, v9, s[12:13] offset:2046
	global_load_ushort v200, v9, s[12:13] offset:2048
	global_load_ushort v201, v9, s[12:13] offset:2050
	global_load_ushort v202, v9, s[14:15] offset:2046
	global_load_ushort v203, v9, s[14:15] offset:2048
	global_load_ushort v204, v9, s[14:15] offset:2050
	global_load_ushort v205, v9, s[12:13] offset:3070
	global_load_ushort v206, v9, s[12:13] offset:3072
	global_load_ushort v207, v9, s[12:13] offset:3074
	global_load_ushort v208, v9, s[14:15] offset:3070
	global_load_ushort v209, v9, s[14:15] offset:3072
	global_load_ushort v210, v9, s[14:15] offset:3074
	global_load_ushort v211, v10, s[12:13] offset:-2
	global_load_ushort v212, v10, s[12:13]
	global_load_ushort v213, v10, s[12:13] offset:2
	global_load_ushort v221, v10, s[14:15] offset:-2
	global_load_ushort v222, v10, s[14:15]
	global_load_ushort v223, v10, s[14:15] offset:2
	global_load_ushort v224, v10, s[12:13] offset:1022
	global_load_ushort v225, v10, s[12:13] offset:1024
	global_load_ushort v226, v10, s[12:13] offset:1026
	global_load_ushort v227, v10, s[14:15] offset:1022
	global_load_ushort v228, v10, s[14:15] offset:1024
	global_load_ushort v229, v10, s[14:15] offset:1026
	global_load_ushort v230, v10, s[12:13] offset:2046
	global_load_ushort v231, v10, s[12:13] offset:2048
	global_load_ushort v232, v10, s[12:13] offset:2050
	global_load_ushort v233, v10, s[14:15] offset:2046
	global_load_ushort v234, v10, s[14:15] offset:2048
	global_load_ushort v235, v10, s[14:15] offset:2050
	global_load_ushort v236, v10, s[12:13] offset:3070
	global_load_ushort v237, v10, s[12:13] offset:3072
	global_load_ushort v238, v10, s[12:13] offset:3074
	global_load_ushort v239, v10, s[14:15] offset:3070
	global_load_ushort v240, v10, s[14:15] offset:3072
	global_load_ushort v241, v10, s[14:15] offset:3074
	global_load_ushort v242, v11, s[12:13] offset:-2
	global_load_ushort v243, v11, s[12:13]
	global_load_ushort v244, v11, s[12:13] offset:2
	global_load_ushort v245, v11, s[14:15] offset:-2
	global_load_ushort v246, v11, s[14:15]
	global_load_ushort v247, v11, s[14:15] offset:2
	global_load_ushort v248, v11, s[12:13] offset:1022
	global_load_ushort v249, v11, s[12:13] offset:1024
	global_load_ushort v250, v11, s[12:13] offset:1026
	global_load_ushort v251, v11, s[14:15] offset:1022
	global_load_ushort v253, v11, s[14:15] offset:1024
	global_load_ushort v254, v11, s[14:15] offset:1026
	global_load_ushort v255, v11, s[12:13] offset:2046
	global_load_ushort v1, v11, s[12:13] offset:2048
	global_load_ushort v3, v11, s[12:13] offset:2050
	global_load_ushort v5, v11, s[14:15] offset:2046
	global_load_ushort v7, v11, s[14:15] offset:2048
	global_load_ushort v16, v11, s[14:15] offset:2050
	global_load_ushort v17, v11, s[12:13] offset:3070
	global_load_ushort v18, v11, s[12:13] offset:3072
	global_load_ushort v19, v13, s[12:13] offset:2
	global_load_ushort v20, v11, s[14:15] offset:3070
	global_load_ushort v21, v11, s[14:15] offset:3072
	global_load_ushort v22, v13, s[14:15] offset:2
	s_waitcnt vmcnt(48)
	v_lshlrev_b32_e32 v163, 16, v163
	v_lshlrev_b32_e32 v164, 16, v164
	v_lshlrev_b32_e32 v165, 16, v165
	v_mul_f32_e32 v163, v14, v163
	v_mul_f32_e32 v163, v6, v163
	v_fmac_f32_e32 v163, v2, v164
	v_fmac_f32_e32 v163, v0, v165
	v_add_f32_e32 v32, v4, v163
	v_lshlrev_b32_e32 v166, 16, v166
	v_lshlrev_b32_e32 v167, 16, v167
	v_lshlrev_b32_e32 v168, 16, v168
	v_mul_f32_e32 v166, v14, v166
	v_mul_f32_e32 v166, v6, v166
	v_fmac_f32_e32 v166, v2, v167
	v_fmac_f32_e32 v166, v0, v168
	v_add_f32_e32 v34, v4, v166
	v_lshlrev_b32_e32 v169, 16, v169
	v_lshlrev_b32_e32 v170, 16, v170
	v_lshlrev_b32_e32 v171, 16, v171
	v_mul_f32_e32 v169, v6, v169
	v_fmac_f32_e32 v169, v2, v170
	v_fmac_f32_e32 v169, v0, v171
	v_add_f32_e32 v33, v4, v169
	v_lshlrev_b32_e32 v172, 16, v172
	v_lshlrev_b32_e32 v173, 16, v173
	v_lshlrev_b32_e32 v174, 16, v174
	v_mul_f32_e32 v172, v6, v172
	v_fmac_f32_e32 v172, v2, v173
	v_fmac_f32_e32 v172, v0, v174
	v_add_f32_e32 v35, v4, v172
	v_lshlrev_b32_e32 v175, 16, v175
	v_lshlrev_b32_e32 v176, 16, v176
	v_lshlrev_b32_e32 v177, 16, v177
	v_mul_f32_e32 v175, v6, v175
	v_fmac_f32_e32 v175, v2, v176
	v_fmac_f32_e32 v175, v0, v177
	v_add_f32_e32 v37, v4, v175
	v_lshlrev_b32_e32 v178, 16, v178
	v_lshlrev_b32_e32 v179, 16, v179
	v_lshlrev_b32_e32 v180, 16, v180
	v_mul_f32_e32 v178, v6, v178
	v_fmac_f32_e32 v178, v2, v179
	v_fmac_f32_e32 v178, v0, v180
	v_add_f32_e32 v31, v4, v178
	v_lshlrev_b32_e32 v181, 16, v181
	v_lshlrev_b32_e32 v182, 16, v182
	v_lshlrev_b32_e32 v183, 16, v183
	v_mul_f32_e32 v181, v6, v181
	v_fmac_f32_e32 v181, v2, v182
	v_fmac_f32_e32 v181, v0, v183
	v_add_f32_e32 v36, v4, v181
	v_lshlrev_b32_e32 v184, 16, v184
	v_lshlrev_b32_e32 v185, 16, v185
	v_lshlrev_b32_e32 v186, 16, v186
	v_mul_f32_e32 v184, v6, v184
	v_fmac_f32_e32 v184, v2, v185
	v_fmac_f32_e32 v184, v0, v186
	v_add_f32_e32 v30, v4, v184
	v_lshlrev_b32_e32 v187, 16, v187
	v_lshlrev_b32_e32 v188, 16, v188
	v_lshlrev_b32_e32 v189, 16, v189
	v_mul_f32_e32 v187, v6, v187
	v_fmac_f32_e32 v187, v2, v188
	v_fmac_f32_e32 v187, v0, v189
	v_add_f32_e32 v39, v4, v187
	v_lshlrev_b32_e32 v190, 16, v190
	v_lshlrev_b32_e32 v191, 16, v191
	v_lshlrev_b32_e32 v192, 16, v192
	v_mul_f32_e32 v190, v6, v190
	v_fmac_f32_e32 v190, v2, v191
	v_fmac_f32_e32 v190, v0, v192
	v_add_f32_e32 v41, v4, v190
	v_lshlrev_b32_e32 v193, 16, v193
	v_lshlrev_b32_e32 v194, 16, v194
	v_lshlrev_b32_e32 v195, 16, v195
	v_mul_f32_e32 v193, v6, v193
	v_fmac_f32_e32 v193, v2, v194
	v_fmac_f32_e32 v193, v0, v195
	v_add_f32_e32 v38, v4, v193
	v_lshlrev_b32_e32 v196, 16, v196
	v_lshlrev_b32_e32 v197, 16, v197
	v_lshlrev_b32_e32 v198, 16, v198
	v_mul_f32_e32 v196, v6, v196
	v_fmac_f32_e32 v196, v2, v197
	v_fmac_f32_e32 v196, v0, v198
	v_add_f32_e32 v40, v4, v196
	v_lshlrev_b32_e32 v199, 16, v199
	v_lshlrev_b32_e32 v200, 16, v200
	v_lshlrev_b32_e32 v201, 16, v201
	v_mul_f32_e32 v199, v6, v199
	v_fmac_f32_e32 v199, v2, v200
	v_fmac_f32_e32 v199, v0, v201
	v_add_f32_e32 v43, v4, v199
	v_lshlrev_b32_e32 v202, 16, v202
	v_lshlrev_b32_e32 v203, 16, v203
	v_lshlrev_b32_e32 v204, 16, v204
	v_mul_f32_e32 v202, v6, v202
	v_fmac_f32_e32 v202, v2, v203
	v_fmac_f32_e32 v202, v0, v204
	v_add_f32_e32 v45, v4, v202
	v_lshlrev_b32_e32 v205, 16, v205
	v_lshlrev_b32_e32 v206, 16, v206
	v_lshlrev_b32_e32 v207, 16, v207
	v_mul_f32_e32 v205, v6, v205
	v_fmac_f32_e32 v205, v2, v206
	v_fmac_f32_e32 v205, v0, v207
	v_add_f32_e32 v42, v4, v205
	v_lshlrev_b32_e32 v208, 16, v208
	v_lshlrev_b32_e32 v209, 16, v209
	v_lshlrev_b32_e32 v210, 16, v210
	v_mul_f32_e32 v208, v6, v208
	v_fmac_f32_e32 v208, v2, v209
	v_fmac_f32_e32 v208, v0, v210
	v_add_f32_e32 v44, v4, v208
	s_waitcnt vmcnt(0)
	v_lshlrev_b32_e32 v211, 16, v211
	v_lshlrev_b32_e32 v212, 16, v212
	v_lshlrev_b32_e32 v213, 16, v213
	v_mul_f32_e32 v211, v6, v211
	v_fmac_f32_e32 v211, v2, v212
	v_fmac_f32_e32 v211, v0, v213
	v_add_f32_e32 v47, v4, v211
	v_lshlrev_b32_e32 v221, 16, v221
	v_lshlrev_b32_e32 v222, 16, v222
	v_lshlrev_b32_e32 v223, 16, v223
	v_mul_f32_e32 v221, v6, v221
	v_fmac_f32_e32 v221, v2, v222
	v_fmac_f32_e32 v221, v0, v223
	v_add_f32_e32 v49, v4, v221
	v_lshlrev_b32_e32 v224, 16, v224
	v_lshlrev_b32_e32 v225, 16, v225
	v_lshlrev_b32_e32 v226, 16, v226
	v_mul_f32_e32 v224, v6, v224
	v_fmac_f32_e32 v224, v2, v225
	v_fmac_f32_e32 v224, v0, v226
	v_add_f32_e32 v46, v4, v224
	v_lshlrev_b32_e32 v227, 16, v227
	v_lshlrev_b32_e32 v228, 16, v228
	v_lshlrev_b32_e32 v229, 16, v229
	v_mul_f32_e32 v227, v6, v227
	v_fmac_f32_e32 v227, v2, v228
	v_fmac_f32_e32 v227, v0, v229
	v_add_f32_e32 v48, v4, v227
	v_lshlrev_b32_e32 v230, 16, v230
	v_lshlrev_b32_e32 v231, 16, v231
	v_lshlrev_b32_e32 v232, 16, v232
	v_mul_f32_e32 v230, v6, v230
	v_fmac_f32_e32 v230, v2, v231
	v_fmac_f32_e32 v230, v0, v232
	v_add_f32_e32 v51, v4, v230
	v_lshlrev_b32_e32 v233, 16, v233
	v_lshlrev_b32_e32 v234, 16, v234
	v_lshlrev_b32_e32 v235, 16, v235
	v_mul_f32_e32 v233, v6, v233
	v_fmac_f32_e32 v233, v2, v234
	v_fmac_f32_e32 v233, v0, v235
	v_add_f32_e32 v53, v4, v233
	v_lshlrev_b32_e32 v236, 16, v236
	v_lshlrev_b32_e32 v237, 16, v237
	v_lshlrev_b32_e32 v238, 16, v238
	v_mul_f32_e32 v236, v6, v236
	v_fmac_f32_e32 v236, v2, v237
	v_fmac_f32_e32 v236, v0, v238
	v_add_f32_e32 v50, v4, v236
	v_lshlrev_b32_e32 v239, 16, v239
	v_lshlrev_b32_e32 v240, 16, v240
	v_lshlrev_b32_e32 v241, 16, v241
	v_mul_f32_e32 v239, v6, v239
	v_fmac_f32_e32 v239, v2, v240
	v_fmac_f32_e32 v239, v0, v241
	v_add_f32_e32 v52, v4, v239
	v_lshlrev_b32_e32 v242, 16, v242
	v_lshlrev_b32_e32 v243, 16, v243
	v_lshlrev_b32_e32 v244, 16, v244
	v_mul_f32_e32 v242, v6, v242
	v_fmac_f32_e32 v242, v2, v243
	v_fmac_f32_e32 v242, v0, v244
	v_add_f32_e32 v55, v4, v242
	v_lshlrev_b32_e32 v245, 16, v245
	v_lshlrev_b32_e32 v246, 16, v246
	v_lshlrev_b32_e32 v247, 16, v247
	v_mul_f32_e32 v245, v6, v245
	v_fmac_f32_e32 v245, v2, v246
	v_fmac_f32_e32 v245, v0, v247
	v_add_f32_e32 v57, v4, v245
	v_lshlrev_b32_e32 v248, 16, v248
	v_lshlrev_b32_e32 v249, 16, v249
	v_lshlrev_b32_e32 v250, 16, v250
	v_mul_f32_e32 v248, v6, v248
	v_fmac_f32_e32 v248, v2, v249
	v_fmac_f32_e32 v248, v0, v250
	v_add_f32_e32 v54, v4, v248
	v_lshlrev_b32_e32 v251, 16, v251
	v_lshlrev_b32_e32 v253, 16, v253
	v_lshlrev_b32_e32 v254, 16, v254
	v_mul_f32_e32 v251, v6, v251
	v_fmac_f32_e32 v251, v2, v253
	v_fmac_f32_e32 v251, v0, v254
	v_add_f32_e32 v56, v4, v251
	v_lshlrev_b32_e32 v255, 16, v255
	v_lshlrev_b32_e32 v1, 16, v1
	v_lshlrev_b32_e32 v3, 16, v3
	v_mul_f32_e32 v255, v6, v255
	v_fmac_f32_e32 v255, v2, v1
	v_fmac_f32_e32 v255, v0, v3
	v_add_f32_e32 v59, v4, v255
	v_lshlrev_b32_e32 v5, 16, v5
	v_lshlrev_b32_e32 v7, 16, v7
	v_lshlrev_b32_e32 v16, 16, v16
	v_mul_f32_e32 v5, v6, v5
	v_fmac_f32_e32 v5, v2, v7
	v_fmac_f32_e32 v5, v0, v16
	v_add_f32_e32 v61, v4, v5
	v_lshlrev_b32_e32 v17, 16, v17
	v_lshlrev_b32_e32 v18, 16, v18
	v_lshlrev_b32_e32 v19, 16, v19
	v_mul_f32_e32 v19, v15, v19
	v_mul_f32_e32 v17, v6, v17
	v_fmac_f32_e32 v17, v2, v18
	v_fmac_f32_e32 v17, v0, v19
	v_add_f32_e32 v58, v4, v17
	v_lshlrev_b32_e32 v20, 16, v20
	v_lshlrev_b32_e32 v21, 16, v21
	v_lshlrev_b32_e32 v22, 16, v22
	v_mul_f32_e32 v22, v15, v22
	v_mul_f32_e32 v20, v6, v20
	v_fmac_f32_e32 v20, v2, v21
	v_fmac_f32_e32 v20, v0, v22
	v_add_f32_e32 v60, v4, v20
	v_readlane_b32 s0, v252, 43
	s_add_u32 s45, s0, s10
	v_readlane_b32 s0, v252, 42
	s_addc_u32 s24, s0, s11
	s_lshl_b64 s[0:1], s[62:63], 1
	v_readlane_b32 s4, v252, 60
	s_add_u32 s70, s4, s0
	v_readlane_b32 s0, v252, 61
	s_addc_u32 s71, s0, s1
	s_mov_b64 s[14:15], -1
	s_branch .LBB0_910
